# GEMM LDS-DMA issue spread across the k-step; attn tile loop: cross-half max via permlane32_swap, no self-max canonicalisation, mask bit extraction hoisted into the QK MFMA shadow; thr rank scan via DP
# speedup vs baseline: 1.1432x; 1.0115x over previous
; #define MFMA(a, b, c) __builtin_amdgcn_mfma_f32_32x32x16_bf16((a), (b), (c), 0, 0, 0)
; #define WAIT_V(n) asm volatile("s_waitcnt vmcnt(%0)" ::"n"(n) : "memory")
; #define RAW_BARRIER() do { asm volatile("s_waitcnt lgkmcnt(0)" ::: "memory"); __builtin_amdgcn_s_barrier(); asm volatile("" ::: "memory"); } while (0)
; #define GLDS_STAGE(slot, kt) do { _Pragma("unroll") for (int i = 0; i < 6; ++i) \
;     __builtin_amdgcn_global_load_lds((const unsigned*)(src[i] + (kt) * 64), (__attribute__((address_space(3))) unsigned*)(smem + (slot) * G_STAGE + (wave + 8 * i) * 1024), 16, 0, 0); } while (0)
; DI void gemm_tile(const u16* __restrict__ X, int ldx, const u16* __restrict__ Wt, int ldw, int K, char* smem,
;                   f32x16 (&acc)[2][2]) {
;     ...
;   const int nk = K / 64;
;   const u16* src[6];
; #pragma unroll
;   for (int i = 0; i < 6; ++i) {
;     const int R = 8 * (wave + 8 * i) + (lane >> 3);
;     const int c = (lane & 7) ^ ((R >> 1) & 7);
;     src[i] = (i < 4) ? (X + (size_t)R * ldx + c * 8) : (Wt + (size_t)(R - 256) * ldw + c * 8);
;   }
;     ...
;   int offA[2], offB[2], xa[2], xb[2];
; #pragma unroll
;   for (int ft = 0; ft < 2; ++ft) { const int R = 256 + fw * 64 + ft * 32 + lr; offA[ft] = R * 128; xa[ft] = (R >> 1) & 7; }
; #pragma unroll
;   for (int tt = 0; tt < 2; ++tt) { const int R = tq * 64 + tt * 32 + lr; offB[tt] = R * 128; xb[tt] = (R >> 1) & 7; }
;   GLDS_STAGE(0, 0); GLDS_STAGE(1, 1); WAIT_V(6); RAW_BARRIER();
;   int cur = 0;
;   for (int kt = 0; kt < nk; ++kt) {
;     const int nxt = (cur >= 1) ? cur - 1 : 2;
;     if (kt + 2 < nk) GLDS_STAGE(nxt, kt + 2);
;     __builtin_amdgcn_sched_barrier(0);
;     const char* st = smem + cur * G_STAGE;
; #pragma unroll
;     for (int ks = 0; ks < 4; ++ks) {
;       bf16x8 a[2], b[2];
; #pragma unroll
;       for (int ft = 0; ft < 2; ++ft) a[ft] = *reinterpret_cast<const bf16x8*>(st + offA[ft] + (((ks * 2 + lh) ^ xa[ft]) << 4));
; #pragma unroll
;       for (int tt = 0; tt < 2; ++tt) b[tt] = *reinterpret_cast<const bf16x8*>(st + offB[tt] + (((ks * 2 + lh) ^ xb[tt]) << 4));
; #pragma unroll
;       for (int ft = 0; ft < 2; ++ft)
; #pragma unroll
;         for (int tt = 0; tt < 2; ++tt) acc[ft][tt] = MFMA(a[ft], b[tt], acc[ft][tt]);
;     }
;     if (kt + 2 < nk) { WAIT_V(6); } else { WAIT_V(0); }
;     RAW_BARRIER();
;     cur = (cur == 2) ? 0 : cur + 1;
;   }
.LBB0_145:
	s_bfe_u32 s8, s10, 0x30003
	s_and_b32 s9, s10, 7
	s_and_b32 s11, s10, 0x7fffffc0
	s_cmpk_lg_i32 s11, 0xd80
	s_cselect_b64 s[6:7], -1, 0
	s_cmpk_eq_i32 s11, 0xd80
	s_mov_b32 s11, 0x8ac0000
	s_cselect_b32 s11, s11, 0x8cc0000
	s_add_u32 s11, s96, s11
	s_addc_u32 s13, s97, 0
	s_lshl_b32 s9, s9, 18
	s_add_u32 s12, s11, s9
	s_addc_u32 s13, s13, 0
	s_lshl_b32 s18, s8, 19
	v_lshl_add_u64 v[0:1], v[90:91], 0, s[18:19]
	v_lshl_add_u64 v[66:67], v[0:1], 0, v[86:87]
	s_mov_b64 s[16:17], 0x40000
	v_lshl_add_u64 v[2:3], v[66:67], 0, s[16:17]
	s_mov_b64 s[16:17], 0x60000
	v_lshl_add_u64 v[4:5], v[66:67], 0, s[16:17]
	v_lshl_add_u64 v[6:7], s[12:13], 0, v[84:85]
	v_readfirstlane_b32 s17, v101
	s_mov_b64 s[14:15], 0x20000
	v_lshl_add_u64 v[64:65], v[6:7], 0, v[86:87]
	s_mov_b32 m0, s17
	v_readfirstlane_b32 s16, v211
	v_lshl_add_u64 v[0:1], v[66:67], 0, s[14:15]
	v_lshl_add_u64 v[6:7], v[64:65], 0, s[14:15]
	global_load_lds_dwordx4 v[66:67], off
	s_mov_b32 m0, s16
	v_readfirstlane_b32 s15, v214
	global_load_lds_dwordx4 v[0:1], off
	s_mov_b32 m0, s15
	v_readfirstlane_b32 s14, v215
	global_load_lds_dwordx4 v[2:3], off
	s_mov_b32 m0, s14
	v_readfirstlane_b32 s13, v216
	global_load_lds_dwordx4 v[4:5], off
	s_mov_b32 m0, s13
	v_readfirstlane_b32 s12, v217
	global_load_lds_dwordx4 v[64:65], off
	s_mov_b32 m0, s12
	s_mov_b64 s[24:25], 0x80
	v_readfirstlane_b32 s11, v103
	global_load_lds_dwordx4 v[6:7], off
	v_lshl_add_u64 v[0:1], v[66:67], 0, s[24:25]
	s_mov_b32 m0, s11
	s_mov_b64 s[30:31], 0x20080
	v_readfirstlane_b32 s9, v218
	global_load_lds_dwordx4 v[0:1], off
	v_lshl_add_u64 v[0:1], v[66:67], 0, s[30:31]
	s_mov_b32 m0, s9
	s_mov_b64 s[34:35], 0x40080
	v_readfirstlane_b32 s18, v219
	global_load_lds_dwordx4 v[0:1], off
	v_lshl_add_u64 v[0:1], v[66:67], 0, s[34:35]
	s_mov_b32 m0, s18
	s_mov_b64 s[34:35], 0x60080
	v_readfirstlane_b32 s18, v220
	global_load_lds_dwordx4 v[0:1], off
	v_lshl_add_u64 v[0:1], v[66:67], 0, s[34:35]
	s_mov_b32 m0, s18
	v_readfirstlane_b32 s18, v221
	global_load_lds_dwordx4 v[0:1], off
	v_lshl_add_u64 v[0:1], v[64:65], 0, s[24:25]
	s_mov_b32 m0, s18
	v_readfirstlane_b32 s18, v222
	global_load_lds_dwordx4 v[0:1], off
	v_lshl_add_u64 v[0:1], v[64:65], 0, s[30:31]
	s_mov_b32 m0, s18
	s_mov_b64 s[24:25], 0x100
	global_load_lds_dwordx4 v[0:1], off
	s_waitcnt vmcnt(6)
	v_readfirstlane_b32 s70, v121
	s_waitcnt lgkmcnt(0)
	s_barrier
	v_lshl_add_u64 v[0:1], v[66:67], 0, s[24:25]
	s_mov_b32 m0, s70
	s_mov_b64 s[48:49], 0x20100
	v_readfirstlane_b32 s55, v123
	global_load_lds_dwordx4 v[0:1], off
	v_lshl_add_u64 v[0:1], v[66:67], 0, s[48:49]
	s_mov_b32 m0, s55
	s_mov_b64 s[30:31], 0x40100
	v_readfirstlane_b32 s35, v125
	global_load_lds_dwordx4 v[0:1], off
	v_lshl_add_u64 v[0:1], v[66:67], 0, s[30:31]
	s_mov_b32 m0, s35
	s_mov_b64 s[30:31], 0x60100
	v_readfirstlane_b32 s54, v127
	global_load_lds_dwordx4 v[0:1], off
	v_lshl_add_u64 v[0:1], v[66:67], 0, s[30:31]
	s_mov_b32 m0, s54
	v_readfirstlane_b32 s31, v163
	global_load_lds_dwordx4 v[0:1], off
	v_lshl_add_u64 v[0:1], v[64:65], 0, s[24:25]
	s_mov_b32 m0, s31
	v_readfirstlane_b32 s34, v165
	global_load_lds_dwordx4 v[0:1], off
	v_lshl_add_u64 v[0:1], v[64:65], 0, s[48:49]
	s_mov_b32 m0, s34
	s_nop 0
	global_load_lds_dwordx4 v[0:1], off
	ds_read_b128 v[0:3], v223 offset:32768
	ds_read_b128 v[4:7], v223 offset:36864
	ds_read_b128 v[8:11], v224
	ds_read_b128 v[12:15], v224 offset:4096
	ds_read_b128 v[68:71], v225 offset:32768
	ds_read_b128 v[72:75], v225 offset:36864
	ds_read_b128 v[76:79], v226
	ds_read_b128 v[80:83], v226 offset:4096
	s_mov_b64 s[24:25], 0x180
	s_mov_b32 m0, s17
	s_waitcnt lgkmcnt(0)
	v_mfma_f32_32x32x16_bf16 v[48:63], v[0:3], v[8:11], 0
	s_mov_b64 s[48:49], 0x40180
	v_mfma_f32_32x32x16_bf16 v[16:31], v[0:3], v[12:15], 0
	v_mfma_f32_32x32x16_bf16 v[32:47], v[4:7], v[8:11], 0
	v_mfma_f32_32x32x16_bf16 v[0:15], v[4:7], v[12:15], 0
	ds_read_b128 v[184:187], v227 offset:32768
	ds_read_b128 v[188:191], v227 offset:36864
	ds_read_b128 v[192:195], v228
	ds_read_b128 v[196:199], v228 offset:4096
	s_waitcnt lgkmcnt(4)
	v_mfma_f32_32x32x16_bf16 v[48:63], v[68:71], v[76:79], v[48:63]
	v_mfma_f32_32x32x16_bf16 v[16:31], v[68:71], v[80:83], v[16:31]
	v_mfma_f32_32x32x16_bf16 v[32:47], v[72:75], v[76:79], v[32:47]
	v_mfma_f32_32x32x16_bf16 v[0:15], v[72:75], v[80:83], v[0:15]
	ds_read_b128 v[68:71], v229 offset:32768
	ds_read_b128 v[72:75], v229 offset:36864
	ds_read_b128 v[76:79], v230
	ds_read_b128 v[80:83], v230 offset:4096
	s_waitcnt lgkmcnt(4)
	v_mfma_f32_32x32x16_bf16 v[48:63], v[184:187], v[192:195], v[48:63]
	v_mfma_f32_32x32x16_bf16 v[16:31], v[184:187], v[196:199], v[16:31]
	v_mfma_f32_32x32x16_bf16 v[32:47], v[188:191], v[192:195], v[32:47]
	v_mfma_f32_32x32x16_bf16 v[0:15], v[188:191], v[196:199], v[0:15]
	s_waitcnt vmcnt(6)
	s_waitcnt lgkmcnt(0)
	s_barrier
; #define MFMA(a, b, c) __builtin_amdgcn_mfma_f32_32x32x16_bf16((a), (b), (c), 0, 0, 0)
; #define WAIT_V(n) asm volatile("s_waitcnt vmcnt(%0)" ::"n"(n) : "memory")
; #define RAW_BARRIER() do { asm volatile("s_waitcnt lgkmcnt(0)" ::: "memory"); __builtin_amdgcn_s_barrier(); asm volatile("" ::: "memory"); } while (0)
; #define GLDS_STAGE(slot, kt) do { _Pragma("unroll") for (int i = 0; i < 6; ++i) \
;     __builtin_amdgcn_global_load_lds((const unsigned*)(src[i] + (kt) * 64), (__attribute__((address_space(3))) unsigned*)(smem + (slot) * G_STAGE + (wave + 8 * i) * 1024), 16, 0, 0); } while (0)
; DI void gemm_tile(const u16* __restrict__ X, int ldx, const u16* __restrict__ Wt, int ldw, int K, char* smem,
;                   f32x16 (&acc)[2][2]) {
;     ...
;   int offA[2], offB[2], xa[2], xb[2];
; #pragma unroll
;   for (int ft = 0; ft < 2; ++ft) { const int R = 256 + fw * 64 + ft * 32 + lr; offA[ft] = R * 128; xa[ft] = (R >> 1) & 7; }
; #pragma unroll
;   for (int tt = 0; tt < 2; ++tt) { const int R = tq * 64 + tt * 32 + lr; offB[tt] = R * 128; xb[tt] = (R >> 1) & 7; }
;   GLDS_STAGE(0, 0); GLDS_STAGE(1, 1); WAIT_V(6); RAW_BARRIER();
;   int cur = 0;
;   for (int kt = 0; kt < nk; ++kt) {
;     const int nxt = (cur >= 1) ? cur - 1 : 2;
;     if (kt + 2 < nk) GLDS_STAGE(nxt, kt + 2);
;     __builtin_amdgcn_sched_barrier(0);
;     const char* st = smem + cur * G_STAGE;
; #pragma unroll
;     for (int ks = 0; ks < 4; ++ks) {
;       bf16x8 a[2], b[2];
; #pragma unroll
;       for (int ft = 0; ft < 2; ++ft) a[ft] = *reinterpret_cast<const bf16x8*>(st + offA[ft] + (((ks * 2 + lh) ^ xa[ft]) << 4));
; #pragma unroll
;       for (int tt = 0; tt < 2; ++tt) b[tt] = *reinterpret_cast<const bf16x8*>(st + offB[tt] + (((ks * 2 + lh) ^ xb[tt]) << 4));
; #pragma unroll
;       for (int ft = 0; ft < 2; ++ft)
; #pragma unroll
;         for (int tt = 0; tt < 2; ++tt) acc[ft][tt] = MFMA(a[ft], b[tt], acc[ft][tt]);
;     }
;     if (kt + 2 < nk) { WAIT_V(6); } else { WAIT_V(0); }
;     RAW_BARRIER();
	ds_read_b128 v[184:187], v231 offset:32768
	ds_read_b128 v[188:191], v231 offset:36864
	ds_read_b128 v[192:195], v224 offset:49152
	ds_read_b128 v[196:199], v224 offset:53248
	s_waitcnt lgkmcnt(4)
	v_mfma_f32_32x32x16_bf16 v[48:63], v[68:71], v[76:79], v[48:63]
	v_mfma_f32_32x32x16_bf16 v[16:31], v[68:71], v[80:83], v[16:31]
	v_lshl_add_u64 v[68:69], v[66:67], 0, s[24:25]
	global_load_lds_dwordx4 v[68:69], off
	v_mfma_f32_32x32x16_bf16 v[32:47], v[72:75], v[76:79], v[32:47]
	v_mfma_f32_32x32x16_bf16 v[0:15], v[72:75], v[80:83], v[0:15]
	v_lshl_add_u64 v[68:69], v[66:67], 0, s[50:51]
	s_mov_b32 m0, s16
	s_nop 0
	global_load_lds_dwordx4 v[68:69], off
	ds_read_b128 v[68:71], v232 offset:32768
	ds_read_b128 v[72:75], v232 offset:36864
	ds_read_b128 v[76:79], v226 offset:49152
	ds_read_b128 v[80:83], v226 offset:53248
	s_waitcnt lgkmcnt(4)
	v_mfma_f32_32x32x16_bf16 v[48:63], v[184:187], v[192:195], v[48:63]
	v_mfma_f32_32x32x16_bf16 v[16:31], v[184:187], v[196:199], v[16:31]
	v_lshl_add_u64 v[252:253], v[66:67], 0, s[48:49]
	s_mov_b32 m0, s15
	s_mov_b64 s[48:49], 0x60180
	global_load_lds_dwordx4 v[252:253], off
	v_mfma_f32_32x32x16_bf16 v[32:47], v[188:191], v[192:195], v[32:47]
	v_mfma_f32_32x32x16_bf16 v[0:15], v[188:191], v[196:199], v[0:15]
	v_lshl_add_u64 v[252:253], v[66:67], 0, s[48:49]
	s_mov_b32 m0, s14
	s_nop 0
	global_load_lds_dwordx4 v[252:253], off
	ds_read_b128 v[184:187], v233 offset:32768
	ds_read_b128 v[188:191], v233 offset:36864
	ds_read_b128 v[192:195], v228 offset:49152
	ds_read_b128 v[196:199], v228 offset:53248
	s_waitcnt lgkmcnt(4)
	v_mfma_f32_32x32x16_bf16 v[48:63], v[68:71], v[76:79], v[48:63]
	v_mfma_f32_32x32x16_bf16 v[16:31], v[68:71], v[80:83], v[16:31]
	v_lshl_add_u64 v[252:253], v[64:65], 0, s[24:25]
	s_mov_b32 m0, s13
	s_nop 0
	global_load_lds_dwordx4 v[252:253], off
	v_mfma_f32_32x32x16_bf16 v[32:47], v[72:75], v[76:79], v[32:47]
	v_mfma_f32_32x32x16_bf16 v[0:15], v[72:75], v[80:83], v[0:15]
	v_lshl_add_u64 v[252:253], v[64:65], 0, s[50:51]
	s_mov_b32 m0, s12
	s_nop 0
	global_load_lds_dwordx4 v[252:253], off
	s_mov_b32 m0, s11
	s_mov_b64 s[24:25], 0x40200
	v_readfirstlane_b32 s18, v173
	v_readfirstlane_b32 s30, v202
	ds_read_b128 v[68:71], v234 offset:32768
	ds_read_b128 v[72:75], v234 offset:36864
	ds_read_b128 v[76:79], v230 offset:49152
	ds_read_b128 v[80:83], v230 offset:53248
	s_waitcnt lgkmcnt(4)
	v_mfma_f32_32x32x16_bf16 v[48:63], v[184:187], v[192:195], v[48:63]
	v_mfma_f32_32x32x16_bf16 v[16:31], v[184:187], v[196:199], v[16:31]
	v_mfma_f32_32x32x16_bf16 v[32:47], v[188:191], v[192:195], v[32:47]
	v_mfma_f32_32x32x16_bf16 v[0:15], v[188:191], v[196:199], v[0:15]
	s_waitcnt vmcnt(6)
	s_waitcnt lgkmcnt(0)
	s_barrier
	ds_read_b128 v[184:187], v235 offset:32768
	ds_read_b128 v[188:191], v235 offset:36864
	ds_read_b128 v[192:195], v236
	ds_read_b128 v[196:199], v236 offset:4096
	s_waitcnt lgkmcnt(4)
	v_mfma_f32_32x32x16_bf16 v[48:63], v[68:71], v[76:79], v[48:63]
	v_mfma_f32_32x32x16_bf16 v[16:31], v[68:71], v[80:83], v[16:31]
	v_lshl_add_u64 v[68:69], v[66:67], 0, s[58:59]
	global_load_lds_dwordx4 v[68:69], off
	v_mfma_f32_32x32x16_bf16 v[32:47], v[72:75], v[76:79], v[32:47]
	v_mfma_f32_32x32x16_bf16 v[0:15], v[72:75], v[80:83], v[0:15]
	v_lshl_add_u64 v[68:69], v[66:67], 0, s[60:61]
	s_mov_b32 m0, s9
	s_nop 0
	global_load_lds_dwordx4 v[68:69], off
	ds_read_b128 v[68:71], v237 offset:32768
	ds_read_b128 v[72:75], v237 offset:36864
	ds_read_b128 v[76:79], v238
	ds_read_b128 v[80:83], v238 offset:4096
	s_waitcnt lgkmcnt(4)
	v_mfma_f32_32x32x16_bf16 v[48:63], v[184:187], v[192:195], v[48:63]
	v_mfma_f32_32x32x16_bf16 v[16:31], v[184:187], v[196:199], v[16:31]
	v_lshl_add_u64 v[252:253], v[66:67], 0, s[24:25]
	s_mov_b32 m0, s18
	s_mov_b64 s[24:25], 0x60200
	global_load_lds_dwordx4 v[252:253], off
	v_mfma_f32_32x32x16_bf16 v[32:47], v[188:191], v[192:195], v[32:47]
	v_mfma_f32_32x32x16_bf16 v[0:15], v[188:191], v[196:199], v[0:15]
	v_lshl_add_u64 v[252:253], v[66:67], 0, s[24:25]
	v_readfirstlane_b32 s25, v200
	s_mov_b32 m0, s25
	v_readfirstlane_b32 s24, v201
	global_load_lds_dwordx4 v[252:253], off
	ds_read_b128 v[184:187], v239 offset:32768
	ds_read_b128 v[188:191], v239 offset:36864
	ds_read_b128 v[192:195], v240
	ds_read_b128 v[196:199], v240 offset:4096
	s_waitcnt lgkmcnt(4)
	v_mfma_f32_32x32x16_bf16 v[48:63], v[68:71], v[76:79], v[48:63]
	v_mfma_f32_32x32x16_bf16 v[16:31], v[68:71], v[80:83], v[16:31]
	v_lshl_add_u64 v[252:253], v[64:65], 0, s[58:59]
	s_mov_b32 m0, s24
	s_nop 0
	global_load_lds_dwordx4 v[252:253], off
	v_mfma_f32_32x32x16_bf16 v[32:47], v[72:75], v[76:79], v[32:47]
	v_mfma_f32_32x32x16_bf16 v[0:15], v[72:75], v[80:83], v[0:15]
	v_lshl_add_u64 v[252:253], v[64:65], 0, s[60:61]
	s_mov_b32 m0, s30
	s_nop 0
	global_load_lds_dwordx4 v[252:253], off
	s_mov_b32 m0, s70
	s_mov_b64 s[48:49], 0x40280
	ds_read_b128 v[68:71], v241 offset:32768
	ds_read_b128 v[72:75], v241 offset:36864
	ds_read_b128 v[76:79], v242
	ds_read_b128 v[80:83], v242 offset:4096
	s_waitcnt lgkmcnt(4)
	v_mfma_f32_32x32x16_bf16 v[48:63], v[184:187], v[192:195], v[48:63]
	v_mfma_f32_32x32x16_bf16 v[16:31], v[184:187], v[196:199], v[16:31]
	v_mfma_f32_32x32x16_bf16 v[32:47], v[188:191], v[192:195], v[32:47]
	v_mfma_f32_32x32x16_bf16 v[0:15], v[188:191], v[196:199], v[0:15]
	s_waitcnt vmcnt(6)
	s_waitcnt lgkmcnt(0)
	s_barrier
; #define MFMA(a, b, c) __builtin_amdgcn_mfma_f32_32x32x16_bf16((a), (b), (c), 0, 0, 0)
; #define WAIT_V(n) asm volatile("s_waitcnt vmcnt(%0)" ::"n"(n) : "memory")
; #define RAW_BARRIER() do { asm volatile("s_waitcnt lgkmcnt(0)" ::: "memory"); __builtin_amdgcn_s_barrier(); asm volatile("" ::: "memory"); } while (0)
; #define GLDS_STAGE(slot, kt) do { _Pragma("unroll") for (int i = 0; i < 6; ++i) \
;     __builtin_amdgcn_global_load_lds((const unsigned*)(src[i] + (kt) * 64), (__attribute__((address_space(3))) unsigned*)(smem + (slot) * G_STAGE + (wave + 8 * i) * 1024), 16, 0, 0); } while (0)
; DI void gemm_tile(const u16* __restrict__ X, int ldx, const u16* __restrict__ Wt, int ldw, int K, char* smem,
;                   f32x16 (&acc)[2][2]) {
;     ...
;   int offA[2], offB[2], xa[2], xb[2];
; #pragma unroll
;   for (int ft = 0; ft < 2; ++ft) { const int R = 256 + fw * 64 + ft * 32 + lr; offA[ft] = R * 128; xa[ft] = (R >> 1) & 7; }
; #pragma unroll
;   for (int tt = 0; tt < 2; ++tt) { const int R = tq * 64 + tt * 32 + lr; offB[tt] = R * 128; xb[tt] = (R >> 1) & 7; }
;   GLDS_STAGE(0, 0); GLDS_STAGE(1, 1); WAIT_V(6); RAW_BARRIER();
;   int cur = 0;
;   for (int kt = 0; kt < nk; ++kt) {
;     const int nxt = (cur >= 1) ? cur - 1 : 2;
;     if (kt + 2 < nk) GLDS_STAGE(nxt, kt + 2);
;     __builtin_amdgcn_sched_barrier(0);
;     const char* st = smem + cur * G_STAGE;
; #pragma unroll
;     for (int ks = 0; ks < 4; ++ks) {
;       bf16x8 a[2], b[2];
; #pragma unroll
;       for (int ft = 0; ft < 2; ++ft) a[ft] = *reinterpret_cast<const bf16x8*>(st + offA[ft] + (((ks * 2 + lh) ^ xa[ft]) << 4));
; #pragma unroll
;       for (int tt = 0; tt < 2; ++tt) b[tt] = *reinterpret_cast<const bf16x8*>(st + offB[tt] + (((ks * 2 + lh) ^ xb[tt]) << 4));
; #pragma unroll
;       for (int ft = 0; ft < 2; ++ft)
; #pragma unroll
;         for (int tt = 0; tt < 2; ++tt) acc[ft][tt] = MFMA(a[ft], b[tt], acc[ft][tt]);
;     }
;     if (kt + 2 < nk) { WAIT_V(6); } else { WAIT_V(0); }
;     RAW_BARRIER();
	ds_read_b128 v[184:187], v223 offset:32768
	ds_read_b128 v[188:191], v223 offset:36864
	ds_read_b128 v[192:195], v224
	ds_read_b128 v[196:199], v224 offset:4096
	s_waitcnt lgkmcnt(4)
	v_mfma_f32_32x32x16_bf16 v[48:63], v[68:71], v[76:79], v[48:63]
	v_mfma_f32_32x32x16_bf16 v[16:31], v[68:71], v[80:83], v[16:31]
	v_lshl_add_u64 v[68:69], v[66:67], 0, s[66:67]
	global_load_lds_dwordx4 v[68:69], off
	v_mfma_f32_32x32x16_bf16 v[32:47], v[72:75], v[76:79], v[32:47]
	v_mfma_f32_32x32x16_bf16 v[0:15], v[72:75], v[80:83], v[0:15]
	v_lshl_add_u64 v[68:69], v[66:67], 0, s[68:69]
	s_mov_b32 m0, s55
	s_nop 0
	global_load_lds_dwordx4 v[68:69], off
	ds_read_b128 v[68:71], v225 offset:32768
	ds_read_b128 v[72:75], v225 offset:36864
	ds_read_b128 v[76:79], v226
	ds_read_b128 v[80:83], v226 offset:4096
	s_waitcnt lgkmcnt(4)
	v_mfma_f32_32x32x16_bf16 v[48:63], v[184:187], v[192:195], v[48:63]
	v_mfma_f32_32x32x16_bf16 v[16:31], v[184:187], v[196:199], v[16:31]
	v_lshl_add_u64 v[252:253], v[66:67], 0, s[48:49]
	s_mov_b32 m0, s35
	s_mov_b64 s[48:49], 0x60280
	global_load_lds_dwordx4 v[252:253], off
	v_mfma_f32_32x32x16_bf16 v[32:47], v[188:191], v[192:195], v[32:47]
	v_mfma_f32_32x32x16_bf16 v[0:15], v[188:191], v[196:199], v[0:15]
	v_lshl_add_u64 v[252:253], v[66:67], 0, s[48:49]
	s_mov_b32 m0, s54
	s_nop 0
	global_load_lds_dwordx4 v[252:253], off
	ds_read_b128 v[184:187], v227 offset:32768
	ds_read_b128 v[188:191], v227 offset:36864
	ds_read_b128 v[192:195], v228
	ds_read_b128 v[196:199], v228 offset:4096
	s_waitcnt lgkmcnt(4)
	v_mfma_f32_32x32x16_bf16 v[48:63], v[68:71], v[76:79], v[48:63]
	v_mfma_f32_32x32x16_bf16 v[16:31], v[68:71], v[80:83], v[16:31]
	v_lshl_add_u64 v[252:253], v[64:65], 0, s[66:67]
	s_mov_b32 m0, s31
	s_nop 0
	global_load_lds_dwordx4 v[252:253], off
	v_mfma_f32_32x32x16_bf16 v[32:47], v[72:75], v[76:79], v[32:47]
	v_mfma_f32_32x32x16_bf16 v[0:15], v[72:75], v[80:83], v[0:15]
	v_lshl_add_u64 v[252:253], v[64:65], 0, s[68:69]
	s_mov_b32 m0, s34
	s_nop 0
	global_load_lds_dwordx4 v[252:253], off
	s_mov_b32 m0, s17
	s_mov_b64 s[48:49], 0x40300
	ds_read_b128 v[68:71], v229 offset:32768
	ds_read_b128 v[72:75], v229 offset:36864
	ds_read_b128 v[76:79], v230
	ds_read_b128 v[80:83], v230 offset:4096
	s_waitcnt lgkmcnt(4)
	v_mfma_f32_32x32x16_bf16 v[48:63], v[184:187], v[192:195], v[48:63]
	v_mfma_f32_32x32x16_bf16 v[16:31], v[184:187], v[196:199], v[16:31]
	v_mfma_f32_32x32x16_bf16 v[32:47], v[188:191], v[192:195], v[32:47]
	v_mfma_f32_32x32x16_bf16 v[0:15], v[188:191], v[196:199], v[0:15]
	s_waitcnt vmcnt(6)
	s_waitcnt lgkmcnt(0)
	s_barrier
	ds_read_b128 v[184:187], v231 offset:32768
	ds_read_b128 v[188:191], v231 offset:36864
	ds_read_b128 v[192:195], v224 offset:49152
	ds_read_b128 v[196:199], v224 offset:53248
	s_waitcnt lgkmcnt(4)
	v_mfma_f32_32x32x16_bf16 v[48:63], v[68:71], v[76:79], v[48:63]
	v_mfma_f32_32x32x16_bf16 v[16:31], v[68:71], v[80:83], v[16:31]
	v_lshl_add_u64 v[68:69], v[66:67], 0, s[74:75]
	global_load_lds_dwordx4 v[68:69], off
	v_mfma_f32_32x32x16_bf16 v[32:47], v[72:75], v[76:79], v[32:47]
	v_mfma_f32_32x32x16_bf16 v[0:15], v[72:75], v[80:83], v[0:15]
	v_lshl_add_u64 v[68:69], v[66:67], 0, s[76:77]
	s_mov_b32 m0, s16
	s_nop 0
	global_load_lds_dwordx4 v[68:69], off
	ds_read_b128 v[68:71], v232 offset:32768
	ds_read_b128 v[72:75], v232 offset:36864
	ds_read_b128 v[76:79], v226 offset:49152
	ds_read_b128 v[80:83], v226 offset:53248
	s_waitcnt lgkmcnt(4)
	v_mfma_f32_32x32x16_bf16 v[48:63], v[184:187], v[192:195], v[48:63]
	v_mfma_f32_32x32x16_bf16 v[16:31], v[184:187], v[196:199], v[16:31]
	v_lshl_add_u64 v[252:253], v[66:67], 0, s[48:49]
	s_mov_b32 m0, s15
	s_mov_b64 s[48:49], 0x60300
	global_load_lds_dwordx4 v[252:253], off
	v_mfma_f32_32x32x16_bf16 v[32:47], v[188:191], v[192:195], v[32:47]
	v_mfma_f32_32x32x16_bf16 v[0:15], v[188:191], v[196:199], v[0:15]
	v_lshl_add_u64 v[252:253], v[66:67], 0, s[48:49]
	s_mov_b32 m0, s14
	s_nop 0
	global_load_lds_dwordx4 v[252:253], off
	ds_read_b128 v[184:187], v233 offset:32768
	ds_read_b128 v[188:191], v233 offset:36864
	ds_read_b128 v[192:195], v228 offset:49152
	ds_read_b128 v[196:199], v228 offset:53248
	s_waitcnt lgkmcnt(4)
	v_mfma_f32_32x32x16_bf16 v[48:63], v[68:71], v[76:79], v[48:63]
	v_mfma_f32_32x32x16_bf16 v[16:31], v[68:71], v[80:83], v[16:31]
	v_lshl_add_u64 v[252:253], v[64:65], 0, s[74:75]
	s_mov_b32 m0, s13
	s_nop 0
	global_load_lds_dwordx4 v[252:253], off
	v_mfma_f32_32x32x16_bf16 v[32:47], v[72:75], v[76:79], v[32:47]
	v_mfma_f32_32x32x16_bf16 v[0:15], v[72:75], v[80:83], v[0:15]
	v_lshl_add_u64 v[252:253], v[64:65], 0, s[76:77]
	s_mov_b32 m0, s12
	s_nop 0
	global_load_lds_dwordx4 v[252:253], off
	s_mov_b32 m0, s11
	s_mov_b64 s[48:49], 0x40380
	ds_read_b128 v[68:71], v234 offset:32768
	ds_read_b128 v[72:75], v234 offset:36864
	ds_read_b128 v[76:79], v230 offset:49152
	ds_read_b128 v[80:83], v230 offset:53248
	s_waitcnt lgkmcnt(4)
	v_mfma_f32_32x32x16_bf16 v[48:63], v[184:187], v[192:195], v[48:63]
	v_mfma_f32_32x32x16_bf16 v[16:31], v[184:187], v[196:199], v[16:31]
	v_mfma_f32_32x32x16_bf16 v[32:47], v[188:191], v[192:195], v[32:47]
	v_mfma_f32_32x32x16_bf16 v[0:15], v[188:191], v[196:199], v[0:15]
	s_waitcnt vmcnt(6)
	s_waitcnt lgkmcnt(0)
	s_barrier
; #define MFMA(a, b, c) __builtin_amdgcn_mfma_f32_32x32x16_bf16((a), (b), (c), 0, 0, 0)
; #define WAIT_V(n) asm volatile("s_waitcnt vmcnt(%0)" ::"n"(n) : "memory")
; #define RAW_BARRIER() do { asm volatile("s_waitcnt lgkmcnt(0)" ::: "memory"); __builtin_amdgcn_s_barrier(); asm volatile("" ::: "memory"); } while (0)
; #define GLDS_STAGE(slot, kt) do { _Pragma("unroll") for (int i = 0; i < 6; ++i) \
;     __builtin_amdgcn_global_load_lds((const unsigned*)(src[i] + (kt) * 64), (__attribute__((address_space(3))) unsigned*)(smem + (slot) * G_STAGE + (wave + 8 * i) * 1024), 16, 0, 0); } while (0)
; DI void gemm_tile(const u16* __restrict__ X, int ldx, const u16* __restrict__ Wt, int ldw, int K, char* smem,
;                   f32x16 (&acc)[2][2]) {
;     ...
;   int offA[2], offB[2], xa[2], xb[2];
; #pragma unroll
;   for (int ft = 0; ft < 2; ++ft) { const int R = 256 + fw * 64 + ft * 32 + lr; offA[ft] = R * 128; xa[ft] = (R >> 1) & 7; }
; #pragma unroll
;   for (int tt = 0; tt < 2; ++tt) { const int R = tq * 64 + tt * 32 + lr; offB[tt] = R * 128; xb[tt] = (R >> 1) & 7; }
;   GLDS_STAGE(0, 0); GLDS_STAGE(1, 1); WAIT_V(6); RAW_BARRIER();
;   int cur = 0;
;   for (int kt = 0; kt < nk; ++kt) {
;     const int nxt = (cur >= 1) ? cur - 1 : 2;
;     if (kt + 2 < nk) GLDS_STAGE(nxt, kt + 2);
;     __builtin_amdgcn_sched_barrier(0);
;     const char* st = smem + cur * G_STAGE;
; #pragma unroll
;     for (int ks = 0; ks < 4; ++ks) {
;       bf16x8 a[2], b[2];
; #pragma unroll
;       for (int ft = 0; ft < 2; ++ft) a[ft] = *reinterpret_cast<const bf16x8*>(st + offA[ft] + (((ks * 2 + lh) ^ xa[ft]) << 4));
; #pragma unroll
;       for (int tt = 0; tt < 2; ++tt) b[tt] = *reinterpret_cast<const bf16x8*>(st + offB[tt] + (((ks * 2 + lh) ^ xb[tt]) << 4));
; #pragma unroll
;       for (int ft = 0; ft < 2; ++ft)
; #pragma unroll
;         for (int tt = 0; tt < 2; ++tt) acc[ft][tt] = MFMA(a[ft], b[tt], acc[ft][tt]);
;     }
;     if (kt + 2 < nk) { WAIT_V(6); } else { WAIT_V(0); }
;     RAW_BARRIER();
	ds_read_b128 v[184:187], v235 offset:32768
	ds_read_b128 v[188:191], v235 offset:36864
	ds_read_b128 v[192:195], v236
	ds_read_b128 v[196:199], v236 offset:4096
	s_waitcnt lgkmcnt(4)
	v_mfma_f32_32x32x16_bf16 v[48:63], v[68:71], v[76:79], v[48:63]
	v_mfma_f32_32x32x16_bf16 v[16:31], v[68:71], v[80:83], v[16:31]
	v_lshl_add_u64 v[68:69], v[66:67], 0, s[40:41]
	global_load_lds_dwordx4 v[68:69], off
	v_mfma_f32_32x32x16_bf16 v[32:47], v[72:75], v[76:79], v[32:47]
	v_mfma_f32_32x32x16_bf16 v[0:15], v[72:75], v[80:83], v[0:15]
	v_lshl_add_u64 v[68:69], v[66:67], 0, s[0:1]
	s_mov_b32 m0, s9
	s_nop 0
	global_load_lds_dwordx4 v[68:69], off
	ds_read_b128 v[68:71], v237 offset:32768
	ds_read_b128 v[72:75], v237 offset:36864
	ds_read_b128 v[76:79], v238
	ds_read_b128 v[80:83], v238 offset:4096
	s_waitcnt lgkmcnt(4)
	v_mfma_f32_32x32x16_bf16 v[48:63], v[184:187], v[192:195], v[48:63]
	v_mfma_f32_32x32x16_bf16 v[16:31], v[184:187], v[196:199], v[16:31]
	v_lshl_add_u64 v[252:253], v[66:67], 0, s[48:49]
	s_mov_b32 m0, s18
	s_mov_b64 s[48:49], 0x60380
	global_load_lds_dwordx4 v[252:253], off
	v_mfma_f32_32x32x16_bf16 v[32:47], v[188:191], v[192:195], v[32:47]
	v_mfma_f32_32x32x16_bf16 v[0:15], v[188:191], v[196:199], v[0:15]
	v_lshl_add_u64 v[252:253], v[66:67], 0, s[48:49]
	s_mov_b32 m0, s25
	s_nop 0
	global_load_lds_dwordx4 v[252:253], off
	ds_read_b128 v[184:187], v239 offset:32768
	ds_read_b128 v[188:191], v239 offset:36864
	ds_read_b128 v[192:195], v240
	ds_read_b128 v[196:199], v240 offset:4096
	s_waitcnt lgkmcnt(4)
	v_mfma_f32_32x32x16_bf16 v[48:63], v[68:71], v[76:79], v[48:63]
	v_mfma_f32_32x32x16_bf16 v[16:31], v[68:71], v[80:83], v[16:31]
	v_lshl_add_u64 v[252:253], v[64:65], 0, s[40:41]
	s_mov_b32 m0, s24
	s_nop 0
	global_load_lds_dwordx4 v[252:253], off
	v_mfma_f32_32x32x16_bf16 v[32:47], v[72:75], v[76:79], v[32:47]
	v_mfma_f32_32x32x16_bf16 v[0:15], v[72:75], v[80:83], v[0:15]
	v_lshl_add_u64 v[252:253], v[64:65], 0, s[0:1]
	s_mov_b32 m0, s30
	s_nop 0
	global_load_lds_dwordx4 v[252:253], off
	s_mov_b32 m0, s70
	s_mov_b64 s[48:49], 0x40400
	ds_read_b128 v[68:71], v241 offset:32768
	ds_read_b128 v[72:75], v241 offset:36864
	ds_read_b128 v[76:79], v242
	ds_read_b128 v[80:83], v242 offset:4096
	s_waitcnt lgkmcnt(4)
	v_mfma_f32_32x32x16_bf16 v[48:63], v[184:187], v[192:195], v[48:63]
	v_mfma_f32_32x32x16_bf16 v[16:31], v[184:187], v[196:199], v[16:31]
	v_mfma_f32_32x32x16_bf16 v[32:47], v[188:191], v[192:195], v[32:47]
	v_mfma_f32_32x32x16_bf16 v[0:15], v[188:191], v[196:199], v[0:15]
	s_waitcnt vmcnt(6)
	s_waitcnt lgkmcnt(0)
	s_barrier
	ds_read_b128 v[184:187], v223 offset:32768
	ds_read_b128 v[188:191], v223 offset:36864
	ds_read_b128 v[192:195], v224
	ds_read_b128 v[196:199], v224 offset:4096
	s_waitcnt lgkmcnt(4)
	v_mfma_f32_32x32x16_bf16 v[48:63], v[68:71], v[76:79], v[48:63]
	v_mfma_f32_32x32x16_bf16 v[16:31], v[68:71], v[80:83], v[16:31]
	v_lshl_add_u64 v[68:69], v[66:67], 0, s[4:5]
	global_load_lds_dwordx4 v[68:69], off
	v_mfma_f32_32x32x16_bf16 v[32:47], v[72:75], v[76:79], v[32:47]
	v_mfma_f32_32x32x16_bf16 v[0:15], v[72:75], v[80:83], v[0:15]
	v_lshl_add_u64 v[68:69], v[66:67], 0, s[26:27]
	s_mov_b32 m0, s55
	s_nop 0
	global_load_lds_dwordx4 v[68:69], off
	ds_read_b128 v[68:71], v225 offset:32768
	ds_read_b128 v[72:75], v225 offset:36864
	ds_read_b128 v[76:79], v226
	ds_read_b128 v[80:83], v226 offset:4096
	s_waitcnt lgkmcnt(4)
	v_mfma_f32_32x32x16_bf16 v[48:63], v[184:187], v[192:195], v[48:63]
	v_mfma_f32_32x32x16_bf16 v[16:31], v[184:187], v[196:199], v[16:31]
	v_lshl_add_u64 v[252:253], v[66:67], 0, s[48:49]
	s_mov_b32 m0, s35
	s_mov_b64 s[48:49], 0x60400
	global_load_lds_dwordx4 v[252:253], off
	v_mfma_f32_32x32x16_bf16 v[32:47], v[188:191], v[192:195], v[32:47]
	v_mfma_f32_32x32x16_bf16 v[0:15], v[188:191], v[196:199], v[0:15]
	v_lshl_add_u64 v[252:253], v[66:67], 0, s[48:49]
	s_mov_b32 m0, s54
	s_nop 0
	global_load_lds_dwordx4 v[252:253], off
	ds_read_b128 v[184:187], v227 offset:32768
	ds_read_b128 v[188:191], v227 offset:36864
	ds_read_b128 v[192:195], v228
	ds_read_b128 v[196:199], v228 offset:4096
	s_waitcnt lgkmcnt(4)
	v_mfma_f32_32x32x16_bf16 v[48:63], v[68:71], v[76:79], v[48:63]
	v_mfma_f32_32x32x16_bf16 v[16:31], v[68:71], v[80:83], v[16:31]
	v_lshl_add_u64 v[252:253], v[64:65], 0, s[4:5]
	s_mov_b32 m0, s31
	s_nop 0
	global_load_lds_dwordx4 v[252:253], off
	v_mfma_f32_32x32x16_bf16 v[32:47], v[72:75], v[76:79], v[32:47]
	v_mfma_f32_32x32x16_bf16 v[0:15], v[72:75], v[80:83], v[0:15]
	v_lshl_add_u64 v[252:253], v[64:65], 0, s[26:27]
	s_mov_b32 m0, s34
	s_nop 0
	global_load_lds_dwordx4 v[252:253], off
	s_mov_b32 m0, s17
	ds_read_b128 v[68:71], v229 offset:32768
	ds_read_b128 v[72:75], v229 offset:36864
	ds_read_b128 v[76:79], v230
	ds_read_b128 v[80:83], v230 offset:4096
	s_waitcnt lgkmcnt(4)
	v_mfma_f32_32x32x16_bf16 v[48:63], v[184:187], v[192:195], v[48:63]
	v_mfma_f32_32x32x16_bf16 v[16:31], v[184:187], v[196:199], v[16:31]
	v_mfma_f32_32x32x16_bf16 v[32:47], v[188:191], v[192:195], v[32:47]
	v_mfma_f32_32x32x16_bf16 v[0:15], v[188:191], v[196:199], v[0:15]
	s_waitcnt vmcnt(6)
	s_waitcnt lgkmcnt(0)
	s_barrier
; #define MFMA(a, b, c) __builtin_amdgcn_mfma_f32_32x32x16_bf16((a), (b), (c), 0, 0, 0)
; #define WAIT_V(n) asm volatile("s_waitcnt vmcnt(%0)" ::"n"(n) : "memory")
; #define RAW_BARRIER() do { asm volatile("s_waitcnt lgkmcnt(0)" ::: "memory"); __builtin_amdgcn_s_barrier(); asm volatile("" ::: "memory"); } while (0)
; #define GLDS_STAGE(slot, kt) do { _Pragma("unroll") for (int i = 0; i < 6; ++i) \
;     __builtin_amdgcn_global_load_lds((const unsigned*)(src[i] + (kt) * 64), (__attribute__((address_space(3))) unsigned*)(smem + (slot) * G_STAGE + (wave + 8 * i) * 1024), 16, 0, 0); } while (0)
; DI void gemm_tile(const u16* __restrict__ X, int ldx, const u16* __restrict__ Wt, int ldw, int K, char* smem,
;                   f32x16 (&acc)[2][2]) {
;     ...
;   int offA[2], offB[2], xa[2], xb[2];
; #pragma unroll
;   for (int ft = 0; ft < 2; ++ft) { const int R = 256 + fw * 64 + ft * 32 + lr; offA[ft] = R * 128; xa[ft] = (R >> 1) & 7; }
; #pragma unroll
;   for (int tt = 0; tt < 2; ++tt) { const int R = tq * 64 + tt * 32 + lr; offB[tt] = R * 128; xb[tt] = (R >> 1) & 7; }
;   GLDS_STAGE(0, 0); GLDS_STAGE(1, 1); WAIT_V(6); RAW_BARRIER();
;   int cur = 0;
;   for (int kt = 0; kt < nk; ++kt) {
;     const int nxt = (cur >= 1) ? cur - 1 : 2;
;     if (kt + 2 < nk) GLDS_STAGE(nxt, kt + 2);
;     __builtin_amdgcn_sched_barrier(0);
;     const char* st = smem + cur * G_STAGE;
; #pragma unroll
;     for (int ks = 0; ks < 4; ++ks) {
;       bf16x8 a[2], b[2];
; #pragma unroll
;       for (int ft = 0; ft < 2; ++ft) a[ft] = *reinterpret_cast<const bf16x8*>(st + offA[ft] + (((ks * 2 + lh) ^ xa[ft]) << 4));
; #pragma unroll
;       for (int tt = 0; tt < 2; ++tt) b[tt] = *reinterpret_cast<const bf16x8*>(st + offB[tt] + (((ks * 2 + lh) ^ xb[tt]) << 4));
; #pragma unroll
;       for (int ft = 0; ft < 2; ++ft)
; #pragma unroll
;         for (int tt = 0; tt < 2; ++tt) acc[ft][tt] = MFMA(a[ft], b[tt], acc[ft][tt]);
;     }
;     if (kt + 2 < nk) { WAIT_V(6); } else { WAIT_V(0); }
;     RAW_BARRIER();
	ds_read_b128 v[184:187], v231 offset:32768
	ds_read_b128 v[188:191], v231 offset:36864
	ds_read_b128 v[192:195], v224 offset:49152
	ds_read_b128 v[196:199], v224 offset:53248
	s_waitcnt lgkmcnt(4)
	v_mfma_f32_32x32x16_bf16 v[48:63], v[68:71], v[76:79], v[48:63]
	v_mfma_f32_32x32x16_bf16 v[16:31], v[68:71], v[80:83], v[16:31]
	v_lshl_add_u64 v[68:69], v[66:67], 0, s[38:39]
	global_load_lds_dwordx4 v[68:69], off
	v_mfma_f32_32x32x16_bf16 v[32:47], v[72:75], v[76:79], v[32:47]
	v_mfma_f32_32x32x16_bf16 v[0:15], v[72:75], v[80:83], v[0:15]
	v_lshl_add_u64 v[68:69], v[66:67], 0, s[44:45]
	s_mov_b32 m0, s16
	s_mov_b64 s[16:17], 0x40480
	global_load_lds_dwordx4 v[68:69], off
	ds_read_b128 v[68:71], v232 offset:32768
	ds_read_b128 v[72:75], v232 offset:36864
	ds_read_b128 v[76:79], v226 offset:49152
	ds_read_b128 v[80:83], v226 offset:53248
	s_waitcnt lgkmcnt(4)
	v_mfma_f32_32x32x16_bf16 v[48:63], v[184:187], v[192:195], v[48:63]
	v_mfma_f32_32x32x16_bf16 v[16:31], v[184:187], v[196:199], v[16:31]
	v_lshl_add_u64 v[252:253], v[66:67], 0, s[16:17]
	s_mov_b32 m0, s15
	s_mov_b64 s[16:17], 0x60480
	global_load_lds_dwordx4 v[252:253], off
	v_mfma_f32_32x32x16_bf16 v[32:47], v[188:191], v[192:195], v[32:47]
	v_mfma_f32_32x32x16_bf16 v[0:15], v[188:191], v[196:199], v[0:15]
	v_lshl_add_u64 v[252:253], v[66:67], 0, s[16:17]
	s_mov_b32 m0, s14
	s_nop 0
	global_load_lds_dwordx4 v[252:253], off
	ds_read_b128 v[184:187], v233 offset:32768
	ds_read_b128 v[188:191], v233 offset:36864
	ds_read_b128 v[192:195], v228 offset:49152
	ds_read_b128 v[196:199], v228 offset:53248
	s_waitcnt lgkmcnt(4)
	v_mfma_f32_32x32x16_bf16 v[48:63], v[68:71], v[76:79], v[48:63]
	v_mfma_f32_32x32x16_bf16 v[16:31], v[68:71], v[80:83], v[16:31]
	v_lshl_add_u64 v[252:253], v[64:65], 0, s[38:39]
	s_mov_b32 m0, s13
	s_nop 0
	global_load_lds_dwordx4 v[252:253], off
	v_mfma_f32_32x32x16_bf16 v[32:47], v[72:75], v[76:79], v[32:47]
	v_mfma_f32_32x32x16_bf16 v[0:15], v[72:75], v[80:83], v[0:15]
	v_lshl_add_u64 v[252:253], v[64:65], 0, s[44:45]
	s_mov_b32 m0, s12
	s_nop 0
	global_load_lds_dwordx4 v[252:253], off
	s_mov_b32 m0, s11
	s_mov_b64 s[12:13], 0x40500
	ds_read_b128 v[68:71], v234 offset:32768
	ds_read_b128 v[72:75], v234 offset:36864
	ds_read_b128 v[76:79], v230 offset:49152
	ds_read_b128 v[80:83], v230 offset:53248
	s_waitcnt lgkmcnt(4)
	v_mfma_f32_32x32x16_bf16 v[48:63], v[184:187], v[192:195], v[48:63]
	v_mfma_f32_32x32x16_bf16 v[16:31], v[184:187], v[196:199], v[16:31]
	v_mfma_f32_32x32x16_bf16 v[32:47], v[188:191], v[192:195], v[32:47]
	v_mfma_f32_32x32x16_bf16 v[0:15], v[188:191], v[196:199], v[0:15]
	s_waitcnt vmcnt(6)
	s_waitcnt lgkmcnt(0)
	s_barrier
	ds_read_b128 v[184:187], v235 offset:32768
	ds_read_b128 v[188:191], v235 offset:36864
	ds_read_b128 v[192:195], v236
	ds_read_b128 v[196:199], v236 offset:4096
	s_waitcnt lgkmcnt(4)
	v_mfma_f32_32x32x16_bf16 v[48:63], v[68:71], v[76:79], v[48:63]
	v_mfma_f32_32x32x16_bf16 v[16:31], v[68:71], v[80:83], v[16:31]
	v_lshl_add_u64 v[68:69], v[66:67], 0, s[56:57]
	global_load_lds_dwordx4 v[68:69], off
	v_mfma_f32_32x32x16_bf16 v[32:47], v[72:75], v[76:79], v[32:47]
	v_mfma_f32_32x32x16_bf16 v[0:15], v[72:75], v[80:83], v[0:15]
	v_lshl_add_u64 v[68:69], v[66:67], 0, s[62:63]
	s_mov_b32 m0, s9
	s_nop 0
	global_load_lds_dwordx4 v[68:69], off
	ds_read_b128 v[68:71], v237 offset:32768
	ds_read_b128 v[72:75], v237 offset:36864
	ds_read_b128 v[76:79], v238
	ds_read_b128 v[80:83], v238 offset:4096
	s_waitcnt lgkmcnt(4)
	v_mfma_f32_32x32x16_bf16 v[48:63], v[184:187], v[192:195], v[48:63]
	v_mfma_f32_32x32x16_bf16 v[16:31], v[184:187], v[196:199], v[16:31]
	v_lshl_add_u64 v[252:253], v[66:67], 0, s[12:13]
	s_mov_b32 m0, s18
	s_mov_b64 s[12:13], 0x60500
	global_load_lds_dwordx4 v[252:253], off
	v_mfma_f32_32x32x16_bf16 v[32:47], v[188:191], v[192:195], v[32:47]
	v_mfma_f32_32x32x16_bf16 v[0:15], v[188:191], v[196:199], v[0:15]
	v_lshl_add_u64 v[252:253], v[66:67], 0, s[12:13]
	s_mov_b32 m0, s25
	s_nop 0
	global_load_lds_dwordx4 v[252:253], off
	ds_read_b128 v[184:187], v239 offset:32768
	ds_read_b128 v[188:191], v239 offset:36864
	ds_read_b128 v[192:195], v240
	ds_read_b128 v[196:199], v240 offset:4096
	s_waitcnt lgkmcnt(4)
	v_mfma_f32_32x32x16_bf16 v[48:63], v[68:71], v[76:79], v[48:63]
	v_mfma_f32_32x32x16_bf16 v[16:31], v[68:71], v[80:83], v[16:31]
	v_lshl_add_u64 v[252:253], v[64:65], 0, s[56:57]
	s_mov_b32 m0, s24
	s_nop 0
	global_load_lds_dwordx4 v[252:253], off
	v_mfma_f32_32x32x16_bf16 v[32:47], v[72:75], v[76:79], v[32:47]
	v_mfma_f32_32x32x16_bf16 v[0:15], v[72:75], v[80:83], v[0:15]
	v_lshl_add_u64 v[252:253], v[64:65], 0, s[62:63]
	s_mov_b32 m0, s30
	s_nop 0
	global_load_lds_dwordx4 v[252:253], off
	v_readfirstlane_b32 s30, v121
	s_mov_b32 m0, s30
	v_readfirstlane_b32 s15, v123
	s_mov_b64 s[12:13], 0x40580
	v_readfirstlane_b32 s16, v125
	v_readfirstlane_b32 s18, v127
	v_readfirstlane_b32 s17, v163
	v_readfirstlane_b32 s24, v165
	ds_read_b128 v[68:71], v241 offset:32768
	ds_read_b128 v[72:75], v241 offset:36864
	ds_read_b128 v[76:79], v242
	ds_read_b128 v[80:83], v242 offset:4096
	s_waitcnt lgkmcnt(4)
	v_mfma_f32_32x32x16_bf16 v[48:63], v[184:187], v[192:195], v[48:63]
	v_mfma_f32_32x32x16_bf16 v[16:31], v[184:187], v[196:199], v[16:31]
	v_mfma_f32_32x32x16_bf16 v[32:47], v[188:191], v[192:195], v[32:47]
	v_mfma_f32_32x32x16_bf16 v[0:15], v[188:191], v[196:199], v[0:15]
	s_waitcnt vmcnt(6)
	s_waitcnt lgkmcnt(0)
	s_barrier
; #define MFMA(a, b, c) __builtin_amdgcn_mfma_f32_32x32x16_bf16((a), (b), (c), 0, 0, 0)
; #define WAIT_V(n) asm volatile("s_waitcnt vmcnt(%0)" ::"n"(n) : "memory")
; #define RAW_BARRIER() do { asm volatile("s_waitcnt lgkmcnt(0)" ::: "memory"); __builtin_amdgcn_s_barrier(); asm volatile("" ::: "memory"); } while (0)
; #define GLDS_STAGE(slot, kt) do { _Pragma("unroll") for (int i = 0; i < 6; ++i) \
;     __builtin_amdgcn_global_load_lds((const unsigned*)(src[i] + (kt) * 64), (__attribute__((address_space(3))) unsigned*)(smem + (slot) * G_STAGE + (wave + 8 * i) * 1024), 16, 0, 0); } while (0)
; DI void gemm_tile(const u16* __restrict__ X, int ldx, const u16* __restrict__ Wt, int ldw, int K, char* smem,
;                   f32x16 (&acc)[2][2]) {
;     ...
;   int offA[2], offB[2], xa[2], xb[2];
; #pragma unroll
;   for (int ft = 0; ft < 2; ++ft) { const int R = 256 + fw * 64 + ft * 32 + lr; offA[ft] = R * 128; xa[ft] = (R >> 1) & 7; }
; #pragma unroll
;   for (int tt = 0; tt < 2; ++tt) { const int R = tq * 64 + tt * 32 + lr; offB[tt] = R * 128; xb[tt] = (R >> 1) & 7; }
;   GLDS_STAGE(0, 0); GLDS_STAGE(1, 1); WAIT_V(6); RAW_BARRIER();
;   int cur = 0;
;   for (int kt = 0; kt < nk; ++kt) {
;     const int nxt = (cur >= 1) ? cur - 1 : 2;
;     if (kt + 2 < nk) GLDS_STAGE(nxt, kt + 2);
;     __builtin_amdgcn_sched_barrier(0);
;     const char* st = smem + cur * G_STAGE;
; #pragma unroll
;     for (int ks = 0; ks < 4; ++ks) {
;       bf16x8 a[2], b[2];
; #pragma unroll
;       for (int ft = 0; ft < 2; ++ft) a[ft] = *reinterpret_cast<const bf16x8*>(st + offA[ft] + (((ks * 2 + lh) ^ xa[ft]) << 4));
; #pragma unroll
;       for (int tt = 0; tt < 2; ++tt) b[tt] = *reinterpret_cast<const bf16x8*>(st + offB[tt] + (((ks * 2 + lh) ^ xb[tt]) << 4));
; #pragma unroll
;       for (int ft = 0; ft < 2; ++ft)
; #pragma unroll
;         for (int tt = 0; tt < 2; ++tt) acc[ft][tt] = MFMA(a[ft], b[tt], acc[ft][tt]);
;     }
;     if (kt + 2 < nk) { WAIT_V(6); } else { WAIT_V(0); }
;     RAW_BARRIER();
	ds_read_b128 v[184:187], v223 offset:32768
	ds_read_b128 v[188:191], v223 offset:36864
	ds_read_b128 v[192:195], v224
	ds_read_b128 v[196:199], v224 offset:4096
	s_waitcnt lgkmcnt(4)
	v_mfma_f32_32x32x16_bf16 v[48:63], v[68:71], v[76:79], v[48:63]
	v_mfma_f32_32x32x16_bf16 v[16:31], v[68:71], v[80:83], v[16:31]
	v_lshl_add_u64 v[68:69], v[66:67], 0, s[72:73]
	global_load_lds_dwordx4 v[68:69], off
	v_mfma_f32_32x32x16_bf16 v[32:47], v[72:75], v[76:79], v[32:47]
	v_mfma_f32_32x32x16_bf16 v[0:15], v[72:75], v[80:83], v[0:15]
	v_lshl_add_u64 v[68:69], v[66:67], 0, s[84:85]
	s_mov_b32 m0, s15
	s_nop 0
	global_load_lds_dwordx4 v[68:69], off
	ds_read_b128 v[68:71], v225 offset:32768
	ds_read_b128 v[72:75], v225 offset:36864
	ds_read_b128 v[76:79], v226
	ds_read_b128 v[80:83], v226 offset:4096
	s_waitcnt lgkmcnt(4)
	v_mfma_f32_32x32x16_bf16 v[48:63], v[184:187], v[192:195], v[48:63]
	v_mfma_f32_32x32x16_bf16 v[16:31], v[184:187], v[196:199], v[16:31]
	v_lshl_add_u64 v[252:253], v[66:67], 0, s[12:13]
	s_mov_b32 m0, s16
	s_mov_b64 s[12:13], 0x60580
	global_load_lds_dwordx4 v[252:253], off
	v_mfma_f32_32x32x16_bf16 v[32:47], v[188:191], v[192:195], v[32:47]
	v_mfma_f32_32x32x16_bf16 v[0:15], v[188:191], v[196:199], v[0:15]
	v_lshl_add_u64 v[252:253], v[66:67], 0, s[12:13]
	s_mov_b32 m0, s18
	s_nop 0
	global_load_lds_dwordx4 v[252:253], off
	ds_read_b128 v[184:187], v227 offset:32768
	ds_read_b128 v[188:191], v227 offset:36864
	ds_read_b128 v[192:195], v228
	ds_read_b128 v[196:199], v228 offset:4096
	s_waitcnt lgkmcnt(4)
	v_mfma_f32_32x32x16_bf16 v[48:63], v[68:71], v[76:79], v[48:63]
	v_mfma_f32_32x32x16_bf16 v[16:31], v[68:71], v[80:83], v[16:31]
	v_lshl_add_u64 v[252:253], v[64:65], 0, s[72:73]
	s_mov_b32 m0, s17
	s_nop 0
	global_load_lds_dwordx4 v[252:253], off
	v_mfma_f32_32x32x16_bf16 v[32:47], v[72:75], v[76:79], v[32:47]
	v_mfma_f32_32x32x16_bf16 v[0:15], v[72:75], v[80:83], v[0:15]
	v_lshl_add_u64 v[252:253], v[64:65], 0, s[84:85]
	s_mov_b32 m0, s24
	s_nop 0
	global_load_lds_dwordx4 v[252:253], off
	v_readfirstlane_b32 s25, v101
	s_mov_b32 m0, s25
	v_readfirstlane_b32 s9, v211
	s_mov_b64 s[12:13], 0x40600
	v_readfirstlane_b32 s11, v214
	v_readfirstlane_b32 s14, v217
	ds_read_b128 v[68:71], v229 offset:32768
	ds_read_b128 v[72:75], v229 offset:36864
	ds_read_b128 v[76:79], v230
	ds_read_b128 v[80:83], v230 offset:4096
	s_waitcnt lgkmcnt(4)
	v_mfma_f32_32x32x16_bf16 v[48:63], v[184:187], v[192:195], v[48:63]
	v_mfma_f32_32x32x16_bf16 v[16:31], v[184:187], v[196:199], v[16:31]
	v_mfma_f32_32x32x16_bf16 v[32:47], v[188:191], v[192:195], v[32:47]
	v_mfma_f32_32x32x16_bf16 v[0:15], v[188:191], v[196:199], v[0:15]
	s_waitcnt vmcnt(6)
	s_waitcnt lgkmcnt(0)
	s_barrier
	ds_read_b128 v[184:187], v231 offset:32768
	ds_read_b128 v[188:191], v231 offset:36864
	ds_read_b128 v[192:195], v224 offset:49152
	ds_read_b128 v[196:199], v224 offset:53248
	s_waitcnt lgkmcnt(4)
	v_mfma_f32_32x32x16_bf16 v[48:63], v[68:71], v[76:79], v[48:63]
	v_mfma_f32_32x32x16_bf16 v[16:31], v[68:71], v[80:83], v[16:31]
	v_lshl_add_u64 v[68:69], v[66:67], 0, s[22:23]
	global_load_lds_dwordx4 v[68:69], off
	v_mfma_f32_32x32x16_bf16 v[32:47], v[72:75], v[76:79], v[32:47]
	v_mfma_f32_32x32x16_bf16 v[0:15], v[72:75], v[80:83], v[0:15]
	v_lshl_add_u64 v[68:69], v[66:67], 0, s[28:29]
	s_mov_b32 m0, s9
	s_nop 0
	global_load_lds_dwordx4 v[68:69], off
	ds_read_b128 v[68:71], v232 offset:32768
	ds_read_b128 v[72:75], v232 offset:36864
	ds_read_b128 v[76:79], v226 offset:49152
	ds_read_b128 v[80:83], v226 offset:53248
	s_waitcnt lgkmcnt(4)
	v_mfma_f32_32x32x16_bf16 v[48:63], v[184:187], v[192:195], v[48:63]
	v_mfma_f32_32x32x16_bf16 v[16:31], v[184:187], v[196:199], v[16:31]
	v_lshl_add_u64 v[252:253], v[66:67], 0, s[12:13]
	s_mov_b32 m0, s11
	s_mov_b64 s[12:13], 0x60600
	global_load_lds_dwordx4 v[252:253], off
	v_mfma_f32_32x32x16_bf16 v[32:47], v[188:191], v[192:195], v[32:47]
	v_mfma_f32_32x32x16_bf16 v[0:15], v[188:191], v[196:199], v[0:15]
	v_lshl_add_u64 v[252:253], v[66:67], 0, s[12:13]
	v_readfirstlane_b32 s13, v215
	s_mov_b32 m0, s13
	v_readfirstlane_b32 s12, v216
	global_load_lds_dwordx4 v[252:253], off
	ds_read_b128 v[184:187], v233 offset:32768
	ds_read_b128 v[188:191], v233 offset:36864
	ds_read_b128 v[192:195], v228 offset:49152
	ds_read_b128 v[196:199], v228 offset:53248
	s_waitcnt lgkmcnt(4)
	v_mfma_f32_32x32x16_bf16 v[48:63], v[68:71], v[76:79], v[48:63]
	v_mfma_f32_32x32x16_bf16 v[16:31], v[68:71], v[80:83], v[16:31]
	v_lshl_add_u64 v[252:253], v[64:65], 0, s[22:23]
	s_mov_b32 m0, s12
	s_nop 0
	global_load_lds_dwordx4 v[252:253], off
	v_mfma_f32_32x32x16_bf16 v[32:47], v[72:75], v[76:79], v[32:47]
	v_mfma_f32_32x32x16_bf16 v[0:15], v[72:75], v[80:83], v[0:15]
	v_lshl_add_u64 v[252:253], v[64:65], 0, s[28:29]
	s_mov_b32 m0, s14
	s_nop 0
	global_load_lds_dwordx4 v[252:253], off
	v_readfirstlane_b32 s31, v103
	s_mov_b32 m0, s31
	v_readfirstlane_b32 s31, v218
	s_mov_b64 s[34:35], 0x40680
	ds_read_b128 v[68:71], v234 offset:32768
	ds_read_b128 v[72:75], v234 offset:36864
	ds_read_b128 v[76:79], v230 offset:49152
	ds_read_b128 v[80:83], v230 offset:53248
	s_waitcnt lgkmcnt(4)
	v_mfma_f32_32x32x16_bf16 v[48:63], v[184:187], v[192:195], v[48:63]
	v_mfma_f32_32x32x16_bf16 v[16:31], v[184:187], v[196:199], v[16:31]
	v_mfma_f32_32x32x16_bf16 v[32:47], v[188:191], v[192:195], v[32:47]
	v_mfma_f32_32x32x16_bf16 v[0:15], v[188:191], v[196:199], v[0:15]
	s_waitcnt vmcnt(6)
	s_waitcnt lgkmcnt(0)
	s_barrier
; #define MFMA(a, b, c) __builtin_amdgcn_mfma_f32_32x32x16_bf16((a), (b), (c), 0, 0, 0)
; #define WAIT_V(n) asm volatile("s_waitcnt vmcnt(%0)" ::"n"(n) : "memory")
; #define RAW_BARRIER() do { asm volatile("s_waitcnt lgkmcnt(0)" ::: "memory"); __builtin_amdgcn_s_barrier(); asm volatile("" ::: "memory"); } while (0)
; #define GLDS_STAGE(slot, kt) do { _Pragma("unroll") for (int i = 0; i < 6; ++i) \
;     __builtin_amdgcn_global_load_lds((const unsigned*)(src[i] + (kt) * 64), (__attribute__((address_space(3))) unsigned*)(smem + (slot) * G_STAGE + (wave + 8 * i) * 1024), 16, 0, 0); } while (0)
; DI void gemm_tile(const u16* __restrict__ X, int ldx, const u16* __restrict__ Wt, int ldw, int K, char* smem,
;                   f32x16 (&acc)[2][2]) {
;     ...
;   int offA[2], offB[2], xa[2], xb[2];
; #pragma unroll
;   for (int ft = 0; ft < 2; ++ft) { const int R = 256 + fw * 64 + ft * 32 + lr; offA[ft] = R * 128; xa[ft] = (R >> 1) & 7; }
; #pragma unroll
;   for (int tt = 0; tt < 2; ++tt) { const int R = tq * 64 + tt * 32 + lr; offB[tt] = R * 128; xb[tt] = (R >> 1) & 7; }
;   GLDS_STAGE(0, 0); GLDS_STAGE(1, 1); WAIT_V(6); RAW_BARRIER();
;   int cur = 0;
;   for (int kt = 0; kt < nk; ++kt) {
;     const int nxt = (cur >= 1) ? cur - 1 : 2;
;     if (kt + 2 < nk) GLDS_STAGE(nxt, kt + 2);
;     __builtin_amdgcn_sched_barrier(0);
;     const char* st = smem + cur * G_STAGE;
; #pragma unroll
;     for (int ks = 0; ks < 4; ++ks) {
;       bf16x8 a[2], b[2];
; #pragma unroll
;       for (int ft = 0; ft < 2; ++ft) a[ft] = *reinterpret_cast<const bf16x8*>(st + offA[ft] + (((ks * 2 + lh) ^ xa[ft]) << 4));
; #pragma unroll
;       for (int tt = 0; tt < 2; ++tt) b[tt] = *reinterpret_cast<const bf16x8*>(st + offB[tt] + (((ks * 2 + lh) ^ xb[tt]) << 4));
; #pragma unroll
;       for (int ft = 0; ft < 2; ++ft)
; #pragma unroll
;         for (int tt = 0; tt < 2; ++tt) acc[ft][tt] = MFMA(a[ft], b[tt], acc[ft][tt]);
;     }
;     if (kt + 2 < nk) { WAIT_V(6); } else { WAIT_V(0); }
;     RAW_BARRIER();
	ds_read_b128 v[184:187], v235 offset:32768
	ds_read_b128 v[188:191], v235 offset:36864
	ds_read_b128 v[192:195], v236
	ds_read_b128 v[196:199], v236 offset:4096
	s_waitcnt lgkmcnt(4)
	v_mfma_f32_32x32x16_bf16 v[48:63], v[68:71], v[76:79], v[48:63]
	v_mfma_f32_32x32x16_bf16 v[16:31], v[68:71], v[80:83], v[16:31]
	v_lshl_add_u64 v[68:69], v[66:67], 0, s[52:53]
	global_load_lds_dwordx4 v[68:69], off
	v_mfma_f32_32x32x16_bf16 v[32:47], v[72:75], v[76:79], v[32:47]
	v_mfma_f32_32x32x16_bf16 v[0:15], v[72:75], v[80:83], v[0:15]
	v_lshl_add_u64 v[68:69], v[66:67], 0, s[64:65]
	s_mov_b32 m0, s31
	v_readfirstlane_b32 s31, v173
	global_load_lds_dwordx4 v[68:69], off
	ds_read_b128 v[68:71], v237 offset:32768
	ds_read_b128 v[72:75], v237 offset:36864
	ds_read_b128 v[76:79], v238
	ds_read_b128 v[80:83], v238 offset:4096
	s_waitcnt lgkmcnt(4)
	v_mfma_f32_32x32x16_bf16 v[48:63], v[184:187], v[192:195], v[48:63]
	v_mfma_f32_32x32x16_bf16 v[16:31], v[184:187], v[196:199], v[16:31]
	v_lshl_add_u64 v[252:253], v[66:67], 0, s[34:35]
	s_mov_b32 m0, s31
	s_mov_b64 s[34:35], 0x60680
	v_readfirstlane_b32 s31, v200
	global_load_lds_dwordx4 v[252:253], off
	v_mfma_f32_32x32x16_bf16 v[32:47], v[188:191], v[192:195], v[32:47]
	v_mfma_f32_32x32x16_bf16 v[0:15], v[188:191], v[196:199], v[0:15]
	v_lshl_add_u64 v[252:253], v[66:67], 0, s[34:35]
	s_mov_b32 m0, s31
	v_readfirstlane_b32 s31, v201
	global_load_lds_dwordx4 v[252:253], off
	ds_read_b128 v[184:187], v239 offset:32768
	ds_read_b128 v[188:191], v239 offset:36864
	ds_read_b128 v[192:195], v240
	ds_read_b128 v[196:199], v240 offset:4096
	s_waitcnt lgkmcnt(4)
	v_mfma_f32_32x32x16_bf16 v[48:63], v[68:71], v[76:79], v[48:63]
	v_mfma_f32_32x32x16_bf16 v[16:31], v[68:71], v[80:83], v[16:31]
	v_lshl_add_u64 v[252:253], v[64:65], 0, s[52:53]
	s_mov_b32 m0, s31
	v_readfirstlane_b32 s31, v202
	global_load_lds_dwordx4 v[252:253], off
	v_mfma_f32_32x32x16_bf16 v[32:47], v[72:75], v[76:79], v[32:47]
	v_mfma_f32_32x32x16_bf16 v[0:15], v[72:75], v[80:83], v[0:15]
	v_lshl_add_u64 v[252:253], v[64:65], 0, s[64:65]
	s_mov_b32 m0, s31
	s_nop 0
	global_load_lds_dwordx4 v[252:253], off
	s_mov_b32 m0, s30
	s_mov_b64 s[30:31], 0x40700
	ds_read_b128 v[68:71], v241 offset:32768
	ds_read_b128 v[72:75], v241 offset:36864
	ds_read_b128 v[76:79], v242
	ds_read_b128 v[80:83], v242 offset:4096
	s_waitcnt lgkmcnt(4)
	v_mfma_f32_32x32x16_bf16 v[48:63], v[184:187], v[192:195], v[48:63]
	v_mfma_f32_32x32x16_bf16 v[16:31], v[184:187], v[196:199], v[16:31]
	v_mfma_f32_32x32x16_bf16 v[32:47], v[188:191], v[192:195], v[32:47]
	v_mfma_f32_32x32x16_bf16 v[0:15], v[188:191], v[196:199], v[0:15]
	s_waitcnt vmcnt(6)
	s_waitcnt lgkmcnt(0)
	s_barrier
	ds_read_b128 v[184:187], v223 offset:32768
	ds_read_b128 v[188:191], v223 offset:36864
	ds_read_b128 v[192:195], v224
	ds_read_b128 v[196:199], v224 offset:4096
	s_waitcnt lgkmcnt(4)
	v_mfma_f32_32x32x16_bf16 v[48:63], v[68:71], v[76:79], v[48:63]
	v_mfma_f32_32x32x16_bf16 v[16:31], v[68:71], v[80:83], v[16:31]
	v_lshl_add_u64 v[68:69], v[66:67], 0, s[20:21]
	global_load_lds_dwordx4 v[68:69], off
	v_mfma_f32_32x32x16_bf16 v[32:47], v[72:75], v[76:79], v[32:47]
	v_mfma_f32_32x32x16_bf16 v[0:15], v[72:75], v[80:83], v[0:15]
	v_lshl_add_u64 v[68:69], v[66:67], 0, s[36:37]
	s_mov_b32 m0, s15
	s_nop 0
	global_load_lds_dwordx4 v[68:69], off
	ds_read_b128 v[68:71], v225 offset:32768
	ds_read_b128 v[72:75], v225 offset:36864
	ds_read_b128 v[76:79], v226
	ds_read_b128 v[80:83], v226 offset:4096
	s_waitcnt lgkmcnt(4)
	v_mfma_f32_32x32x16_bf16 v[48:63], v[184:187], v[192:195], v[48:63]
	v_mfma_f32_32x32x16_bf16 v[16:31], v[184:187], v[196:199], v[16:31]
	v_lshl_add_u64 v[252:253], v[66:67], 0, s[30:31]
	s_mov_b32 m0, s16
	s_mov_b64 s[30:31], 0x60700
	global_load_lds_dwordx4 v[252:253], off
	v_mfma_f32_32x32x16_bf16 v[32:47], v[188:191], v[192:195], v[32:47]
	v_mfma_f32_32x32x16_bf16 v[0:15], v[188:191], v[196:199], v[0:15]
	v_lshl_add_u64 v[252:253], v[66:67], 0, s[30:31]
	s_mov_b32 m0, s18
	s_nop 0
	global_load_lds_dwordx4 v[252:253], off
	ds_read_b128 v[184:187], v227 offset:32768
	ds_read_b128 v[188:191], v227 offset:36864
	ds_read_b128 v[192:195], v228
	ds_read_b128 v[196:199], v228 offset:4096
	s_waitcnt lgkmcnt(4)
	v_mfma_f32_32x32x16_bf16 v[48:63], v[68:71], v[76:79], v[48:63]
	v_mfma_f32_32x32x16_bf16 v[16:31], v[68:71], v[80:83], v[16:31]
	v_lshl_add_u64 v[252:253], v[64:65], 0, s[20:21]
	s_mov_b32 m0, s17
	s_nop 0
	global_load_lds_dwordx4 v[252:253], off
	v_mfma_f32_32x32x16_bf16 v[32:47], v[72:75], v[76:79], v[32:47]
	v_mfma_f32_32x32x16_bf16 v[0:15], v[72:75], v[80:83], v[0:15]
	v_lshl_add_u64 v[252:253], v[64:65], 0, s[36:37]
	s_mov_b32 m0, s24
	s_nop 0
	global_load_lds_dwordx4 v[252:253], off
	s_mov_b32 m0, s25
	s_mov_b64 s[16:17], 0x40780
	s_waitcnt lgkmcnt(0)
	v_mfma_f32_32x32x16_bf16 v[48:63], v[184:187], v[192:195], v[48:63]
	v_mfma_f32_32x32x16_bf16 v[16:31], v[184:187], v[196:199], v[16:31]
	v_mfma_f32_32x32x16_bf16 v[32:47], v[188:191], v[192:195], v[32:47]
	v_mfma_f32_32x32x16_bf16 v[0:15], v[188:191], v[196:199], v[0:15]
	ds_read_b128 v[68:71], v229 offset:32768
	ds_read_b128 v[72:75], v229 offset:36864
	ds_read_b128 v[76:79], v230
	ds_read_b128 v[80:83], v230 offset:4096
	s_waitcnt vmcnt(6)
	s_waitcnt lgkmcnt(0)
	s_barrier
; #define MFMA(a, b, c) __builtin_amdgcn_mfma_f32_32x32x16_bf16((a), (b), (c), 0, 0, 0)
; #define WAIT_V(n) asm volatile("s_waitcnt vmcnt(%0)" ::"n"(n) : "memory")
; #define RAW_BARRIER() do { asm volatile("s_waitcnt lgkmcnt(0)" ::: "memory"); __builtin_amdgcn_s_barrier(); asm volatile("" ::: "memory"); } while (0)
; #define GLDS_STAGE(slot, kt) do { _Pragma("unroll") for (int i = 0; i < 6; ++i) \
;     __builtin_amdgcn_global_load_lds((const unsigned*)(src[i] + (kt) * 64), (__attribute__((address_space(3))) unsigned*)(smem + (slot) * G_STAGE + (wave + 8 * i) * 1024), 16, 0, 0); } while (0)
; DI void gemm_tile(const u16* __restrict__ X, int ldx, const u16* __restrict__ Wt, int ldw, int K, char* smem,
;                   f32x16 (&acc)[2][2]) {
;     ...
;   for (int kt = 0; kt < nk; ++kt) {
;     const int nxt = (cur >= 1) ? cur - 1 : 2;
;     if (kt + 2 < nk) GLDS_STAGE(nxt, kt + 2);
;     __builtin_amdgcn_sched_barrier(0);
;     const char* st = smem + cur * G_STAGE;
; #pragma unroll
;     for (int ks = 0; ks < 4; ++ks) {
;       bf16x8 a[2], b[2];
; #pragma unroll
;       for (int ft = 0; ft < 2; ++ft) a[ft] = *reinterpret_cast<const bf16x8*>(st + offA[ft] + (((ks * 2 + lh) ^ xa[ft]) << 4));
; #pragma unroll
;       for (int tt = 0; tt < 2; ++tt) b[tt] = *reinterpret_cast<const bf16x8*>(st + offB[tt] + (((ks * 2 + lh) ^ xb[tt]) << 4));
; #pragma unroll
;       for (int ft = 0; ft < 2; ++ft)
; #pragma unroll
;         for (int tt = 0; tt < 2; ++tt) acc[ft][tt] = MFMA(a[ft], b[tt], acc[ft][tt]);
;     }
;     if (kt + 2 < nk) { WAIT_V(6); } else { WAIT_V(0); }
;     RAW_BARRIER();
;     cur = (cur == 2) ? 0 : cur + 1;
;   }
	s_waitcnt lgkmcnt(0)
	v_mfma_f32_32x32x16_bf16 v[48:63], v[68:71], v[76:79], v[48:63]
	v_mfma_f32_32x32x16_bf16 v[16:31], v[68:71], v[80:83], v[16:31]
	v_lshl_add_u64 v[68:69], v[66:67], 0, s[86:87]
	global_load_lds_dwordx4 v[68:69], off
	v_lshl_add_u64 v[68:69], v[66:67], 0, s[46:47]
	s_mov_b32 m0, s9
	s_nop 0
	global_load_lds_dwordx4 v[68:69], off
	v_lshl_add_u64 v[68:69], v[66:67], 0, s[16:17]
	s_mov_b32 m0, s11
	s_mov_b64 s[16:17], 0x60780
	global_load_lds_dwordx4 v[68:69], off
	v_lshl_add_u64 v[66:67], v[66:67], 0, s[16:17]
	s_mov_b32 m0, s13
	v_mfma_f32_32x32x16_bf16 v[32:47], v[72:75], v[76:79], v[32:47]
	global_load_lds_dwordx4 v[66:67], off
	v_lshl_add_u64 v[66:67], v[64:65], 0, s[86:87]
	s_mov_b32 m0, s12
	v_lshl_add_u64 v[64:65], v[64:65], 0, s[46:47]
	global_load_lds_dwordx4 v[66:67], off
	s_mov_b32 m0, s14
	v_mfma_f32_32x32x16_bf16 v[0:15], v[72:75], v[80:83], v[0:15]
	global_load_lds_dwordx4 v[64:65], off
	ds_read_b128 v[64:67], v231 offset:32768
	ds_read_b128 v[68:71], v224 offset:49152
	ds_read_b128 v[72:75], v224 offset:53248
	s_waitcnt lgkmcnt(0)
	v_mfma_f32_32x32x16_bf16 v[48:63], v[64:67], v[68:71], v[48:63]
	v_mfma_f32_32x32x16_bf16 v[16:31], v[64:67], v[72:75], v[16:31]
	ds_read_b128 v[64:67], v231 offset:36864
	s_waitcnt lgkmcnt(0)
	v_mfma_f32_32x32x16_bf16 v[32:47], v[64:67], v[68:71], v[32:47]
	v_mfma_f32_32x32x16_bf16 v[0:15], v[64:67], v[72:75], v[0:15]
	ds_read_b128 v[64:67], v232 offset:32768
	ds_read_b128 v[68:71], v226 offset:49152
	ds_read_b128 v[72:75], v226 offset:53248
	s_waitcnt lgkmcnt(0)
	v_mfma_f32_32x32x16_bf16 v[48:63], v[64:67], v[68:71], v[48:63]
	v_mfma_f32_32x32x16_bf16 v[16:31], v[64:67], v[72:75], v[16:31]
	ds_read_b128 v[64:67], v232 offset:36864
	s_waitcnt lgkmcnt(0)
	v_mfma_f32_32x32x16_bf16 v[32:47], v[64:67], v[68:71], v[32:47]
	v_mfma_f32_32x32x16_bf16 v[0:15], v[64:67], v[72:75], v[0:15]
	ds_read_b128 v[64:67], v233 offset:32768
	ds_read_b128 v[68:71], v228 offset:49152
	ds_read_b128 v[72:75], v228 offset:53248
	s_waitcnt lgkmcnt(0)
	v_mfma_f32_32x32x16_bf16 v[48:63], v[64:67], v[68:71], v[48:63]
	v_mfma_f32_32x32x16_bf16 v[16:31], v[64:67], v[72:75], v[16:31]
	ds_read_b128 v[64:67], v233 offset:36864
	s_waitcnt lgkmcnt(0)
	v_mfma_f32_32x32x16_bf16 v[32:47], v[64:67], v[68:71], v[32:47]
	v_mfma_f32_32x32x16_bf16 v[0:15], v[64:67], v[72:75], v[0:15]
	ds_read_b128 v[64:67], v234 offset:32768
	ds_read_b128 v[68:71], v230 offset:49152
	ds_read_b128 v[72:75], v230 offset:53248
	s_waitcnt lgkmcnt(0)
	v_mfma_f32_32x32x16_bf16 v[48:63], v[64:67], v[68:71], v[48:63]
	v_mfma_f32_32x32x16_bf16 v[16:31], v[64:67], v[72:75], v[16:31]
	ds_read_b128 v[64:67], v234 offset:36864
	s_waitcnt vmcnt(6)
	s_waitcnt lgkmcnt(0)
	s_barrier
	s_waitcnt lgkmcnt(0)
	v_mfma_f32_32x32x16_bf16 v[32:47], v[64:67], v[68:71], v[32:47]
	v_mfma_f32_32x32x16_bf16 v[0:15], v[64:67], v[72:75], v[0:15]
	ds_read_b128 v[64:67], v235 offset:32768
	ds_read_b128 v[68:71], v236
	ds_read_b128 v[72:75], v236 offset:4096
	s_waitcnt lgkmcnt(0)
	v_mfma_f32_32x32x16_bf16 v[48:63], v[64:67], v[68:71], v[48:63]
	v_mfma_f32_32x32x16_bf16 v[16:31], v[64:67], v[72:75], v[16:31]
	ds_read_b128 v[64:67], v235 offset:36864
	s_waitcnt lgkmcnt(0)
	v_mfma_f32_32x32x16_bf16 v[32:47], v[64:67], v[68:71], v[32:47]
	v_mfma_f32_32x32x16_bf16 v[0:15], v[64:67], v[72:75], v[0:15]
	ds_read_b128 v[64:67], v237 offset:32768
	ds_read_b128 v[68:71], v238
	ds_read_b128 v[72:75], v238 offset:4096
	s_waitcnt lgkmcnt(0)
	v_mfma_f32_32x32x16_bf16 v[48:63], v[64:67], v[68:71], v[48:63]
	v_mfma_f32_32x32x16_bf16 v[16:31], v[64:67], v[72:75], v[16:31]
	ds_read_b128 v[64:67], v237 offset:36864
	s_waitcnt lgkmcnt(0)
	v_mfma_f32_32x32x16_bf16 v[32:47], v[64:67], v[68:71], v[32:47]
	v_mfma_f32_32x32x16_bf16 v[0:15], v[64:67], v[72:75], v[0:15]
	ds_read_b128 v[64:67], v239 offset:32768
	ds_read_b128 v[68:71], v240
	ds_read_b128 v[72:75], v240 offset:4096
	s_waitcnt lgkmcnt(0)
	v_mfma_f32_32x32x16_bf16 v[48:63], v[64:67], v[68:71], v[48:63]
	v_mfma_f32_32x32x16_bf16 v[16:31], v[64:67], v[72:75], v[16:31]
	ds_read_b128 v[64:67], v239 offset:36864
	s_waitcnt lgkmcnt(0)
	v_mfma_f32_32x32x16_bf16 v[32:47], v[64:67], v[68:71], v[32:47]
	v_mfma_f32_32x32x16_bf16 v[0:15], v[64:67], v[72:75], v[0:15]
	ds_read_b128 v[64:67], v241 offset:32768
	ds_read_b128 v[68:71], v242
	ds_read_b128 v[72:75], v242 offset:4096
	s_waitcnt lgkmcnt(0)
	v_mfma_f32_32x32x16_bf16 v[48:63], v[64:67], v[68:71], v[48:63]
	v_mfma_f32_32x32x16_bf16 v[16:31], v[64:67], v[72:75], v[16:31]
	ds_read_b128 v[64:67], v241 offset:36864
	s_waitcnt vmcnt(0)
	s_waitcnt lgkmcnt(0)
	s_barrier
; #define MFMA(a, b, c) __builtin_amdgcn_mfma_f32_32x32x16_bf16((a), (b), (c), 0, 0, 0)
; DI u16 f2bf(float a) { return (u16)(pk_bf16(a, 0.f) & 0xffffu); }
; DI int crow(int i, int h) { return (i & 3) + 8 * (i >> 2) + 4 * h; }
; #define WAIT_V(n) asm volatile("s_waitcnt vmcnt(%0)" ::"n"(n) : "memory")
; #define RAW_BARRIER() do { asm volatile("s_waitcnt lgkmcnt(0)" ::: "memory"); __builtin_amdgcn_s_barrier(); asm volatile("" ::: "memory"); } while (0)
; #define GLDS_STAGE(slot, kt) do { _Pragma("unroll") for (int i = 0; i < 6; ++i) \
;     __builtin_amdgcn_global_load_lds((const unsigned*)(src[i] + (kt) * 64), (__attribute__((address_space(3))) unsigned*)(smem + (slot) * G_STAGE + (wave + 8 * i) * 1024), 16, 0, 0); } while (0)
; DI void gemm_tile(const u16* __restrict__ X, int ldx, const u16* __restrict__ Wt, int ldw, int K, char* smem,
;                   f32x16 (&acc)[2][2]) {
;     ...
;   for (int kt = 0; kt < nk; ++kt) {
;     const int nxt = (cur >= 1) ? cur - 1 : 2;
;     if (kt + 2 < nk) GLDS_STAGE(nxt, kt + 2);
;     __builtin_amdgcn_sched_barrier(0);
;     const char* st = smem + cur * G_STAGE;
; #pragma unroll
;     for (int ks = 0; ks < 4; ++ks) {
;       bf16x8 a[2], b[2];
; #pragma unroll
;       for (int ft = 0; ft < 2; ++ft) a[ft] = *reinterpret_cast<const bf16x8*>(st + offA[ft] + (((ks * 2 + lh) ^ xa[ft]) << 4));
; #pragma unroll
;       for (int tt = 0; tt < 2; ++tt) b[tt] = *reinterpret_cast<const bf16x8*>(st + offB[tt] + (((ks * 2 + lh) ^ xb[tt]) << 4));
; #pragma unroll
;       for (int ft = 0; ft < 2; ++ft)
; #pragma unroll
;         for (int tt = 0; tt < 2; ++tt) acc[ft][tt] = MFMA(a[ft], b[tt], acc[ft][tt]);
;     }
;     if (kt + 2 < nk) { WAIT_V(6); } else { WAIT_V(0); }
;     RAW_BARRIER();
;     cur = (cur == 2) ? 0 : cur + 1;
;   }
; DI void phase_inproj(const Params& p, char* smem) {
;     ...
;         } else {
;           u16* mv = (u16*)(p.ws + OFF_MEMVT);
;           const int s = lr >> 4, r16 = lr & 15, j = 4 * (r16 >> 3) + (r16 & 3), lh2 = (r16 >> 2) & 1;
; #pragma unroll
;           for (int ft = 0; ft < 2; ++ft) {
;             const int dt = (nt & 1) * 4 + fw * 2 + ft;
; #pragma unroll
;             for (int i = 0; i < 16; ++i) {
;               const int lane2 = lh2 * 32 + crow(i, lh);
;               mv[((((((size_t)(bb * 4 + hh) * 8 + dt) * 8 + kt) * 2 + s) * 64 + lane2) * 8) + j] = f2bf(acc[ft][tt][i]);
;             }
;           }
	s_waitcnt lgkmcnt(0)
	v_mfma_f32_32x32x16_bf16 v[32:47], v[64:67], v[68:71], v[32:47]
	v_mfma_f32_32x32x16_bf16 v[0:15], v[64:67], v[72:75], v[0:15]
	ds_read_b128 v[64:67], v223 offset:32768
	ds_read_b128 v[68:71], v224
	ds_read_b128 v[72:75], v224 offset:4096
	s_and_b64 vcc, exec, s[6:7]
	s_waitcnt lgkmcnt(0)
	v_mfma_f32_32x32x16_bf16 v[48:63], v[64:67], v[68:71], v[48:63]
	v_mfma_f32_32x32x16_bf16 v[16:31], v[64:67], v[72:75], v[16:31]
	ds_read_b128 v[64:67], v223 offset:36864
	s_waitcnt lgkmcnt(0)
	v_mfma_f32_32x32x16_bf16 v[32:47], v[64:67], v[68:71], v[32:47]
	v_mfma_f32_32x32x16_bf16 v[0:15], v[64:67], v[72:75], v[0:15]
	ds_read_b128 v[64:67], v225 offset:32768
	ds_read_b128 v[68:71], v226
	ds_read_b128 v[72:75], v226 offset:4096
	s_waitcnt lgkmcnt(0)
	v_mfma_f32_32x32x16_bf16 v[48:63], v[64:67], v[68:71], v[48:63]
	v_mfma_f32_32x32x16_bf16 v[16:31], v[64:67], v[72:75], v[16:31]
	ds_read_b128 v[64:67], v225 offset:36864
	s_waitcnt lgkmcnt(0)
	v_mfma_f32_32x32x16_bf16 v[32:47], v[64:67], v[68:71], v[32:47]
	v_mfma_f32_32x32x16_bf16 v[0:15], v[64:67], v[72:75], v[0:15]
	ds_read_b128 v[64:67], v227 offset:32768
	ds_read_b128 v[68:71], v228
	ds_read_b128 v[72:75], v228 offset:4096
	s_waitcnt lgkmcnt(0)
	v_mfma_f32_32x32x16_bf16 v[48:63], v[64:67], v[68:71], v[48:63]
	v_mfma_f32_32x32x16_bf16 v[16:31], v[64:67], v[72:75], v[16:31]
	ds_read_b128 v[64:67], v227 offset:36864
	s_waitcnt lgkmcnt(0)
	v_mfma_f32_32x32x16_bf16 v[32:47], v[64:67], v[68:71], v[32:47]
	v_mfma_f32_32x32x16_bf16 v[0:15], v[64:67], v[72:75], v[0:15]
	ds_read_b128 v[64:67], v229 offset:32768
	ds_read_b128 v[68:71], v230
	ds_read_b128 v[72:75], v230 offset:4096
	ds_read_b128 v[76:79], v229 offset:36864
	s_waitcnt vmcnt(0)
	s_waitcnt lgkmcnt(0)
	s_barrier
	s_waitcnt lgkmcnt(0)
	v_mfma_f32_32x32x16_bf16 v[48:63], v[64:67], v[68:71], v[48:63]
	v_mfma_f32_32x32x16_bf16 v[16:31], v[64:67], v[72:75], v[16:31]
	v_add_u32_e32 v64, s8, v107
	s_lshl_b32 s8, s10, 2
	s_and_b32 s9, s8, 4
	s_and_b32 s8, s8, 24
	v_lshl_or_b32 v64, v64, 5, s8
	v_or3_b32 v65, s9, v109, v64
	s_mov_b64 s[8:9], -1
	v_mfma_f32_32x32x16_bf16 v[32:47], v[76:79], v[68:71], v[32:47]
	v_mfma_f32_32x32x16_bf16 v[0:15], v[76:79], v[72:75], v[0:15]
	s_cbranch_vccz .LBB0_147
	v_lshl_or_b32 v66, v65, 14, v243
	v_mov_b32_e32 v67, v87
	v_lshl_add_u64 v[68:69], v[160:161], 0, v[66:67]
	v_cvt_pk_bf16_f32 v67, v48, s0
	v_lshl_add_u64 v[70:71], v[68:69], 0, v[128:129]
	global_store_short v[70:71], v67, off
	v_cvt_pk_bf16_f32 v67, v49, s0
	v_lshl_add_u64 v[70:71], v[68:69], 0, v[130:131]
	global_store_short v[70:71], v67, off
	v_cvt_pk_bf16_f32 v67, v50, s0
	v_lshl_add_u64 v[70:71], v[68:69], 0, v[132:133]
	global_store_short v[70:71], v67, off
	v_cvt_pk_bf16_f32 v67, v51, s0
	v_lshl_add_u64 v[70:71], v[68:69], 0, v[134:135]
	global_store_short v[70:71], v67, off
	v_cvt_pk_bf16_f32 v67, v52, s0
	v_lshl_add_u64 v[70:71], v[68:69], 0, v[136:137]
	global_store_short v[70:71], v67, off
	v_cvt_pk_bf16_f32 v67, v53, s0
	v_lshl_add_u64 v[70:71], v[68:69], 0, v[138:139]
	global_store_short v[70:71], v67, off
	v_cvt_pk_bf16_f32 v67, v54, s0
	v_lshl_add_u64 v[70:71], v[68:69], 0, v[140:141]
	global_store_short v[70:71], v67, off
	v_cvt_pk_bf16_f32 v67, v55, s0
	v_lshl_add_u64 v[70:71], v[68:69], 0, v[142:143]
	global_store_short v[70:71], v67, off
	v_cvt_pk_bf16_f32 v67, v56, s0
	v_lshl_add_u64 v[70:71], v[68:69], 0, v[144:145]
	global_store_short v[70:71], v67, off
	v_cvt_pk_bf16_f32 v67, v57, s0
	v_lshl_add_u64 v[70:71], v[68:69], 0, v[146:147]
	global_store_short v[70:71], v67, off
	v_cvt_pk_bf16_f32 v67, v58, s0
	v_lshl_add_u64 v[70:71], v[68:69], 0, v[148:149]
	global_store_short v[70:71], v67, off
	v_cvt_pk_bf16_f32 v67, v59, s0
	v_lshl_add_u64 v[70:71], v[68:69], 0, v[150:151]
	global_store_short v[70:71], v67, off
	v_cvt_pk_bf16_f32 v67, v60, s0
	v_lshl_add_u64 v[70:71], v[68:69], 0, v[152:153]
	global_store_short v[70:71], v67, off
	v_cvt_pk_bf16_f32 v67, v61, s0
	v_lshl_add_u64 v[70:71], v[68:69], 0, v[154:155]
	global_store_short v[70:71], v67, off
	v_cvt_pk_bf16_f32 v67, v62, s0
	v_lshl_add_u64 v[70:71], v[68:69], 0, v[156:157]
	global_store_short v[70:71], v67, off
	v_cvt_pk_bf16_f32 v67, v63, s0
	v_lshl_add_u64 v[68:69], v[68:69], 0, v[158:159]
	global_store_short v[68:69], v67, off
	v_or_b32_e32 v66, 0x4000, v66
	v_mov_b32_e32 v67, v87
	v_lshl_add_u64 v[66:67], v[160:161], 0, v[66:67]
	v_cvt_pk_bf16_f32 v70, v32, s0
	v_lshl_add_u64 v[68:69], v[66:67], 0, v[128:129]
	global_store_short v[68:69], v70, off
	v_cvt_pk_bf16_f32 v70, v33, s0
	v_lshl_add_u64 v[68:69], v[66:67], 0, v[130:131]
	global_store_short v[68:69], v70, off
	v_cvt_pk_bf16_f32 v70, v34, s0
	v_lshl_add_u64 v[68:69], v[66:67], 0, v[132:133]
	global_store_short v[68:69], v70, off
	v_cvt_pk_bf16_f32 v70, v35, s0
	v_lshl_add_u64 v[68:69], v[66:67], 0, v[134:135]
	global_store_short v[68:69], v70, off
	v_cvt_pk_bf16_f32 v70, v36, s0
	v_lshl_add_u64 v[68:69], v[66:67], 0, v[136:137]
	global_store_short v[68:69], v70, off
	v_cvt_pk_bf16_f32 v70, v37, s0
	v_lshl_add_u64 v[68:69], v[66:67], 0, v[138:139]
	global_store_short v[68:69], v70, off
	v_cvt_pk_bf16_f32 v70, v38, s0
	v_lshl_add_u64 v[68:69], v[66:67], 0, v[140:141]
	global_store_short v[68:69], v70, off
	v_cvt_pk_bf16_f32 v70, v39, s0
	v_lshl_add_u64 v[68:69], v[66:67], 0, v[142:143]
	global_store_short v[68:69], v70, off
	v_cvt_pk_bf16_f32 v70, v40, s0
	v_lshl_add_u64 v[68:69], v[66:67], 0, v[144:145]
	global_store_short v[68:69], v70, off
	v_cvt_pk_bf16_f32 v70, v41, s0
	v_lshl_add_u64 v[68:69], v[66:67], 0, v[146:147]
	global_store_short v[68:69], v70, off
	v_cvt_pk_bf16_f32 v70, v42, s0
	v_lshl_add_u64 v[68:69], v[66:67], 0, v[148:149]
	global_store_short v[68:69], v70, off
	v_cvt_pk_bf16_f32 v70, v43, s0
	v_lshl_add_u64 v[68:69], v[66:67], 0, v[150:151]
	global_store_short v[68:69], v70, off
	v_cvt_pk_bf16_f32 v70, v44, s0
	v_lshl_add_u64 v[68:69], v[66:67], 0, v[152:153]
	global_store_short v[68:69], v70, off
	v_cvt_pk_bf16_f32 v70, v45, s0
	v_lshl_add_u64 v[68:69], v[66:67], 0, v[154:155]
	global_store_short v[68:69], v70, off
	v_cvt_pk_bf16_f32 v70, v46, s0
	v_lshl_add_u64 v[68:69], v[66:67], 0, v[156:157]
	global_store_short v[68:69], v70, off
	v_cvt_pk_bf16_f32 v68, v47, s0
	v_lshl_add_u64 v[66:67], v[66:67], 0, v[158:159]
	global_store_short v[66:67], v68, off
	s_mov_b64 s[8:9], 0

; DI int wave_incl_scan(int v, int lane) {
; #pragma unroll
;   for (int d = 1; d < 64; d <<= 1) {
;     int t = __shfl_up(v, d);
;     if (lane >= d) v += t;
;   }
;   return v;
; }
; DI void dsa_thr_item(const Params& p, int b, int qblk, char* smem) {
;     ...
; #pragma unroll 1
;     for (int qq = 0; qq < 4; ++qq) {
;       const int q = wave * 4 + qq;
;       const int rk = rank[q];
;       int c[4];
; #pragma unroll
;       for (int j = 0; j < 4; ++j) c[j] = (int)hist[(255 - 4 * lane - j) * 32 + q];
;       int s = c[0] + c[1] + c[2] + c[3];
;       int P = wave_incl_scan(s, lane);
;       int excl = P - s;
;       if (P >= rk && excl < rk) {
.LBB0_338:
	v_add_u32_e32 v0, s58, v70
	v_add_u32_e32 v1, s58, v69
	ds_read_b32 v6, v0
	ds_read_b32 v4, v1 offset:256
	ds_read2_b32 v[0:1], v1 offset1:32
	s_waitcnt lgkmcnt(1)
	v_add_u32_e32 v2, v4, v6
	s_waitcnt lgkmcnt(0)
	v_add3_u32 v5, v2, v1, v0
	v_mov_b32_e32 v8, v5
	v_add_u32_e32 v2, s58, v68
	ds_read_b32 v3, v2 offset:128
	s_nop 0
	v_add_u32_dpp v8, v8, v8 row_shr:1 row_mask:0xf bank_mask:0xf bound_ctrl:0
	s_nop 1
	v_add_u32_dpp v8, v8, v8 row_shr:2 row_mask:0xf bank_mask:0xf bound_ctrl:0
	s_nop 1
	v_add_u32_dpp v8, v8, v8 row_shr:4 row_mask:0xf bank_mask:0xf bound_ctrl:0
	s_nop 1
	v_add_u32_dpp v8, v8, v8 row_shr:8 row_mask:0xf bank_mask:0xf bound_ctrl:0
	s_nop 1
	v_add_u32_dpp v8, v8, v8 row_bcast:15 row_mask:0xa bank_mask:0xf
	s_nop 1
	v_add_u32_dpp v8, v8, v8 row_bcast:31 row_mask:0xc bank_mask:0xf
	v_sub_u32_e32 v7, v8, v5
	s_waitcnt lgkmcnt(0)
	v_cmp_ge_i32_e64 s[0:1], v8, v3
	v_cmp_gt_i32_e64 s[52:53], v3, v7
	s_and_b64 s[0:1], s[0:1], s[52:53]
	s_and_saveexec_b64 s[52:53], s[0:1]
	s_cbranch_execz .LBB0_337
	v_add_u32_e32 v8, v7, v6
	v_cmp_lt_i32_e64 s[0:1], v8, v3
	v_sub_u32_e32 v5, v3, v7
	s_mov_b64 s[54:55], -1
	v_cndmask_b32_e64 v6, 0, v6, s[0:1]
	v_add_u32_e32 v7, v6, v7
	s_mov_b64 s[62:63], -1
	v_mov_b32_e32 v6, v60
	s_and_saveexec_b64 s[60:61], s[0:1]
	s_cbranch_execz .LBB0_343
	v_add_u32_e32 v5, v7, v4
	v_cmp_ge_i32_e64 s[0:1], v5, v3
	v_mov_b32_e32 v6, 0
	v_mov_b32_e32 v5, 1
	s_mov_b64 s[62:63], 0
	s_and_saveexec_b64 s[64:65], s[0:1]
	s_mov_b64 s[62:63], exec
	v_sub_u32_e32 v5, v3, v7
	v_mov_b32_e32 v6, v62
	s_or_b64 exec, exec, s[64:65]
	s_orn2_b64 s[62:63], s[62:63], exec

; #define MFMA(a, b, c) __builtin_amdgcn_mfma_f32_32x32x16_bf16((a), (b), (c), 0, 0, 0)
; DI f32x16 zero16() { f32x16 z; for (int i = 0; i < 16; ++i) z[i] = 0.f; return z; }
; DI void dsa_attn_item(const Params& p, int b, int qblk, char* smem) {
;     ...
;         const int gn = min(g + 1, qblk);
;         const u16* kr = kfr + (size_t)gn * 2048;
; #pragma unroll
;         for (int ks = 0; ks < 4; ++ks) Kn[ks] = ldg8(kr + ks * 512);
; #pragma unroll
;         for (int dt = 0; dt < 2; ++dt)
; #pragma unroll
;           for (int s = 0; s < 2; ++s) Vn[dt][s] = ldg8(vfr + (size_t)gn * 2048 + (dt * 2 + s) * 512);
;       }
;       const unsigned bits = maskbuf[(buf * 8 + t8) * 64 + lane];
;       f32x16 Sx = zero16();
;       __builtin_amdgcn_s_setprio(1);
; #pragma unroll
;       for (int ks = 0; ks < 4; ++ks) Sx = MFMA(Kf[ks], Qf[ks], Sx);
;       __builtin_amdgcn_s_setprio(0);
;       float sm[16];
; #pragma unroll
;       for (int i = 0; i < 16; ++i) {
;         const unsigned t = (unsigned)__builtin_amdgcn_sbfe((int)bits, i, 1);
;         sm[i] = __uint_as_float((t & __float_as_uint(Sx[i])) | (~t & 0xff800000u));
;       }
;       float mt = fmaxf(fmaxf(fmaxf(sm[0], sm[1]), fmaxf(sm[2], sm[3])), fmaxf(fmaxf(sm[4], sm[5]), fmaxf(sm[6], sm[7])));
;       mt = fmaxf(mt, fmaxf(fmaxf(fmaxf(sm[8], sm[9]), fmaxf(sm[10], sm[11])), fmaxf(fmaxf(sm[12], sm[13]), fmaxf(sm[14], sm[15]))));
;       mt = fmaxf(mt, __shfl_xor(mt, 32));
;       if (__builtin_amdgcn_ballot_w64(mt > mrun + 8.f) != 0ull) {
;         const float mnew = fmaxf(mrun, mt);
;         const float ms = (mnew == -INFINITY) ? 0.f : mnew;
;         const float alpha = __builtin_amdgcn_exp2f(mrun - ms);
;         lrun *= alpha;
;         mrun = mnew;
; #pragma unroll
;         for (int dt = 0; dt < 2; ++dt)
; #pragma unroll
;           for (int i = 0; i < 16; ++i) O[dt][i] *= alpha;
;       }
.LBB0_439:
	s_add_i32 s7, s53, s6
	s_cmp_le_u32 s7, s52
	s_cselect_b64 s[0:1], -1, 0
	s_cmp_gt_u32 s7, s52
	s_cbranch_scc1 .LBB0_443
	s_add_i32 s7, s7, 1
	s_min_i32 s40, s7, s52
	s_lshl_b64 s[10:11], s[40:41], 12
	v_lshl_add_u64 v[34:35], v[198:199], 0, s[10:11]
	global_load_dwordx4 v[66:69], v[34:35], off
	global_load_dwordx4 v[70:73], v[34:35], off offset:1024
	global_load_dwordx4 v[74:77], v[34:35], off offset:2048
	global_load_dwordx4 v[78:81], v[34:35], off offset:3072
	v_lshl_add_u64 v[34:35], v[200:201], 0, s[10:11]
	global_load_dwordx4 v[50:53], v[34:35], off
	global_load_dwordx4 v[54:57], v[34:35], off offset:1024
	global_load_dwordx4 v[58:61], v[34:35], off offset:2048
	global_load_dwordx4 v[62:65], v[34:35], off offset:3072
	s_waitcnt vmcnt(11)
	ds_read_u16 v154, v0
	s_setprio 1
	v_mfma_f32_32x32x16_bf16 v[34:49], v[150:153], v[98:101], 0
	v_mfma_f32_32x32x16_bf16 v[34:49], v[146:149], v[102:105], v[34:49]
	v_mfma_f32_32x32x16_bf16 v[34:49], v[142:145], v[106:109], v[34:49]
	v_mfma_f32_32x32x16_bf16 v[34:49], v[138:141], v[110:113], v[34:49]
	s_setprio 0
	s_waitcnt lgkmcnt(0)
	v_bfe_i32 v238, v154, 0, 1
	v_bfe_i32 v239, v154, 1, 1
	v_bfe_i32 v240, v154, 2, 1
	v_bfe_i32 v241, v154, 3, 1
	v_bfe_i32 v242, v154, 4, 1
	v_bfe_i32 v243, v154, 5, 1
	v_bfe_i32 v244, v154, 6, 1
	v_bfe_i32 v245, v154, 7, 1
	v_bfe_i32 v246, v154, 8, 1
	v_bfe_i32 v247, v154, 9, 1
	v_bfe_i32 v248, v154, 10, 1
	v_bfe_i32 v249, v154, 11, 1
	v_bfe_i32 v250, v154, 12, 1
	v_bfe_i32 v251, v154, 13, 1
	v_bfe_i32 v252, v154, 14, 1
	v_bfe_i32 v253, v154, 15, 1
	v_bitop3_b32 v34, v34, s50, v238 bitop3:0xe4
	v_bitop3_b32 v35, v35, s50, v239 bitop3:0xe4
	v_bitop3_b32 v36, v36, s50, v240 bitop3:0xe4
	v_bitop3_b32 v37, v37, s50, v241 bitop3:0xe4
	v_bitop3_b32 v38, v38, s50, v242 bitop3:0xe4
	v_bitop3_b32 v39, v39, s50, v243 bitop3:0xe4
	v_bitop3_b32 v40, v40, s50, v244 bitop3:0xe4
	v_bitop3_b32 v41, v41, s50, v245 bitop3:0xe4
	v_bitop3_b32 v42, v42, s50, v246 bitop3:0xe4
	v_bitop3_b32 v43, v43, s50, v247 bitop3:0xe4
	v_bitop3_b32 v44, v44, s50, v248 bitop3:0xe4
	v_bitop3_b32 v45, v45, s50, v249 bitop3:0xe4
	v_bitop3_b32 v46, v46, s50, v250 bitop3:0xe4
	v_bitop3_b32 v47, v47, s50, v251 bitop3:0xe4
	v_bitop3_b32 v48, v48, s50, v252 bitop3:0xe4
	v_bitop3_b32 v49, v49, s50, v253 bitop3:0xe4
	v_max_f32_e32 v138, v36, v37
	v_max_f32_e32 v139, v40, v41
	v_max_f32_e32 v140, v42, v43
	v_max_f32_e32 v141, v44, v45
	v_max_f32_e32 v142, v48, v49
	v_max3_f32 v142, v46, v47, v142
	v_max3_f32 v138, v34, v35, v138
	v_max3_f32 v139, v38, v39, v139
	v_max3_f32 v140, v140, v141, v142
	v_max3_f32 v138, v138, v139, v140
	v_mov_b32_e32 v139, v138
	s_nop 1
	v_permlane32_swap_b32_e32 v139, v138
	v_max_f32_e32 v138, v138, v139
	v_add_f32_e32 v139, 0x41000000, v193
	v_cmp_gt_f32_e32 vcc, v138, v139
	s_cbranch_vccz .LBB0_442
	v_max_f32_e32 v138, v138, v138
	v_max_f32_e32 v139, v193, v193
	v_max_f32_e32 v139, v139, v138
	v_cmp_neq_f32_e32 vcc, s50, v139
	s_nop 1
	v_cndmask_b32_e32 v138, 0, v139, vcc
	v_sub_f32_e32 v138, v193, v138
	v_exp_f32_e32 v138, v138
	v_mov_b32_e32 v193, v139
	v_pk_mul_f32 v[32:33], v[32:33], v[138:139] op_sel_hi:[1,0]
	v_pk_mul_f32 v[30:31], v[30:31], v[138:139] op_sel_hi:[1,0]
	v_pk_mul_f32 v[28:29], v[28:29], v[138:139] op_sel_hi:[1,0]
	v_pk_mul_f32 v[26:27], v[26:27], v[138:139] op_sel_hi:[1,0]
	v_pk_mul_f32 v[24:25], v[24:25], v[138:139] op_sel_hi:[1,0]
	v_pk_mul_f32 v[22:23], v[22:23], v[138:139] op_sel_hi:[1,0]
	v_pk_mul_f32 v[20:21], v[20:21], v[138:139] op_sel_hi:[1,0]
	v_pk_mul_f32 v[18:19], v[18:19], v[138:139] op_sel_hi:[1,0]
	v_pk_mul_f32 v[16:17], v[16:17], v[138:139] op_sel_hi:[1,0]
	v_pk_mul_f32 v[14:15], v[14:15], v[138:139] op_sel_hi:[1,0]
	v_pk_mul_f32 v[12:13], v[12:13], v[138:139] op_sel_hi:[1,0]
	v_pk_mul_f32 v[10:11], v[10:11], v[138:139] op_sel_hi:[1,0]
	v_pk_mul_f32 v[8:9], v[8:9], v[138:139] op_sel_hi:[1,0]
	v_pk_mul_f32 v[6:7], v[6:7], v[138:139] op_sel_hi:[1,0]
	v_pk_mul_f32 v[4:5], v[4:5], v[138:139] op_sel_hi:[1,0]
	v_pk_mul_f32 v[2:3], v[2:3], v[138:139] op_sel_hi:[1,0]
	v_mul_f32_e32 v171, v171, v138

; #define MFMA(a, b, c) __builtin_amdgcn_mfma_f32_32x32x16_bf16((a), (b), (c), 0, 0, 0)
; #define WAIT_V(n) asm volatile("s_waitcnt vmcnt(%0)" ::"n"(n) : "memory")
; #define RAW_BARRIER() do { asm volatile("s_waitcnt lgkmcnt(0)" ::: "memory"); __builtin_amdgcn_s_barrier(); asm volatile("" ::: "memory"); } while (0)
; #define GLDS_STAGE(slot, kt) do { _Pragma("unroll") for (int i = 0; i < 6; ++i) \
;     __builtin_amdgcn_global_load_lds((const unsigned*)(src[i] + (kt) * 64), (__attribute__((address_space(3))) unsigned*)(smem + (slot) * G_STAGE + (wave + 8 * i) * 1024), 16, 0, 0); } while (0)
; DI void gemm_tile(const u16* __restrict__ X, int ldx, const u16* __restrict__ Wt, int ldw, int K, char* smem,
;                   f32x16 (&acc)[2][2]) {
;     ...
;   const int nk = K / 64;
;   const u16* src[6];
; #pragma unroll
;   for (int i = 0; i < 6; ++i) {
;     const int R = 8 * (wave + 8 * i) + (lane >> 3);
;     const int c = (lane & 7) ^ ((R >> 1) & 7);
;     src[i] = (i < 4) ? (X + (size_t)R * ldx + c * 8) : (Wt + (size_t)(R - 256) * ldw + c * 8);
;   }
;     ...
;   int offA[2], offB[2], xa[2], xb[2];
; #pragma unroll
;   for (int ft = 0; ft < 2; ++ft) { const int R = 256 + fw * 64 + ft * 32 + lr; offA[ft] = R * 128; xa[ft] = (R >> 1) & 7; }
; #pragma unroll
;   for (int tt = 0; tt < 2; ++tt) { const int R = tq * 64 + tt * 32 + lr; offB[tt] = R * 128; xb[tt] = (R >> 1) & 7; }
;   GLDS_STAGE(0, 0); GLDS_STAGE(1, 1); WAIT_V(6); RAW_BARRIER();
;   int cur = 0;
;   for (int kt = 0; kt < nk; ++kt) {
;     const int nxt = (cur >= 1) ? cur - 1 : 2;
;     if (kt + 2 < nk) GLDS_STAGE(nxt, kt + 2);
;     __builtin_amdgcn_sched_barrier(0);
;     const char* st = smem + cur * G_STAGE;
; #pragma unroll
;     for (int ks = 0; ks < 4; ++ks) {
;       bf16x8 a[2], b[2];
; #pragma unroll
;       for (int ft = 0; ft < 2; ++ft) a[ft] = *reinterpret_cast<const bf16x8*>(st + offA[ft] + (((ks * 2 + lh) ^ xa[ft]) << 4));
; #pragma unroll
;       for (int tt = 0; tt < 2; ++tt) b[tt] = *reinterpret_cast<const bf16x8*>(st + offB[tt] + (((ks * 2 + lh) ^ xb[tt]) << 4));
; #pragma unroll
;       for (int ft = 0; ft < 2; ++ft)
; #pragma unroll
;         for (int tt = 0; tt < 2; ++tt) acc[ft][tt] = MFMA(a[ft], b[tt], acc[ft][tt]);
;     }
;     if (kt + 2 < nk) { WAIT_V(6); } else { WAIT_V(0); }
;     RAW_BARRIER();
;     cur = (cur == 2) ? 0 : cur + 1;
;   }
.LBB0_566:
	s_lshl_b32 s0, s77, 8
	s_and_b32 s0, s0, 0x7800
	s_and_b32 s4, s3, 7
	v_add_u32_e32 v0, s0, v105
	v_lshl_or_b32 v1, s4, 9, v108
	v_lshl_or_b32 v64, v0, 12, v1
	v_add_u32_e32 v0, s0, v106
	v_lshl_add_u64 v[72:73], s[82:83], 0, v[64:65]
	v_lshl_add_u64 v[74:75], s[80:81], 0, v[64:65]
	v_lshl_or_b32 v64, v0, 12, v1
	v_add_u32_e32 v0, s0, v107
	v_lshl_add_u64 v[76:77], s[82:83], 0, v[64:65]
	v_lshl_add_u64 v[78:79], s[80:81], 0, v[64:65]
	v_lshl_or_b32 v64, v0, 12, v1
	v_add_u32_e32 v0, s0, v104
	s_and_b32 s0, s77, 0x78
	s_or_b32 s0, s0, s33
	s_and_b32 s6, s77, 7
	s_lshl_b32 s0, s0, 19
	v_lshl_add_u64 v[80:81], s[82:83], 0, v[64:65]
	v_lshl_add_u64 v[82:83], s[80:81], 0, v[64:65]
	v_lshl_or_b32 v64, v0, 12, v1
	v_lshl_add_u64 v[0:1], v[66:67], 0, s[0:1]
	s_lshl_b32 s0, s6, 18
	v_readfirstlane_b32 s6, v143
	v_lshl_add_u64 v[88:89], v[0:1], 0, v[70:71]
	s_mov_b32 m0, s6
	v_readfirstlane_b32 s86, v109
	v_lshl_add_u64 v[0:1], v[88:89], 0, s[8:9]
	s_mov_b64 s[4:5], 0x40000
	global_load_lds_dwordx4 v[88:89], off
	s_mov_b32 m0, s86
	v_readfirstlane_b32 s85, v110
	v_lshl_add_u64 v[2:3], v[88:89], 0, s[4:5]
	s_mov_b64 s[4:5], 0x60000
	global_load_lds_dwordx4 v[0:1], off
	s_mov_b32 m0, s85
	v_readfirstlane_b32 s84, v111
	v_lshl_add_u64 v[4:5], v[88:89], 0, s[4:5]
	v_lshl_add_u64 v[6:7], v[68:69], 0, s[0:1]
	global_load_lds_dwordx4 v[2:3], off
	s_mov_b32 m0, s84
	v_readfirstlane_b32 s79, v112
	v_lshl_add_u64 v[90:91], v[6:7], 0, v[70:71]
	global_load_lds_dwordx4 v[4:5], off
	s_mov_b32 m0, s79
	v_readfirstlane_b32 s55, v113
	v_lshl_add_u64 v[6:7], v[90:91], 0, s[8:9]
	global_load_lds_dwordx4 v[90:91], off
	s_mov_b32 m0, s55
	v_readfirstlane_b32 s54, v92
	global_load_lds_dwordx4 v[6:7], off
	v_lshl_add_u64 v[0:1], v[88:89], 0, s[10:11]
	s_mov_b32 m0, s54
	v_readfirstlane_b32 s0, v114
	global_load_lds_dwordx4 v[0:1], off
	v_lshl_add_u64 v[0:1], v[88:89], 0, s[14:15]
	s_mov_b32 m0, s0
	s_mov_b64 s[4:5], 0x40080
	global_load_lds_dwordx4 v[0:1], off
	v_lshl_add_u64 v[0:1], v[88:89], 0, s[4:5]
	v_readfirstlane_b32 s4, v115
	s_mov_b32 m0, s4
	s_mov_b64 s[4:5], 0x60080
	global_load_lds_dwordx4 v[0:1], off
	v_lshl_add_u64 v[0:1], v[88:89], 0, s[4:5]
	v_readfirstlane_b32 s4, v116
	s_mov_b32 m0, s4
	v_readfirstlane_b32 s4, v117
	global_load_lds_dwordx4 v[0:1], off
	v_lshl_add_u64 v[0:1], v[90:91], 0, s[10:11]
	s_mov_b32 m0, s4
	v_readfirstlane_b32 s4, v118
	global_load_lds_dwordx4 v[0:1], off
	v_lshl_add_u64 v[0:1], v[90:91], 0, s[14:15]
	s_mov_b32 m0, s4
	v_readfirstlane_b32 s4, v93
	global_load_lds_dwordx4 v[0:1], off
	s_waitcnt vmcnt(6)
	s_waitcnt lgkmcnt(0)
	s_barrier
	v_lshl_add_u64 v[0:1], v[88:89], 0, s[16:17]
	s_mov_b32 m0, s4
	v_readfirstlane_b32 s90, v94
	global_load_lds_dwordx4 v[0:1], off
	v_lshl_add_u64 v[0:1], v[88:89], 0, s[18:19]
	s_mov_b32 m0, s90
	s_mov_b64 s[88:89], 0x40100
	global_load_lds_dwordx4 v[0:1], off
	v_lshl_add_u64 v[0:1], v[88:89], 0, s[88:89]
	v_readfirstlane_b32 s88, v95
	s_mov_b32 m0, s88
	s_mov_b64 s[92:93], 0x60100
	v_readfirstlane_b32 s89, v96
	global_load_lds_dwordx4 v[0:1], off
	v_lshl_add_u64 v[0:1], v[88:89], 0, s[92:93]
	s_mov_b32 m0, s89
	v_readfirstlane_b32 s7, v97
	global_load_lds_dwordx4 v[0:1], off
	v_lshl_add_u64 v[0:1], v[90:91], 0, s[16:17]
	s_mov_b32 m0, s7
	v_readfirstlane_b32 s87, v98
	global_load_lds_dwordx4 v[0:1], off
	v_lshl_add_u64 v[0:1], v[90:91], 0, s[18:19]
	s_mov_b32 m0, s87
	v_lshl_add_u64 v[84:85], s[80:81], 0, v[64:65]
	global_load_lds_dwordx4 v[0:1], off
	v_lshl_add_u64 v[86:87], s[82:83], 0, v[64:65]
	ds_read_b128 v[0:3], v119 offset:32768
	ds_read_b128 v[4:7], v119 offset:36864
	ds_read_b128 v[8:11], v120
	ds_read_b128 v[12:15], v120 offset:4096
	ds_read_b128 v[150:153], v121 offset:32768
	ds_read_b128 v[154:157], v121 offset:36864
	ds_read_b128 v[158:161], v122
	ds_read_b128 v[180:183], v122 offset:4096
	s_mov_b32 m0, s6
	s_mov_b64 s[92:93], 0x40180
	s_waitcnt lgkmcnt(0)
	v_mfma_f32_32x32x16_bf16 v[48:63], v[0:3], v[8:11], 0
	v_mfma_f32_32x32x16_bf16 v[16:31], v[0:3], v[12:15], 0
	s_waitcnt vmcnt(0)
	v_mfma_f32_32x32x16_bf16 v[32:47], v[4:7], v[8:11], 0
	v_mfma_f32_32x32x16_bf16 v[0:15], v[4:7], v[12:15], 0
	ds_read_b128 v[184:187], v123 offset:32768
	ds_read_b128 v[188:191], v123 offset:36864
	ds_read_b128 v[192:195], v124
	ds_read_b128 v[196:199], v124 offset:4096
	s_waitcnt lgkmcnt(4)
	v_mfma_f32_32x32x16_bf16 v[48:63], v[150:153], v[158:161], v[48:63]
	v_mfma_f32_32x32x16_bf16 v[16:31], v[150:153], v[180:183], v[16:31]
	v_mfma_f32_32x32x16_bf16 v[32:47], v[154:157], v[158:161], v[32:47]
	v_mfma_f32_32x32x16_bf16 v[0:15], v[154:157], v[180:183], v[0:15]
	ds_read_b128 v[150:153], v125 offset:32768
	ds_read_b128 v[154:157], v125 offset:36864
	ds_read_b128 v[158:161], v126
	ds_read_b128 v[180:183], v126 offset:4096
	s_waitcnt lgkmcnt(4)
	v_mfma_f32_32x32x16_bf16 v[48:63], v[184:187], v[192:195], v[48:63]
	v_mfma_f32_32x32x16_bf16 v[16:31], v[184:187], v[196:199], v[16:31]
	v_mfma_f32_32x32x16_bf16 v[32:47], v[188:191], v[192:195], v[32:47]
	v_mfma_f32_32x32x16_bf16 v[0:15], v[188:191], v[196:199], v[0:15]
	s_waitcnt vmcnt(6)
	s_waitcnt lgkmcnt(0)
	s_barrier
; #define MFMA(a, b, c) __builtin_amdgcn_mfma_f32_32x32x16_bf16((a), (b), (c), 0, 0, 0)
; #define WAIT_V(n) asm volatile("s_waitcnt vmcnt(%0)" ::"n"(n) : "memory")
; #define RAW_BARRIER() do { asm volatile("s_waitcnt lgkmcnt(0)" ::: "memory"); __builtin_amdgcn_s_barrier(); asm volatile("" ::: "memory"); } while (0)
; #define GLDS_STAGE(slot, kt) do { _Pragma("unroll") for (int i = 0; i < 6; ++i) \
;     __builtin_amdgcn_global_load_lds((const unsigned*)(src[i] + (kt) * 64), (__attribute__((address_space(3))) unsigned*)(smem + (slot) * G_STAGE + (wave + 8 * i) * 1024), 16, 0, 0); } while (0)
; DI void gemm_tile(const u16* __restrict__ X, int ldx, const u16* __restrict__ Wt, int ldw, int K, char* smem,
;                   f32x16 (&acc)[2][2]) {
;     ...
;   int offA[2], offB[2], xa[2], xb[2];
; #pragma unroll
;   for (int ft = 0; ft < 2; ++ft) { const int R = 256 + fw * 64 + ft * 32 + lr; offA[ft] = R * 128; xa[ft] = (R >> 1) & 7; }
; #pragma unroll
;   for (int tt = 0; tt < 2; ++tt) { const int R = tq * 64 + tt * 32 + lr; offB[tt] = R * 128; xb[tt] = (R >> 1) & 7; }
;   GLDS_STAGE(0, 0); GLDS_STAGE(1, 1); WAIT_V(6); RAW_BARRIER();
;   int cur = 0;
;   for (int kt = 0; kt < nk; ++kt) {
;     const int nxt = (cur >= 1) ? cur - 1 : 2;
;     if (kt + 2 < nk) GLDS_STAGE(nxt, kt + 2);
;     __builtin_amdgcn_sched_barrier(0);
;     const char* st = smem + cur * G_STAGE;
; #pragma unroll
;     for (int ks = 0; ks < 4; ++ks) {
;       bf16x8 a[2], b[2];
; #pragma unroll
;       for (int ft = 0; ft < 2; ++ft) a[ft] = *reinterpret_cast<const bf16x8*>(st + offA[ft] + (((ks * 2 + lh) ^ xa[ft]) << 4));
; #pragma unroll
;       for (int tt = 0; tt < 2; ++tt) b[tt] = *reinterpret_cast<const bf16x8*>(st + offB[tt] + (((ks * 2 + lh) ^ xb[tt]) << 4));
; #pragma unroll
;       for (int ft = 0; ft < 2; ++ft)
; #pragma unroll
;         for (int tt = 0; tt < 2; ++tt) acc[ft][tt] = MFMA(a[ft], b[tt], acc[ft][tt]);
;     }
;     if (kt + 2 < nk) { WAIT_V(6); } else { WAIT_V(0); }
;     RAW_BARRIER();
	ds_read_b128 v[184:187], v127 offset:32768
	ds_read_b128 v[188:191], v127 offset:36864
	ds_read_b128 v[192:195], v120 offset:49152
	ds_read_b128 v[196:199], v120 offset:53248
	s_waitcnt lgkmcnt(4)
	v_mfma_f32_32x32x16_bf16 v[48:63], v[150:153], v[158:161], v[48:63]
	v_mfma_f32_32x32x16_bf16 v[16:31], v[150:153], v[180:183], v[16:31]
	v_lshl_add_u64 v[150:151], v[88:89], 0, s[20:21]
	global_load_lds_dwordx4 v[150:151], off
	v_mfma_f32_32x32x16_bf16 v[0:15], v[154:157], v[180:183], v[0:15]
	v_mfma_f32_32x32x16_bf16 v[32:47], v[154:157], v[158:161], v[32:47]
	v_lshl_add_u64 v[150:151], v[88:89], 0, s[22:23]
	s_mov_b32 m0, s86
	s_nop 0
	global_load_lds_dwordx4 v[150:151], off
	ds_read_b128 v[150:153], v128 offset:32768
	ds_read_b128 v[154:157], v128 offset:36864
	ds_read_b128 v[158:161], v122 offset:49152
	ds_read_b128 v[180:183], v122 offset:53248
	s_waitcnt lgkmcnt(4)
	v_mfma_f32_32x32x16_bf16 v[48:63], v[184:187], v[192:195], v[48:63]
	v_mfma_f32_32x32x16_bf16 v[16:31], v[184:187], v[196:199], v[16:31]
	v_lshl_add_u64 v[252:253], v[88:89], 0, s[92:93]
	s_mov_b32 m0, s85
	s_mov_b64 s[92:93], 0x60180
	global_load_lds_dwordx4 v[252:253], off
	v_mfma_f32_32x32x16_bf16 v[32:47], v[188:191], v[192:195], v[32:47]
	v_mfma_f32_32x32x16_bf16 v[0:15], v[188:191], v[196:199], v[0:15]
	v_lshl_add_u64 v[252:253], v[88:89], 0, s[92:93]
	s_mov_b32 m0, s84
	s_nop 0
	global_load_lds_dwordx4 v[252:253], off
	ds_read_b128 v[184:187], v129 offset:32768
	ds_read_b128 v[188:191], v129 offset:36864
	ds_read_b128 v[192:195], v124 offset:49152
	ds_read_b128 v[196:199], v124 offset:53248
	s_waitcnt lgkmcnt(4)
	v_mfma_f32_32x32x16_bf16 v[48:63], v[150:153], v[158:161], v[48:63]
	v_mfma_f32_32x32x16_bf16 v[16:31], v[150:153], v[180:183], v[16:31]
	v_lshl_add_u64 v[252:253], v[90:91], 0, s[20:21]
	s_mov_b32 m0, s79
	s_nop 0
	global_load_lds_dwordx4 v[252:253], off
	v_mfma_f32_32x32x16_bf16 v[32:47], v[154:157], v[158:161], v[32:47]
	v_mfma_f32_32x32x16_bf16 v[0:15], v[154:157], v[180:183], v[0:15]
	v_lshl_add_u64 v[252:253], v[90:91], 0, s[22:23]
	s_mov_b32 m0, s55
	s_nop 0
	global_load_lds_dwordx4 v[252:253], off
	s_mov_b32 m0, s54
	s_mov_b64 s[92:93], 0x40200
	v_readfirstlane_b32 s91, v99
	v_readfirstlane_b32 s95, v102
	ds_read_b128 v[150:153], v130 offset:32768
	ds_read_b128 v[154:157], v130 offset:36864
	ds_read_b128 v[158:161], v126 offset:49152
	ds_read_b128 v[180:183], v126 offset:53248
	s_waitcnt lgkmcnt(4)
	v_mfma_f32_32x32x16_bf16 v[48:63], v[184:187], v[192:195], v[48:63]
	v_mfma_f32_32x32x16_bf16 v[16:31], v[184:187], v[196:199], v[16:31]
	v_mfma_f32_32x32x16_bf16 v[32:47], v[188:191], v[192:195], v[32:47]
	v_mfma_f32_32x32x16_bf16 v[0:15], v[188:191], v[196:199], v[0:15]
	s_waitcnt vmcnt(6)
	s_waitcnt lgkmcnt(0)
	s_barrier
	ds_read_b128 v[184:187], v131 offset:32768
	ds_read_b128 v[188:191], v131 offset:36864
	ds_read_b128 v[192:195], v132
	ds_read_b128 v[196:199], v132 offset:4096
	s_waitcnt lgkmcnt(4)
	v_mfma_f32_32x32x16_bf16 v[48:63], v[150:153], v[158:161], v[48:63]
	v_mfma_f32_32x32x16_bf16 v[16:31], v[150:153], v[180:183], v[16:31]
	v_lshl_add_u64 v[150:151], v[88:89], 0, s[24:25]
	global_load_lds_dwordx4 v[150:151], off
	v_mfma_f32_32x32x16_bf16 v[0:15], v[154:157], v[180:183], v[0:15]
	v_mfma_f32_32x32x16_bf16 v[32:47], v[154:157], v[158:161], v[32:47]
	v_lshl_add_u64 v[150:151], v[88:89], 0, s[26:27]
	s_mov_b32 m0, s0
	s_nop 0
	global_load_lds_dwordx4 v[150:151], off
	ds_read_b128 v[150:153], v133 offset:32768
	ds_read_b128 v[154:157], v133 offset:36864
	ds_read_b128 v[158:161], v134
	ds_read_b128 v[180:183], v134 offset:4096
	s_waitcnt lgkmcnt(4)
	v_mfma_f32_32x32x16_bf16 v[48:63], v[184:187], v[192:195], v[48:63]
	v_mfma_f32_32x32x16_bf16 v[16:31], v[184:187], v[196:199], v[16:31]
	v_lshl_add_u64 v[252:253], v[88:89], 0, s[92:93]
	s_mov_b32 m0, s91
	s_mov_b64 s[92:93], 0x60200
	global_load_lds_dwordx4 v[252:253], off
	v_mfma_f32_32x32x16_bf16 v[32:47], v[188:191], v[192:195], v[32:47]
	v_mfma_f32_32x32x16_bf16 v[0:15], v[188:191], v[196:199], v[0:15]
	v_lshl_add_u64 v[252:253], v[88:89], 0, s[92:93]
	v_readfirstlane_b32 s93, v100
	s_mov_b32 m0, s93
	v_readfirstlane_b32 s92, v101
	global_load_lds_dwordx4 v[252:253], off
	ds_read_b128 v[184:187], v135 offset:32768
	ds_read_b128 v[188:191], v135 offset:36864
	ds_read_b128 v[192:195], v136
	ds_read_b128 v[196:199], v136 offset:4096
	s_waitcnt lgkmcnt(4)
	v_mfma_f32_32x32x16_bf16 v[48:63], v[150:153], v[158:161], v[48:63]
	v_mfma_f32_32x32x16_bf16 v[16:31], v[150:153], v[180:183], v[16:31]
	v_lshl_add_u64 v[252:253], v[90:91], 0, s[24:25]
	s_mov_b32 m0, s92
	s_nop 0
	global_load_lds_dwordx4 v[252:253], off
	v_mfma_f32_32x32x16_bf16 v[32:47], v[154:157], v[158:161], v[32:47]
	v_mfma_f32_32x32x16_bf16 v[0:15], v[154:157], v[180:183], v[0:15]
	v_lshl_add_u64 v[252:253], v[90:91], 0, s[26:27]
	s_mov_b32 m0, s95
	s_nop 0
	global_load_lds_dwordx4 v[252:253], off
	s_mov_b32 m0, s4
	s_mov_b64 vcc, 0x40280
	ds_read_b128 v[150:153], v137 offset:32768
	ds_read_b128 v[154:157], v137 offset:36864
	ds_read_b128 v[158:161], v138
	ds_read_b128 v[180:183], v138 offset:4096
	s_waitcnt lgkmcnt(4)
	v_mfma_f32_32x32x16_bf16 v[48:63], v[184:187], v[192:195], v[48:63]
	v_mfma_f32_32x32x16_bf16 v[16:31], v[184:187], v[196:199], v[16:31]
	v_mfma_f32_32x32x16_bf16 v[32:47], v[188:191], v[192:195], v[32:47]
	v_mfma_f32_32x32x16_bf16 v[0:15], v[188:191], v[196:199], v[0:15]
	s_waitcnt vmcnt(6)
	s_waitcnt lgkmcnt(0)
	s_barrier
; #define MFMA(a, b, c) __builtin_amdgcn_mfma_f32_32x32x16_bf16((a), (b), (c), 0, 0, 0)
; #define WAIT_V(n) asm volatile("s_waitcnt vmcnt(%0)" ::"n"(n) : "memory")
; #define RAW_BARRIER() do { asm volatile("s_waitcnt lgkmcnt(0)" ::: "memory"); __builtin_amdgcn_s_barrier(); asm volatile("" ::: "memory"); } while (0)
; #define GLDS_STAGE(slot, kt) do { _Pragma("unroll") for (int i = 0; i < 6; ++i) \
;     __builtin_amdgcn_global_load_lds((const unsigned*)(src[i] + (kt) * 64), (__attribute__((address_space(3))) unsigned*)(smem + (slot) * G_STAGE + (wave + 8 * i) * 1024), 16, 0, 0); } while (0)
; DI void gemm_tile(const u16* __restrict__ X, int ldx, const u16* __restrict__ Wt, int ldw, int K, char* smem,
;                   f32x16 (&acc)[2][2]) {
;     ...
;   int offA[2], offB[2], xa[2], xb[2];
; #pragma unroll
;   for (int ft = 0; ft < 2; ++ft) { const int R = 256 + fw * 64 + ft * 32 + lr; offA[ft] = R * 128; xa[ft] = (R >> 1) & 7; }
; #pragma unroll
;   for (int tt = 0; tt < 2; ++tt) { const int R = tq * 64 + tt * 32 + lr; offB[tt] = R * 128; xb[tt] = (R >> 1) & 7; }
;   GLDS_STAGE(0, 0); GLDS_STAGE(1, 1); WAIT_V(6); RAW_BARRIER();
;   int cur = 0;
;   for (int kt = 0; kt < nk; ++kt) {
;     const int nxt = (cur >= 1) ? cur - 1 : 2;
;     if (kt + 2 < nk) GLDS_STAGE(nxt, kt + 2);
;     __builtin_amdgcn_sched_barrier(0);
;     const char* st = smem + cur * G_STAGE;
; #pragma unroll
;     for (int ks = 0; ks < 4; ++ks) {
;       bf16x8 a[2], b[2];
; #pragma unroll
;       for (int ft = 0; ft < 2; ++ft) a[ft] = *reinterpret_cast<const bf16x8*>(st + offA[ft] + (((ks * 2 + lh) ^ xa[ft]) << 4));
; #pragma unroll
;       for (int tt = 0; tt < 2; ++tt) b[tt] = *reinterpret_cast<const bf16x8*>(st + offB[tt] + (((ks * 2 + lh) ^ xb[tt]) << 4));
; #pragma unroll
;       for (int ft = 0; ft < 2; ++ft)
; #pragma unroll
;         for (int tt = 0; tt < 2; ++tt) acc[ft][tt] = MFMA(a[ft], b[tt], acc[ft][tt]);
;     }
;     if (kt + 2 < nk) { WAIT_V(6); } else { WAIT_V(0); }
;     RAW_BARRIER();
	ds_read_b128 v[184:187], v119 offset:32768
	ds_read_b128 v[188:191], v119 offset:36864
	ds_read_b128 v[192:195], v120
	ds_read_b128 v[196:199], v120 offset:4096
	s_waitcnt lgkmcnt(4)
	v_mfma_f32_32x32x16_bf16 v[48:63], v[150:153], v[158:161], v[48:63]
	v_mfma_f32_32x32x16_bf16 v[16:31], v[150:153], v[180:183], v[16:31]
	v_lshl_add_u64 v[150:151], v[88:89], 0, s[28:29]
	global_load_lds_dwordx4 v[150:151], off
	v_mfma_f32_32x32x16_bf16 v[0:15], v[154:157], v[180:183], v[0:15]
	v_mfma_f32_32x32x16_bf16 v[32:47], v[154:157], v[158:161], v[32:47]
	v_lshl_add_u64 v[150:151], v[88:89], 0, s[30:31]
	s_mov_b32 m0, s90
	s_nop 0
	global_load_lds_dwordx4 v[150:151], off
	ds_read_b128 v[150:153], v121 offset:32768
	ds_read_b128 v[154:157], v121 offset:36864
	ds_read_b128 v[158:161], v122
	ds_read_b128 v[180:183], v122 offset:4096
	s_waitcnt lgkmcnt(4)
	v_mfma_f32_32x32x16_bf16 v[48:63], v[184:187], v[192:195], v[48:63]
	v_mfma_f32_32x32x16_bf16 v[16:31], v[184:187], v[196:199], v[16:31]
	v_lshl_add_u64 v[252:253], v[88:89], 0, vcc
	s_mov_b32 m0, s88
	s_mov_b64 vcc, 0x60280
	global_load_lds_dwordx4 v[252:253], off
	v_mfma_f32_32x32x16_bf16 v[32:47], v[188:191], v[192:195], v[32:47]
	v_mfma_f32_32x32x16_bf16 v[0:15], v[188:191], v[196:199], v[0:15]
	v_lshl_add_u64 v[252:253], v[88:89], 0, vcc
	s_mov_b32 m0, s89
	s_nop 0
	global_load_lds_dwordx4 v[252:253], off
	ds_read_b128 v[184:187], v123 offset:32768
	ds_read_b128 v[188:191], v123 offset:36864
	ds_read_b128 v[192:195], v124
	ds_read_b128 v[196:199], v124 offset:4096
	s_waitcnt lgkmcnt(4)
	v_mfma_f32_32x32x16_bf16 v[48:63], v[150:153], v[158:161], v[48:63]
	v_mfma_f32_32x32x16_bf16 v[16:31], v[150:153], v[180:183], v[16:31]
	v_lshl_add_u64 v[252:253], v[90:91], 0, s[28:29]
	s_mov_b32 m0, s7
	s_nop 0
	global_load_lds_dwordx4 v[252:253], off
	v_mfma_f32_32x32x16_bf16 v[32:47], v[154:157], v[158:161], v[32:47]
	v_mfma_f32_32x32x16_bf16 v[0:15], v[154:157], v[180:183], v[0:15]
	v_lshl_add_u64 v[252:253], v[90:91], 0, s[30:31]
	s_mov_b32 m0, s87
	s_nop 0
	global_load_lds_dwordx4 v[252:253], off
	s_mov_b32 m0, s6
	s_mov_b64 vcc, 0x40300
	ds_read_b128 v[150:153], v125 offset:32768
	ds_read_b128 v[154:157], v125 offset:36864
	ds_read_b128 v[158:161], v126
	ds_read_b128 v[180:183], v126 offset:4096
	s_waitcnt lgkmcnt(4)
	v_mfma_f32_32x32x16_bf16 v[48:63], v[184:187], v[192:195], v[48:63]
	v_mfma_f32_32x32x16_bf16 v[16:31], v[184:187], v[196:199], v[16:31]
	v_mfma_f32_32x32x16_bf16 v[32:47], v[188:191], v[192:195], v[32:47]
	v_mfma_f32_32x32x16_bf16 v[0:15], v[188:191], v[196:199], v[0:15]
	s_waitcnt vmcnt(6)
	s_waitcnt lgkmcnt(0)
	s_barrier
	ds_read_b128 v[184:187], v127 offset:32768
	ds_read_b128 v[188:191], v127 offset:36864
	ds_read_b128 v[192:195], v120 offset:49152
	ds_read_b128 v[196:199], v120 offset:53248
	s_waitcnt lgkmcnt(4)
	v_mfma_f32_32x32x16_bf16 v[48:63], v[150:153], v[158:161], v[48:63]
	v_mfma_f32_32x32x16_bf16 v[16:31], v[150:153], v[180:183], v[16:31]
	v_lshl_add_u64 v[150:151], v[88:89], 0, s[34:35]
	global_load_lds_dwordx4 v[150:151], off
	v_mfma_f32_32x32x16_bf16 v[0:15], v[154:157], v[180:183], v[0:15]
	v_mfma_f32_32x32x16_bf16 v[32:47], v[154:157], v[158:161], v[32:47]
	v_lshl_add_u64 v[150:151], v[88:89], 0, s[36:37]
	s_mov_b32 m0, s86
	s_nop 0
	global_load_lds_dwordx4 v[150:151], off
	ds_read_b128 v[150:153], v128 offset:32768
	ds_read_b128 v[154:157], v128 offset:36864
	ds_read_b128 v[158:161], v122 offset:49152
	ds_read_b128 v[180:183], v122 offset:53248
	s_waitcnt lgkmcnt(4)
	v_mfma_f32_32x32x16_bf16 v[48:63], v[184:187], v[192:195], v[48:63]
	v_mfma_f32_32x32x16_bf16 v[16:31], v[184:187], v[196:199], v[16:31]
	v_lshl_add_u64 v[252:253], v[88:89], 0, vcc
	s_mov_b32 m0, s85
	s_mov_b64 vcc, 0x60300
	global_load_lds_dwordx4 v[252:253], off
	v_mfma_f32_32x32x16_bf16 v[32:47], v[188:191], v[192:195], v[32:47]
	v_mfma_f32_32x32x16_bf16 v[0:15], v[188:191], v[196:199], v[0:15]
	v_lshl_add_u64 v[252:253], v[88:89], 0, vcc
	s_mov_b32 m0, s84
	s_nop 0
	global_load_lds_dwordx4 v[252:253], off
	ds_read_b128 v[184:187], v129 offset:32768
	ds_read_b128 v[188:191], v129 offset:36864
	ds_read_b128 v[192:195], v124 offset:49152
	ds_read_b128 v[196:199], v124 offset:53248
	s_waitcnt lgkmcnt(4)
	v_mfma_f32_32x32x16_bf16 v[48:63], v[150:153], v[158:161], v[48:63]
	v_mfma_f32_32x32x16_bf16 v[16:31], v[150:153], v[180:183], v[16:31]
	v_lshl_add_u64 v[252:253], v[90:91], 0, s[34:35]
	s_mov_b32 m0, s79
	s_nop 0
	global_load_lds_dwordx4 v[252:253], off
	v_mfma_f32_32x32x16_bf16 v[32:47], v[154:157], v[158:161], v[32:47]
	v_mfma_f32_32x32x16_bf16 v[0:15], v[154:157], v[180:183], v[0:15]
	v_lshl_add_u64 v[252:253], v[90:91], 0, s[36:37]
	s_mov_b32 m0, s55
	s_nop 0
	global_load_lds_dwordx4 v[252:253], off
	s_mov_b32 m0, s54
	s_mov_b64 vcc, 0x40380
	ds_read_b128 v[150:153], v130 offset:32768
	ds_read_b128 v[154:157], v130 offset:36864
	ds_read_b128 v[158:161], v126 offset:49152
	ds_read_b128 v[180:183], v126 offset:53248
	s_waitcnt lgkmcnt(4)
	v_mfma_f32_32x32x16_bf16 v[48:63], v[184:187], v[192:195], v[48:63]
	v_mfma_f32_32x32x16_bf16 v[16:31], v[184:187], v[196:199], v[16:31]
	v_mfma_f32_32x32x16_bf16 v[32:47], v[188:191], v[192:195], v[32:47]
	v_mfma_f32_32x32x16_bf16 v[0:15], v[188:191], v[196:199], v[0:15]
	s_waitcnt vmcnt(6)
	s_waitcnt lgkmcnt(0)
	s_barrier
; #define MFMA(a, b, c) __builtin_amdgcn_mfma_f32_32x32x16_bf16((a), (b), (c), 0, 0, 0)
; #define WAIT_V(n) asm volatile("s_waitcnt vmcnt(%0)" ::"n"(n) : "memory")
; #define RAW_BARRIER() do { asm volatile("s_waitcnt lgkmcnt(0)" ::: "memory"); __builtin_amdgcn_s_barrier(); asm volatile("" ::: "memory"); } while (0)
; #define GLDS_STAGE(slot, kt) do { _Pragma("unroll") for (int i = 0; i < 6; ++i) \
;     __builtin_amdgcn_global_load_lds((const unsigned*)(src[i] + (kt) * 64), (__attribute__((address_space(3))) unsigned*)(smem + (slot) * G_STAGE + (wave + 8 * i) * 1024), 16, 0, 0); } while (0)
; DI void gemm_tile(const u16* __restrict__ X, int ldx, const u16* __restrict__ Wt, int ldw, int K, char* smem,
;                   f32x16 (&acc)[2][2]) {
;     ...
;   int offA[2], offB[2], xa[2], xb[2];
; #pragma unroll
;   for (int ft = 0; ft < 2; ++ft) { const int R = 256 + fw * 64 + ft * 32 + lr; offA[ft] = R * 128; xa[ft] = (R >> 1) & 7; }
; #pragma unroll
;   for (int tt = 0; tt < 2; ++tt) { const int R = tq * 64 + tt * 32 + lr; offB[tt] = R * 128; xb[tt] = (R >> 1) & 7; }
;   GLDS_STAGE(0, 0); GLDS_STAGE(1, 1); WAIT_V(6); RAW_BARRIER();
;   int cur = 0;
;   for (int kt = 0; kt < nk; ++kt) {
;     const int nxt = (cur >= 1) ? cur - 1 : 2;
;     if (kt + 2 < nk) GLDS_STAGE(nxt, kt + 2);
;     __builtin_amdgcn_sched_barrier(0);
;     const char* st = smem + cur * G_STAGE;
; #pragma unroll
;     for (int ks = 0; ks < 4; ++ks) {
;       bf16x8 a[2], b[2];
; #pragma unroll
;       for (int ft = 0; ft < 2; ++ft) a[ft] = *reinterpret_cast<const bf16x8*>(st + offA[ft] + (((ks * 2 + lh) ^ xa[ft]) << 4));
; #pragma unroll
;       for (int tt = 0; tt < 2; ++tt) b[tt] = *reinterpret_cast<const bf16x8*>(st + offB[tt] + (((ks * 2 + lh) ^ xb[tt]) << 4));
; #pragma unroll
;       for (int ft = 0; ft < 2; ++ft)
; #pragma unroll
;         for (int tt = 0; tt < 2; ++tt) acc[ft][tt] = MFMA(a[ft], b[tt], acc[ft][tt]);
;     }
;     if (kt + 2 < nk) { WAIT_V(6); } else { WAIT_V(0); }
;     RAW_BARRIER();
	ds_read_b128 v[184:187], v131 offset:32768
	ds_read_b128 v[188:191], v131 offset:36864
	ds_read_b128 v[192:195], v132
	ds_read_b128 v[196:199], v132 offset:4096
	s_waitcnt lgkmcnt(4)
	v_mfma_f32_32x32x16_bf16 v[48:63], v[150:153], v[158:161], v[48:63]
	v_mfma_f32_32x32x16_bf16 v[16:31], v[150:153], v[180:183], v[16:31]
	v_lshl_add_u64 v[150:151], v[88:89], 0, s[38:39]
	global_load_lds_dwordx4 v[150:151], off
	v_mfma_f32_32x32x16_bf16 v[0:15], v[154:157], v[180:183], v[0:15]
	v_mfma_f32_32x32x16_bf16 v[32:47], v[154:157], v[158:161], v[32:47]
	v_lshl_add_u64 v[150:151], v[88:89], 0, s[40:41]
	s_mov_b32 m0, s0
	s_nop 0
	global_load_lds_dwordx4 v[150:151], off
	ds_read_b128 v[150:153], v133 offset:32768
	ds_read_b128 v[154:157], v133 offset:36864
	ds_read_b128 v[158:161], v134
	ds_read_b128 v[180:183], v134 offset:4096
	s_waitcnt lgkmcnt(4)
	v_mfma_f32_32x32x16_bf16 v[48:63], v[184:187], v[192:195], v[48:63]
	v_mfma_f32_32x32x16_bf16 v[16:31], v[184:187], v[196:199], v[16:31]
	v_lshl_add_u64 v[252:253], v[88:89], 0, vcc
	s_mov_b32 m0, s91
	s_mov_b64 vcc, 0x60380
	global_load_lds_dwordx4 v[252:253], off
	v_mfma_f32_32x32x16_bf16 v[32:47], v[188:191], v[192:195], v[32:47]
	v_mfma_f32_32x32x16_bf16 v[0:15], v[188:191], v[196:199], v[0:15]
	v_lshl_add_u64 v[252:253], v[88:89], 0, vcc
	s_mov_b32 m0, s93
	s_nop 0
	global_load_lds_dwordx4 v[252:253], off
	ds_read_b128 v[184:187], v135 offset:32768
	ds_read_b128 v[188:191], v135 offset:36864
	ds_read_b128 v[192:195], v136
	ds_read_b128 v[196:199], v136 offset:4096
	s_waitcnt lgkmcnt(4)
	v_mfma_f32_32x32x16_bf16 v[48:63], v[150:153], v[158:161], v[48:63]
	v_mfma_f32_32x32x16_bf16 v[16:31], v[150:153], v[180:183], v[16:31]
	v_lshl_add_u64 v[252:253], v[90:91], 0, s[38:39]
	s_mov_b32 m0, s92
	s_nop 0
	global_load_lds_dwordx4 v[252:253], off
	v_mfma_f32_32x32x16_bf16 v[32:47], v[154:157], v[158:161], v[32:47]
	v_mfma_f32_32x32x16_bf16 v[0:15], v[154:157], v[180:183], v[0:15]
	v_lshl_add_u64 v[252:253], v[90:91], 0, s[40:41]
	s_mov_b32 m0, s95
	s_nop 0
	global_load_lds_dwordx4 v[252:253], off
	s_mov_b32 m0, s4
	s_mov_b64 s[4:5], 0x40400
	ds_read_b128 v[150:153], v137 offset:32768
	ds_read_b128 v[154:157], v137 offset:36864
	ds_read_b128 v[158:161], v138
	ds_read_b128 v[180:183], v138 offset:4096
	s_waitcnt lgkmcnt(4)
	v_mfma_f32_32x32x16_bf16 v[48:63], v[184:187], v[192:195], v[48:63]
	v_mfma_f32_32x32x16_bf16 v[16:31], v[184:187], v[196:199], v[16:31]
	v_mfma_f32_32x32x16_bf16 v[32:47], v[188:191], v[192:195], v[32:47]
	v_mfma_f32_32x32x16_bf16 v[0:15], v[188:191], v[196:199], v[0:15]
	s_waitcnt vmcnt(6)
	s_waitcnt lgkmcnt(0)
	s_barrier
	ds_read_b128 v[184:187], v119 offset:32768
	ds_read_b128 v[188:191], v119 offset:36864
	ds_read_b128 v[192:195], v120
	ds_read_b128 v[196:199], v120 offset:4096
	s_waitcnt lgkmcnt(4)
	v_mfma_f32_32x32x16_bf16 v[48:63], v[150:153], v[158:161], v[48:63]
	v_mfma_f32_32x32x16_bf16 v[16:31], v[150:153], v[180:183], v[16:31]
	v_lshl_add_u64 v[150:151], v[88:89], 0, s[42:43]
	global_load_lds_dwordx4 v[150:151], off
	v_mfma_f32_32x32x16_bf16 v[0:15], v[154:157], v[180:183], v[0:15]
	v_mfma_f32_32x32x16_bf16 v[32:47], v[154:157], v[158:161], v[32:47]
	v_lshl_add_u64 v[150:151], v[88:89], 0, s[44:45]
	s_mov_b32 m0, s90
	s_nop 0
	global_load_lds_dwordx4 v[150:151], off
	ds_read_b128 v[150:153], v121 offset:32768
	ds_read_b128 v[154:157], v121 offset:36864
	ds_read_b128 v[158:161], v122
	ds_read_b128 v[180:183], v122 offset:4096
	s_waitcnt lgkmcnt(4)
	v_mfma_f32_32x32x16_bf16 v[48:63], v[184:187], v[192:195], v[48:63]
	v_mfma_f32_32x32x16_bf16 v[16:31], v[184:187], v[196:199], v[16:31]
	v_lshl_add_u64 v[252:253], v[88:89], 0, s[4:5]
	s_mov_b32 m0, s88
	s_mov_b64 s[4:5], 0x60400
	global_load_lds_dwordx4 v[252:253], off
	v_mfma_f32_32x32x16_bf16 v[32:47], v[188:191], v[192:195], v[32:47]
	v_mfma_f32_32x32x16_bf16 v[0:15], v[188:191], v[196:199], v[0:15]
	v_lshl_add_u64 v[252:253], v[88:89], 0, s[4:5]
	s_mov_b32 m0, s89
	s_nop 0
	global_load_lds_dwordx4 v[252:253], off
	ds_read_b128 v[184:187], v123 offset:32768
	ds_read_b128 v[188:191], v123 offset:36864
	ds_read_b128 v[192:195], v124
	ds_read_b128 v[196:199], v124 offset:4096
	s_waitcnt lgkmcnt(4)
	v_mfma_f32_32x32x16_bf16 v[48:63], v[150:153], v[158:161], v[48:63]
	v_mfma_f32_32x32x16_bf16 v[16:31], v[150:153], v[180:183], v[16:31]
	v_lshl_add_u64 v[252:253], v[90:91], 0, s[42:43]
	s_mov_b32 m0, s7
	s_nop 0
	global_load_lds_dwordx4 v[252:253], off
	v_mfma_f32_32x32x16_bf16 v[32:47], v[154:157], v[158:161], v[32:47]
	v_mfma_f32_32x32x16_bf16 v[0:15], v[154:157], v[180:183], v[0:15]
	v_lshl_add_u64 v[252:253], v[90:91], 0, s[44:45]
	s_mov_b32 m0, s87
	s_nop 0
	global_load_lds_dwordx4 v[252:253], off
	s_mov_b32 m0, s6
	s_mov_b64 s[4:5], 0x40480
	ds_read_b128 v[150:153], v125 offset:32768
	ds_read_b128 v[154:157], v125 offset:36864
	ds_read_b128 v[158:161], v126
	ds_read_b128 v[180:183], v126 offset:4096
	s_waitcnt lgkmcnt(4)
	v_mfma_f32_32x32x16_bf16 v[48:63], v[184:187], v[192:195], v[48:63]
	v_mfma_f32_32x32x16_bf16 v[16:31], v[184:187], v[196:199], v[16:31]
	v_mfma_f32_32x32x16_bf16 v[32:47], v[188:191], v[192:195], v[32:47]
	v_mfma_f32_32x32x16_bf16 v[0:15], v[188:191], v[196:199], v[0:15]
	s_waitcnt vmcnt(6)
	s_waitcnt lgkmcnt(0)
	s_barrier
; #define MFMA(a, b, c) __builtin_amdgcn_mfma_f32_32x32x16_bf16((a), (b), (c), 0, 0, 0)
; #define WAIT_V(n) asm volatile("s_waitcnt vmcnt(%0)" ::"n"(n) : "memory")
; #define RAW_BARRIER() do { asm volatile("s_waitcnt lgkmcnt(0)" ::: "memory"); __builtin_amdgcn_s_barrier(); asm volatile("" ::: "memory"); } while (0)
; #define GLDS_STAGE(slot, kt) do { _Pragma("unroll") for (int i = 0; i < 6; ++i) \
;     __builtin_amdgcn_global_load_lds((const unsigned*)(src[i] + (kt) * 64), (__attribute__((address_space(3))) unsigned*)(smem + (slot) * G_STAGE + (wave + 8 * i) * 1024), 16, 0, 0); } while (0)
; DI void gemm_tile(const u16* __restrict__ X, int ldx, const u16* __restrict__ Wt, int ldw, int K, char* smem,
;                   f32x16 (&acc)[2][2]) {
;     ...
;   int offA[2], offB[2], xa[2], xb[2];
; #pragma unroll
;   for (int ft = 0; ft < 2; ++ft) { const int R = 256 + fw * 64 + ft * 32 + lr; offA[ft] = R * 128; xa[ft] = (R >> 1) & 7; }
; #pragma unroll
;   for (int tt = 0; tt < 2; ++tt) { const int R = tq * 64 + tt * 32 + lr; offB[tt] = R * 128; xb[tt] = (R >> 1) & 7; }
;   GLDS_STAGE(0, 0); GLDS_STAGE(1, 1); WAIT_V(6); RAW_BARRIER();
;   int cur = 0;
;   for (int kt = 0; kt < nk; ++kt) {
;     const int nxt = (cur >= 1) ? cur - 1 : 2;
;     if (kt + 2 < nk) GLDS_STAGE(nxt, kt + 2);
;     __builtin_amdgcn_sched_barrier(0);
;     const char* st = smem + cur * G_STAGE;
; #pragma unroll
;     for (int ks = 0; ks < 4; ++ks) {
;       bf16x8 a[2], b[2];
; #pragma unroll
;       for (int ft = 0; ft < 2; ++ft) a[ft] = *reinterpret_cast<const bf16x8*>(st + offA[ft] + (((ks * 2 + lh) ^ xa[ft]) << 4));
; #pragma unroll
;       for (int tt = 0; tt < 2; ++tt) b[tt] = *reinterpret_cast<const bf16x8*>(st + offB[tt] + (((ks * 2 + lh) ^ xb[tt]) << 4));
; #pragma unroll
;       for (int ft = 0; ft < 2; ++ft)
; #pragma unroll
;         for (int tt = 0; tt < 2; ++tt) acc[ft][tt] = MFMA(a[ft], b[tt], acc[ft][tt]);
;     }
;     if (kt + 2 < nk) { WAIT_V(6); } else { WAIT_V(0); }
;     RAW_BARRIER();
;     cur = (cur == 2) ? 0 : cur + 1;
;   }
	ds_read_b128 v[184:187], v127 offset:32768
	ds_read_b128 v[188:191], v127 offset:36864
	ds_read_b128 v[192:195], v120 offset:49152
	ds_read_b128 v[196:199], v120 offset:53248
	s_waitcnt lgkmcnt(4)
	v_mfma_f32_32x32x16_bf16 v[48:63], v[150:153], v[158:161], v[48:63]
	v_mfma_f32_32x32x16_bf16 v[16:31], v[150:153], v[180:183], v[16:31]
	v_lshl_add_u64 v[150:151], v[88:89], 0, s[46:47]
	global_load_lds_dwordx4 v[150:151], off
	v_mfma_f32_32x32x16_bf16 v[0:15], v[154:157], v[180:183], v[0:15]
	v_mfma_f32_32x32x16_bf16 v[32:47], v[154:157], v[158:161], v[32:47]
	v_lshl_add_u64 v[150:151], v[88:89], 0, s[48:49]
	s_mov_b32 m0, s86
	s_nop 0
	global_load_lds_dwordx4 v[150:151], off
	ds_read_b128 v[150:153], v128 offset:32768
	ds_read_b128 v[154:157], v128 offset:36864
	ds_read_b128 v[158:161], v122 offset:49152
	ds_read_b128 v[180:183], v122 offset:53248
	s_waitcnt lgkmcnt(4)
	v_mfma_f32_32x32x16_bf16 v[48:63], v[184:187], v[192:195], v[48:63]
	v_mfma_f32_32x32x16_bf16 v[16:31], v[184:187], v[196:199], v[16:31]
	v_lshl_add_u64 v[252:253], v[88:89], 0, s[4:5]
	s_mov_b32 m0, s85
	s_mov_b64 s[4:5], 0x60480
	global_load_lds_dwordx4 v[252:253], off
	v_mfma_f32_32x32x16_bf16 v[32:47], v[188:191], v[192:195], v[32:47]
	v_mfma_f32_32x32x16_bf16 v[0:15], v[188:191], v[196:199], v[0:15]
	v_lshl_add_u64 v[252:253], v[88:89], 0, s[4:5]
	s_mov_b32 m0, s84
	s_nop 0
	global_load_lds_dwordx4 v[252:253], off
	ds_read_b128 v[184:187], v129 offset:32768
	ds_read_b128 v[188:191], v129 offset:36864
	ds_read_b128 v[192:195], v124 offset:49152
	ds_read_b128 v[196:199], v124 offset:53248
	s_waitcnt lgkmcnt(4)
	v_mfma_f32_32x32x16_bf16 v[48:63], v[150:153], v[158:161], v[48:63]
	v_mfma_f32_32x32x16_bf16 v[16:31], v[150:153], v[180:183], v[16:31]
	v_lshl_add_u64 v[252:253], v[90:91], 0, s[46:47]
	s_mov_b32 m0, s79
	s_nop 0
	global_load_lds_dwordx4 v[252:253], off
	v_mfma_f32_32x32x16_bf16 v[32:47], v[154:157], v[158:161], v[32:47]
	v_mfma_f32_32x32x16_bf16 v[0:15], v[154:157], v[180:183], v[0:15]
	v_lshl_add_u64 v[252:253], v[90:91], 0, s[48:49]
	s_mov_b32 m0, s55
	s_nop 0
	global_load_lds_dwordx4 v[252:253], off
	s_mov_b32 m0, s54
	s_mov_b64 s[4:5], 0x40500
	ds_read_b128 v[150:153], v130 offset:32768
	ds_read_b128 v[154:157], v130 offset:36864
	ds_read_b128 v[158:161], v126 offset:49152
	ds_read_b128 v[180:183], v126 offset:53248
	s_waitcnt lgkmcnt(4)
	v_mfma_f32_32x32x16_bf16 v[48:63], v[184:187], v[192:195], v[48:63]
	v_mfma_f32_32x32x16_bf16 v[16:31], v[184:187], v[196:199], v[16:31]
	v_mfma_f32_32x32x16_bf16 v[32:47], v[188:191], v[192:195], v[32:47]
	v_mfma_f32_32x32x16_bf16 v[0:15], v[188:191], v[196:199], v[0:15]
	s_waitcnt vmcnt(6)
	s_waitcnt lgkmcnt(0)
	s_barrier
	ds_read_b128 v[184:187], v131 offset:32768
	ds_read_b128 v[188:191], v131 offset:36864
	ds_read_b128 v[192:195], v132
	ds_read_b128 v[196:199], v132 offset:4096
	s_waitcnt lgkmcnt(4)
	v_mfma_f32_32x32x16_bf16 v[48:63], v[150:153], v[158:161], v[48:63]
	v_mfma_f32_32x32x16_bf16 v[16:31], v[150:153], v[180:183], v[16:31]
	v_lshl_add_u64 v[150:151], v[88:89], 0, s[50:51]
	global_load_lds_dwordx4 v[150:151], off
	v_mfma_f32_32x32x16_bf16 v[0:15], v[154:157], v[180:183], v[0:15]
	v_mfma_f32_32x32x16_bf16 v[32:47], v[154:157], v[158:161], v[32:47]
	v_lshl_add_u64 v[150:151], v[88:89], 0, s[52:53]
	s_mov_b32 m0, s0
	s_nop 0
	global_load_lds_dwordx4 v[150:151], off
	ds_read_b128 v[150:153], v133 offset:32768
	ds_read_b128 v[154:157], v133 offset:36864
	ds_read_b128 v[158:161], v134
	ds_read_b128 v[180:183], v134 offset:4096
	s_waitcnt lgkmcnt(4)
	v_mfma_f32_32x32x16_bf16 v[48:63], v[184:187], v[192:195], v[48:63]
	v_mfma_f32_32x32x16_bf16 v[16:31], v[184:187], v[196:199], v[16:31]
	v_lshl_add_u64 v[252:253], v[88:89], 0, s[4:5]
	s_mov_b32 m0, s91
	s_mov_b64 s[4:5], 0x60500
	global_load_lds_dwordx4 v[252:253], off
	v_mfma_f32_32x32x16_bf16 v[32:47], v[188:191], v[192:195], v[32:47]
	v_mfma_f32_32x32x16_bf16 v[0:15], v[188:191], v[196:199], v[0:15]
	v_lshl_add_u64 v[252:253], v[88:89], 0, s[4:5]
	s_mov_b32 m0, s93
	s_nop 0
	global_load_lds_dwordx4 v[252:253], off
	ds_read_b128 v[184:187], v135 offset:32768
	ds_read_b128 v[188:191], v135 offset:36864
	ds_read_b128 v[192:195], v136
	ds_read_b128 v[196:199], v136 offset:4096
	s_waitcnt lgkmcnt(4)
	v_mfma_f32_32x32x16_bf16 v[48:63], v[150:153], v[158:161], v[48:63]
	v_mfma_f32_32x32x16_bf16 v[16:31], v[150:153], v[180:183], v[16:31]
	v_lshl_add_u64 v[252:253], v[90:91], 0, s[50:51]
	s_mov_b32 m0, s92
	s_nop 0
	global_load_lds_dwordx4 v[252:253], off
	v_mfma_f32_32x32x16_bf16 v[32:47], v[154:157], v[158:161], v[32:47]
	v_mfma_f32_32x32x16_bf16 v[0:15], v[154:157], v[180:183], v[0:15]
	v_lshl_add_u64 v[252:253], v[90:91], 0, s[52:53]
	s_mov_b32 m0, s95
	s_nop 0
	global_load_lds_dwordx4 v[252:253], off
	v_readfirstlane_b32 s87, v93
	s_mov_b32 m0, s87
	v_readfirstlane_b32 s54, v94
	s_mov_b64 s[4:5], 0x40580
	v_readfirstlane_b32 s55, v95
	v_readfirstlane_b32 s84, v96
	v_readfirstlane_b32 s79, v97
	v_readfirstlane_b32 s85, v98
	ds_read_b128 v[150:153], v137 offset:32768
	ds_read_b128 v[154:157], v137 offset:36864
	ds_read_b128 v[158:161], v138
	ds_read_b128 v[180:183], v138 offset:4096
	s_waitcnt lgkmcnt(4)
	v_mfma_f32_32x32x16_bf16 v[48:63], v[184:187], v[192:195], v[48:63]
	v_mfma_f32_32x32x16_bf16 v[16:31], v[184:187], v[196:199], v[16:31]
	v_mfma_f32_32x32x16_bf16 v[32:47], v[188:191], v[192:195], v[32:47]
	v_mfma_f32_32x32x16_bf16 v[0:15], v[188:191], v[196:199], v[0:15]
	s_waitcnt vmcnt(6)
	s_waitcnt lgkmcnt(0)
	s_barrier
; #define MFMA(a, b, c) __builtin_amdgcn_mfma_f32_32x32x16_bf16((a), (b), (c), 0, 0, 0)
; #define WAIT_V(n) asm volatile("s_waitcnt vmcnt(%0)" ::"n"(n) : "memory")
; #define RAW_BARRIER() do { asm volatile("s_waitcnt lgkmcnt(0)" ::: "memory"); __builtin_amdgcn_s_barrier(); asm volatile("" ::: "memory"); } while (0)
; #define GLDS_STAGE(slot, kt) do { _Pragma("unroll") for (int i = 0; i < 6; ++i) \
;     __builtin_amdgcn_global_load_lds((const unsigned*)(src[i] + (kt) * 64), (__attribute__((address_space(3))) unsigned*)(smem + (slot) * G_STAGE + (wave + 8 * i) * 1024), 16, 0, 0); } while (0)
; DI void gemm_tile(const u16* __restrict__ X, int ldx, const u16* __restrict__ Wt, int ldw, int K, char* smem,
;                   f32x16 (&acc)[2][2]) {
;     ...
;   int offA[2], offB[2], xa[2], xb[2];
; #pragma unroll
;   for (int ft = 0; ft < 2; ++ft) { const int R = 256 + fw * 64 + ft * 32 + lr; offA[ft] = R * 128; xa[ft] = (R >> 1) & 7; }
; #pragma unroll
;   for (int tt = 0; tt < 2; ++tt) { const int R = tq * 64 + tt * 32 + lr; offB[tt] = R * 128; xb[tt] = (R >> 1) & 7; }
;   GLDS_STAGE(0, 0); GLDS_STAGE(1, 1); WAIT_V(6); RAW_BARRIER();
;   int cur = 0;
;   for (int kt = 0; kt < nk; ++kt) {
;     const int nxt = (cur >= 1) ? cur - 1 : 2;
;     if (kt + 2 < nk) GLDS_STAGE(nxt, kt + 2);
;     __builtin_amdgcn_sched_barrier(0);
;     const char* st = smem + cur * G_STAGE;
; #pragma unroll
;     for (int ks = 0; ks < 4; ++ks) {
;       bf16x8 a[2], b[2];
; #pragma unroll
;       for (int ft = 0; ft < 2; ++ft) a[ft] = *reinterpret_cast<const bf16x8*>(st + offA[ft] + (((ks * 2 + lh) ^ xa[ft]) << 4));
; #pragma unroll
;       for (int tt = 0; tt < 2; ++tt) b[tt] = *reinterpret_cast<const bf16x8*>(st + offB[tt] + (((ks * 2 + lh) ^ xb[tt]) << 4));
; #pragma unroll
;       for (int ft = 0; ft < 2; ++ft)
; #pragma unroll
;         for (int tt = 0; tt < 2; ++tt) acc[ft][tt] = MFMA(a[ft], b[tt], acc[ft][tt]);
;     }
;     if (kt + 2 < nk) { WAIT_V(6); } else { WAIT_V(0); }
;     RAW_BARRIER();
;     cur = (cur == 2) ? 0 : cur + 1;
;   }
	ds_read_b128 v[184:187], v119 offset:32768
	ds_read_b128 v[188:191], v119 offset:36864
	ds_read_b128 v[192:195], v120
	ds_read_b128 v[196:199], v120 offset:4096
	s_waitcnt lgkmcnt(4)
	v_mfma_f32_32x32x16_bf16 v[48:63], v[150:153], v[158:161], v[48:63]
	v_mfma_f32_32x32x16_bf16 v[16:31], v[150:153], v[180:183], v[16:31]
	v_lshl_add_u64 v[150:151], v[88:89], 0, s[56:57]
	global_load_lds_dwordx4 v[150:151], off
	v_mfma_f32_32x32x16_bf16 v[0:15], v[154:157], v[180:183], v[0:15]
	v_mfma_f32_32x32x16_bf16 v[32:47], v[154:157], v[158:161], v[32:47]
	v_lshl_add_u64 v[150:151], v[88:89], 0, s[58:59]
	s_mov_b32 m0, s54
	s_nop 0
	global_load_lds_dwordx4 v[150:151], off
	ds_read_b128 v[150:153], v121 offset:32768
	ds_read_b128 v[154:157], v121 offset:36864
	ds_read_b128 v[158:161], v122
	ds_read_b128 v[180:183], v122 offset:4096
	s_waitcnt lgkmcnt(4)
	v_mfma_f32_32x32x16_bf16 v[48:63], v[184:187], v[192:195], v[48:63]
	v_mfma_f32_32x32x16_bf16 v[16:31], v[184:187], v[196:199], v[16:31]
	v_lshl_add_u64 v[252:253], v[88:89], 0, s[4:5]
	s_mov_b32 m0, s55
	s_mov_b64 s[4:5], 0x60580
	global_load_lds_dwordx4 v[252:253], off
	v_mfma_f32_32x32x16_bf16 v[32:47], v[188:191], v[192:195], v[32:47]
	v_mfma_f32_32x32x16_bf16 v[0:15], v[188:191], v[196:199], v[0:15]
	v_lshl_add_u64 v[252:253], v[88:89], 0, s[4:5]
	s_mov_b32 m0, s84
	s_nop 0
	global_load_lds_dwordx4 v[252:253], off
	ds_read_b128 v[184:187], v123 offset:32768
	ds_read_b128 v[188:191], v123 offset:36864
	ds_read_b128 v[192:195], v124
	ds_read_b128 v[196:199], v124 offset:4096
	s_waitcnt lgkmcnt(4)
	v_mfma_f32_32x32x16_bf16 v[48:63], v[150:153], v[158:161], v[48:63]
	v_mfma_f32_32x32x16_bf16 v[16:31], v[150:153], v[180:183], v[16:31]
	v_lshl_add_u64 v[252:253], v[90:91], 0, s[56:57]
	s_mov_b32 m0, s79
	s_nop 0
	global_load_lds_dwordx4 v[252:253], off
	v_mfma_f32_32x32x16_bf16 v[32:47], v[154:157], v[158:161], v[32:47]
	v_mfma_f32_32x32x16_bf16 v[0:15], v[154:157], v[180:183], v[0:15]
	v_lshl_add_u64 v[252:253], v[90:91], 0, s[58:59]
	s_mov_b32 m0, s85
	s_nop 0
	global_load_lds_dwordx4 v[252:253], off
	v_readfirstlane_b32 s86, v143
	s_mov_b32 m0, s86
	v_readfirstlane_b32 s0, v109
	s_mov_b64 s[4:5], 0x40600
	s_mov_b64 s[6:7], 0x60600
	ds_read_b128 v[150:153], v125 offset:32768
	ds_read_b128 v[154:157], v125 offset:36864
	ds_read_b128 v[158:161], v126
	ds_read_b128 v[180:183], v126 offset:4096
	s_waitcnt lgkmcnt(4)
	v_mfma_f32_32x32x16_bf16 v[48:63], v[184:187], v[192:195], v[48:63]
	v_mfma_f32_32x32x16_bf16 v[16:31], v[184:187], v[196:199], v[16:31]
	v_mfma_f32_32x32x16_bf16 v[32:47], v[188:191], v[192:195], v[32:47]
	v_mfma_f32_32x32x16_bf16 v[0:15], v[188:191], v[196:199], v[0:15]
	s_waitcnt vmcnt(6)
	s_waitcnt lgkmcnt(0)
	s_barrier
	ds_read_b128 v[184:187], v127 offset:32768
	ds_read_b128 v[188:191], v127 offset:36864
	ds_read_b128 v[192:195], v120 offset:49152
	ds_read_b128 v[196:199], v120 offset:53248
	s_waitcnt lgkmcnt(4)
	v_mfma_f32_32x32x16_bf16 v[48:63], v[150:153], v[158:161], v[48:63]
	v_mfma_f32_32x32x16_bf16 v[16:31], v[150:153], v[180:183], v[16:31]
	v_lshl_add_u64 v[150:151], v[88:89], 0, s[60:61]
	global_load_lds_dwordx4 v[150:151], off
	v_mfma_f32_32x32x16_bf16 v[0:15], v[154:157], v[180:183], v[0:15]
	v_mfma_f32_32x32x16_bf16 v[32:47], v[154:157], v[158:161], v[32:47]
	v_lshl_add_u64 v[150:151], v[88:89], 0, s[62:63]
	s_mov_b32 m0, s0
	s_nop 0
	global_load_lds_dwordx4 v[150:151], off
	ds_read_b128 v[150:153], v128 offset:32768
	ds_read_b128 v[154:157], v128 offset:36864
	ds_read_b128 v[158:161], v122 offset:49152
	ds_read_b128 v[180:183], v122 offset:53248
	s_waitcnt lgkmcnt(4)
	v_mfma_f32_32x32x16_bf16 v[48:63], v[184:187], v[192:195], v[48:63]
	v_mfma_f32_32x32x16_bf16 v[16:31], v[184:187], v[196:199], v[16:31]
	v_lshl_add_u64 v[252:253], v[88:89], 0, s[4:5]
	v_readfirstlane_b32 s4, v110
	s_mov_b32 m0, s4
	v_readfirstlane_b32 s5, v112
	global_load_lds_dwordx4 v[252:253], off
	v_mfma_f32_32x32x16_bf16 v[32:47], v[188:191], v[192:195], v[32:47]
	v_mfma_f32_32x32x16_bf16 v[0:15], v[188:191], v[196:199], v[0:15]
	v_lshl_add_u64 v[252:253], v[88:89], 0, s[6:7]
	v_readfirstlane_b32 s6, v111
	s_mov_b32 m0, s6
	v_readfirstlane_b32 s7, v113
	global_load_lds_dwordx4 v[252:253], off
	ds_read_b128 v[184:187], v129 offset:32768
	ds_read_b128 v[188:191], v129 offset:36864
	ds_read_b128 v[192:195], v124 offset:49152
	ds_read_b128 v[196:199], v124 offset:53248
	s_waitcnt lgkmcnt(4)
	v_mfma_f32_32x32x16_bf16 v[48:63], v[150:153], v[158:161], v[48:63]
	v_mfma_f32_32x32x16_bf16 v[16:31], v[150:153], v[180:183], v[16:31]
	v_lshl_add_u64 v[252:253], v[90:91], 0, s[60:61]
	s_mov_b32 m0, s5
	s_nop 0
	global_load_lds_dwordx4 v[252:253], off
	v_mfma_f32_32x32x16_bf16 v[32:47], v[154:157], v[158:161], v[32:47]
	v_mfma_f32_32x32x16_bf16 v[0:15], v[154:157], v[180:183], v[0:15]
	v_lshl_add_u64 v[252:253], v[90:91], 0, s[62:63]
	s_mov_b32 m0, s7
	s_nop 0
	global_load_lds_dwordx4 v[252:253], off
	v_readfirstlane_b32 s88, v92
	s_mov_b32 m0, s88
	v_readfirstlane_b32 s88, v114
	ds_read_b128 v[150:153], v130 offset:32768
	ds_read_b128 v[154:157], v130 offset:36864
	ds_read_b128 v[158:161], v126 offset:49152
	ds_read_b128 v[180:183], v126 offset:53248
	s_waitcnt lgkmcnt(4)
	v_mfma_f32_32x32x16_bf16 v[48:63], v[184:187], v[192:195], v[48:63]
	v_mfma_f32_32x32x16_bf16 v[16:31], v[184:187], v[196:199], v[16:31]
	v_mfma_f32_32x32x16_bf16 v[32:47], v[188:191], v[192:195], v[32:47]
	v_mfma_f32_32x32x16_bf16 v[0:15], v[188:191], v[196:199], v[0:15]
	s_waitcnt vmcnt(6)
	s_waitcnt lgkmcnt(0)
	s_barrier
; #define MFMA(a, b, c) __builtin_amdgcn_mfma_f32_32x32x16_bf16((a), (b), (c), 0, 0, 0)
; #define WAIT_V(n) asm volatile("s_waitcnt vmcnt(%0)" ::"n"(n) : "memory")
; #define RAW_BARRIER() do { asm volatile("s_waitcnt lgkmcnt(0)" ::: "memory"); __builtin_amdgcn_s_barrier(); asm volatile("" ::: "memory"); } while (0)
; #define GLDS_STAGE(slot, kt) do { _Pragma("unroll") for (int i = 0; i < 6; ++i) \
;     __builtin_amdgcn_global_load_lds((const unsigned*)(src[i] + (kt) * 64), (__attribute__((address_space(3))) unsigned*)(smem + (slot) * G_STAGE + (wave + 8 * i) * 1024), 16, 0, 0); } while (0)
; DI void gemm_tile(const u16* __restrict__ X, int ldx, const u16* __restrict__ Wt, int ldw, int K, char* smem,
;                   f32x16 (&acc)[2][2]) {
;     ...
;   int offA[2], offB[2], xa[2], xb[2];
; #pragma unroll
;   for (int ft = 0; ft < 2; ++ft) { const int R = 256 + fw * 64 + ft * 32 + lr; offA[ft] = R * 128; xa[ft] = (R >> 1) & 7; }
; #pragma unroll
;   for (int tt = 0; tt < 2; ++tt) { const int R = tq * 64 + tt * 32 + lr; offB[tt] = R * 128; xb[tt] = (R >> 1) & 7; }
;   GLDS_STAGE(0, 0); GLDS_STAGE(1, 1); WAIT_V(6); RAW_BARRIER();
;   int cur = 0;
;   for (int kt = 0; kt < nk; ++kt) {
;     const int nxt = (cur >= 1) ? cur - 1 : 2;
;     if (kt + 2 < nk) GLDS_STAGE(nxt, kt + 2);
;     __builtin_amdgcn_sched_barrier(0);
;     const char* st = smem + cur * G_STAGE;
; #pragma unroll
;     for (int ks = 0; ks < 4; ++ks) {
;       bf16x8 a[2], b[2];
; #pragma unroll
;       for (int ft = 0; ft < 2; ++ft) a[ft] = *reinterpret_cast<const bf16x8*>(st + offA[ft] + (((ks * 2 + lh) ^ xa[ft]) << 4));
; #pragma unroll
;       for (int tt = 0; tt < 2; ++tt) b[tt] = *reinterpret_cast<const bf16x8*>(st + offB[tt] + (((ks * 2 + lh) ^ xb[tt]) << 4));
; #pragma unroll
;       for (int ft = 0; ft < 2; ++ft)
; #pragma unroll
;         for (int tt = 0; tt < 2; ++tt) acc[ft][tt] = MFMA(a[ft], b[tt], acc[ft][tt]);
;     }
;     if (kt + 2 < nk) { WAIT_V(6); } else { WAIT_V(0); }
;     RAW_BARRIER();
;     cur = (cur == 2) ? 0 : cur + 1;
;   }
	ds_read_b128 v[184:187], v131 offset:32768
	ds_read_b128 v[188:191], v131 offset:36864
	ds_read_b128 v[192:195], v132
	ds_read_b128 v[196:199], v132 offset:4096
	s_waitcnt lgkmcnt(4)
	v_mfma_f32_32x32x16_bf16 v[48:63], v[150:153], v[158:161], v[48:63]
	v_mfma_f32_32x32x16_bf16 v[16:31], v[150:153], v[180:183], v[16:31]
	v_lshl_add_u64 v[150:151], v[88:89], 0, s[64:65]
	global_load_lds_dwordx4 v[150:151], off
	v_mfma_f32_32x32x16_bf16 v[0:15], v[154:157], v[180:183], v[0:15]
	v_mfma_f32_32x32x16_bf16 v[32:47], v[154:157], v[158:161], v[32:47]
	v_lshl_add_u64 v[150:151], v[88:89], 0, s[66:67]
	s_mov_b32 m0, s88
	s_mov_b64 s[88:89], 0x40680
	global_load_lds_dwordx4 v[150:151], off
	ds_read_b128 v[150:153], v133 offset:32768
	ds_read_b128 v[154:157], v133 offset:36864
	ds_read_b128 v[158:161], v134
	ds_read_b128 v[180:183], v134 offset:4096
	s_waitcnt lgkmcnt(4)
	v_mfma_f32_32x32x16_bf16 v[48:63], v[184:187], v[192:195], v[48:63]
	v_mfma_f32_32x32x16_bf16 v[16:31], v[184:187], v[196:199], v[16:31]
	v_lshl_add_u64 v[252:253], v[88:89], 0, s[88:89]
	v_readfirstlane_b32 s88, v99
	s_mov_b32 m0, s88
	s_mov_b64 s[88:89], 0x60680
	global_load_lds_dwordx4 v[252:253], off
	v_mfma_f32_32x32x16_bf16 v[32:47], v[188:191], v[192:195], v[32:47]
	v_mfma_f32_32x32x16_bf16 v[0:15], v[188:191], v[196:199], v[0:15]
	v_lshl_add_u64 v[252:253], v[88:89], 0, s[88:89]
	v_readfirstlane_b32 s88, v100
	s_mov_b32 m0, s88
	v_readfirstlane_b32 s88, v101
	global_load_lds_dwordx4 v[252:253], off
	ds_read_b128 v[184:187], v135 offset:32768
	ds_read_b128 v[188:191], v135 offset:36864
	ds_read_b128 v[192:195], v136
	ds_read_b128 v[196:199], v136 offset:4096
	s_waitcnt lgkmcnt(4)
	v_mfma_f32_32x32x16_bf16 v[48:63], v[150:153], v[158:161], v[48:63]
	v_mfma_f32_32x32x16_bf16 v[16:31], v[150:153], v[180:183], v[16:31]
	v_lshl_add_u64 v[252:253], v[90:91], 0, s[64:65]
	s_mov_b32 m0, s88
	v_readfirstlane_b32 s88, v102
	global_load_lds_dwordx4 v[252:253], off
	v_mfma_f32_32x32x16_bf16 v[32:47], v[154:157], v[158:161], v[32:47]
	v_mfma_f32_32x32x16_bf16 v[0:15], v[154:157], v[180:183], v[0:15]
	v_lshl_add_u64 v[252:253], v[90:91], 0, s[66:67]
	s_mov_b32 m0, s88
	s_nop 0
	global_load_lds_dwordx4 v[252:253], off
	s_mov_b32 m0, s87
	s_mov_b64 s[88:89], 0x40700
	ds_read_b128 v[150:153], v137 offset:32768
	ds_read_b128 v[154:157], v137 offset:36864
	ds_read_b128 v[158:161], v138
	ds_read_b128 v[180:183], v138 offset:4096
	s_waitcnt lgkmcnt(4)
	v_mfma_f32_32x32x16_bf16 v[48:63], v[184:187], v[192:195], v[48:63]
	v_mfma_f32_32x32x16_bf16 v[16:31], v[184:187], v[196:199], v[16:31]
	v_mfma_f32_32x32x16_bf16 v[32:47], v[188:191], v[192:195], v[32:47]
	v_mfma_f32_32x32x16_bf16 v[0:15], v[188:191], v[196:199], v[0:15]
	s_waitcnt vmcnt(6)
	s_waitcnt lgkmcnt(0)
	s_barrier
	ds_read_b128 v[184:187], v119 offset:32768
	ds_read_b128 v[188:191], v119 offset:36864
	ds_read_b128 v[192:195], v120
	ds_read_b128 v[196:199], v120 offset:4096
	s_waitcnt lgkmcnt(4)
	v_mfma_f32_32x32x16_bf16 v[48:63], v[150:153], v[158:161], v[48:63]
	v_mfma_f32_32x32x16_bf16 v[16:31], v[150:153], v[180:183], v[16:31]
	v_lshl_add_u64 v[150:151], v[88:89], 0, s[68:69]
	global_load_lds_dwordx4 v[150:151], off
	v_mfma_f32_32x32x16_bf16 v[0:15], v[154:157], v[180:183], v[0:15]
	v_mfma_f32_32x32x16_bf16 v[32:47], v[154:157], v[158:161], v[32:47]
	v_lshl_add_u64 v[150:151], v[88:89], 0, s[70:71]
	s_mov_b32 m0, s54
	s_nop 0
	global_load_lds_dwordx4 v[150:151], off
	ds_read_b128 v[150:153], v121 offset:32768
	ds_read_b128 v[154:157], v121 offset:36864
	ds_read_b128 v[158:161], v122
	ds_read_b128 v[180:183], v122 offset:4096
	s_waitcnt lgkmcnt(4)
	v_mfma_f32_32x32x16_bf16 v[48:63], v[184:187], v[192:195], v[48:63]
	v_mfma_f32_32x32x16_bf16 v[16:31], v[184:187], v[196:199], v[16:31]
	v_lshl_add_u64 v[252:253], v[88:89], 0, s[88:89]
	s_mov_b32 m0, s55
	s_mov_b64 s[54:55], 0x60700
	global_load_lds_dwordx4 v[252:253], off
	v_mfma_f32_32x32x16_bf16 v[32:47], v[188:191], v[192:195], v[32:47]
	v_mfma_f32_32x32x16_bf16 v[0:15], v[188:191], v[196:199], v[0:15]
	v_lshl_add_u64 v[252:253], v[88:89], 0, s[54:55]
	s_mov_b32 m0, s84
	s_nop 0
	global_load_lds_dwordx4 v[252:253], off
	ds_read_b128 v[184:187], v123 offset:32768
	ds_read_b128 v[188:191], v123 offset:36864
	ds_read_b128 v[192:195], v124
	ds_read_b128 v[196:199], v124 offset:4096
	s_waitcnt lgkmcnt(4)
	v_mfma_f32_32x32x16_bf16 v[48:63], v[150:153], v[158:161], v[48:63]
	v_mfma_f32_32x32x16_bf16 v[16:31], v[150:153], v[180:183], v[16:31]
	v_lshl_add_u64 v[252:253], v[90:91], 0, s[68:69]
	s_mov_b32 m0, s79
	s_nop 0
	global_load_lds_dwordx4 v[252:253], off
	v_mfma_f32_32x32x16_bf16 v[32:47], v[154:157], v[158:161], v[32:47]
	v_mfma_f32_32x32x16_bf16 v[0:15], v[154:157], v[180:183], v[0:15]
	v_lshl_add_u64 v[252:253], v[90:91], 0, s[70:71]
	s_mov_b32 m0, s85
	s_nop 0
	global_load_lds_dwordx4 v[252:253], off
	s_mov_b32 m0, s86
	s_mov_b64 s[54:55], 0x40780
	s_waitcnt lgkmcnt(0)
	v_mfma_f32_32x32x16_bf16 v[48:63], v[184:187], v[192:195], v[48:63]
	v_mfma_f32_32x32x16_bf16 v[16:31], v[184:187], v[196:199], v[16:31]
	v_mfma_f32_32x32x16_bf16 v[32:47], v[188:191], v[192:195], v[32:47]
	v_mfma_f32_32x32x16_bf16 v[0:15], v[188:191], v[196:199], v[0:15]
	ds_read_b128 v[150:153], v125 offset:32768
	ds_read_b128 v[154:157], v125 offset:36864
	ds_read_b128 v[158:161], v126
	ds_read_b128 v[180:183], v126 offset:4096
	s_waitcnt vmcnt(6)
	s_waitcnt lgkmcnt(0)
	s_barrier
; #define MFMA(a, b, c) __builtin_amdgcn_mfma_f32_32x32x16_bf16((a), (b), (c), 0, 0, 0)
; #define WAIT_V(n) asm volatile("s_waitcnt vmcnt(%0)" ::"n"(n) : "memory")
; #define RAW_BARRIER() do { asm volatile("s_waitcnt lgkmcnt(0)" ::: "memory"); __builtin_amdgcn_s_barrier(); asm volatile("" ::: "memory"); } while (0)
; #define GLDS_STAGE(slot, kt) do { _Pragma("unroll") for (int i = 0; i < 6; ++i) \
;     __builtin_amdgcn_global_load_lds((const unsigned*)(src[i] + (kt) * 64), (__attribute__((address_space(3))) unsigned*)(smem + (slot) * G_STAGE + (wave + 8 * i) * 1024), 16, 0, 0); } while (0)
; DI void gemm_tile(const u16* __restrict__ X, int ldx, const u16* __restrict__ Wt, int ldw, int K, char* smem,
;                   f32x16 (&acc)[2][2]) {
;     ...
;   int offA[2], offB[2], xa[2], xb[2];
; #pragma unroll
;   for (int ft = 0; ft < 2; ++ft) { const int R = 256 + fw * 64 + ft * 32 + lr; offA[ft] = R * 128; xa[ft] = (R >> 1) & 7; }
; #pragma unroll
;   for (int tt = 0; tt < 2; ++tt) { const int R = tq * 64 + tt * 32 + lr; offB[tt] = R * 128; xb[tt] = (R >> 1) & 7; }
;   GLDS_STAGE(0, 0); GLDS_STAGE(1, 1); WAIT_V(6); RAW_BARRIER();
;   int cur = 0;
;   for (int kt = 0; kt < nk; ++kt) {
;     const int nxt = (cur >= 1) ? cur - 1 : 2;
;     if (kt + 2 < nk) GLDS_STAGE(nxt, kt + 2);
;     __builtin_amdgcn_sched_barrier(0);
;     const char* st = smem + cur * G_STAGE;
; #pragma unroll
;     for (int ks = 0; ks < 4; ++ks) {
;       bf16x8 a[2], b[2];
; #pragma unroll
;       for (int ft = 0; ft < 2; ++ft) a[ft] = *reinterpret_cast<const bf16x8*>(st + offA[ft] + (((ks * 2 + lh) ^ xa[ft]) << 4));
; #pragma unroll
;       for (int tt = 0; tt < 2; ++tt) b[tt] = *reinterpret_cast<const bf16x8*>(st + offB[tt] + (((ks * 2 + lh) ^ xb[tt]) << 4));
; #pragma unroll
;       for (int ft = 0; ft < 2; ++ft)
; #pragma unroll
;         for (int tt = 0; tt < 2; ++tt) acc[ft][tt] = MFMA(a[ft], b[tt], acc[ft][tt]);
;     }
;     if (kt + 2 < nk) { WAIT_V(6); } else { WAIT_V(0); }
;     RAW_BARRIER();
;     cur = (cur == 2) ? 0 : cur + 1;
;   }
	s_waitcnt lgkmcnt(0)
	v_mfma_f32_32x32x16_bf16 v[48:63], v[150:153], v[158:161], v[48:63]
	v_mfma_f32_32x32x16_bf16 v[16:31], v[150:153], v[180:183], v[16:31]
	v_lshl_add_u64 v[150:151], v[88:89], 0, s[72:73]
	global_load_lds_dwordx4 v[150:151], off
	v_lshl_add_u64 v[150:151], v[88:89], 0, s[74:75]
	s_mov_b32 m0, s0
	s_nop 0
	global_load_lds_dwordx4 v[150:151], off
	v_lshl_add_u64 v[150:151], v[88:89], 0, s[54:55]
	s_mov_b32 m0, s4
	s_mov_b64 s[54:55], 0x60780
	global_load_lds_dwordx4 v[150:151], off
	v_lshl_add_u64 v[88:89], v[88:89], 0, s[54:55]
	s_mov_b32 m0, s6
	v_mfma_f32_32x32x16_bf16 v[0:15], v[154:157], v[180:183], v[0:15]
	global_load_lds_dwordx4 v[88:89], off
	v_lshl_add_u64 v[88:89], v[90:91], 0, s[72:73]
	s_mov_b32 m0, s5
	s_nop 0
	global_load_lds_dwordx4 v[88:89], off
	v_lshl_add_u64 v[88:89], v[90:91], 0, s[74:75]
	s_mov_b32 m0, s7
	v_mfma_f32_32x32x16_bf16 v[32:47], v[154:157], v[158:161], v[32:47]
	global_load_lds_dwordx4 v[88:89], off
	ds_read_b128 v[88:91], v127 offset:32768
	ds_read_b128 v[150:153], v120 offset:49152
	ds_read_b128 v[154:157], v120 offset:53248
	s_waitcnt lgkmcnt(0)
	v_mfma_f32_32x32x16_bf16 v[48:63], v[88:91], v[150:153], v[48:63]
	v_mfma_f32_32x32x16_bf16 v[16:31], v[88:91], v[154:157], v[16:31]
	ds_read_b128 v[88:91], v127 offset:36864
	s_waitcnt lgkmcnt(0)
	v_mfma_f32_32x32x16_bf16 v[32:47], v[88:91], v[150:153], v[32:47]
	v_mfma_f32_32x32x16_bf16 v[0:15], v[88:91], v[154:157], v[0:15]
	ds_read_b128 v[88:91], v128 offset:32768
	ds_read_b128 v[150:153], v122 offset:49152
	ds_read_b128 v[154:157], v122 offset:53248
	s_waitcnt lgkmcnt(0)
	v_mfma_f32_32x32x16_bf16 v[48:63], v[88:91], v[150:153], v[48:63]
	v_mfma_f32_32x32x16_bf16 v[16:31], v[88:91], v[154:157], v[16:31]
	ds_read_b128 v[88:91], v128 offset:36864
	s_waitcnt lgkmcnt(0)
	v_mfma_f32_32x32x16_bf16 v[32:47], v[88:91], v[150:153], v[32:47]
	v_mfma_f32_32x32x16_bf16 v[0:15], v[88:91], v[154:157], v[0:15]
	ds_read_b128 v[88:91], v129 offset:32768
	ds_read_b128 v[150:153], v124 offset:49152
	ds_read_b128 v[154:157], v124 offset:53248
	s_waitcnt lgkmcnt(0)
	v_mfma_f32_32x32x16_bf16 v[48:63], v[88:91], v[150:153], v[48:63]
	v_mfma_f32_32x32x16_bf16 v[16:31], v[88:91], v[154:157], v[16:31]
	ds_read_b128 v[88:91], v129 offset:36864
	s_waitcnt lgkmcnt(0)
	v_mfma_f32_32x32x16_bf16 v[32:47], v[88:91], v[150:153], v[32:47]
	v_mfma_f32_32x32x16_bf16 v[0:15], v[88:91], v[154:157], v[0:15]
	ds_read_b128 v[88:91], v130 offset:32768
	ds_read_b128 v[150:153], v126 offset:49152
	ds_read_b128 v[154:157], v126 offset:53248
	s_waitcnt lgkmcnt(0)
	v_mfma_f32_32x32x16_bf16 v[48:63], v[88:91], v[150:153], v[48:63]
	v_mfma_f32_32x32x16_bf16 v[16:31], v[88:91], v[154:157], v[16:31]
	ds_read_b128 v[88:91], v130 offset:36864
	s_waitcnt vmcnt(6)
	s_waitcnt lgkmcnt(0)
	s_barrier
; #define MFMA(a, b, c) __builtin_amdgcn_mfma_f32_32x32x16_bf16((a), (b), (c), 0, 0, 0)
; #define WAIT_V(n) asm volatile("s_waitcnt vmcnt(%0)" ::"n"(n) : "memory")
; #define RAW_BARRIER() do { asm volatile("s_waitcnt lgkmcnt(0)" ::: "memory"); __builtin_amdgcn_s_barrier(); asm volatile("" ::: "memory"); } while (0)
; #define GLDS_STAGE(slot, kt) do { _Pragma("unroll") for (int i = 0; i < 6; ++i) \
;     __builtin_amdgcn_global_load_lds((const unsigned*)(src[i] + (kt) * 64), (__attribute__((address_space(3))) unsigned*)(smem + (slot) * G_STAGE + (wave + 8 * i) * 1024), 16, 0, 0); } while (0)
; DI void gemm_tile(const u16* __restrict__ X, int ldx, const u16* __restrict__ Wt, int ldw, int K, char* smem,
;                   f32x16 (&acc)[2][2]) {
;     ...
;   for (int kt = 0; kt < nk; ++kt) {
;     const int nxt = (cur >= 1) ? cur - 1 : 2;
;     if (kt + 2 < nk) GLDS_STAGE(nxt, kt + 2);
;     __builtin_amdgcn_sched_barrier(0);
;     const char* st = smem + cur * G_STAGE;
; #pragma unroll
;     for (int ks = 0; ks < 4; ++ks) {
;       bf16x8 a[2], b[2];
; #pragma unroll
;       for (int ft = 0; ft < 2; ++ft) a[ft] = *reinterpret_cast<const bf16x8*>(st + offA[ft] + (((ks * 2 + lh) ^ xa[ft]) << 4));
; #pragma unroll
;       for (int tt = 0; tt < 2; ++tt) b[tt] = *reinterpret_cast<const bf16x8*>(st + offB[tt] + (((ks * 2 + lh) ^ xb[tt]) << 4));
; #pragma unroll
;       for (int ft = 0; ft < 2; ++ft)
; #pragma unroll
;         for (int tt = 0; tt < 2; ++tt) acc[ft][tt] = MFMA(a[ft], b[tt], acc[ft][tt]);
;     }
;     if (kt + 2 < nk) { WAIT_V(6); } else { WAIT_V(0); }
;     RAW_BARRIER();
;     cur = (cur == 2) ? 0 : cur + 1;
;   }
; template <int MODE>
; DI void phase_gemm(const Params& p, const u16* X, const u16* Wt, int N, const float* resid, float* outf, u16* outb, int ldo, char* smem) {
;     ...
;       float* wl = (float*)(smem + wave * 17408);
; #pragma unroll
;       for (int tt = 0; tt < 2; ++tt)
; #pragma unroll
;         for (int ft = 0; ft < 2; ++ft)
; #pragma unroll
;           for (int g = 0; g < 4; ++g) {
;             f32x4 v = {acc[ft][tt][4 * g], acc[ft][tt][4 * g + 1], acc[ft][tt][4 * g + 2], acc[ft][tt][4 * g + 3]};
;             *reinterpret_cast<f32x4*>(wl + (tt * 32 + lr) * 68 + ft * 32 + 8 * g + 4 * lh) = v;
;           }
	s_waitcnt lgkmcnt(0)
	v_mfma_f32_32x32x16_bf16 v[0:15], v[88:91], v[154:157], v[0:15]
	v_mfma_f32_32x32x16_bf16 v[32:47], v[88:91], v[150:153], v[32:47]
	ds_read_b128 v[88:91], v131 offset:32768
	ds_read_b128 v[150:153], v132
	ds_read_b128 v[154:157], v132 offset:4096
	s_waitcnt lgkmcnt(0)
	v_mfma_f32_32x32x16_bf16 v[48:63], v[88:91], v[150:153], v[48:63]
	v_mfma_f32_32x32x16_bf16 v[16:31], v[88:91], v[154:157], v[16:31]
	ds_read_b128 v[88:91], v131 offset:36864
	s_waitcnt lgkmcnt(0)
	v_mfma_f32_32x32x16_bf16 v[32:47], v[88:91], v[150:153], v[32:47]
	v_mfma_f32_32x32x16_bf16 v[0:15], v[88:91], v[154:157], v[0:15]
	ds_read_b128 v[88:91], v133 offset:32768
	ds_read_b128 v[150:153], v134
	ds_read_b128 v[154:157], v134 offset:4096
	s_waitcnt lgkmcnt(0)
	v_mfma_f32_32x32x16_bf16 v[48:63], v[88:91], v[150:153], v[48:63]
	v_mfma_f32_32x32x16_bf16 v[16:31], v[88:91], v[154:157], v[16:31]
	ds_read_b128 v[88:91], v133 offset:36864
	s_waitcnt lgkmcnt(0)
	v_mfma_f32_32x32x16_bf16 v[32:47], v[88:91], v[150:153], v[32:47]
	v_mfma_f32_32x32x16_bf16 v[0:15], v[88:91], v[154:157], v[0:15]
	ds_read_b128 v[88:91], v135 offset:32768
	ds_read_b128 v[150:153], v136
	ds_read_b128 v[154:157], v136 offset:4096
	s_waitcnt lgkmcnt(0)
	v_mfma_f32_32x32x16_bf16 v[48:63], v[88:91], v[150:153], v[48:63]
	v_mfma_f32_32x32x16_bf16 v[16:31], v[88:91], v[154:157], v[16:31]
	ds_read_b128 v[88:91], v135 offset:36864
	s_waitcnt lgkmcnt(0)
	v_mfma_f32_32x32x16_bf16 v[32:47], v[88:91], v[150:153], v[32:47]
	v_mfma_f32_32x32x16_bf16 v[0:15], v[88:91], v[154:157], v[0:15]
	ds_read_b128 v[88:91], v137 offset:32768
	ds_read_b128 v[150:153], v138
	ds_read_b128 v[154:157], v138 offset:4096
	s_waitcnt lgkmcnt(0)
	v_mfma_f32_32x32x16_bf16 v[48:63], v[88:91], v[150:153], v[48:63]
	v_mfma_f32_32x32x16_bf16 v[16:31], v[88:91], v[154:157], v[16:31]
	ds_read_b128 v[88:91], v137 offset:36864
	s_waitcnt vmcnt(0)
	s_waitcnt lgkmcnt(0)
	s_barrier
	s_waitcnt lgkmcnt(0)
	v_mfma_f32_32x32x16_bf16 v[0:15], v[88:91], v[154:157], v[0:15]
	v_mfma_f32_32x32x16_bf16 v[32:47], v[88:91], v[150:153], v[32:47]
	ds_read_b128 v[88:91], v119 offset:32768
	ds_read_b128 v[150:153], v120
	ds_read_b128 v[154:157], v119 offset:36864
	ds_read_b128 v[158:161], v120 offset:4096
	s_mov_b64 s[54:55], 0
	s_waitcnt lgkmcnt(0)
	v_mfma_f32_32x32x16_bf16 v[48:63], v[88:91], v[150:153], v[48:63]
	v_mfma_f32_32x32x16_bf16 v[32:47], v[154:157], v[150:153], v[32:47]
	v_mfma_f32_32x32x16_bf16 v[0:15], v[154:157], v[158:161], v[0:15]
	v_mfma_f32_32x32x16_bf16 v[16:31], v[88:91], v[158:161], v[16:31]
	ds_read_b128 v[88:91], v121 offset:32768
	ds_read_b128 v[150:153], v122
	ds_read_b128 v[154:157], v121 offset:36864
	ds_read_b128 v[158:161], v122 offset:4096
	s_waitcnt lgkmcnt(0)
	v_mfma_f32_32x32x16_bf16 v[48:63], v[88:91], v[150:153], v[48:63]
	v_mfma_f32_32x32x16_bf16 v[32:47], v[154:157], v[150:153], v[32:47]
	v_mfma_f32_32x32x16_bf16 v[0:15], v[154:157], v[158:161], v[0:15]
	v_mfma_f32_32x32x16_bf16 v[16:31], v[88:91], v[158:161], v[16:31]
	ds_read_b128 v[88:91], v123 offset:32768
	ds_read_b128 v[150:153], v124
	ds_read_b128 v[154:157], v123 offset:36864
	ds_read_b128 v[158:161], v124 offset:4096
	s_waitcnt lgkmcnt(0)
	v_mfma_f32_32x32x16_bf16 v[48:63], v[88:91], v[150:153], v[48:63]
	v_mfma_f32_32x32x16_bf16 v[32:47], v[154:157], v[150:153], v[32:47]
	v_mfma_f32_32x32x16_bf16 v[0:15], v[154:157], v[158:161], v[0:15]
	v_mfma_f32_32x32x16_bf16 v[16:31], v[88:91], v[158:161], v[16:31]
	ds_read_b128 v[88:91], v125 offset:32768
	ds_read_b128 v[150:153], v126
	ds_read_b128 v[154:157], v125 offset:36864
	ds_read_b128 v[158:161], v126 offset:4096
	s_waitcnt vmcnt(0)
	s_waitcnt lgkmcnt(0)
	s_barrier
	s_waitcnt lgkmcnt(0)
	v_mfma_f32_32x32x16_bf16 v[48:63], v[88:91], v[150:153], v[48:63]
	v_mfma_f32_32x32x16_bf16 v[32:47], v[154:157], v[150:153], v[32:47]
	s_nop 10
	ds_write_b128 v139, v[48:51]
	ds_write_b128 v139, v[52:55] offset:32
	ds_write_b128 v139, v[56:59] offset:64
	ds_write_b128 v139, v[60:63] offset:96
	ds_write_b128 v139, v[32:35] offset:128
	v_mfma_f32_32x32x16_bf16 v[0:15], v[154:157], v[158:161], v[0:15]
	v_mfma_f32_32x32x16_bf16 v[16:31], v[88:91], v[158:161], v[16:31]
	ds_write_b128 v139, v[36:39] offset:160
	ds_write_b128 v139, v[40:43] offset:192
	ds_write_b128 v139, v[44:47] offset:224
	s_nop 8
	ds_write_b128 v139, v[16:19] offset:8704
	ds_write_b128 v139, v[20:23] offset:8736
	ds_write_b128 v139, v[24:27] offset:8768
	ds_write_b128 v139, v[28:31] offset:8800
	ds_write_b128 v139, v[0:3] offset:8832
	ds_write_b128 v139, v[4:7] offset:8864
	ds_write_b128 v139, v[8:11] offset:8896
	ds_write_b128 v139, v[12:15] offset:8928
	v_mov_b32_e32 v0, v103

; #define MFMA(a, b, c) __builtin_amdgcn_mfma_f32_32x32x16_bf16((a), (b), (c), 0, 0, 0)
; #define WAIT_V(n) asm volatile("s_waitcnt vmcnt(%0)" ::"n"(n) : "memory")
; DI void gemm_tile(const u16* __restrict__ X, int ldx, const u16* __restrict__ Wt, int ldw, int K, char* smem,
;                   f32x16 (&acc)[2][2]) {
;     ...
;   const int nk = K / 64;
;   const u16* src[6];
; #pragma unroll
;   for (int i = 0; i < 6; ++i) {
;     const int R = 8 * (wave + 8 * i) + (lane >> 3);
;     const int c = (lane & 7) ^ ((R >> 1) & 7);
;     src[i] = (i < 4) ? (X + (size_t)R * ldx + c * 8) : (Wt + (size_t)(R - 256) * ldw + c * 8);
;   }
;     ...
;   int offA[2], offB[2], xa[2], xb[2];
; #pragma unroll
;   for (int ft = 0; ft < 2; ++ft) { const int R = 256 + fw * 64 + ft * 32 + lr; offA[ft] = R * 128; xa[ft] = (R >> 1) & 7; }
; #pragma unroll
;   for (int tt = 0; tt < 2; ++tt) { const int R = tq * 64 + tt * 32 + lr; offB[tt] = R * 128; xb[tt] = (R >> 1) & 7; }
;   GLDS_STAGE(0, 0); GLDS_STAGE(1, 1); WAIT_V(6); RAW_BARRIER();
;   int cur = 0;
;   for (int kt = 0; kt < nk; ++kt) {
;     const int nxt = (cur >= 1) ? cur - 1 : 2;
;     if (kt + 2 < nk) GLDS_STAGE(nxt, kt + 2);
;     __builtin_amdgcn_sched_barrier(0);
;     const char* st = smem + cur * G_STAGE;
; #pragma unroll
;     for (int ks = 0; ks < 4; ++ks) {
;       bf16x8 a[2], b[2];
; #pragma unroll
;       for (int ft = 0; ft < 2; ++ft) a[ft] = *reinterpret_cast<const bf16x8*>(st + offA[ft] + (((ks * 2 + lh) ^ xa[ft]) << 4));
; #pragma unroll
;       for (int tt = 0; tt < 2; ++tt) b[tt] = *reinterpret_cast<const bf16x8*>(st + offB[tt] + (((ks * 2 + lh) ^ xb[tt]) << 4));
; #pragma unroll
;       for (int ft = 0; ft < 2; ++ft)
; #pragma unroll
;         for (int tt = 0; tt < 2; ++tt) acc[ft][tt] = MFMA(a[ft], b[tt], acc[ft][tt]);
;     }
;     if (kt + 2 < nk) { WAIT_V(6); } else { WAIT_V(0); }
;     RAW_BARRIER();
;     cur = (cur == 2) ? 0 : cur + 1;
;   }
; template <int MODE>
; DI void phase_gemm(const Params& p, const u16* X, const u16* Wt, int N, const float* resid, float* outf, u16* outb, int ldo, char* smem) {
;     ...
;   for (int u = xi; u < per_group; u += xn) {
;     const int mt = xg + 8 * (u / ntn), nt = u % ntn;
;     f32x16 acc[2][2];
;     gemm_tile(X + (size_t)mt * 256 * 1024, 1024, Wt + (size_t)nt * 128 * 1024, 1024, 1024, smem, acc);
.LBB0_678:
	s_and_b32 s0, s54, 0x78
	s_or_b32 s89, s0, s33
	s_lshl_b32 s12, s89, 19
	v_lshl_add_u64 v[0:1], v[66:67], 0, s[12:13]
	v_readfirstlane_b32 s7, v143
	v_lshl_add_u64 v[74:75], v[0:1], 0, v[72:73]
	s_mov_b32 m0, s7
	v_readfirstlane_b32 s6, v90
	s_and_b32 s4, s87, 0xe0000
	v_lshl_add_u64 v[0:1], v[74:75], 0, s[14:15]
	s_mov_b64 s[0:1], 0x40000
	global_load_lds_dwordx4 v[74:75], off
	s_mov_b32 m0, s6
	v_readfirstlane_b32 s95, v91
	v_lshl_add_u64 v[2:3], v[74:75], 0, s[0:1]
	s_mov_b64 s[0:1], 0x60000
	s_lshl_b32 s12, s4, 1
	global_load_lds_dwordx4 v[0:1], off
	s_mov_b32 m0, s95
	v_readfirstlane_b32 s93, v92
	v_lshl_add_u64 v[4:5], v[74:75], 0, s[0:1]
	v_lshl_add_u64 v[6:7], v[68:69], 0, s[12:13]
	global_load_lds_dwordx4 v[2:3], off
	s_mov_b32 m0, s93
	v_readfirstlane_b32 s92, v93
	v_lshl_add_u64 v[76:77], v[6:7], 0, v[72:73]
	global_load_lds_dwordx4 v[4:5], off
	s_mov_b32 m0, s92
	v_readfirstlane_b32 s91, v94
	v_lshl_add_u64 v[6:7], v[76:77], 0, s[14:15]
	global_load_lds_dwordx4 v[76:77], off
	s_mov_b32 m0, s91
	v_readfirstlane_b32 s90, v78
	global_load_lds_dwordx4 v[6:7], off
	v_lshl_add_u64 v[0:1], v[74:75], 0, s[16:17]
	s_mov_b32 m0, s90
	v_readfirstlane_b32 s12, v95
	global_load_lds_dwordx4 v[0:1], off
	v_lshl_add_u64 v[0:1], v[74:75], 0, s[18:19]
	s_mov_b32 m0, s12
	s_mov_b64 s[0:1], 0x40080
	global_load_lds_dwordx4 v[0:1], off
	v_lshl_add_u64 v[0:1], v[74:75], 0, s[0:1]
	v_readfirstlane_b32 s0, v96
	s_mov_b32 m0, s0
	s_mov_b64 s[0:1], 0x60080
	global_load_lds_dwordx4 v[0:1], off
	v_lshl_add_u64 v[0:1], v[74:75], 0, s[0:1]
	v_readfirstlane_b32 s0, v97
	s_mov_b32 m0, s0
	v_readfirstlane_b32 s0, v98
	global_load_lds_dwordx4 v[0:1], off
	v_lshl_add_u64 v[0:1], v[76:77], 0, s[16:17]
	s_mov_b32 m0, s0
	v_readfirstlane_b32 s0, v99
	global_load_lds_dwordx4 v[0:1], off
	v_lshl_add_u64 v[0:1], v[76:77], 0, s[18:19]
	s_mov_b32 m0, s0
	v_readfirstlane_b32 s5, v79
	global_load_lds_dwordx4 v[0:1], off
	s_waitcnt vmcnt(6)
	s_waitcnt lgkmcnt(0)
	s_barrier
	v_lshl_add_u64 v[0:1], v[74:75], 0, s[20:21]
	s_mov_b32 m0, s5
	v_readfirstlane_b32 s4, v80
	global_load_lds_dwordx4 v[0:1], off
	v_lshl_add_u64 v[0:1], v[74:75], 0, s[22:23]
	s_mov_b32 m0, s4
	s_mov_b64 s[0:1], 0x40100
	global_load_lds_dwordx4 v[0:1], off
	v_lshl_add_u64 v[0:1], v[74:75], 0, s[0:1]
	v_readfirstlane_b32 s0, v81
	s_mov_b32 m0, s0
	s_mov_b64 s[8:9], 0x60100
	v_readfirstlane_b32 s1, v82
	global_load_lds_dwordx4 v[0:1], off
	v_lshl_add_u64 v[0:1], v[74:75], 0, s[8:9]
	s_mov_b32 m0, s1
	v_readfirstlane_b32 s10, v83
	global_load_lds_dwordx4 v[0:1], off
	v_lshl_add_u64 v[0:1], v[76:77], 0, s[20:21]
	s_mov_b32 m0, s10
	v_readfirstlane_b32 s11, v84
	global_load_lds_dwordx4 v[0:1], off
	v_lshl_add_u64 v[0:1], v[76:77], 0, s[22:23]
	s_mov_b32 m0, s11
	s_nop 0
	global_load_lds_dwordx4 v[0:1], off
	ds_read_b128 v[0:3], v100 offset:32768
	ds_read_b128 v[4:7], v100 offset:36864
	ds_read_b128 v[8:11], v101
	ds_read_b128 v[12:15], v101 offset:4096
	ds_read_b128 v[120:123], v102 offset:32768
	ds_read_b128 v[124:127], v102 offset:36864
	ds_read_b128 v[128:131], v103
	ds_read_b128 v[132:135], v103 offset:4096
	s_mov_b32 m0, s7
	s_mov_b64 s[8:9], 0x40180
	s_waitcnt lgkmcnt(0)
	v_mfma_f32_32x32x16_bf16 v[48:63], v[0:3], v[8:11], 0
	v_mfma_f32_32x32x16_bf16 v[16:31], v[0:3], v[12:15], 0
	v_mfma_f32_32x32x16_bf16 v[32:47], v[4:7], v[8:11], 0
	v_mfma_f32_32x32x16_bf16 v[0:15], v[4:7], v[12:15], 0
	ds_read_b128 v[184:187], v104 offset:32768
	ds_read_b128 v[188:191], v104 offset:36864
	ds_read_b128 v[192:195], v105
	ds_read_b128 v[196:199], v105 offset:4096
	s_waitcnt lgkmcnt(4)
	v_mfma_f32_32x32x16_bf16 v[48:63], v[120:123], v[128:131], v[48:63]
	v_mfma_f32_32x32x16_bf16 v[16:31], v[120:123], v[132:135], v[16:31]
	v_mfma_f32_32x32x16_bf16 v[32:47], v[124:127], v[128:131], v[32:47]
	v_mfma_f32_32x32x16_bf16 v[0:15], v[124:127], v[132:135], v[0:15]
	ds_read_b128 v[120:123], v106 offset:32768
	ds_read_b128 v[124:127], v106 offset:36864
	ds_read_b128 v[128:131], v107
	ds_read_b128 v[132:135], v107 offset:4096
	s_waitcnt lgkmcnt(4)
	v_mfma_f32_32x32x16_bf16 v[48:63], v[184:187], v[192:195], v[48:63]
	v_mfma_f32_32x32x16_bf16 v[16:31], v[184:187], v[196:199], v[16:31]
	v_mfma_f32_32x32x16_bf16 v[32:47], v[188:191], v[192:195], v[32:47]
	v_mfma_f32_32x32x16_bf16 v[0:15], v[188:191], v[196:199], v[0:15]
	s_waitcnt vmcnt(6)
	s_waitcnt lgkmcnt(0)
	s_barrier
; #define MFMA(a, b, c) __builtin_amdgcn_mfma_f32_32x32x16_bf16((a), (b), (c), 0, 0, 0)
; #define WAIT_V(n) asm volatile("s_waitcnt vmcnt(%0)" ::"n"(n) : "memory")
; #define RAW_BARRIER() do { asm volatile("s_waitcnt lgkmcnt(0)" ::: "memory"); __builtin_amdgcn_s_barrier(); asm volatile("" ::: "memory"); } while (0)
; #define GLDS_STAGE(slot, kt) do { _Pragma("unroll") for (int i = 0; i < 6; ++i) \
;     __builtin_amdgcn_global_load_lds((const unsigned*)(src[i] + (kt) * 64), (__attribute__((address_space(3))) unsigned*)(smem + (slot) * G_STAGE + (wave + 8 * i) * 1024), 16, 0, 0); } while (0)
; DI void gemm_tile(const u16* __restrict__ X, int ldx, const u16* __restrict__ Wt, int ldw, int K, char* smem,
;                   f32x16 (&acc)[2][2]) {
;     ...
;   int offA[2], offB[2], xa[2], xb[2];
; #pragma unroll
;   for (int ft = 0; ft < 2; ++ft) { const int R = 256 + fw * 64 + ft * 32 + lr; offA[ft] = R * 128; xa[ft] = (R >> 1) & 7; }
; #pragma unroll
;   for (int tt = 0; tt < 2; ++tt) { const int R = tq * 64 + tt * 32 + lr; offB[tt] = R * 128; xb[tt] = (R >> 1) & 7; }
;   GLDS_STAGE(0, 0); GLDS_STAGE(1, 1); WAIT_V(6); RAW_BARRIER();
;   int cur = 0;
;   for (int kt = 0; kt < nk; ++kt) {
;     const int nxt = (cur >= 1) ? cur - 1 : 2;
;     if (kt + 2 < nk) GLDS_STAGE(nxt, kt + 2);
;     __builtin_amdgcn_sched_barrier(0);
;     const char* st = smem + cur * G_STAGE;
; #pragma unroll
;     for (int ks = 0; ks < 4; ++ks) {
;       bf16x8 a[2], b[2];
; #pragma unroll
;       for (int ft = 0; ft < 2; ++ft) a[ft] = *reinterpret_cast<const bf16x8*>(st + offA[ft] + (((ks * 2 + lh) ^ xa[ft]) << 4));
; #pragma unroll
;       for (int tt = 0; tt < 2; ++tt) b[tt] = *reinterpret_cast<const bf16x8*>(st + offB[tt] + (((ks * 2 + lh) ^ xb[tt]) << 4));
; #pragma unroll
;       for (int ft = 0; ft < 2; ++ft)
; #pragma unroll
;         for (int tt = 0; tt < 2; ++tt) acc[ft][tt] = MFMA(a[ft], b[tt], acc[ft][tt]);
;     }
;     if (kt + 2 < nk) { WAIT_V(6); } else { WAIT_V(0); }
;     RAW_BARRIER();
;     cur = (cur == 2) ? 0 : cur + 1;
;   }
	ds_read_b128 v[184:187], v108 offset:32768
	ds_read_b128 v[188:191], v108 offset:36864
	ds_read_b128 v[192:195], v101 offset:49152
	ds_read_b128 v[196:199], v101 offset:53248
	s_waitcnt lgkmcnt(4)
	v_mfma_f32_32x32x16_bf16 v[48:63], v[120:123], v[128:131], v[48:63]
	v_mfma_f32_32x32x16_bf16 v[16:31], v[120:123], v[132:135], v[16:31]
	v_lshl_add_u64 v[120:121], v[74:75], 0, s[24:25]
	global_load_lds_dwordx4 v[120:121], off
	v_mfma_f32_32x32x16_bf16 v[32:47], v[124:127], v[128:131], v[32:47]
	v_mfma_f32_32x32x16_bf16 v[0:15], v[124:127], v[132:135], v[0:15]
	v_lshl_add_u64 v[120:121], v[74:75], 0, s[26:27]
	s_mov_b32 m0, s6
	s_nop 0
	global_load_lds_dwordx4 v[120:121], off
	ds_read_b128 v[120:123], v109 offset:32768
	ds_read_b128 v[124:127], v109 offset:36864
	ds_read_b128 v[128:131], v103 offset:49152
	ds_read_b128 v[132:135], v103 offset:53248
	s_waitcnt lgkmcnt(4)
	v_mfma_f32_32x32x16_bf16 v[48:63], v[184:187], v[192:195], v[48:63]
	v_mfma_f32_32x32x16_bf16 v[16:31], v[184:187], v[196:199], v[16:31]
	v_lshl_add_u64 v[252:253], v[74:75], 0, s[8:9]
	s_mov_b32 m0, s95
	s_mov_b64 s[8:9], 0x60180
	global_load_lds_dwordx4 v[252:253], off
	v_mfma_f32_32x32x16_bf16 v[32:47], v[188:191], v[192:195], v[32:47]
	v_mfma_f32_32x32x16_bf16 v[0:15], v[188:191], v[196:199], v[0:15]
	v_lshl_add_u64 v[252:253], v[74:75], 0, s[8:9]
	s_mov_b32 m0, s93
	s_nop 0
	global_load_lds_dwordx4 v[252:253], off
	ds_read_b128 v[184:187], v110 offset:32768
	ds_read_b128 v[188:191], v110 offset:36864
	ds_read_b128 v[192:195], v105 offset:49152
	ds_read_b128 v[196:199], v105 offset:53248
	s_waitcnt lgkmcnt(4)
	v_mfma_f32_32x32x16_bf16 v[48:63], v[120:123], v[128:131], v[48:63]
	v_mfma_f32_32x32x16_bf16 v[16:31], v[120:123], v[132:135], v[16:31]
	v_lshl_add_u64 v[252:253], v[76:77], 0, s[24:25]
	s_mov_b32 m0, s92
	s_nop 0
	global_load_lds_dwordx4 v[252:253], off
	v_mfma_f32_32x32x16_bf16 v[32:47], v[124:127], v[128:131], v[32:47]
	v_mfma_f32_32x32x16_bf16 v[0:15], v[124:127], v[132:135], v[0:15]
	v_lshl_add_u64 v[252:253], v[76:77], 0, s[26:27]
	s_mov_b32 m0, s91
	s_nop 0
	global_load_lds_dwordx4 v[252:253], off
	s_mov_b32 m0, s90
	s_mov_b64 s[8:9], 0x40200
	s_mov_b64 s[46:47], 0x60200
	ds_read_b128 v[120:123], v111 offset:32768
	ds_read_b128 v[124:127], v111 offset:36864
	ds_read_b128 v[128:131], v107 offset:49152
	ds_read_b128 v[132:135], v107 offset:53248
	s_waitcnt lgkmcnt(4)
	v_mfma_f32_32x32x16_bf16 v[48:63], v[184:187], v[192:195], v[48:63]
	v_mfma_f32_32x32x16_bf16 v[16:31], v[184:187], v[196:199], v[16:31]
	v_mfma_f32_32x32x16_bf16 v[32:47], v[188:191], v[192:195], v[32:47]
	v_mfma_f32_32x32x16_bf16 v[0:15], v[188:191], v[196:199], v[0:15]
	s_waitcnt vmcnt(6)
	s_waitcnt lgkmcnt(0)
	s_barrier
	ds_read_b128 v[184:187], v112 offset:32768
	ds_read_b128 v[188:191], v112 offset:36864
	ds_read_b128 v[192:195], v113
	ds_read_b128 v[196:199], v113 offset:4096
	s_waitcnt lgkmcnt(4)
	v_mfma_f32_32x32x16_bf16 v[48:63], v[120:123], v[128:131], v[48:63]
	v_mfma_f32_32x32x16_bf16 v[16:31], v[120:123], v[132:135], v[16:31]
	v_lshl_add_u64 v[120:121], v[74:75], 0, s[28:29]
	global_load_lds_dwordx4 v[120:121], off
	v_mfma_f32_32x32x16_bf16 v[32:47], v[124:127], v[128:131], v[32:47]
	v_mfma_f32_32x32x16_bf16 v[0:15], v[124:127], v[132:135], v[0:15]
	v_lshl_add_u64 v[120:121], v[74:75], 0, s[30:31]
	s_mov_b32 m0, s12
	s_nop 0
	global_load_lds_dwordx4 v[120:121], off
	ds_read_b128 v[120:123], v114 offset:32768
	ds_read_b128 v[124:127], v114 offset:36864
	ds_read_b128 v[128:131], v115
	ds_read_b128 v[132:135], v115 offset:4096
	s_waitcnt lgkmcnt(4)
	v_mfma_f32_32x32x16_bf16 v[48:63], v[184:187], v[192:195], v[48:63]
	v_mfma_f32_32x32x16_bf16 v[16:31], v[184:187], v[196:199], v[16:31]
	v_lshl_add_u64 v[252:253], v[74:75], 0, s[8:9]
	v_readfirstlane_b32 s8, v85
	s_mov_b32 m0, s8
	v_readfirstlane_b32 s9, v87
	global_load_lds_dwordx4 v[252:253], off
	v_mfma_f32_32x32x16_bf16 v[32:47], v[188:191], v[192:195], v[32:47]
	v_mfma_f32_32x32x16_bf16 v[0:15], v[188:191], v[196:199], v[0:15]
	v_lshl_add_u64 v[252:253], v[74:75], 0, s[46:47]
	v_readfirstlane_b32 s46, v86
	s_mov_b32 m0, s46
	v_readfirstlane_b32 s47, v88
	global_load_lds_dwordx4 v[252:253], off
	ds_read_b128 v[184:187], v116 offset:32768
	ds_read_b128 v[188:191], v116 offset:36864
	ds_read_b128 v[192:195], v117
	ds_read_b128 v[196:199], v117 offset:4096
	s_waitcnt lgkmcnt(4)
	v_mfma_f32_32x32x16_bf16 v[48:63], v[120:123], v[128:131], v[48:63]
	v_mfma_f32_32x32x16_bf16 v[16:31], v[120:123], v[132:135], v[16:31]
	v_lshl_add_u64 v[252:253], v[76:77], 0, s[28:29]
	s_mov_b32 m0, s9
	s_nop 0
	global_load_lds_dwordx4 v[252:253], off
	v_mfma_f32_32x32x16_bf16 v[32:47], v[124:127], v[128:131], v[32:47]
	v_mfma_f32_32x32x16_bf16 v[0:15], v[124:127], v[132:135], v[0:15]
	v_lshl_add_u64 v[252:253], v[76:77], 0, s[30:31]
	s_mov_b32 m0, s47
	s_nop 0
	global_load_lds_dwordx4 v[252:253], off
	s_mov_b32 m0, s5
	s_mov_b64 vcc, 0x40280
	ds_read_b128 v[120:123], v118 offset:32768
	ds_read_b128 v[124:127], v118 offset:36864
	ds_read_b128 v[128:131], v119
	ds_read_b128 v[132:135], v119 offset:4096
	s_waitcnt lgkmcnt(4)
	v_mfma_f32_32x32x16_bf16 v[48:63], v[184:187], v[192:195], v[48:63]
	v_mfma_f32_32x32x16_bf16 v[16:31], v[184:187], v[196:199], v[16:31]
	v_mfma_f32_32x32x16_bf16 v[32:47], v[188:191], v[192:195], v[32:47]
	v_mfma_f32_32x32x16_bf16 v[0:15], v[188:191], v[196:199], v[0:15]
	s_waitcnt vmcnt(6)
	s_waitcnt lgkmcnt(0)
	s_barrier
; #define MFMA(a, b, c) __builtin_amdgcn_mfma_f32_32x32x16_bf16((a), (b), (c), 0, 0, 0)
; #define WAIT_V(n) asm volatile("s_waitcnt vmcnt(%0)" ::"n"(n) : "memory")
; #define RAW_BARRIER() do { asm volatile("s_waitcnt lgkmcnt(0)" ::: "memory"); __builtin_amdgcn_s_barrier(); asm volatile("" ::: "memory"); } while (0)
; #define GLDS_STAGE(slot, kt) do { _Pragma("unroll") for (int i = 0; i < 6; ++i) \
;     __builtin_amdgcn_global_load_lds((const unsigned*)(src[i] + (kt) * 64), (__attribute__((address_space(3))) unsigned*)(smem + (slot) * G_STAGE + (wave + 8 * i) * 1024), 16, 0, 0); } while (0)
; DI void gemm_tile(const u16* __restrict__ X, int ldx, const u16* __restrict__ Wt, int ldw, int K, char* smem,
;                   f32x16 (&acc)[2][2]) {
;     ...
;   int offA[2], offB[2], xa[2], xb[2];
; #pragma unroll
;   for (int ft = 0; ft < 2; ++ft) { const int R = 256 + fw * 64 + ft * 32 + lr; offA[ft] = R * 128; xa[ft] = (R >> 1) & 7; }
; #pragma unroll
;   for (int tt = 0; tt < 2; ++tt) { const int R = tq * 64 + tt * 32 + lr; offB[tt] = R * 128; xb[tt] = (R >> 1) & 7; }
;   GLDS_STAGE(0, 0); GLDS_STAGE(1, 1); WAIT_V(6); RAW_BARRIER();
;   int cur = 0;
;   for (int kt = 0; kt < nk; ++kt) {
;     const int nxt = (cur >= 1) ? cur - 1 : 2;
;     if (kt + 2 < nk) GLDS_STAGE(nxt, kt + 2);
;     __builtin_amdgcn_sched_barrier(0);
;     const char* st = smem + cur * G_STAGE;
; #pragma unroll
;     for (int ks = 0; ks < 4; ++ks) {
;       bf16x8 a[2], b[2];
; #pragma unroll
;       for (int ft = 0; ft < 2; ++ft) a[ft] = *reinterpret_cast<const bf16x8*>(st + offA[ft] + (((ks * 2 + lh) ^ xa[ft]) << 4));
; #pragma unroll
;       for (int tt = 0; tt < 2; ++tt) b[tt] = *reinterpret_cast<const bf16x8*>(st + offB[tt] + (((ks * 2 + lh) ^ xb[tt]) << 4));
; #pragma unroll
;       for (int ft = 0; ft < 2; ++ft)
; #pragma unroll
;         for (int tt = 0; tt < 2; ++tt) acc[ft][tt] = MFMA(a[ft], b[tt], acc[ft][tt]);
;     }
;     if (kt + 2 < nk) { WAIT_V(6); } else { WAIT_V(0); }
;     RAW_BARRIER();
;     cur = (cur == 2) ? 0 : cur + 1;
;   }
	ds_read_b128 v[184:187], v100 offset:32768
	ds_read_b128 v[188:191], v100 offset:36864
	ds_read_b128 v[192:195], v101
	ds_read_b128 v[196:199], v101 offset:4096
	s_waitcnt lgkmcnt(4)
	v_mfma_f32_32x32x16_bf16 v[48:63], v[120:123], v[128:131], v[48:63]
	v_mfma_f32_32x32x16_bf16 v[16:31], v[120:123], v[132:135], v[16:31]
	v_lshl_add_u64 v[120:121], v[74:75], 0, s[34:35]
	global_load_lds_dwordx4 v[120:121], off
	v_mfma_f32_32x32x16_bf16 v[32:47], v[124:127], v[128:131], v[32:47]
	v_mfma_f32_32x32x16_bf16 v[0:15], v[124:127], v[132:135], v[0:15]
	v_lshl_add_u64 v[120:121], v[74:75], 0, s[36:37]
	s_mov_b32 m0, s4
	s_nop 0
	global_load_lds_dwordx4 v[120:121], off
	ds_read_b128 v[120:123], v102 offset:32768
	ds_read_b128 v[124:127], v102 offset:36864
	ds_read_b128 v[128:131], v103
	ds_read_b128 v[132:135], v103 offset:4096
	s_waitcnt lgkmcnt(4)
	v_mfma_f32_32x32x16_bf16 v[48:63], v[184:187], v[192:195], v[48:63]
	v_mfma_f32_32x32x16_bf16 v[16:31], v[184:187], v[196:199], v[16:31]
	v_lshl_add_u64 v[252:253], v[74:75], 0, vcc
	s_mov_b32 m0, s0
	s_mov_b64 vcc, 0x60280
	global_load_lds_dwordx4 v[252:253], off
	v_mfma_f32_32x32x16_bf16 v[32:47], v[188:191], v[192:195], v[32:47]
	v_mfma_f32_32x32x16_bf16 v[0:15], v[188:191], v[196:199], v[0:15]
	v_lshl_add_u64 v[252:253], v[74:75], 0, vcc
	s_mov_b32 m0, s1
	s_nop 0
	global_load_lds_dwordx4 v[252:253], off
	ds_read_b128 v[184:187], v104 offset:32768
	ds_read_b128 v[188:191], v104 offset:36864
	ds_read_b128 v[192:195], v105
	ds_read_b128 v[196:199], v105 offset:4096
	s_waitcnt lgkmcnt(4)
	v_mfma_f32_32x32x16_bf16 v[48:63], v[120:123], v[128:131], v[48:63]
	v_mfma_f32_32x32x16_bf16 v[16:31], v[120:123], v[132:135], v[16:31]
	v_lshl_add_u64 v[252:253], v[76:77], 0, s[34:35]
	s_mov_b32 m0, s10
	s_nop 0
	global_load_lds_dwordx4 v[252:253], off
	v_mfma_f32_32x32x16_bf16 v[32:47], v[124:127], v[128:131], v[32:47]
	v_mfma_f32_32x32x16_bf16 v[0:15], v[124:127], v[132:135], v[0:15]
	v_lshl_add_u64 v[252:253], v[76:77], 0, s[36:37]
	s_mov_b32 m0, s11
	s_nop 0
	global_load_lds_dwordx4 v[252:253], off
	s_mov_b32 m0, s7
	s_mov_b64 vcc, 0x40300
	ds_read_b128 v[120:123], v106 offset:32768
	ds_read_b128 v[124:127], v106 offset:36864
	ds_read_b128 v[128:131], v107
	ds_read_b128 v[132:135], v107 offset:4096
	s_waitcnt lgkmcnt(4)
	v_mfma_f32_32x32x16_bf16 v[48:63], v[184:187], v[192:195], v[48:63]
	v_mfma_f32_32x32x16_bf16 v[16:31], v[184:187], v[196:199], v[16:31]
	v_mfma_f32_32x32x16_bf16 v[32:47], v[188:191], v[192:195], v[32:47]
	v_mfma_f32_32x32x16_bf16 v[0:15], v[188:191], v[196:199], v[0:15]
	s_waitcnt vmcnt(6)
	s_waitcnt lgkmcnt(0)
	s_barrier
	ds_read_b128 v[184:187], v108 offset:32768
	ds_read_b128 v[188:191], v108 offset:36864
	ds_read_b128 v[192:195], v101 offset:49152
	ds_read_b128 v[196:199], v101 offset:53248
	s_waitcnt lgkmcnt(4)
	v_mfma_f32_32x32x16_bf16 v[48:63], v[120:123], v[128:131], v[48:63]
	v_mfma_f32_32x32x16_bf16 v[16:31], v[120:123], v[132:135], v[16:31]
	v_lshl_add_u64 v[120:121], v[74:75], 0, s[38:39]
	global_load_lds_dwordx4 v[120:121], off
	v_mfma_f32_32x32x16_bf16 v[32:47], v[124:127], v[128:131], v[32:47]
	v_mfma_f32_32x32x16_bf16 v[0:15], v[124:127], v[132:135], v[0:15]
	v_lshl_add_u64 v[120:121], v[74:75], 0, s[40:41]
	s_mov_b32 m0, s6
	s_nop 0
	global_load_lds_dwordx4 v[120:121], off
	ds_read_b128 v[120:123], v109 offset:32768
	ds_read_b128 v[124:127], v109 offset:36864
	ds_read_b128 v[128:131], v103 offset:49152
	ds_read_b128 v[132:135], v103 offset:53248
	s_waitcnt lgkmcnt(4)
	v_mfma_f32_32x32x16_bf16 v[48:63], v[184:187], v[192:195], v[48:63]
	v_mfma_f32_32x32x16_bf16 v[16:31], v[184:187], v[196:199], v[16:31]
	v_lshl_add_u64 v[252:253], v[74:75], 0, vcc
	s_mov_b32 m0, s95
	s_mov_b64 vcc, 0x60300
	global_load_lds_dwordx4 v[252:253], off
	v_mfma_f32_32x32x16_bf16 v[32:47], v[188:191], v[192:195], v[32:47]
	v_mfma_f32_32x32x16_bf16 v[0:15], v[188:191], v[196:199], v[0:15]
	v_lshl_add_u64 v[252:253], v[74:75], 0, vcc
	s_mov_b32 m0, s93
	s_nop 0
	global_load_lds_dwordx4 v[252:253], off
	ds_read_b128 v[184:187], v110 offset:32768
	ds_read_b128 v[188:191], v110 offset:36864
	ds_read_b128 v[192:195], v105 offset:49152
	ds_read_b128 v[196:199], v105 offset:53248
	s_waitcnt lgkmcnt(4)
	v_mfma_f32_32x32x16_bf16 v[48:63], v[120:123], v[128:131], v[48:63]
	v_mfma_f32_32x32x16_bf16 v[16:31], v[120:123], v[132:135], v[16:31]
	v_lshl_add_u64 v[252:253], v[76:77], 0, s[38:39]
	s_mov_b32 m0, s92
	s_nop 0
	global_load_lds_dwordx4 v[252:253], off
	v_mfma_f32_32x32x16_bf16 v[32:47], v[124:127], v[128:131], v[32:47]
	v_mfma_f32_32x32x16_bf16 v[0:15], v[124:127], v[132:135], v[0:15]
	v_lshl_add_u64 v[252:253], v[76:77], 0, s[40:41]
	s_mov_b32 m0, s91
	s_nop 0
	global_load_lds_dwordx4 v[252:253], off
	s_mov_b32 m0, s90
	s_mov_b64 vcc, 0x40380
	ds_read_b128 v[120:123], v111 offset:32768
	ds_read_b128 v[124:127], v111 offset:36864
	ds_read_b128 v[128:131], v107 offset:49152
	ds_read_b128 v[132:135], v107 offset:53248
	s_waitcnt lgkmcnt(4)
	v_mfma_f32_32x32x16_bf16 v[48:63], v[184:187], v[192:195], v[48:63]
	v_mfma_f32_32x32x16_bf16 v[16:31], v[184:187], v[196:199], v[16:31]
	v_mfma_f32_32x32x16_bf16 v[32:47], v[188:191], v[192:195], v[32:47]
	v_mfma_f32_32x32x16_bf16 v[0:15], v[188:191], v[196:199], v[0:15]
	s_waitcnt vmcnt(6)
	s_waitcnt lgkmcnt(0)
	s_barrier
; #define MFMA(a, b, c) __builtin_amdgcn_mfma_f32_32x32x16_bf16((a), (b), (c), 0, 0, 0)
; #define WAIT_V(n) asm volatile("s_waitcnt vmcnt(%0)" ::"n"(n) : "memory")
; #define RAW_BARRIER() do { asm volatile("s_waitcnt lgkmcnt(0)" ::: "memory"); __builtin_amdgcn_s_barrier(); asm volatile("" ::: "memory"); } while (0)
; #define GLDS_STAGE(slot, kt) do { _Pragma("unroll") for (int i = 0; i < 6; ++i) \
;     __builtin_amdgcn_global_load_lds((const unsigned*)(src[i] + (kt) * 64), (__attribute__((address_space(3))) unsigned*)(smem + (slot) * G_STAGE + (wave + 8 * i) * 1024), 16, 0, 0); } while (0)
; DI void gemm_tile(const u16* __restrict__ X, int ldx, const u16* __restrict__ Wt, int ldw, int K, char* smem,
;                   f32x16 (&acc)[2][2]) {
;     ...
;   int offA[2], offB[2], xa[2], xb[2];
; #pragma unroll
;   for (int ft = 0; ft < 2; ++ft) { const int R = 256 + fw * 64 + ft * 32 + lr; offA[ft] = R * 128; xa[ft] = (R >> 1) & 7; }
; #pragma unroll
;   for (int tt = 0; tt < 2; ++tt) { const int R = tq * 64 + tt * 32 + lr; offB[tt] = R * 128; xb[tt] = (R >> 1) & 7; }
;   GLDS_STAGE(0, 0); GLDS_STAGE(1, 1); WAIT_V(6); RAW_BARRIER();
;   int cur = 0;
;   for (int kt = 0; kt < nk; ++kt) {
;     const int nxt = (cur >= 1) ? cur - 1 : 2;
;     if (kt + 2 < nk) GLDS_STAGE(nxt, kt + 2);
;     __builtin_amdgcn_sched_barrier(0);
;     const char* st = smem + cur * G_STAGE;
; #pragma unroll
;     for (int ks = 0; ks < 4; ++ks) {
;       bf16x8 a[2], b[2];
; #pragma unroll
;       for (int ft = 0; ft < 2; ++ft) a[ft] = *reinterpret_cast<const bf16x8*>(st + offA[ft] + (((ks * 2 + lh) ^ xa[ft]) << 4));
; #pragma unroll
;       for (int tt = 0; tt < 2; ++tt) b[tt] = *reinterpret_cast<const bf16x8*>(st + offB[tt] + (((ks * 2 + lh) ^ xb[tt]) << 4));
; #pragma unroll
;       for (int ft = 0; ft < 2; ++ft)
; #pragma unroll
;         for (int tt = 0; tt < 2; ++tt) acc[ft][tt] = MFMA(a[ft], b[tt], acc[ft][tt]);
;     }
;     if (kt + 2 < nk) { WAIT_V(6); } else { WAIT_V(0); }
;     RAW_BARRIER();
;     cur = (cur == 2) ? 0 : cur + 1;
;   }
	ds_read_b128 v[184:187], v112 offset:32768
	ds_read_b128 v[188:191], v112 offset:36864
	ds_read_b128 v[192:195], v113
	ds_read_b128 v[196:199], v113 offset:4096
	s_waitcnt lgkmcnt(4)
	v_mfma_f32_32x32x16_bf16 v[48:63], v[120:123], v[128:131], v[48:63]
	v_mfma_f32_32x32x16_bf16 v[16:31], v[120:123], v[132:135], v[16:31]
	v_lshl_add_u64 v[120:121], v[74:75], 0, s[42:43]
	global_load_lds_dwordx4 v[120:121], off
	v_mfma_f32_32x32x16_bf16 v[32:47], v[124:127], v[128:131], v[32:47]
	v_mfma_f32_32x32x16_bf16 v[0:15], v[124:127], v[132:135], v[0:15]
	v_lshl_add_u64 v[120:121], v[74:75], 0, s[44:45]
	s_mov_b32 m0, s12
	s_nop 0
	global_load_lds_dwordx4 v[120:121], off
	ds_read_b128 v[120:123], v114 offset:32768
	ds_read_b128 v[124:127], v114 offset:36864
	ds_read_b128 v[128:131], v115
	ds_read_b128 v[132:135], v115 offset:4096
	s_waitcnt lgkmcnt(4)
	v_mfma_f32_32x32x16_bf16 v[48:63], v[184:187], v[192:195], v[48:63]
	v_mfma_f32_32x32x16_bf16 v[16:31], v[184:187], v[196:199], v[16:31]
	v_lshl_add_u64 v[252:253], v[74:75], 0, vcc
	s_mov_b32 m0, s8
	s_mov_b64 vcc, 0x60380
	global_load_lds_dwordx4 v[252:253], off
	v_mfma_f32_32x32x16_bf16 v[32:47], v[188:191], v[192:195], v[32:47]
	v_mfma_f32_32x32x16_bf16 v[0:15], v[188:191], v[196:199], v[0:15]
	v_lshl_add_u64 v[252:253], v[74:75], 0, vcc
	s_mov_b32 m0, s46
	s_nop 0
	global_load_lds_dwordx4 v[252:253], off
	ds_read_b128 v[184:187], v116 offset:32768
	ds_read_b128 v[188:191], v116 offset:36864
	ds_read_b128 v[192:195], v117
	ds_read_b128 v[196:199], v117 offset:4096
	s_waitcnt lgkmcnt(4)
	v_mfma_f32_32x32x16_bf16 v[48:63], v[120:123], v[128:131], v[48:63]
	v_mfma_f32_32x32x16_bf16 v[16:31], v[120:123], v[132:135], v[16:31]
	v_lshl_add_u64 v[252:253], v[76:77], 0, s[42:43]
	s_mov_b32 m0, s9
	s_nop 0
	global_load_lds_dwordx4 v[252:253], off
	v_mfma_f32_32x32x16_bf16 v[32:47], v[124:127], v[128:131], v[32:47]
	v_mfma_f32_32x32x16_bf16 v[0:15], v[124:127], v[132:135], v[0:15]
	v_lshl_add_u64 v[252:253], v[76:77], 0, s[44:45]
	s_mov_b32 m0, s47
	s_nop 0
	global_load_lds_dwordx4 v[252:253], off
	s_mov_b32 m0, s5
	ds_read_b128 v[120:123], v118 offset:32768
	ds_read_b128 v[124:127], v118 offset:36864
	ds_read_b128 v[128:131], v119
	ds_read_b128 v[132:135], v119 offset:4096
	s_waitcnt lgkmcnt(4)
	v_mfma_f32_32x32x16_bf16 v[48:63], v[184:187], v[192:195], v[48:63]
	v_mfma_f32_32x32x16_bf16 v[16:31], v[184:187], v[196:199], v[16:31]
	v_mfma_f32_32x32x16_bf16 v[32:47], v[188:191], v[192:195], v[32:47]
	v_mfma_f32_32x32x16_bf16 v[0:15], v[188:191], v[196:199], v[0:15]
	s_waitcnt vmcnt(6)
	s_waitcnt lgkmcnt(0)
	s_barrier
	ds_read_b128 v[184:187], v100 offset:32768
	ds_read_b128 v[188:191], v100 offset:36864
	ds_read_b128 v[192:195], v101
	ds_read_b128 v[196:199], v101 offset:4096
	s_waitcnt lgkmcnt(4)
	v_mfma_f32_32x32x16_bf16 v[48:63], v[120:123], v[128:131], v[48:63]
	v_mfma_f32_32x32x16_bf16 v[16:31], v[120:123], v[132:135], v[16:31]
	v_lshl_add_u64 v[120:121], v[74:75], 0, s[48:49]
	global_load_lds_dwordx4 v[120:121], off
	v_mfma_f32_32x32x16_bf16 v[32:47], v[124:127], v[128:131], v[32:47]
	v_mfma_f32_32x32x16_bf16 v[0:15], v[124:127], v[132:135], v[0:15]
	v_lshl_add_u64 v[120:121], v[74:75], 0, s[50:51]
	s_mov_b32 m0, s4
	s_mov_b64 s[4:5], 0x40400
	global_load_lds_dwordx4 v[120:121], off
	ds_read_b128 v[120:123], v102 offset:32768
	ds_read_b128 v[124:127], v102 offset:36864
	ds_read_b128 v[128:131], v103
	ds_read_b128 v[132:135], v103 offset:4096
	s_waitcnt lgkmcnt(4)
	v_mfma_f32_32x32x16_bf16 v[48:63], v[184:187], v[192:195], v[48:63]
	v_mfma_f32_32x32x16_bf16 v[16:31], v[184:187], v[196:199], v[16:31]
	v_lshl_add_u64 v[252:253], v[74:75], 0, s[4:5]
	s_mov_b32 m0, s0
	s_mov_b64 s[4:5], 0x60400
	global_load_lds_dwordx4 v[252:253], off
	v_mfma_f32_32x32x16_bf16 v[32:47], v[188:191], v[192:195], v[32:47]
	v_mfma_f32_32x32x16_bf16 v[0:15], v[188:191], v[196:199], v[0:15]
	v_lshl_add_u64 v[252:253], v[74:75], 0, s[4:5]
	s_mov_b32 m0, s1
	s_nop 0
	global_load_lds_dwordx4 v[252:253], off
	ds_read_b128 v[184:187], v104 offset:32768
	ds_read_b128 v[188:191], v104 offset:36864
	ds_read_b128 v[192:195], v105
	ds_read_b128 v[196:199], v105 offset:4096
	s_waitcnt lgkmcnt(4)
	v_mfma_f32_32x32x16_bf16 v[48:63], v[120:123], v[128:131], v[48:63]
	v_mfma_f32_32x32x16_bf16 v[16:31], v[120:123], v[132:135], v[16:31]
	v_lshl_add_u64 v[252:253], v[76:77], 0, s[48:49]
	s_mov_b32 m0, s10
	s_nop 0
	global_load_lds_dwordx4 v[252:253], off
	v_mfma_f32_32x32x16_bf16 v[32:47], v[124:127], v[128:131], v[32:47]
	v_mfma_f32_32x32x16_bf16 v[0:15], v[124:127], v[132:135], v[0:15]
	v_lshl_add_u64 v[252:253], v[76:77], 0, s[50:51]
	s_mov_b32 m0, s11
	s_nop 0
	global_load_lds_dwordx4 v[252:253], off
	s_mov_b32 m0, s7
	s_mov_b64 s[0:1], 0x40480
	ds_read_b128 v[120:123], v106 offset:32768
	ds_read_b128 v[124:127], v106 offset:36864
	ds_read_b128 v[128:131], v107
	ds_read_b128 v[132:135], v107 offset:4096
	s_waitcnt lgkmcnt(4)
	v_mfma_f32_32x32x16_bf16 v[48:63], v[184:187], v[192:195], v[48:63]
	v_mfma_f32_32x32x16_bf16 v[16:31], v[184:187], v[196:199], v[16:31]
	v_mfma_f32_32x32x16_bf16 v[32:47], v[188:191], v[192:195], v[32:47]
	v_mfma_f32_32x32x16_bf16 v[0:15], v[188:191], v[196:199], v[0:15]
	s_waitcnt vmcnt(6)
	s_waitcnt lgkmcnt(0)
	s_barrier
; #define MFMA(a, b, c) __builtin_amdgcn_mfma_f32_32x32x16_bf16((a), (b), (c), 0, 0, 0)
; #define WAIT_V(n) asm volatile("s_waitcnt vmcnt(%0)" ::"n"(n) : "memory")
; #define RAW_BARRIER() do { asm volatile("s_waitcnt lgkmcnt(0)" ::: "memory"); __builtin_amdgcn_s_barrier(); asm volatile("" ::: "memory"); } while (0)
; #define GLDS_STAGE(slot, kt) do { _Pragma("unroll") for (int i = 0; i < 6; ++i) \
;     __builtin_amdgcn_global_load_lds((const unsigned*)(src[i] + (kt) * 64), (__attribute__((address_space(3))) unsigned*)(smem + (slot) * G_STAGE + (wave + 8 * i) * 1024), 16, 0, 0); } while (0)
; DI void gemm_tile(const u16* __restrict__ X, int ldx, const u16* __restrict__ Wt, int ldw, int K, char* smem,
;                   f32x16 (&acc)[2][2]) {
;     ...
;   int offA[2], offB[2], xa[2], xb[2];
; #pragma unroll
;   for (int ft = 0; ft < 2; ++ft) { const int R = 256 + fw * 64 + ft * 32 + lr; offA[ft] = R * 128; xa[ft] = (R >> 1) & 7; }
; #pragma unroll
;   for (int tt = 0; tt < 2; ++tt) { const int R = tq * 64 + tt * 32 + lr; offB[tt] = R * 128; xb[tt] = (R >> 1) & 7; }
;   GLDS_STAGE(0, 0); GLDS_STAGE(1, 1); WAIT_V(6); RAW_BARRIER();
;   int cur = 0;
;   for (int kt = 0; kt < nk; ++kt) {
;     const int nxt = (cur >= 1) ? cur - 1 : 2;
;     if (kt + 2 < nk) GLDS_STAGE(nxt, kt + 2);
;     __builtin_amdgcn_sched_barrier(0);
;     const char* st = smem + cur * G_STAGE;
; #pragma unroll
;     for (int ks = 0; ks < 4; ++ks) {
;       bf16x8 a[2], b[2];
; #pragma unroll
;       for (int ft = 0; ft < 2; ++ft) a[ft] = *reinterpret_cast<const bf16x8*>(st + offA[ft] + (((ks * 2 + lh) ^ xa[ft]) << 4));
; #pragma unroll
;       for (int tt = 0; tt < 2; ++tt) b[tt] = *reinterpret_cast<const bf16x8*>(st + offB[tt] + (((ks * 2 + lh) ^ xb[tt]) << 4));
; #pragma unroll
;       for (int ft = 0; ft < 2; ++ft)
; #pragma unroll
;         for (int tt = 0; tt < 2; ++tt) acc[ft][tt] = MFMA(a[ft], b[tt], acc[ft][tt]);
;     }
;     if (kt + 2 < nk) { WAIT_V(6); } else { WAIT_V(0); }
;     RAW_BARRIER();
;     cur = (cur == 2) ? 0 : cur + 1;
;   }
	ds_read_b128 v[184:187], v108 offset:32768
	ds_read_b128 v[188:191], v108 offset:36864
	ds_read_b128 v[192:195], v101 offset:49152
	ds_read_b128 v[196:199], v101 offset:53248
	s_waitcnt lgkmcnt(4)
	v_mfma_f32_32x32x16_bf16 v[48:63], v[120:123], v[128:131], v[48:63]
	v_mfma_f32_32x32x16_bf16 v[16:31], v[120:123], v[132:135], v[16:31]
	v_lshl_add_u64 v[120:121], v[74:75], 0, s[52:53]
	global_load_lds_dwordx4 v[120:121], off
	v_mfma_f32_32x32x16_bf16 v[32:47], v[124:127], v[128:131], v[32:47]
	v_mfma_f32_32x32x16_bf16 v[0:15], v[124:127], v[132:135], v[0:15]
	v_lshl_add_u64 v[120:121], v[74:75], 0, s[56:57]
	s_mov_b32 m0, s6
	s_nop 0
	global_load_lds_dwordx4 v[120:121], off
	ds_read_b128 v[120:123], v109 offset:32768
	ds_read_b128 v[124:127], v109 offset:36864
	ds_read_b128 v[128:131], v103 offset:49152
	ds_read_b128 v[132:135], v103 offset:53248
	s_waitcnt lgkmcnt(4)
	v_mfma_f32_32x32x16_bf16 v[48:63], v[184:187], v[192:195], v[48:63]
	v_mfma_f32_32x32x16_bf16 v[16:31], v[184:187], v[196:199], v[16:31]
	v_lshl_add_u64 v[252:253], v[74:75], 0, s[0:1]
	s_mov_b32 m0, s95
	s_mov_b64 s[0:1], 0x60480
	global_load_lds_dwordx4 v[252:253], off
	v_mfma_f32_32x32x16_bf16 v[32:47], v[188:191], v[192:195], v[32:47]
	v_mfma_f32_32x32x16_bf16 v[0:15], v[188:191], v[196:199], v[0:15]
	v_lshl_add_u64 v[252:253], v[74:75], 0, s[0:1]
	s_mov_b32 m0, s93
	s_nop 0
	global_load_lds_dwordx4 v[252:253], off
	ds_read_b128 v[184:187], v110 offset:32768
	ds_read_b128 v[188:191], v110 offset:36864
	ds_read_b128 v[192:195], v105 offset:49152
	ds_read_b128 v[196:199], v105 offset:53248
	s_waitcnt lgkmcnt(4)
	v_mfma_f32_32x32x16_bf16 v[48:63], v[120:123], v[128:131], v[48:63]
	v_mfma_f32_32x32x16_bf16 v[16:31], v[120:123], v[132:135], v[16:31]
	v_lshl_add_u64 v[252:253], v[76:77], 0, s[52:53]
	s_mov_b32 m0, s92
	s_nop 0
	global_load_lds_dwordx4 v[252:253], off
	v_mfma_f32_32x32x16_bf16 v[32:47], v[124:127], v[128:131], v[32:47]
	v_mfma_f32_32x32x16_bf16 v[0:15], v[124:127], v[132:135], v[0:15]
	v_lshl_add_u64 v[252:253], v[76:77], 0, s[56:57]
	s_mov_b32 m0, s91
	s_nop 0
	global_load_lds_dwordx4 v[252:253], off
	s_mov_b32 m0, s90
	s_mov_b64 s[0:1], 0x40500
	ds_read_b128 v[120:123], v111 offset:32768
	ds_read_b128 v[124:127], v111 offset:36864
	ds_read_b128 v[128:131], v107 offset:49152
	ds_read_b128 v[132:135], v107 offset:53248
	s_waitcnt lgkmcnt(4)
	v_mfma_f32_32x32x16_bf16 v[48:63], v[184:187], v[192:195], v[48:63]
	v_mfma_f32_32x32x16_bf16 v[16:31], v[184:187], v[196:199], v[16:31]
	v_mfma_f32_32x32x16_bf16 v[32:47], v[188:191], v[192:195], v[32:47]
	v_mfma_f32_32x32x16_bf16 v[0:15], v[188:191], v[196:199], v[0:15]
	s_waitcnt vmcnt(6)
	s_waitcnt lgkmcnt(0)
	s_barrier
	ds_read_b128 v[184:187], v112 offset:32768
	ds_read_b128 v[188:191], v112 offset:36864
	ds_read_b128 v[192:195], v113
	ds_read_b128 v[196:199], v113 offset:4096
	s_waitcnt lgkmcnt(4)
	v_mfma_f32_32x32x16_bf16 v[48:63], v[120:123], v[128:131], v[48:63]
	v_mfma_f32_32x32x16_bf16 v[16:31], v[120:123], v[132:135], v[16:31]
	v_lshl_add_u64 v[120:121], v[74:75], 0, s[58:59]
	global_load_lds_dwordx4 v[120:121], off
	v_mfma_f32_32x32x16_bf16 v[32:47], v[124:127], v[128:131], v[32:47]
	v_mfma_f32_32x32x16_bf16 v[0:15], v[124:127], v[132:135], v[0:15]
	v_lshl_add_u64 v[120:121], v[74:75], 0, s[60:61]
	s_mov_b32 m0, s12
	s_nop 0
	global_load_lds_dwordx4 v[120:121], off
	ds_read_b128 v[120:123], v114 offset:32768
	ds_read_b128 v[124:127], v114 offset:36864
	ds_read_b128 v[128:131], v115
	ds_read_b128 v[132:135], v115 offset:4096
	s_waitcnt lgkmcnt(4)
	v_mfma_f32_32x32x16_bf16 v[48:63], v[184:187], v[192:195], v[48:63]
	v_mfma_f32_32x32x16_bf16 v[16:31], v[184:187], v[196:199], v[16:31]
	v_lshl_add_u64 v[252:253], v[74:75], 0, s[0:1]
	s_mov_b32 m0, s8
	s_mov_b64 s[0:1], 0x60500
	global_load_lds_dwordx4 v[252:253], off
	v_mfma_f32_32x32x16_bf16 v[32:47], v[188:191], v[192:195], v[32:47]
	v_mfma_f32_32x32x16_bf16 v[0:15], v[188:191], v[196:199], v[0:15]
	v_lshl_add_u64 v[252:253], v[74:75], 0, s[0:1]
	s_mov_b32 m0, s46
	s_nop 0
	global_load_lds_dwordx4 v[252:253], off
	ds_read_b128 v[184:187], v116 offset:32768
	ds_read_b128 v[188:191], v116 offset:36864
	ds_read_b128 v[192:195], v117
	ds_read_b128 v[196:199], v117 offset:4096
	s_waitcnt lgkmcnt(4)
	v_mfma_f32_32x32x16_bf16 v[48:63], v[120:123], v[128:131], v[48:63]
	v_mfma_f32_32x32x16_bf16 v[16:31], v[120:123], v[132:135], v[16:31]
	v_lshl_add_u64 v[252:253], v[76:77], 0, s[58:59]
	s_mov_b32 m0, s9
	s_nop 0
	global_load_lds_dwordx4 v[252:253], off
	v_mfma_f32_32x32x16_bf16 v[32:47], v[124:127], v[128:131], v[32:47]
	v_mfma_f32_32x32x16_bf16 v[0:15], v[124:127], v[132:135], v[0:15]
	v_lshl_add_u64 v[252:253], v[76:77], 0, s[60:61]
	s_mov_b32 m0, s47
	s_nop 0
	global_load_lds_dwordx4 v[252:253], off
	v_readfirstlane_b32 s46, v79
	s_mov_b32 m0, s46
	v_readfirstlane_b32 s7, v80
	s_mov_b64 s[0:1], 0x40580
	v_readfirstlane_b32 s8, v81
	v_readfirstlane_b32 s10, v82
	v_readfirstlane_b32 s9, v83
	v_readfirstlane_b32 s11, v84
	ds_read_b128 v[120:123], v118 offset:32768
	ds_read_b128 v[124:127], v118 offset:36864
	ds_read_b128 v[128:131], v119
	ds_read_b128 v[132:135], v119 offset:4096
	s_waitcnt lgkmcnt(4)
	v_mfma_f32_32x32x16_bf16 v[48:63], v[184:187], v[192:195], v[48:63]
	v_mfma_f32_32x32x16_bf16 v[16:31], v[184:187], v[196:199], v[16:31]
	v_mfma_f32_32x32x16_bf16 v[32:47], v[188:191], v[192:195], v[32:47]
	v_mfma_f32_32x32x16_bf16 v[0:15], v[188:191], v[196:199], v[0:15]
	s_waitcnt vmcnt(6)
	s_waitcnt lgkmcnt(0)
	s_barrier
; #define MFMA(a, b, c) __builtin_amdgcn_mfma_f32_32x32x16_bf16((a), (b), (c), 0, 0, 0)
; #define WAIT_V(n) asm volatile("s_waitcnt vmcnt(%0)" ::"n"(n) : "memory")
; #define RAW_BARRIER() do { asm volatile("s_waitcnt lgkmcnt(0)" ::: "memory"); __builtin_amdgcn_s_barrier(); asm volatile("" ::: "memory"); } while (0)
; #define GLDS_STAGE(slot, kt) do { _Pragma("unroll") for (int i = 0; i < 6; ++i) \
;     __builtin_amdgcn_global_load_lds((const unsigned*)(src[i] + (kt) * 64), (__attribute__((address_space(3))) unsigned*)(smem + (slot) * G_STAGE + (wave + 8 * i) * 1024), 16, 0, 0); } while (0)
; DI void gemm_tile(const u16* __restrict__ X, int ldx, const u16* __restrict__ Wt, int ldw, int K, char* smem,
;                   f32x16 (&acc)[2][2]) {
;     ...
;   int offA[2], offB[2], xa[2], xb[2];
; #pragma unroll
;   for (int ft = 0; ft < 2; ++ft) { const int R = 256 + fw * 64 + ft * 32 + lr; offA[ft] = R * 128; xa[ft] = (R >> 1) & 7; }
; #pragma unroll
;   for (int tt = 0; tt < 2; ++tt) { const int R = tq * 64 + tt * 32 + lr; offB[tt] = R * 128; xb[tt] = (R >> 1) & 7; }
;   GLDS_STAGE(0, 0); GLDS_STAGE(1, 1); WAIT_V(6); RAW_BARRIER();
;   int cur = 0;
;   for (int kt = 0; kt < nk; ++kt) {
;     const int nxt = (cur >= 1) ? cur - 1 : 2;
;     if (kt + 2 < nk) GLDS_STAGE(nxt, kt + 2);
;     __builtin_amdgcn_sched_barrier(0);
;     const char* st = smem + cur * G_STAGE;
; #pragma unroll
;     for (int ks = 0; ks < 4; ++ks) {
;       bf16x8 a[2], b[2];
; #pragma unroll
;       for (int ft = 0; ft < 2; ++ft) a[ft] = *reinterpret_cast<const bf16x8*>(st + offA[ft] + (((ks * 2 + lh) ^ xa[ft]) << 4));
; #pragma unroll
;       for (int tt = 0; tt < 2; ++tt) b[tt] = *reinterpret_cast<const bf16x8*>(st + offB[tt] + (((ks * 2 + lh) ^ xb[tt]) << 4));
; #pragma unroll
;       for (int ft = 0; ft < 2; ++ft)
; #pragma unroll
;         for (int tt = 0; tt < 2; ++tt) acc[ft][tt] = MFMA(a[ft], b[tt], acc[ft][tt]);
;     }
;     if (kt + 2 < nk) { WAIT_V(6); } else { WAIT_V(0); }
;     RAW_BARRIER();
;     cur = (cur == 2) ? 0 : cur + 1;
;   }
	ds_read_b128 v[184:187], v100 offset:32768
	ds_read_b128 v[188:191], v100 offset:36864
	ds_read_b128 v[192:195], v101
	ds_read_b128 v[196:199], v101 offset:4096
	s_waitcnt lgkmcnt(4)
	v_mfma_f32_32x32x16_bf16 v[48:63], v[120:123], v[128:131], v[48:63]
	v_mfma_f32_32x32x16_bf16 v[16:31], v[120:123], v[132:135], v[16:31]
	v_lshl_add_u64 v[120:121], v[74:75], 0, s[62:63]
	global_load_lds_dwordx4 v[120:121], off
	v_mfma_f32_32x32x16_bf16 v[32:47], v[124:127], v[128:131], v[32:47]
	v_mfma_f32_32x32x16_bf16 v[0:15], v[124:127], v[132:135], v[0:15]
	v_lshl_add_u64 v[120:121], v[74:75], 0, s[64:65]
	s_mov_b32 m0, s7
	s_nop 0
	global_load_lds_dwordx4 v[120:121], off
	ds_read_b128 v[120:123], v102 offset:32768
	ds_read_b128 v[124:127], v102 offset:36864
	ds_read_b128 v[128:131], v103
	ds_read_b128 v[132:135], v103 offset:4096
	s_waitcnt lgkmcnt(4)
	v_mfma_f32_32x32x16_bf16 v[48:63], v[184:187], v[192:195], v[48:63]
	v_mfma_f32_32x32x16_bf16 v[16:31], v[184:187], v[196:199], v[16:31]
	v_lshl_add_u64 v[252:253], v[74:75], 0, s[0:1]
	s_mov_b32 m0, s8
	s_mov_b64 s[0:1], 0x60580
	global_load_lds_dwordx4 v[252:253], off
	v_mfma_f32_32x32x16_bf16 v[32:47], v[188:191], v[192:195], v[32:47]
	v_mfma_f32_32x32x16_bf16 v[0:15], v[188:191], v[196:199], v[0:15]
	v_lshl_add_u64 v[252:253], v[74:75], 0, s[0:1]
	s_mov_b32 m0, s10
	s_nop 0
	global_load_lds_dwordx4 v[252:253], off
	ds_read_b128 v[184:187], v104 offset:32768
	ds_read_b128 v[188:191], v104 offset:36864
	ds_read_b128 v[192:195], v105
	ds_read_b128 v[196:199], v105 offset:4096
	s_waitcnt lgkmcnt(4)
	v_mfma_f32_32x32x16_bf16 v[48:63], v[120:123], v[128:131], v[48:63]
	v_mfma_f32_32x32x16_bf16 v[16:31], v[120:123], v[132:135], v[16:31]
	v_lshl_add_u64 v[252:253], v[76:77], 0, s[62:63]
	s_mov_b32 m0, s9
	s_nop 0
	global_load_lds_dwordx4 v[252:253], off
	v_mfma_f32_32x32x16_bf16 v[32:47], v[124:127], v[128:131], v[32:47]
	v_mfma_f32_32x32x16_bf16 v[0:15], v[124:127], v[132:135], v[0:15]
	v_lshl_add_u64 v[252:253], v[76:77], 0, s[64:65]
	s_mov_b32 m0, s11
	s_nop 0
	global_load_lds_dwordx4 v[252:253], off
	v_readfirstlane_b32 s12, v143
	s_mov_b32 m0, s12
	v_readfirstlane_b32 s0, v90
	s_mov_b64 s[4:5], 0x40600
	v_readfirstlane_b32 s1, v91
	v_readfirstlane_b32 s6, v94
	ds_read_b128 v[120:123], v106 offset:32768
	ds_read_b128 v[124:127], v106 offset:36864
	ds_read_b128 v[128:131], v107
	ds_read_b128 v[132:135], v107 offset:4096
	s_waitcnt lgkmcnt(4)
	v_mfma_f32_32x32x16_bf16 v[48:63], v[184:187], v[192:195], v[48:63]
	v_mfma_f32_32x32x16_bf16 v[16:31], v[184:187], v[196:199], v[16:31]
	v_mfma_f32_32x32x16_bf16 v[32:47], v[188:191], v[192:195], v[32:47]
	v_mfma_f32_32x32x16_bf16 v[0:15], v[188:191], v[196:199], v[0:15]
	s_waitcnt vmcnt(6)
	s_waitcnt lgkmcnt(0)
	s_barrier
	ds_read_b128 v[184:187], v108 offset:32768
	ds_read_b128 v[188:191], v108 offset:36864
	ds_read_b128 v[192:195], v101 offset:49152
	ds_read_b128 v[196:199], v101 offset:53248
	s_waitcnt lgkmcnt(4)
	v_mfma_f32_32x32x16_bf16 v[48:63], v[120:123], v[128:131], v[48:63]
	v_mfma_f32_32x32x16_bf16 v[16:31], v[120:123], v[132:135], v[16:31]
	v_lshl_add_u64 v[120:121], v[74:75], 0, s[66:67]
	global_load_lds_dwordx4 v[120:121], off
	v_mfma_f32_32x32x16_bf16 v[32:47], v[124:127], v[128:131], v[32:47]
	v_mfma_f32_32x32x16_bf16 v[0:15], v[124:127], v[132:135], v[0:15]
	v_lshl_add_u64 v[120:121], v[74:75], 0, s[68:69]
	s_mov_b32 m0, s0
	s_nop 0
	global_load_lds_dwordx4 v[120:121], off
	ds_read_b128 v[120:123], v109 offset:32768
	ds_read_b128 v[124:127], v109 offset:36864
	ds_read_b128 v[128:131], v103 offset:49152
	ds_read_b128 v[132:135], v103 offset:53248
	s_waitcnt lgkmcnt(4)
	v_mfma_f32_32x32x16_bf16 v[48:63], v[184:187], v[192:195], v[48:63]
	v_mfma_f32_32x32x16_bf16 v[16:31], v[184:187], v[196:199], v[16:31]
	v_lshl_add_u64 v[252:253], v[74:75], 0, s[4:5]
	s_mov_b32 m0, s1
	s_mov_b64 s[4:5], 0x60600
	global_load_lds_dwordx4 v[252:253], off
	v_mfma_f32_32x32x16_bf16 v[32:47], v[188:191], v[192:195], v[32:47]
	v_mfma_f32_32x32x16_bf16 v[0:15], v[188:191], v[196:199], v[0:15]
	v_lshl_add_u64 v[252:253], v[74:75], 0, s[4:5]
	v_readfirstlane_b32 s5, v92
	s_mov_b32 m0, s5
	v_readfirstlane_b32 s4, v93
	global_load_lds_dwordx4 v[252:253], off
	ds_read_b128 v[184:187], v110 offset:32768
	ds_read_b128 v[188:191], v110 offset:36864
	ds_read_b128 v[192:195], v105 offset:49152
	ds_read_b128 v[196:199], v105 offset:53248
	s_waitcnt lgkmcnt(4)
	v_mfma_f32_32x32x16_bf16 v[48:63], v[120:123], v[128:131], v[48:63]
	v_mfma_f32_32x32x16_bf16 v[16:31], v[120:123], v[132:135], v[16:31]
	v_lshl_add_u64 v[252:253], v[76:77], 0, s[66:67]
	s_mov_b32 m0, s4
	s_nop 0
	global_load_lds_dwordx4 v[252:253], off
	v_mfma_f32_32x32x16_bf16 v[32:47], v[124:127], v[128:131], v[32:47]
	v_mfma_f32_32x32x16_bf16 v[0:15], v[124:127], v[132:135], v[0:15]
	v_lshl_add_u64 v[252:253], v[76:77], 0, s[68:69]
	s_mov_b32 m0, s6
	s_nop 0
	global_load_lds_dwordx4 v[252:253], off
	v_readfirstlane_b32 s47, v78
	s_mov_b32 m0, s47
	v_readfirstlane_b32 s47, v95
	s_mov_b64 s[90:91], 0x40680
	ds_read_b128 v[120:123], v111 offset:32768
	ds_read_b128 v[124:127], v111 offset:36864
	ds_read_b128 v[128:131], v107 offset:49152
	ds_read_b128 v[132:135], v107 offset:53248
	s_waitcnt lgkmcnt(4)
	v_mfma_f32_32x32x16_bf16 v[48:63], v[184:187], v[192:195], v[48:63]
	v_mfma_f32_32x32x16_bf16 v[16:31], v[184:187], v[196:199], v[16:31]
	v_mfma_f32_32x32x16_bf16 v[32:47], v[188:191], v[192:195], v[32:47]
	v_mfma_f32_32x32x16_bf16 v[0:15], v[188:191], v[196:199], v[0:15]
	s_waitcnt vmcnt(6)
	s_waitcnt lgkmcnt(0)
	s_barrier
; #define MFMA(a, b, c) __builtin_amdgcn_mfma_f32_32x32x16_bf16((a), (b), (c), 0, 0, 0)
; #define WAIT_V(n) asm volatile("s_waitcnt vmcnt(%0)" ::"n"(n) : "memory")
; #define RAW_BARRIER() do { asm volatile("s_waitcnt lgkmcnt(0)" ::: "memory"); __builtin_amdgcn_s_barrier(); asm volatile("" ::: "memory"); } while (0)
; #define GLDS_STAGE(slot, kt) do { _Pragma("unroll") for (int i = 0; i < 6; ++i) \
;     __builtin_amdgcn_global_load_lds((const unsigned*)(src[i] + (kt) * 64), (__attribute__((address_space(3))) unsigned*)(smem + (slot) * G_STAGE + (wave + 8 * i) * 1024), 16, 0, 0); } while (0)
; DI void gemm_tile(const u16* __restrict__ X, int ldx, const u16* __restrict__ Wt, int ldw, int K, char* smem,
;                   f32x16 (&acc)[2][2]) {
;     ...
;   int offA[2], offB[2], xa[2], xb[2];
; #pragma unroll
;   for (int ft = 0; ft < 2; ++ft) { const int R = 256 + fw * 64 + ft * 32 + lr; offA[ft] = R * 128; xa[ft] = (R >> 1) & 7; }
; #pragma unroll
;   for (int tt = 0; tt < 2; ++tt) { const int R = tq * 64 + tt * 32 + lr; offB[tt] = R * 128; xb[tt] = (R >> 1) & 7; }
;   GLDS_STAGE(0, 0); GLDS_STAGE(1, 1); WAIT_V(6); RAW_BARRIER();
;   int cur = 0;
;   for (int kt = 0; kt < nk; ++kt) {
;     const int nxt = (cur >= 1) ? cur - 1 : 2;
;     if (kt + 2 < nk) GLDS_STAGE(nxt, kt + 2);
;     __builtin_amdgcn_sched_barrier(0);
;     const char* st = smem + cur * G_STAGE;
; #pragma unroll
;     for (int ks = 0; ks < 4; ++ks) {
;       bf16x8 a[2], b[2];
; #pragma unroll
;       for (int ft = 0; ft < 2; ++ft) a[ft] = *reinterpret_cast<const bf16x8*>(st + offA[ft] + (((ks * 2 + lh) ^ xa[ft]) << 4));
; #pragma unroll
;       for (int tt = 0; tt < 2; ++tt) b[tt] = *reinterpret_cast<const bf16x8*>(st + offB[tt] + (((ks * 2 + lh) ^ xb[tt]) << 4));
; #pragma unroll
;       for (int ft = 0; ft < 2; ++ft)
; #pragma unroll
;         for (int tt = 0; tt < 2; ++tt) acc[ft][tt] = MFMA(a[ft], b[tt], acc[ft][tt]);
;     }
;     if (kt + 2 < nk) { WAIT_V(6); } else { WAIT_V(0); }
;     RAW_BARRIER();
;     cur = (cur == 2) ? 0 : cur + 1;
;   }
	ds_read_b128 v[184:187], v112 offset:32768
	ds_read_b128 v[188:191], v112 offset:36864
	ds_read_b128 v[192:195], v113
	ds_read_b128 v[196:199], v113 offset:4096
	s_waitcnt lgkmcnt(4)
	v_mfma_f32_32x32x16_bf16 v[48:63], v[120:123], v[128:131], v[48:63]
	v_mfma_f32_32x32x16_bf16 v[16:31], v[120:123], v[132:135], v[16:31]
	v_lshl_add_u64 v[120:121], v[74:75], 0, s[70:71]
	global_load_lds_dwordx4 v[120:121], off
	v_mfma_f32_32x32x16_bf16 v[32:47], v[124:127], v[128:131], v[32:47]
	v_mfma_f32_32x32x16_bf16 v[0:15], v[124:127], v[132:135], v[0:15]
	v_lshl_add_u64 v[120:121], v[74:75], 0, s[72:73]
	s_mov_b32 m0, s47
	v_readfirstlane_b32 s47, v85
	global_load_lds_dwordx4 v[120:121], off
	ds_read_b128 v[120:123], v114 offset:32768
	ds_read_b128 v[124:127], v114 offset:36864
	ds_read_b128 v[128:131], v115
	ds_read_b128 v[132:135], v115 offset:4096
	s_waitcnt lgkmcnt(4)
	v_mfma_f32_32x32x16_bf16 v[48:63], v[184:187], v[192:195], v[48:63]
	v_mfma_f32_32x32x16_bf16 v[16:31], v[184:187], v[196:199], v[16:31]
	v_lshl_add_u64 v[252:253], v[74:75], 0, s[90:91]
	s_mov_b32 m0, s47
	s_mov_b64 s[90:91], 0x60680
	v_readfirstlane_b32 s47, v86
	global_load_lds_dwordx4 v[252:253], off
	v_mfma_f32_32x32x16_bf16 v[32:47], v[188:191], v[192:195], v[32:47]
	v_mfma_f32_32x32x16_bf16 v[0:15], v[188:191], v[196:199], v[0:15]
	v_lshl_add_u64 v[252:253], v[74:75], 0, s[90:91]
	s_mov_b32 m0, s47
	v_readfirstlane_b32 s47, v87
	global_load_lds_dwordx4 v[252:253], off
	ds_read_b128 v[184:187], v116 offset:32768
	ds_read_b128 v[188:191], v116 offset:36864
	ds_read_b128 v[192:195], v117
	ds_read_b128 v[196:199], v117 offset:4096
	s_waitcnt lgkmcnt(4)
	v_mfma_f32_32x32x16_bf16 v[48:63], v[120:123], v[128:131], v[48:63]
	v_mfma_f32_32x32x16_bf16 v[16:31], v[120:123], v[132:135], v[16:31]
	v_lshl_add_u64 v[252:253], v[76:77], 0, s[70:71]
	s_mov_b32 m0, s47
	v_readfirstlane_b32 s47, v88
	global_load_lds_dwordx4 v[252:253], off
	v_mfma_f32_32x32x16_bf16 v[32:47], v[124:127], v[128:131], v[32:47]
	v_mfma_f32_32x32x16_bf16 v[0:15], v[124:127], v[132:135], v[0:15]
	v_lshl_add_u64 v[252:253], v[76:77], 0, s[72:73]
	s_mov_b32 m0, s47
	s_nop 0
	global_load_lds_dwordx4 v[252:253], off
	s_mov_b32 m0, s46
	s_mov_b64 s[46:47], 0x40700
	ds_read_b128 v[120:123], v118 offset:32768
	ds_read_b128 v[124:127], v118 offset:36864
	ds_read_b128 v[128:131], v119
	ds_read_b128 v[132:135], v119 offset:4096
	s_waitcnt lgkmcnt(4)
	v_mfma_f32_32x32x16_bf16 v[48:63], v[184:187], v[192:195], v[48:63]
	v_mfma_f32_32x32x16_bf16 v[16:31], v[184:187], v[196:199], v[16:31]
	v_mfma_f32_32x32x16_bf16 v[32:47], v[188:191], v[192:195], v[32:47]
	v_mfma_f32_32x32x16_bf16 v[0:15], v[188:191], v[196:199], v[0:15]
	s_waitcnt vmcnt(6)
	s_waitcnt lgkmcnt(0)
	s_barrier
	ds_read_b128 v[184:187], v100 offset:32768
	ds_read_b128 v[188:191], v100 offset:36864
	ds_read_b128 v[192:195], v101
	ds_read_b128 v[196:199], v101 offset:4096
	s_waitcnt lgkmcnt(4)
	v_mfma_f32_32x32x16_bf16 v[48:63], v[120:123], v[128:131], v[48:63]
	v_mfma_f32_32x32x16_bf16 v[16:31], v[120:123], v[132:135], v[16:31]
	v_lshl_add_u64 v[120:121], v[74:75], 0, s[74:75]
	global_load_lds_dwordx4 v[120:121], off
	v_mfma_f32_32x32x16_bf16 v[32:47], v[124:127], v[128:131], v[32:47]
	v_mfma_f32_32x32x16_bf16 v[0:15], v[124:127], v[132:135], v[0:15]
	v_lshl_add_u64 v[120:121], v[74:75], 0, s[76:77]
	s_mov_b32 m0, s7
	s_nop 0
	global_load_lds_dwordx4 v[120:121], off
	ds_read_b128 v[120:123], v102 offset:32768
	ds_read_b128 v[124:127], v102 offset:36864
	ds_read_b128 v[128:131], v103
	ds_read_b128 v[132:135], v103 offset:4096
	s_waitcnt lgkmcnt(4)
	v_mfma_f32_32x32x16_bf16 v[48:63], v[184:187], v[192:195], v[48:63]
	v_mfma_f32_32x32x16_bf16 v[16:31], v[184:187], v[196:199], v[16:31]
	v_lshl_add_u64 v[252:253], v[74:75], 0, s[46:47]
	s_mov_b32 m0, s8
	s_mov_b64 s[46:47], 0x60700
	global_load_lds_dwordx4 v[252:253], off
	v_mfma_f32_32x32x16_bf16 v[32:47], v[188:191], v[192:195], v[32:47]
	v_mfma_f32_32x32x16_bf16 v[0:15], v[188:191], v[196:199], v[0:15]
	v_lshl_add_u64 v[252:253], v[74:75], 0, s[46:47]
	s_mov_b32 m0, s10
	s_nop 0
	global_load_lds_dwordx4 v[252:253], off
	ds_read_b128 v[184:187], v104 offset:32768
	ds_read_b128 v[188:191], v104 offset:36864
	ds_read_b128 v[192:195], v105
	ds_read_b128 v[196:199], v105 offset:4096
	s_waitcnt lgkmcnt(4)
	v_mfma_f32_32x32x16_bf16 v[48:63], v[120:123], v[128:131], v[48:63]
	v_mfma_f32_32x32x16_bf16 v[16:31], v[120:123], v[132:135], v[16:31]
	v_lshl_add_u64 v[252:253], v[76:77], 0, s[74:75]
	s_mov_b32 m0, s9
	s_nop 0
	global_load_lds_dwordx4 v[252:253], off
	v_mfma_f32_32x32x16_bf16 v[32:47], v[124:127], v[128:131], v[32:47]
	v_mfma_f32_32x32x16_bf16 v[0:15], v[124:127], v[132:135], v[0:15]
	v_lshl_add_u64 v[252:253], v[76:77], 0, s[76:77]
	s_mov_b32 m0, s11
	s_nop 0
	global_load_lds_dwordx4 v[252:253], off
	s_mov_b32 m0, s12
	s_mov_b64 s[8:9], 0x40780
	s_waitcnt lgkmcnt(0)
	v_mfma_f32_32x32x16_bf16 v[48:63], v[184:187], v[192:195], v[48:63]
	v_mfma_f32_32x32x16_bf16 v[16:31], v[184:187], v[196:199], v[16:31]
	v_mfma_f32_32x32x16_bf16 v[32:47], v[188:191], v[192:195], v[32:47]
	v_mfma_f32_32x32x16_bf16 v[0:15], v[188:191], v[196:199], v[0:15]
	ds_read_b128 v[120:123], v106 offset:32768
	ds_read_b128 v[124:127], v106 offset:36864
	ds_read_b128 v[128:131], v107
	ds_read_b128 v[132:135], v107 offset:4096
	s_waitcnt vmcnt(6)
	s_waitcnt lgkmcnt(0)
	s_barrier
; #define MFMA(a, b, c) __builtin_amdgcn_mfma_f32_32x32x16_bf16((a), (b), (c), 0, 0, 0)
; #define WAIT_V(n) asm volatile("s_waitcnt vmcnt(%0)" ::"n"(n) : "memory")
; #define RAW_BARRIER() do { asm volatile("s_waitcnt lgkmcnt(0)" ::: "memory"); __builtin_amdgcn_s_barrier(); asm volatile("" ::: "memory"); } while (0)
; #define GLDS_STAGE(slot, kt) do { _Pragma("unroll") for (int i = 0; i < 6; ++i) \
;     __builtin_amdgcn_global_load_lds((const unsigned*)(src[i] + (kt) * 64), (__attribute__((address_space(3))) unsigned*)(smem + (slot) * G_STAGE + (wave + 8 * i) * 1024), 16, 0, 0); } while (0)
; DI void gemm_tile(const u16* __restrict__ X, int ldx, const u16* __restrict__ Wt, int ldw, int K, char* smem,
;                   f32x16 (&acc)[2][2]) {
;     ...
;   int offA[2], offB[2], xa[2], xb[2];
; #pragma unroll
;   for (int ft = 0; ft < 2; ++ft) { const int R = 256 + fw * 64 + ft * 32 + lr; offA[ft] = R * 128; xa[ft] = (R >> 1) & 7; }
; #pragma unroll
;   for (int tt = 0; tt < 2; ++tt) { const int R = tq * 64 + tt * 32 + lr; offB[tt] = R * 128; xb[tt] = (R >> 1) & 7; }
;   GLDS_STAGE(0, 0); GLDS_STAGE(1, 1); WAIT_V(6); RAW_BARRIER();
;   int cur = 0;
;   for (int kt = 0; kt < nk; ++kt) {
;     const int nxt = (cur >= 1) ? cur - 1 : 2;
;     if (kt + 2 < nk) GLDS_STAGE(nxt, kt + 2);
;     __builtin_amdgcn_sched_barrier(0);
;     const char* st = smem + cur * G_STAGE;
; #pragma unroll
;     for (int ks = 0; ks < 4; ++ks) {
;       bf16x8 a[2], b[2];
; #pragma unroll
;       for (int ft = 0; ft < 2; ++ft) a[ft] = *reinterpret_cast<const bf16x8*>(st + offA[ft] + (((ks * 2 + lh) ^ xa[ft]) << 4));
; #pragma unroll
;       for (int tt = 0; tt < 2; ++tt) b[tt] = *reinterpret_cast<const bf16x8*>(st + offB[tt] + (((ks * 2 + lh) ^ xb[tt]) << 4));
; #pragma unroll
;       for (int ft = 0; ft < 2; ++ft)
; #pragma unroll
;         for (int tt = 0; tt < 2; ++tt) acc[ft][tt] = MFMA(a[ft], b[tt], acc[ft][tt]);
;     }
;     if (kt + 2 < nk) { WAIT_V(6); } else { WAIT_V(0); }
;     RAW_BARRIER();
;     cur = (cur == 2) ? 0 : cur + 1;
;   }
	s_waitcnt lgkmcnt(0)
	v_mfma_f32_32x32x16_bf16 v[48:63], v[120:123], v[128:131], v[48:63]
	v_mfma_f32_32x32x16_bf16 v[16:31], v[120:123], v[132:135], v[16:31]
	v_lshl_add_u64 v[120:121], v[74:75], 0, s[80:81]
	global_load_lds_dwordx4 v[120:121], off
	v_lshl_add_u64 v[120:121], v[74:75], 0, s[84:85]
	s_mov_b32 m0, s0
	s_nop 0
	global_load_lds_dwordx4 v[120:121], off
	v_lshl_add_u64 v[120:121], v[74:75], 0, s[8:9]
	s_mov_b32 m0, s1
	s_mov_b64 s[0:1], 0x60780
	global_load_lds_dwordx4 v[120:121], off
	v_lshl_add_u64 v[74:75], v[74:75], 0, s[0:1]
	s_mov_b32 m0, s5
	v_mfma_f32_32x32x16_bf16 v[32:47], v[124:127], v[128:131], v[32:47]
	global_load_lds_dwordx4 v[74:75], off
	v_lshl_add_u64 v[74:75], v[76:77], 0, s[80:81]
	s_mov_b32 m0, s4
	s_nop 0
	global_load_lds_dwordx4 v[74:75], off
	v_lshl_add_u64 v[74:75], v[76:77], 0, s[84:85]
	s_mov_b32 m0, s6
	v_mfma_f32_32x32x16_bf16 v[0:15], v[124:127], v[132:135], v[0:15]
	global_load_lds_dwordx4 v[74:75], off
	ds_read_b128 v[74:77], v108 offset:32768
	ds_read_b128 v[120:123], v101 offset:49152
	ds_read_b128 v[124:127], v101 offset:53248
	s_waitcnt lgkmcnt(0)
	v_mfma_f32_32x32x16_bf16 v[48:63], v[74:77], v[120:123], v[48:63]
	v_mfma_f32_32x32x16_bf16 v[16:31], v[74:77], v[124:127], v[16:31]
	ds_read_b128 v[74:77], v108 offset:36864
	s_waitcnt lgkmcnt(0)
	v_mfma_f32_32x32x16_bf16 v[32:47], v[74:77], v[120:123], v[32:47]
	v_mfma_f32_32x32x16_bf16 v[0:15], v[74:77], v[124:127], v[0:15]
	ds_read_b128 v[74:77], v109 offset:32768
	ds_read_b128 v[120:123], v103 offset:49152
	ds_read_b128 v[124:127], v103 offset:53248
	s_waitcnt lgkmcnt(0)
	v_mfma_f32_32x32x16_bf16 v[48:63], v[74:77], v[120:123], v[48:63]
	v_mfma_f32_32x32x16_bf16 v[16:31], v[74:77], v[124:127], v[16:31]
	ds_read_b128 v[74:77], v109 offset:36864
	s_waitcnt lgkmcnt(0)
	v_mfma_f32_32x32x16_bf16 v[32:47], v[74:77], v[120:123], v[32:47]
	v_mfma_f32_32x32x16_bf16 v[0:15], v[74:77], v[124:127], v[0:15]
	ds_read_b128 v[74:77], v110 offset:32768
	ds_read_b128 v[120:123], v105 offset:49152
	ds_read_b128 v[124:127], v105 offset:53248
	s_waitcnt lgkmcnt(0)
	v_mfma_f32_32x32x16_bf16 v[48:63], v[74:77], v[120:123], v[48:63]
	v_mfma_f32_32x32x16_bf16 v[16:31], v[74:77], v[124:127], v[16:31]
	ds_read_b128 v[74:77], v110 offset:36864
	s_waitcnt lgkmcnt(0)
	v_mfma_f32_32x32x16_bf16 v[32:47], v[74:77], v[120:123], v[32:47]
	v_mfma_f32_32x32x16_bf16 v[0:15], v[74:77], v[124:127], v[0:15]
	ds_read_b128 v[74:77], v111 offset:32768
	ds_read_b128 v[120:123], v107 offset:49152
	ds_read_b128 v[124:127], v107 offset:53248
	s_waitcnt lgkmcnt(0)
	v_mfma_f32_32x32x16_bf16 v[48:63], v[74:77], v[120:123], v[48:63]
	v_mfma_f32_32x32x16_bf16 v[16:31], v[74:77], v[124:127], v[16:31]
	ds_read_b128 v[74:77], v111 offset:36864
	s_waitcnt vmcnt(6)
	s_waitcnt lgkmcnt(0)
	s_barrier
	s_waitcnt lgkmcnt(0)
	v_mfma_f32_32x32x16_bf16 v[32:47], v[74:77], v[120:123], v[32:47]
	v_mfma_f32_32x32x16_bf16 v[0:15], v[74:77], v[124:127], v[0:15]
	ds_read_b128 v[74:77], v112 offset:32768
	ds_read_b128 v[120:123], v113
	ds_read_b128 v[124:127], v113 offset:4096
	s_waitcnt lgkmcnt(0)
	v_mfma_f32_32x32x16_bf16 v[48:63], v[74:77], v[120:123], v[48:63]
	v_mfma_f32_32x32x16_bf16 v[16:31], v[74:77], v[124:127], v[16:31]
	ds_read_b128 v[74:77], v112 offset:36864
	s_waitcnt lgkmcnt(0)
	v_mfma_f32_32x32x16_bf16 v[32:47], v[74:77], v[120:123], v[32:47]
	v_mfma_f32_32x32x16_bf16 v[0:15], v[74:77], v[124:127], v[0:15]
	ds_read_b128 v[74:77], v114 offset:32768
	ds_read_b128 v[120:123], v115
	ds_read_b128 v[124:127], v115 offset:4096
	s_waitcnt lgkmcnt(0)
	v_mfma_f32_32x32x16_bf16 v[48:63], v[74:77], v[120:123], v[48:63]
	v_mfma_f32_32x32x16_bf16 v[16:31], v[74:77], v[124:127], v[16:31]
	ds_read_b128 v[74:77], v114 offset:36864
	s_waitcnt lgkmcnt(0)
	v_mfma_f32_32x32x16_bf16 v[32:47], v[74:77], v[120:123], v[32:47]
	v_mfma_f32_32x32x16_bf16 v[0:15], v[74:77], v[124:127], v[0:15]
	ds_read_b128 v[74:77], v116 offset:32768
	ds_read_b128 v[120:123], v117
	ds_read_b128 v[124:127], v117 offset:4096
	s_waitcnt lgkmcnt(0)
	v_mfma_f32_32x32x16_bf16 v[48:63], v[74:77], v[120:123], v[48:63]
	v_mfma_f32_32x32x16_bf16 v[16:31], v[74:77], v[124:127], v[16:31]
	ds_read_b128 v[74:77], v116 offset:36864
	s_waitcnt lgkmcnt(0)
	v_mfma_f32_32x32x16_bf16 v[32:47], v[74:77], v[120:123], v[32:47]
	v_mfma_f32_32x32x16_bf16 v[0:15], v[74:77], v[124:127], v[0:15]
	ds_read_b128 v[74:77], v118 offset:32768
	ds_read_b128 v[120:123], v119
	ds_read_b128 v[124:127], v119 offset:4096
	s_waitcnt lgkmcnt(0)
	v_mfma_f32_32x32x16_bf16 v[48:63], v[74:77], v[120:123], v[48:63]
	v_mfma_f32_32x32x16_bf16 v[16:31], v[74:77], v[124:127], v[16:31]
	ds_read_b128 v[74:77], v118 offset:36864
	s_waitcnt vmcnt(0)
	s_waitcnt lgkmcnt(0)
	s_barrier
; #define MFMA(a, b, c) __builtin_amdgcn_mfma_f32_32x32x16_bf16((a), (b), (c), 0, 0, 0)
; #define WAIT_V(n) asm volatile("s_waitcnt vmcnt(%0)" ::"n"(n) : "memory")
; DI void gemm_tile(const u16* __restrict__ X, int ldx, const u16* __restrict__ Wt, int ldw, int K, char* smem,
;                   f32x16 (&acc)[2][2]) {
;     ...
;   for (int kt = 0; kt < nk; ++kt) {
;     const int nxt = (cur >= 1) ? cur - 1 : 2;
;     if (kt + 2 < nk) GLDS_STAGE(nxt, kt + 2);
;     __builtin_amdgcn_sched_barrier(0);
;     const char* st = smem + cur * G_STAGE;
; #pragma unroll
;     for (int ks = 0; ks < 4; ++ks) {
;       bf16x8 a[2], b[2];
; #pragma unroll
;       for (int ft = 0; ft < 2; ++ft) a[ft] = *reinterpret_cast<const bf16x8*>(st + offA[ft] + (((ks * 2 + lh) ^ xa[ft]) << 4));
; #pragma unroll
;       for (int tt = 0; tt < 2; ++tt) b[tt] = *reinterpret_cast<const bf16x8*>(st + offB[tt] + (((ks * 2 + lh) ^ xb[tt]) << 4));
; #pragma unroll
;       for (int ft = 0; ft < 2; ++ft)
; #pragma unroll
;         for (int tt = 0; tt < 2; ++tt) acc[ft][tt] = MFMA(a[ft], b[tt], acc[ft][tt]);
;     }
;     if (kt + 2 < nk) { WAIT_V(6); } else { WAIT_V(0); }
;     RAW_BARRIER();
;     cur = (cur == 2) ? 0 : cur + 1;
;   }
; template <int MODE>
; DI void phase_gemm(const Params& p, const u16* X, const u16* Wt, int N, const float* resid, float* outf, u16* outb, int ldo, char* smem) {
;     ...
; #pragma unroll
;       for (int tt = 0; tt < 2; ++tt) {
;         const int tok = mt * 256 + tq * 64 + tt * 32 + lr;
; #pragma unroll
;         for (int ft = 0; ft < 2; ++ft)
; #pragma unroll
;           for (int g = 0; g < 4; ++g) {
;             const int f = nt * 128 + fw * 64 + ft * 32 + 8 * g + 4 * lh;
;             if (MODE == 2) {
;               const int hh = f >> 8, fh = f & 255, ks = fh >> 4, lane2 = ((fh >> 3) & 1) * 32 + lr;
;               st4bf(outb + ((((size_t)(tok >> 5) * 4 + hh) * 16 + ks) * 64 + lane2) * 8 + 4 * lh, acc[ft][tt][4 * g], acc[ft][tt][4 * g + 1], acc[ft][tt][4 * g + 2], acc[ft][tt][4 * g + 3]);
;             } else {
;               const int hh = f >> 8, fq = f & 127, half = (f >> 7) & 1, ks = fq >> 4, lane2 = ((fq >> 3) & 1) * 32 + lr;
;               st4bf(outb + (((((size_t)(tok >> 5) * 8 + hh) * 2 + half) * 8 + ks) * 64 + lane2) * 8 + 4 * lh, acc[ft][tt][4 * g], acc[ft][tt][4 * g + 1], acc[ft][tt][4 * g + 2], acc[ft][tt][4 * g + 3]);
;             }
;           }
	s_waitcnt lgkmcnt(0)
	v_mfma_f32_32x32x16_bf16 v[32:47], v[74:77], v[120:123], v[32:47]
	v_mfma_f32_32x32x16_bf16 v[0:15], v[74:77], v[124:127], v[0:15]
	ds_read_b128 v[74:77], v100 offset:32768
	ds_read_b128 v[120:123], v100 offset:36864
	ds_read_b128 v[124:127], v101
	ds_read_b128 v[128:131], v101 offset:4096
	s_and_b32 s0, s55, 0x80
	v_or_b32_e32 v64, s0, v209
	s_add_i32 s54, s54, s94
	s_waitcnt lgkmcnt(0)
	v_mfma_f32_32x32x16_bf16 v[48:63], v[74:77], v[124:127], v[48:63]
	s_add_i32 s55, s55, s86
	s_add_i32 s87, s87, s88
	v_mfma_f32_32x32x16_bf16 v[16:31], v[74:77], v[128:131], v[16:31]
	v_mfma_f32_32x32x16_bf16 v[32:47], v[120:123], v[124:127], v[32:47]
	v_mfma_f32_32x32x16_bf16 v[0:15], v[120:123], v[128:131], v[0:15]
	ds_read_b128 v[74:77], v102 offset:32768
	ds_read_b128 v[120:123], v102 offset:36864
	ds_read_b128 v[124:127], v103
	ds_read_b128 v[128:131], v103 offset:4096
	s_waitcnt lgkmcnt(0)
	v_mfma_f32_32x32x16_bf16 v[48:63], v[74:77], v[124:127], v[48:63]
	v_mfma_f32_32x32x16_bf16 v[16:31], v[74:77], v[128:131], v[16:31]
	v_mfma_f32_32x32x16_bf16 v[32:47], v[120:123], v[124:127], v[32:47]
	v_mfma_f32_32x32x16_bf16 v[0:15], v[120:123], v[128:131], v[0:15]
	ds_read_b128 v[74:77], v104 offset:32768
	ds_read_b128 v[120:123], v104 offset:36864
	ds_read_b128 v[124:127], v105
	ds_read_b128 v[128:131], v105 offset:4096
	s_waitcnt lgkmcnt(0)
	v_mfma_f32_32x32x16_bf16 v[48:63], v[74:77], v[124:127], v[48:63]
	v_mfma_f32_32x32x16_bf16 v[16:31], v[74:77], v[128:131], v[16:31]
	v_mfma_f32_32x32x16_bf16 v[32:47], v[120:123], v[124:127], v[32:47]
	v_mfma_f32_32x32x16_bf16 v[0:15], v[120:123], v[128:131], v[0:15]
	ds_read_b128 v[74:77], v106 offset:32768
	ds_read_b128 v[120:123], v106 offset:36864
	ds_read_b128 v[124:127], v107
	ds_read_b128 v[128:131], v107 offset:4096
	s_waitcnt vmcnt(0)
	s_waitcnt lgkmcnt(0)
	s_barrier
	s_waitcnt lgkmcnt(0)
	v_mfma_f32_32x32x16_bf16 v[48:63], v[74:77], v[124:127], v[48:63]
	v_mfma_f32_32x32x16_bf16 v[16:31], v[74:77], v[128:131], v[16:31]
	v_lshrrev_b32_e32 v76, 4, v64
	v_lshl_add_u32 v64, s89, 9, v89
	s_nop 8
	v_cvt_pk_bf16_f32 v48, v48, v49
	v_cvt_pk_bf16_f32 v49, v50, v51
	v_cvt_pk_bf16_f32 v50, v56, v57
	v_cvt_pk_bf16_f32 v51, v58, v59
	v_or_b32_e32 v77, 2, v76
	v_mfma_f32_32x32x16_bf16 v[32:47], v[120:123], v[124:127], v[32:47]
	v_cvt_pk_bf16_f32 v16, v16, v17
	v_cvt_pk_bf16_f32 v17, v18, v19
	v_cvt_pk_bf16_f32 v18, v24, v25
	v_cvt_pk_bf16_f32 v19, v26, v27
	v_mfma_f32_32x32x16_bf16 v[0:15], v[120:123], v[128:131], v[0:15]
	v_and_or_b32 v120, s79, 48, v64
	v_or_b32_e32 v64, v120, v76
	v_lshlrev_b32_e32 v64, 10, v64
	v_lshl_add_u64 v[74:75], v[70:71], 0, v[64:65]
	global_store_dwordx2 v[74:75], v[48:49], off
	v_cvt_pk_bf16_f32 v48, v52, v53
	v_cvt_pk_bf16_f32 v49, v54, v55
	v_or_b32_e32 v52, 1, v76
	global_store_dwordx2 v[74:75], v[48:49], off offset:512
	v_or_b32_e32 v48, v52, v120
	v_lshlrev_b32_e32 v64, 10, v48
	v_lshl_add_u64 v[48:49], v[70:71], 0, v[64:65]
	global_store_dwordx2 v[48:49], v[50:51], off
	v_cvt_pk_bf16_f32 v50, v60, v61
	v_cvt_pk_bf16_f32 v51, v62, v63
	global_store_dwordx2 v[48:49], v[50:51], off offset:512
	v_or_b32_e32 v48, v77, v120
	v_lshlrev_b32_e32 v64, 10, v48
	v_lshl_add_u64 v[48:49], v[70:71], 0, v[64:65]
	v_cvt_pk_bf16_f32 v32, v32, v33
	v_cvt_pk_bf16_f32 v33, v34, v35
	global_store_dwordx2 v[48:49], v[32:33], off
	v_cvt_pk_bf16_f32 v32, v36, v37
	v_cvt_pk_bf16_f32 v33, v38, v39
	v_or_b32_e32 v36, 3, v76
	global_store_dwordx2 v[48:49], v[32:33], off offset:512
	v_or_b32_e32 v32, v36, v120
	v_lshlrev_b32_e32 v64, 10, v32
	v_lshl_add_u64 v[32:33], v[70:71], 0, v[64:65]
	v_cvt_pk_bf16_f32 v34, v40, v41
	v_cvt_pk_bf16_f32 v35, v42, v43
	global_store_dwordx2 v[32:33], v[34:35], off
	v_cvt_pk_bf16_f32 v34, v44, v45
	v_cvt_pk_bf16_f32 v35, v46, v47
	global_store_dwordx2 v[32:33], v[34:35], off offset:512
	v_or_b32_e32 v34, 64, v120
	v_or_b32_e32 v64, v34, v76
	v_lshlrev_b64 v[32:33], 10, v[64:65]
	v_lshl_add_u64 v[32:33], v[70:71], 0, v[32:33]
	global_store_dwordx2 v[32:33], v[16:17], off
	v_cvt_pk_bf16_f32 v16, v20, v21
	v_cvt_pk_bf16_f32 v17, v22, v23
	v_or_b32_e32 v64, v34, v52
	global_store_dwordx2 v[32:33], v[16:17], off offset:512
	v_lshlrev_b64 v[16:17], 10, v[64:65]
	v_lshl_add_u64 v[16:17], v[70:71], 0, v[16:17]
	global_store_dwordx2 v[16:17], v[18:19], off
	v_cvt_pk_bf16_f32 v18, v28, v29
	v_cvt_pk_bf16_f32 v19, v30, v31
	v_or_b32_e32 v64, v34, v77
	global_store_dwordx2 v[16:17], v[18:19], off offset:512
	v_lshlrev_b64 v[16:17], 10, v[64:65]
	v_lshl_add_u64 v[16:17], v[70:71], 0, v[16:17]
	v_cvt_pk_bf16_f32 v0, v0, v1
	v_cvt_pk_bf16_f32 v1, v2, v3
	global_store_dwordx2 v[16:17], v[0:1], off
	v_cvt_pk_bf16_f32 v0, v4, v5
	v_cvt_pk_bf16_f32 v1, v6, v7
	v_or_b32_e32 v64, v34, v36
	global_store_dwordx2 v[16:17], v[0:1], off offset:512
	v_lshlrev_b64 v[0:1], 10, v[64:65]
	v_lshl_add_u64 v[0:1], v[70:71], 0, v[0:1]
	v_cvt_pk_bf16_f32 v2, v8, v9
	v_cvt_pk_bf16_f32 v3, v10, v11
	s_add_i32 s79, s79, s3
	global_store_dwordx2 v[0:1], v[2:3], off
	v_cvt_pk_bf16_f32 v2, v12, v13
	v_cvt_pk_bf16_f32 v3, v14, v15
	s_cmpk_lt_u32 s54, 0x80
	global_store_dwordx2 v[0:1], v[2:3], off offset:512
	s_cbranch_scc1 .LBB0_678
	v_readlane_b32 s52, v255, 23
	v_readlane_b32 s60, v255, 31
	v_readlane_b32 s61, v255, 32
	v_readlane_b32 s60, v255, 43
	v_readlane_b32 s8, v255, 49
	v_readlane_b32 s64, v255, 35
	v_readlane_b32 s65, v255, 36
	v_readlane_b32 s66, v255, 37
	v_readlane_b32 s67, v255, 38
	v_readlane_b32 s61, v255, 44
	v_readlane_b32 s9, v255, 50
	v_readlane_b32 s53, v255, 24
	v_readlane_b32 s54, v255, 25
	v_readlane_b32 s55, v255, 26
	v_readlane_b32 s56, v255, 27
	v_readlane_b32 s57, v255, 28
	v_readlane_b32 s58, v255, 29
	v_readlane_b32 s59, v255, 30
	v_readlane_b32 s62, v255, 33
	v_readlane_b32 s63, v255, 34

; #define MFMA(a, b, c) __builtin_amdgcn_mfma_f32_32x32x16_bf16((a), (b), (c), 0, 0, 0)
; #define WAIT_V(n) asm volatile("s_waitcnt vmcnt(%0)" ::"n"(n) : "memory")
; DI void gemm_tile(const u16* __restrict__ X, int ldx, const u16* __restrict__ Wt, int ldw, int K, char* smem,
;                   f32x16 (&acc)[2][2]) {
;     ...
;   const int nk = K / 64;
;   const u16* src[6];
; #pragma unroll
;   for (int i = 0; i < 6; ++i) {
;     const int R = 8 * (wave + 8 * i) + (lane >> 3);
;     const int c = (lane & 7) ^ ((R >> 1) & 7);
;     src[i] = (i < 4) ? (X + (size_t)R * ldx + c * 8) : (Wt + (size_t)(R - 256) * ldw + c * 8);
;   }
;     ...
;   int offA[2], offB[2], xa[2], xb[2];
; #pragma unroll
;   for (int ft = 0; ft < 2; ++ft) { const int R = 256 + fw * 64 + ft * 32 + lr; offA[ft] = R * 128; xa[ft] = (R >> 1) & 7; }
; #pragma unroll
;   for (int tt = 0; tt < 2; ++tt) { const int R = tq * 64 + tt * 32 + lr; offB[tt] = R * 128; xb[tt] = (R >> 1) & 7; }
;   GLDS_STAGE(0, 0); GLDS_STAGE(1, 1); WAIT_V(6); RAW_BARRIER();
;   int cur = 0;
;   for (int kt = 0; kt < nk; ++kt) {
;     const int nxt = (cur >= 1) ? cur - 1 : 2;
;     if (kt + 2 < nk) GLDS_STAGE(nxt, kt + 2);
;     __builtin_amdgcn_sched_barrier(0);
;     const char* st = smem + cur * G_STAGE;
; #pragma unroll
;     for (int ks = 0; ks < 4; ++ks) {
;       bf16x8 a[2], b[2];
; #pragma unroll
;       for (int ft = 0; ft < 2; ++ft) a[ft] = *reinterpret_cast<const bf16x8*>(st + offA[ft] + (((ks * 2 + lh) ^ xa[ft]) << 4));
; #pragma unroll
;       for (int tt = 0; tt < 2; ++tt) b[tt] = *reinterpret_cast<const bf16x8*>(st + offB[tt] + (((ks * 2 + lh) ^ xb[tt]) << 4));
; #pragma unroll
;       for (int ft = 0; ft < 2; ++ft)
; #pragma unroll
;         for (int tt = 0; tt < 2; ++tt) acc[ft][tt] = MFMA(a[ft], b[tt], acc[ft][tt]);
;     }
;     if (kt + 2 < nk) { WAIT_V(6); } else { WAIT_V(0); }
;     RAW_BARRIER();
;     cur = (cur == 2) ? 0 : cur + 1;
;   }
; template <int MODE>
; DI void phase_gemm(const Params& p, const u16* X, const u16* Wt, int N, const float* resid, float* outf, u16* outb, int ldo, char* smem) {
;     ...
;   for (int u = xi; u < per_group; u += xn) {
;     const int mt = xg + 8 * (u / ntn), nt = u % ntn;
;     f32x16 acc[2][2];
;     gemm_tile(X + (size_t)mt * 256 * 1024, 1024, Wt + (size_t)nt * 128 * 1024, 1024, 1024, smem, acc);
.LBB0_793:
	s_and_b32 s0, s85, 0x78
	s_or_b32 s0, s0, s33
	s_lshl_b32 s10, s0, 19
	v_lshl_add_u64 v[0:1], v[66:67], 0, s[10:11]
	v_readfirstlane_b32 s6, v143
	v_lshl_add_u64 v[80:81], v[0:1], 0, v[70:71]
	s_mov_b32 m0, s6
	v_readfirstlane_b32 s89, v101
	s_and_b32 s4, s85, 7
	v_lshl_add_u64 v[0:1], v[80:81], 0, s[12:13]
	s_mov_b64 s[0:1], 0x40000
	global_load_lds_dwordx4 v[80:81], off
	s_mov_b32 m0, s89
	v_readfirstlane_b32 s88, v102
	v_lshl_add_u64 v[2:3], v[80:81], 0, s[0:1]
	s_mov_b64 s[0:1], 0x60000
	s_lshl_b32 s10, s4, 18
	global_load_lds_dwordx4 v[0:1], off
	s_mov_b32 m0, s88
	v_readfirstlane_b32 s87, v103
	v_lshl_add_u64 v[4:5], v[80:81], 0, s[0:1]
	v_lshl_add_u64 v[6:7], v[68:69], 0, s[10:11]
	global_load_lds_dwordx4 v[2:3], off
	s_mov_b32 m0, s87
	v_readfirstlane_b32 s86, v104
	v_lshl_add_u64 v[82:83], v[6:7], 0, v[70:71]
	global_load_lds_dwordx4 v[4:5], off
	s_mov_b32 m0, s86
	v_readfirstlane_b32 s55, v105
	v_lshl_add_u64 v[6:7], v[82:83], 0, s[12:13]
	global_load_lds_dwordx4 v[82:83], off
	s_mov_b32 m0, s55
	v_readfirstlane_b32 s54, v84
	global_load_lds_dwordx4 v[6:7], off
	v_lshl_add_u64 v[0:1], v[80:81], 0, s[14:15]
	s_mov_b32 m0, s54
	v_readfirstlane_b32 s10, v106
	global_load_lds_dwordx4 v[0:1], off
	v_lshl_add_u64 v[0:1], v[80:81], 0, s[16:17]
	s_mov_b32 m0, s10
	s_mov_b64 s[0:1], 0x40080
	global_load_lds_dwordx4 v[0:1], off
	v_lshl_add_u64 v[0:1], v[80:81], 0, s[0:1]
	v_readfirstlane_b32 s0, v107
	s_mov_b32 m0, s0
	s_mov_b64 s[0:1], 0x60080
	global_load_lds_dwordx4 v[0:1], off
	v_lshl_add_u64 v[0:1], v[80:81], 0, s[0:1]
	v_readfirstlane_b32 s0, v108
	s_mov_b32 m0, s0
	v_readfirstlane_b32 s0, v109
	global_load_lds_dwordx4 v[0:1], off
	v_lshl_add_u64 v[0:1], v[82:83], 0, s[14:15]
	s_mov_b32 m0, s0
	v_readfirstlane_b32 s0, v110
	global_load_lds_dwordx4 v[0:1], off
	v_lshl_add_u64 v[0:1], v[82:83], 0, s[16:17]
	s_mov_b32 m0, s0
	v_readfirstlane_b32 s0, v85
	global_load_lds_dwordx4 v[0:1], off
	s_waitcnt vmcnt(6)
	s_waitcnt lgkmcnt(0)
	s_barrier
	v_lshl_add_u64 v[0:1], v[80:81], 0, s[18:19]
	s_mov_b32 m0, s0
	v_readfirstlane_b32 s93, v86
	global_load_lds_dwordx4 v[0:1], off
	v_lshl_add_u64 v[0:1], v[80:81], 0, s[20:21]
	s_mov_b32 m0, s93
	s_mov_b64 s[4:5], 0x40100
	v_readfirstlane_b32 s91, v87
	global_load_lds_dwordx4 v[0:1], off
	v_lshl_add_u64 v[0:1], v[80:81], 0, s[4:5]
	s_mov_b32 m0, s91
	s_mov_b64 s[4:5], 0x60100
	v_readfirstlane_b32 s92, v88
	global_load_lds_dwordx4 v[0:1], off
	v_lshl_add_u64 v[0:1], v[80:81], 0, s[4:5]
	s_mov_b32 m0, s92
	v_readfirstlane_b32 s7, v89
	global_load_lds_dwordx4 v[0:1], off
	v_lshl_add_u64 v[0:1], v[82:83], 0, s[18:19]
	s_mov_b32 m0, s7
	v_readfirstlane_b32 s90, v90
	global_load_lds_dwordx4 v[0:1], off
	v_lshl_add_u64 v[0:1], v[82:83], 0, s[20:21]
	s_mov_b32 m0, s90
	s_lshl_b32 s1, s85, 8
	global_load_lds_dwordx4 v[0:1], off
	s_and_b32 s4, s79, 7
	s_and_b32 s1, s1, 0x7800
	s_lshl_b32 s4, s4, 7
	v_add_lshl_u32 v64, v97, s1, 12
	v_add_lshl_u32 v0, v98, s4, 2
	v_mov_b32_e32 v1, v65
	v_lshl_add_u64 v[2:3], v[64:65], 0, v[0:1]
	v_add_lshl_u32 v64, v99, s1, 12
	v_lshl_add_u64 v[72:73], s[82:83], 0, v[2:3]
	v_lshl_add_u64 v[2:3], v[64:65], 0, v[0:1]
	v_add_lshl_u32 v64, v100, s1, 12
	v_lshl_add_u64 v[74:75], s[82:83], 0, v[2:3]
	v_lshl_add_u64 v[2:3], v[64:65], 0, v[0:1]
	v_add_lshl_u32 v64, v96, s1, 12
	v_lshl_add_u64 v[0:1], v[64:65], 0, v[0:1]
	v_lshl_add_u64 v[76:77], s[82:83], 0, v[2:3]
	v_lshl_add_u64 v[78:79], s[82:83], 0, v[0:1]
	ds_read_b128 v[0:3], v111 offset:32768
	ds_read_b128 v[4:7], v111 offset:36864
	ds_read_b128 v[8:11], v112
	ds_read_b128 v[12:15], v112 offset:4096
	ds_read_b128 v[132:135], v113 offset:32768
	ds_read_b128 v[136:139], v113 offset:36864
	ds_read_b128 v[152:155], v114
	ds_read_b128 v[156:159], v114 offset:4096
	s_mov_b32 m0, s6
	s_mov_b64 s[4:5], 0x40180
	s_waitcnt lgkmcnt(0)
	v_mfma_f32_32x32x16_bf16 v[48:63], v[0:3], v[8:11], 0
	v_mfma_f32_32x32x16_bf16 v[16:31], v[0:3], v[12:15], 0
	v_mfma_f32_32x32x16_bf16 v[32:47], v[4:7], v[8:11], 0
	v_mfma_f32_32x32x16_bf16 v[0:15], v[4:7], v[12:15], 0
	ds_read_b128 v[184:187], v115 offset:32768
	ds_read_b128 v[188:191], v115 offset:36864
	ds_read_b128 v[192:195], v116
	ds_read_b128 v[196:199], v116 offset:4096
	s_waitcnt lgkmcnt(4)
	v_mfma_f32_32x32x16_bf16 v[48:63], v[132:135], v[152:155], v[48:63]
	v_mfma_f32_32x32x16_bf16 v[16:31], v[132:135], v[156:159], v[16:31]
	v_mfma_f32_32x32x16_bf16 v[32:47], v[136:139], v[152:155], v[32:47]
	v_mfma_f32_32x32x16_bf16 v[0:15], v[136:139], v[156:159], v[0:15]
	ds_read_b128 v[132:135], v117 offset:32768
	ds_read_b128 v[136:139], v117 offset:36864
	ds_read_b128 v[152:155], v118
	ds_read_b128 v[156:159], v118 offset:4096
	s_waitcnt lgkmcnt(4)
	v_mfma_f32_32x32x16_bf16 v[48:63], v[184:187], v[192:195], v[48:63]
	v_mfma_f32_32x32x16_bf16 v[16:31], v[184:187], v[196:199], v[16:31]
	v_mfma_f32_32x32x16_bf16 v[32:47], v[188:191], v[192:195], v[32:47]
	v_mfma_f32_32x32x16_bf16 v[0:15], v[188:191], v[196:199], v[0:15]
	s_waitcnt vmcnt(6)
	s_waitcnt lgkmcnt(0)
	s_barrier
; #define MFMA(a, b, c) __builtin_amdgcn_mfma_f32_32x32x16_bf16((a), (b), (c), 0, 0, 0)
; #define WAIT_V(n) asm volatile("s_waitcnt vmcnt(%0)" ::"n"(n) : "memory")
; #define RAW_BARRIER() do { asm volatile("s_waitcnt lgkmcnt(0)" ::: "memory"); __builtin_amdgcn_s_barrier(); asm volatile("" ::: "memory"); } while (0)
; #define GLDS_STAGE(slot, kt) do { _Pragma("unroll") for (int i = 0; i < 6; ++i) \
;     __builtin_amdgcn_global_load_lds((const unsigned*)(src[i] + (kt) * 64), (__attribute__((address_space(3))) unsigned*)(smem + (slot) * G_STAGE + (wave + 8 * i) * 1024), 16, 0, 0); } while (0)
; DI void gemm_tile(const u16* __restrict__ X, int ldx, const u16* __restrict__ Wt, int ldw, int K, char* smem,
;                   f32x16 (&acc)[2][2]) {
;     ...
;   int offA[2], offB[2], xa[2], xb[2];
; #pragma unroll
;   for (int ft = 0; ft < 2; ++ft) { const int R = 256 + fw * 64 + ft * 32 + lr; offA[ft] = R * 128; xa[ft] = (R >> 1) & 7; }
; #pragma unroll
;   for (int tt = 0; tt < 2; ++tt) { const int R = tq * 64 + tt * 32 + lr; offB[tt] = R * 128; xb[tt] = (R >> 1) & 7; }
;   GLDS_STAGE(0, 0); GLDS_STAGE(1, 1); WAIT_V(6); RAW_BARRIER();
;   int cur = 0;
;   for (int kt = 0; kt < nk; ++kt) {
;     const int nxt = (cur >= 1) ? cur - 1 : 2;
;     if (kt + 2 < nk) GLDS_STAGE(nxt, kt + 2);
;     __builtin_amdgcn_sched_barrier(0);
;     const char* st = smem + cur * G_STAGE;
; #pragma unroll
;     for (int ks = 0; ks < 4; ++ks) {
;       bf16x8 a[2], b[2];
; #pragma unroll
;       for (int ft = 0; ft < 2; ++ft) a[ft] = *reinterpret_cast<const bf16x8*>(st + offA[ft] + (((ks * 2 + lh) ^ xa[ft]) << 4));
; #pragma unroll
;       for (int tt = 0; tt < 2; ++tt) b[tt] = *reinterpret_cast<const bf16x8*>(st + offB[tt] + (((ks * 2 + lh) ^ xb[tt]) << 4));
; #pragma unroll
;       for (int ft = 0; ft < 2; ++ft)
; #pragma unroll
;         for (int tt = 0; tt < 2; ++tt) acc[ft][tt] = MFMA(a[ft], b[tt], acc[ft][tt]);
;     }
;     if (kt + 2 < nk) { WAIT_V(6); } else { WAIT_V(0); }
;     RAW_BARRIER();
;     cur = (cur == 2) ? 0 : cur + 1;
;   }
	ds_read_b128 v[184:187], v119 offset:32768
	ds_read_b128 v[188:191], v119 offset:36864
	ds_read_b128 v[192:195], v112 offset:49152
	ds_read_b128 v[196:199], v112 offset:53248
	s_waitcnt lgkmcnt(4)
	v_mfma_f32_32x32x16_bf16 v[48:63], v[132:135], v[152:155], v[48:63]
	v_mfma_f32_32x32x16_bf16 v[16:31], v[132:135], v[156:159], v[16:31]
	v_lshl_add_u64 v[132:133], v[80:81], 0, s[22:23]
	global_load_lds_dwordx4 v[132:133], off
	v_mfma_f32_32x32x16_bf16 v[0:15], v[136:139], v[156:159], v[0:15]
	v_mfma_f32_32x32x16_bf16 v[32:47], v[136:139], v[152:155], v[32:47]
	v_lshl_add_u64 v[132:133], v[80:81], 0, s[24:25]
	s_mov_b32 m0, s89
	s_nop 0
	global_load_lds_dwordx4 v[132:133], off
	ds_read_b128 v[132:135], v120 offset:32768
	ds_read_b128 v[136:139], v120 offset:36864
	ds_read_b128 v[152:155], v114 offset:49152
	ds_read_b128 v[156:159], v114 offset:53248
	s_waitcnt lgkmcnt(4)
	v_mfma_f32_32x32x16_bf16 v[48:63], v[184:187], v[192:195], v[48:63]
	v_mfma_f32_32x32x16_bf16 v[16:31], v[184:187], v[196:199], v[16:31]
	v_lshl_add_u64 v[252:253], v[80:81], 0, s[4:5]
	s_mov_b32 m0, s88
	s_mov_b64 s[4:5], 0x60180
	global_load_lds_dwordx4 v[252:253], off
	v_mfma_f32_32x32x16_bf16 v[32:47], v[188:191], v[192:195], v[32:47]
	v_mfma_f32_32x32x16_bf16 v[0:15], v[188:191], v[196:199], v[0:15]
	v_lshl_add_u64 v[252:253], v[80:81], 0, s[4:5]
	s_mov_b32 m0, s87
	s_nop 0
	global_load_lds_dwordx4 v[252:253], off
	ds_read_b128 v[184:187], v121 offset:32768
	ds_read_b128 v[188:191], v121 offset:36864
	ds_read_b128 v[192:195], v116 offset:49152
	ds_read_b128 v[196:199], v116 offset:53248
	s_waitcnt lgkmcnt(4)
	v_mfma_f32_32x32x16_bf16 v[48:63], v[132:135], v[152:155], v[48:63]
	v_mfma_f32_32x32x16_bf16 v[16:31], v[132:135], v[156:159], v[16:31]
	v_lshl_add_u64 v[252:253], v[82:83], 0, s[22:23]
	s_mov_b32 m0, s86
	s_nop 0
	global_load_lds_dwordx4 v[252:253], off
	v_mfma_f32_32x32x16_bf16 v[32:47], v[136:139], v[152:155], v[32:47]
	v_mfma_f32_32x32x16_bf16 v[0:15], v[136:139], v[156:159], v[0:15]
	v_lshl_add_u64 v[252:253], v[82:83], 0, s[24:25]
	s_mov_b32 m0, s55
	s_nop 0
	global_load_lds_dwordx4 v[252:253], off
	s_mov_b32 m0, s54
	s_mov_b64 s[4:5], 0x40200
	v_readfirstlane_b32 s95, v91
	v_readfirstlane_b32 s9, v92
	v_readfirstlane_b32 s8, v93
	v_readfirstlane_b32 s46, v94
	ds_read_b128 v[132:135], v122 offset:32768
	ds_read_b128 v[136:139], v122 offset:36864
	ds_read_b128 v[152:155], v118 offset:49152
	ds_read_b128 v[156:159], v118 offset:53248
	s_waitcnt lgkmcnt(4)
	v_mfma_f32_32x32x16_bf16 v[48:63], v[184:187], v[192:195], v[48:63]
	v_mfma_f32_32x32x16_bf16 v[16:31], v[184:187], v[196:199], v[16:31]
	v_mfma_f32_32x32x16_bf16 v[32:47], v[188:191], v[192:195], v[32:47]
	v_mfma_f32_32x32x16_bf16 v[0:15], v[188:191], v[196:199], v[0:15]
	s_waitcnt vmcnt(6)
	s_waitcnt lgkmcnt(0)
	s_barrier
	ds_read_b128 v[184:187], v123 offset:32768
	ds_read_b128 v[188:191], v123 offset:36864
	ds_read_b128 v[192:195], v124
	ds_read_b128 v[196:199], v124 offset:4096
	s_waitcnt lgkmcnt(4)
	v_mfma_f32_32x32x16_bf16 v[48:63], v[132:135], v[152:155], v[48:63]
	v_mfma_f32_32x32x16_bf16 v[16:31], v[132:135], v[156:159], v[16:31]
	v_lshl_add_u64 v[132:133], v[80:81], 0, s[26:27]
	global_load_lds_dwordx4 v[132:133], off
	v_mfma_f32_32x32x16_bf16 v[0:15], v[136:139], v[156:159], v[0:15]
	v_mfma_f32_32x32x16_bf16 v[32:47], v[136:139], v[152:155], v[32:47]
	v_lshl_add_u64 v[132:133], v[80:81], 0, s[28:29]
	s_mov_b32 m0, s10
	s_nop 0
	global_load_lds_dwordx4 v[132:133], off
	ds_read_b128 v[132:135], v125 offset:32768
	ds_read_b128 v[136:139], v125 offset:36864
	ds_read_b128 v[152:155], v126
	ds_read_b128 v[156:159], v126 offset:4096
	s_waitcnt lgkmcnt(4)
	v_mfma_f32_32x32x16_bf16 v[48:63], v[184:187], v[192:195], v[48:63]
	v_mfma_f32_32x32x16_bf16 v[16:31], v[184:187], v[196:199], v[16:31]
	v_lshl_add_u64 v[252:253], v[80:81], 0, s[4:5]
	s_mov_b32 m0, s95
	s_mov_b64 s[4:5], 0x60200
	global_load_lds_dwordx4 v[252:253], off
	v_mfma_f32_32x32x16_bf16 v[32:47], v[188:191], v[192:195], v[32:47]
	v_mfma_f32_32x32x16_bf16 v[0:15], v[188:191], v[196:199], v[0:15]
	v_lshl_add_u64 v[252:253], v[80:81], 0, s[4:5]
	s_mov_b32 m0, s9
	s_nop 0
	global_load_lds_dwordx4 v[252:253], off
	ds_read_b128 v[184:187], v127 offset:32768
	ds_read_b128 v[188:191], v127 offset:36864
	ds_read_b128 v[192:195], v128
	ds_read_b128 v[196:199], v128 offset:4096
	s_waitcnt lgkmcnt(4)
	v_mfma_f32_32x32x16_bf16 v[48:63], v[132:135], v[152:155], v[48:63]
	v_mfma_f32_32x32x16_bf16 v[16:31], v[132:135], v[156:159], v[16:31]
	v_lshl_add_u64 v[252:253], v[82:83], 0, s[26:27]
	s_mov_b32 m0, s8
	s_nop 0
	global_load_lds_dwordx4 v[252:253], off
	v_mfma_f32_32x32x16_bf16 v[32:47], v[136:139], v[152:155], v[32:47]
	v_mfma_f32_32x32x16_bf16 v[0:15], v[136:139], v[156:159], v[0:15]
	v_lshl_add_u64 v[252:253], v[82:83], 0, s[28:29]
	s_mov_b32 m0, s46
	s_nop 0
	global_load_lds_dwordx4 v[252:253], off
	s_mov_b32 m0, s0
	s_mov_b64 s[4:5], 0x40280
	ds_read_b128 v[132:135], v129 offset:32768
	ds_read_b128 v[136:139], v129 offset:36864
	ds_read_b128 v[152:155], v130
	ds_read_b128 v[156:159], v130 offset:4096
	s_waitcnt lgkmcnt(4)
	v_mfma_f32_32x32x16_bf16 v[48:63], v[184:187], v[192:195], v[48:63]
	v_mfma_f32_32x32x16_bf16 v[16:31], v[184:187], v[196:199], v[16:31]
	v_mfma_f32_32x32x16_bf16 v[32:47], v[188:191], v[192:195], v[32:47]
	v_mfma_f32_32x32x16_bf16 v[0:15], v[188:191], v[196:199], v[0:15]
	s_waitcnt vmcnt(6)
	s_waitcnt lgkmcnt(0)
	s_barrier
; #define MFMA(a, b, c) __builtin_amdgcn_mfma_f32_32x32x16_bf16((a), (b), (c), 0, 0, 0)
; #define WAIT_V(n) asm volatile("s_waitcnt vmcnt(%0)" ::"n"(n) : "memory")
; #define RAW_BARRIER() do { asm volatile("s_waitcnt lgkmcnt(0)" ::: "memory"); __builtin_amdgcn_s_barrier(); asm volatile("" ::: "memory"); } while (0)
; #define GLDS_STAGE(slot, kt) do { _Pragma("unroll") for (int i = 0; i < 6; ++i) \
;     __builtin_amdgcn_global_load_lds((const unsigned*)(src[i] + (kt) * 64), (__attribute__((address_space(3))) unsigned*)(smem + (slot) * G_STAGE + (wave + 8 * i) * 1024), 16, 0, 0); } while (0)
; DI void gemm_tile(const u16* __restrict__ X, int ldx, const u16* __restrict__ Wt, int ldw, int K, char* smem,
;                   f32x16 (&acc)[2][2]) {
;     ...
;   int offA[2], offB[2], xa[2], xb[2];
; #pragma unroll
;   for (int ft = 0; ft < 2; ++ft) { const int R = 256 + fw * 64 + ft * 32 + lr; offA[ft] = R * 128; xa[ft] = (R >> 1) & 7; }
; #pragma unroll
;   for (int tt = 0; tt < 2; ++tt) { const int R = tq * 64 + tt * 32 + lr; offB[tt] = R * 128; xb[tt] = (R >> 1) & 7; }
;   GLDS_STAGE(0, 0); GLDS_STAGE(1, 1); WAIT_V(6); RAW_BARRIER();
;   int cur = 0;
;   for (int kt = 0; kt < nk; ++kt) {
;     const int nxt = (cur >= 1) ? cur - 1 : 2;
;     if (kt + 2 < nk) GLDS_STAGE(nxt, kt + 2);
;     __builtin_amdgcn_sched_barrier(0);
;     const char* st = smem + cur * G_STAGE;
; #pragma unroll
;     for (int ks = 0; ks < 4; ++ks) {
;       bf16x8 a[2], b[2];
; #pragma unroll
;       for (int ft = 0; ft < 2; ++ft) a[ft] = *reinterpret_cast<const bf16x8*>(st + offA[ft] + (((ks * 2 + lh) ^ xa[ft]) << 4));
; #pragma unroll
;       for (int tt = 0; tt < 2; ++tt) b[tt] = *reinterpret_cast<const bf16x8*>(st + offB[tt] + (((ks * 2 + lh) ^ xb[tt]) << 4));
; #pragma unroll
;       for (int ft = 0; ft < 2; ++ft)
; #pragma unroll
;         for (int tt = 0; tt < 2; ++tt) acc[ft][tt] = MFMA(a[ft], b[tt], acc[ft][tt]);
;     }
;     if (kt + 2 < nk) { WAIT_V(6); } else { WAIT_V(0); }
;     RAW_BARRIER();
;     cur = (cur == 2) ? 0 : cur + 1;
;   }
	ds_read_b128 v[184:187], v111 offset:32768
	ds_read_b128 v[188:191], v111 offset:36864
	ds_read_b128 v[192:195], v112
	ds_read_b128 v[196:199], v112 offset:4096
	s_waitcnt lgkmcnt(4)
	v_mfma_f32_32x32x16_bf16 v[48:63], v[132:135], v[152:155], v[48:63]
	v_mfma_f32_32x32x16_bf16 v[16:31], v[132:135], v[156:159], v[16:31]
	v_lshl_add_u64 v[132:133], v[80:81], 0, s[30:31]
	global_load_lds_dwordx4 v[132:133], off
	v_mfma_f32_32x32x16_bf16 v[0:15], v[136:139], v[156:159], v[0:15]
	v_mfma_f32_32x32x16_bf16 v[32:47], v[136:139], v[152:155], v[32:47]
	v_lshl_add_u64 v[132:133], v[80:81], 0, s[34:35]
	s_mov_b32 m0, s93
	s_nop 0
	global_load_lds_dwordx4 v[132:133], off
	ds_read_b128 v[132:135], v113 offset:32768
	ds_read_b128 v[136:139], v113 offset:36864
	ds_read_b128 v[152:155], v114
	ds_read_b128 v[156:159], v114 offset:4096
	s_waitcnt lgkmcnt(4)
	v_mfma_f32_32x32x16_bf16 v[48:63], v[184:187], v[192:195], v[48:63]
	v_mfma_f32_32x32x16_bf16 v[16:31], v[184:187], v[196:199], v[16:31]
	v_lshl_add_u64 v[252:253], v[80:81], 0, s[4:5]
	s_mov_b32 m0, s91
	s_mov_b64 s[4:5], 0x60280
	global_load_lds_dwordx4 v[252:253], off
	v_mfma_f32_32x32x16_bf16 v[32:47], v[188:191], v[192:195], v[32:47]
	v_mfma_f32_32x32x16_bf16 v[0:15], v[188:191], v[196:199], v[0:15]
	v_lshl_add_u64 v[252:253], v[80:81], 0, s[4:5]
	s_mov_b32 m0, s92
	s_nop 0
	global_load_lds_dwordx4 v[252:253], off
	ds_read_b128 v[184:187], v115 offset:32768
	ds_read_b128 v[188:191], v115 offset:36864
	ds_read_b128 v[192:195], v116
	ds_read_b128 v[196:199], v116 offset:4096
	s_waitcnt lgkmcnt(4)
	v_mfma_f32_32x32x16_bf16 v[48:63], v[132:135], v[152:155], v[48:63]
	v_mfma_f32_32x32x16_bf16 v[16:31], v[132:135], v[156:159], v[16:31]
	v_lshl_add_u64 v[252:253], v[82:83], 0, s[30:31]
	s_mov_b32 m0, s7
	s_nop 0
	global_load_lds_dwordx4 v[252:253], off
	v_mfma_f32_32x32x16_bf16 v[32:47], v[136:139], v[152:155], v[32:47]
	v_mfma_f32_32x32x16_bf16 v[0:15], v[136:139], v[156:159], v[0:15]
	v_lshl_add_u64 v[252:253], v[82:83], 0, s[34:35]
	s_mov_b32 m0, s90
	s_nop 0
	global_load_lds_dwordx4 v[252:253], off
	s_mov_b32 m0, s6
	s_mov_b64 s[4:5], 0x40300
	ds_read_b128 v[132:135], v117 offset:32768
	ds_read_b128 v[136:139], v117 offset:36864
	ds_read_b128 v[152:155], v118
	ds_read_b128 v[156:159], v118 offset:4096
	s_waitcnt lgkmcnt(4)
	v_mfma_f32_32x32x16_bf16 v[48:63], v[184:187], v[192:195], v[48:63]
	v_mfma_f32_32x32x16_bf16 v[16:31], v[184:187], v[196:199], v[16:31]
	v_mfma_f32_32x32x16_bf16 v[32:47], v[188:191], v[192:195], v[32:47]
	v_mfma_f32_32x32x16_bf16 v[0:15], v[188:191], v[196:199], v[0:15]
	s_waitcnt vmcnt(6)
	s_waitcnt lgkmcnt(0)
	s_barrier
	ds_read_b128 v[184:187], v119 offset:32768
	ds_read_b128 v[188:191], v119 offset:36864
	ds_read_b128 v[192:195], v112 offset:49152
	ds_read_b128 v[196:199], v112 offset:53248
	s_waitcnt lgkmcnt(4)
	v_mfma_f32_32x32x16_bf16 v[48:63], v[132:135], v[152:155], v[48:63]
	v_mfma_f32_32x32x16_bf16 v[16:31], v[132:135], v[156:159], v[16:31]
	v_lshl_add_u64 v[132:133], v[80:81], 0, s[36:37]
	global_load_lds_dwordx4 v[132:133], off
	v_mfma_f32_32x32x16_bf16 v[0:15], v[136:139], v[156:159], v[0:15]
	v_mfma_f32_32x32x16_bf16 v[32:47], v[136:139], v[152:155], v[32:47]
	v_lshl_add_u64 v[132:133], v[80:81], 0, s[38:39]
	s_mov_b32 m0, s89
	s_nop 0
	global_load_lds_dwordx4 v[132:133], off
	ds_read_b128 v[132:135], v120 offset:32768
	ds_read_b128 v[136:139], v120 offset:36864
	ds_read_b128 v[152:155], v114 offset:49152
	ds_read_b128 v[156:159], v114 offset:53248
	s_waitcnt lgkmcnt(4)
	v_mfma_f32_32x32x16_bf16 v[48:63], v[184:187], v[192:195], v[48:63]
	v_mfma_f32_32x32x16_bf16 v[16:31], v[184:187], v[196:199], v[16:31]
	v_lshl_add_u64 v[252:253], v[80:81], 0, s[4:5]
	s_mov_b32 m0, s88
	s_mov_b64 s[4:5], 0x60300
	global_load_lds_dwordx4 v[252:253], off
	v_mfma_f32_32x32x16_bf16 v[32:47], v[188:191], v[192:195], v[32:47]
	v_mfma_f32_32x32x16_bf16 v[0:15], v[188:191], v[196:199], v[0:15]
	v_lshl_add_u64 v[252:253], v[80:81], 0, s[4:5]
	s_mov_b32 m0, s87
	s_nop 0
	global_load_lds_dwordx4 v[252:253], off
	ds_read_b128 v[184:187], v121 offset:32768
	ds_read_b128 v[188:191], v121 offset:36864
	ds_read_b128 v[192:195], v116 offset:49152
	ds_read_b128 v[196:199], v116 offset:53248
	s_waitcnt lgkmcnt(4)
	v_mfma_f32_32x32x16_bf16 v[48:63], v[132:135], v[152:155], v[48:63]
	v_mfma_f32_32x32x16_bf16 v[16:31], v[132:135], v[156:159], v[16:31]
	v_lshl_add_u64 v[252:253], v[82:83], 0, s[36:37]
	s_mov_b32 m0, s86
	s_nop 0
	global_load_lds_dwordx4 v[252:253], off
	v_mfma_f32_32x32x16_bf16 v[32:47], v[136:139], v[152:155], v[32:47]
	v_mfma_f32_32x32x16_bf16 v[0:15], v[136:139], v[156:159], v[0:15]
	v_lshl_add_u64 v[252:253], v[82:83], 0, s[38:39]
	s_mov_b32 m0, s55
	s_nop 0
	global_load_lds_dwordx4 v[252:253], off
	s_mov_b32 m0, s54
	s_mov_b64 s[4:5], 0x40380
	ds_read_b128 v[132:135], v122 offset:32768
	ds_read_b128 v[136:139], v122 offset:36864
	ds_read_b128 v[152:155], v118 offset:49152
	ds_read_b128 v[156:159], v118 offset:53248
	s_waitcnt lgkmcnt(4)
	v_mfma_f32_32x32x16_bf16 v[48:63], v[184:187], v[192:195], v[48:63]
	v_mfma_f32_32x32x16_bf16 v[16:31], v[184:187], v[196:199], v[16:31]
	v_mfma_f32_32x32x16_bf16 v[32:47], v[188:191], v[192:195], v[32:47]
	v_mfma_f32_32x32x16_bf16 v[0:15], v[188:191], v[196:199], v[0:15]
	s_waitcnt vmcnt(6)
	s_waitcnt lgkmcnt(0)
	s_barrier
; #define MFMA(a, b, c) __builtin_amdgcn_mfma_f32_32x32x16_bf16((a), (b), (c), 0, 0, 0)
; #define WAIT_V(n) asm volatile("s_waitcnt vmcnt(%0)" ::"n"(n) : "memory")
; #define RAW_BARRIER() do { asm volatile("s_waitcnt lgkmcnt(0)" ::: "memory"); __builtin_amdgcn_s_barrier(); asm volatile("" ::: "memory"); } while (0)
; #define GLDS_STAGE(slot, kt) do { _Pragma("unroll") for (int i = 0; i < 6; ++i) \
;     __builtin_amdgcn_global_load_lds((const unsigned*)(src[i] + (kt) * 64), (__attribute__((address_space(3))) unsigned*)(smem + (slot) * G_STAGE + (wave + 8 * i) * 1024), 16, 0, 0); } while (0)
; DI void gemm_tile(const u16* __restrict__ X, int ldx, const u16* __restrict__ Wt, int ldw, int K, char* smem,
;                   f32x16 (&acc)[2][2]) {
;     ...
;   int offA[2], offB[2], xa[2], xb[2];
; #pragma unroll
;   for (int ft = 0; ft < 2; ++ft) { const int R = 256 + fw * 64 + ft * 32 + lr; offA[ft] = R * 128; xa[ft] = (R >> 1) & 7; }
; #pragma unroll
;   for (int tt = 0; tt < 2; ++tt) { const int R = tq * 64 + tt * 32 + lr; offB[tt] = R * 128; xb[tt] = (R >> 1) & 7; }
;   GLDS_STAGE(0, 0); GLDS_STAGE(1, 1); WAIT_V(6); RAW_BARRIER();
;   int cur = 0;
;   for (int kt = 0; kt < nk; ++kt) {
;     const int nxt = (cur >= 1) ? cur - 1 : 2;
;     if (kt + 2 < nk) GLDS_STAGE(nxt, kt + 2);
;     __builtin_amdgcn_sched_barrier(0);
;     const char* st = smem + cur * G_STAGE;
; #pragma unroll
;     for (int ks = 0; ks < 4; ++ks) {
;       bf16x8 a[2], b[2];
; #pragma unroll
;       for (int ft = 0; ft < 2; ++ft) a[ft] = *reinterpret_cast<const bf16x8*>(st + offA[ft] + (((ks * 2 + lh) ^ xa[ft]) << 4));
; #pragma unroll
;       for (int tt = 0; tt < 2; ++tt) b[tt] = *reinterpret_cast<const bf16x8*>(st + offB[tt] + (((ks * 2 + lh) ^ xb[tt]) << 4));
; #pragma unroll
;       for (int ft = 0; ft < 2; ++ft)
; #pragma unroll
;         for (int tt = 0; tt < 2; ++tt) acc[ft][tt] = MFMA(a[ft], b[tt], acc[ft][tt]);
;     }
;     if (kt + 2 < nk) { WAIT_V(6); } else { WAIT_V(0); }
;     RAW_BARRIER();
;     cur = (cur == 2) ? 0 : cur + 1;
;   }
	ds_read_b128 v[184:187], v123 offset:32768
	ds_read_b128 v[188:191], v123 offset:36864
	ds_read_b128 v[192:195], v124
	ds_read_b128 v[196:199], v124 offset:4096
	s_waitcnt lgkmcnt(4)
	v_mfma_f32_32x32x16_bf16 v[48:63], v[132:135], v[152:155], v[48:63]
	v_mfma_f32_32x32x16_bf16 v[16:31], v[132:135], v[156:159], v[16:31]
	v_lshl_add_u64 v[132:133], v[80:81], 0, s[40:41]
	global_load_lds_dwordx4 v[132:133], off
	v_mfma_f32_32x32x16_bf16 v[0:15], v[136:139], v[156:159], v[0:15]
	v_mfma_f32_32x32x16_bf16 v[32:47], v[136:139], v[152:155], v[32:47]
	v_lshl_add_u64 v[132:133], v[80:81], 0, s[42:43]
	s_mov_b32 m0, s10
	s_nop 0
	global_load_lds_dwordx4 v[132:133], off
	ds_read_b128 v[132:135], v125 offset:32768
	ds_read_b128 v[136:139], v125 offset:36864
	ds_read_b128 v[152:155], v126
	ds_read_b128 v[156:159], v126 offset:4096
	s_waitcnt lgkmcnt(4)
	v_mfma_f32_32x32x16_bf16 v[48:63], v[184:187], v[192:195], v[48:63]
	v_mfma_f32_32x32x16_bf16 v[16:31], v[184:187], v[196:199], v[16:31]
	v_lshl_add_u64 v[252:253], v[80:81], 0, s[4:5]
	s_mov_b32 m0, s95
	s_mov_b64 s[4:5], 0x60380
	global_load_lds_dwordx4 v[252:253], off
	v_mfma_f32_32x32x16_bf16 v[32:47], v[188:191], v[192:195], v[32:47]
	v_mfma_f32_32x32x16_bf16 v[0:15], v[188:191], v[196:199], v[0:15]
	v_lshl_add_u64 v[252:253], v[80:81], 0, s[4:5]
	s_mov_b32 m0, s9
	s_nop 0
	global_load_lds_dwordx4 v[252:253], off
	ds_read_b128 v[184:187], v127 offset:32768
	ds_read_b128 v[188:191], v127 offset:36864
	ds_read_b128 v[192:195], v128
	ds_read_b128 v[196:199], v128 offset:4096
	s_waitcnt lgkmcnt(4)
	v_mfma_f32_32x32x16_bf16 v[48:63], v[132:135], v[152:155], v[48:63]
	v_mfma_f32_32x32x16_bf16 v[16:31], v[132:135], v[156:159], v[16:31]
	v_lshl_add_u64 v[252:253], v[82:83], 0, s[40:41]
	s_mov_b32 m0, s8
	s_nop 0
	global_load_lds_dwordx4 v[252:253], off
	v_mfma_f32_32x32x16_bf16 v[32:47], v[136:139], v[152:155], v[32:47]
	v_mfma_f32_32x32x16_bf16 v[0:15], v[136:139], v[156:159], v[0:15]
	v_lshl_add_u64 v[252:253], v[82:83], 0, s[42:43]
	s_mov_b32 m0, s46
	s_nop 0
	global_load_lds_dwordx4 v[252:253], off
	s_mov_b32 m0, s0
	s_mov_b64 s[0:1], 0x40400
	ds_read_b128 v[132:135], v129 offset:32768
	ds_read_b128 v[136:139], v129 offset:36864
	ds_read_b128 v[152:155], v130
	ds_read_b128 v[156:159], v130 offset:4096
	s_waitcnt lgkmcnt(4)
	v_mfma_f32_32x32x16_bf16 v[48:63], v[184:187], v[192:195], v[48:63]
	v_mfma_f32_32x32x16_bf16 v[16:31], v[184:187], v[196:199], v[16:31]
	v_mfma_f32_32x32x16_bf16 v[32:47], v[188:191], v[192:195], v[32:47]
	v_mfma_f32_32x32x16_bf16 v[0:15], v[188:191], v[196:199], v[0:15]
	s_waitcnt vmcnt(6)
	s_waitcnt lgkmcnt(0)
	s_barrier
	ds_read_b128 v[184:187], v111 offset:32768
	ds_read_b128 v[188:191], v111 offset:36864
	ds_read_b128 v[192:195], v112
	ds_read_b128 v[196:199], v112 offset:4096
	s_waitcnt lgkmcnt(4)
	v_mfma_f32_32x32x16_bf16 v[48:63], v[132:135], v[152:155], v[48:63]
	v_mfma_f32_32x32x16_bf16 v[16:31], v[132:135], v[156:159], v[16:31]
	v_lshl_add_u64 v[132:133], v[80:81], 0, s[44:45]
	global_load_lds_dwordx4 v[132:133], off
	v_mfma_f32_32x32x16_bf16 v[0:15], v[136:139], v[156:159], v[0:15]
	v_mfma_f32_32x32x16_bf16 v[32:47], v[136:139], v[152:155], v[32:47]
	v_lshl_add_u64 v[132:133], v[80:81], 0, s[48:49]
	s_mov_b32 m0, s93
	s_nop 0
	global_load_lds_dwordx4 v[132:133], off
	ds_read_b128 v[132:135], v113 offset:32768
	ds_read_b128 v[136:139], v113 offset:36864
	ds_read_b128 v[152:155], v114
	ds_read_b128 v[156:159], v114 offset:4096
	s_waitcnt lgkmcnt(4)
	v_mfma_f32_32x32x16_bf16 v[48:63], v[184:187], v[192:195], v[48:63]
	v_mfma_f32_32x32x16_bf16 v[16:31], v[184:187], v[196:199], v[16:31]
	v_lshl_add_u64 v[252:253], v[80:81], 0, s[0:1]
	s_mov_b32 m0, s91
	s_mov_b64 s[0:1], 0x60400
	global_load_lds_dwordx4 v[252:253], off
	v_mfma_f32_32x32x16_bf16 v[32:47], v[188:191], v[192:195], v[32:47]
	v_mfma_f32_32x32x16_bf16 v[0:15], v[188:191], v[196:199], v[0:15]
	v_lshl_add_u64 v[252:253], v[80:81], 0, s[0:1]
	s_mov_b32 m0, s92
	s_nop 0
	global_load_lds_dwordx4 v[252:253], off
	ds_read_b128 v[184:187], v115 offset:32768
	ds_read_b128 v[188:191], v115 offset:36864
	ds_read_b128 v[192:195], v116
	ds_read_b128 v[196:199], v116 offset:4096
	s_waitcnt lgkmcnt(4)
	v_mfma_f32_32x32x16_bf16 v[48:63], v[132:135], v[152:155], v[48:63]
	v_mfma_f32_32x32x16_bf16 v[16:31], v[132:135], v[156:159], v[16:31]
	v_lshl_add_u64 v[252:253], v[82:83], 0, s[44:45]
	s_mov_b32 m0, s7
	s_nop 0
	global_load_lds_dwordx4 v[252:253], off
	v_mfma_f32_32x32x16_bf16 v[32:47], v[136:139], v[152:155], v[32:47]
	v_mfma_f32_32x32x16_bf16 v[0:15], v[136:139], v[156:159], v[0:15]
	v_lshl_add_u64 v[252:253], v[82:83], 0, s[48:49]
	s_mov_b32 m0, s90
	s_nop 0
	global_load_lds_dwordx4 v[252:253], off
	s_mov_b32 m0, s6
	s_mov_b64 s[0:1], 0x40480
	ds_read_b128 v[132:135], v117 offset:32768
	ds_read_b128 v[136:139], v117 offset:36864
	ds_read_b128 v[152:155], v118
	ds_read_b128 v[156:159], v118 offset:4096
	s_waitcnt lgkmcnt(4)
	v_mfma_f32_32x32x16_bf16 v[48:63], v[184:187], v[192:195], v[48:63]
	v_mfma_f32_32x32x16_bf16 v[16:31], v[184:187], v[196:199], v[16:31]
	v_mfma_f32_32x32x16_bf16 v[32:47], v[188:191], v[192:195], v[32:47]
	v_mfma_f32_32x32x16_bf16 v[0:15], v[188:191], v[196:199], v[0:15]
	s_waitcnt vmcnt(6)
	s_waitcnt lgkmcnt(0)
	s_barrier
; #define MFMA(a, b, c) __builtin_amdgcn_mfma_f32_32x32x16_bf16((a), (b), (c), 0, 0, 0)
; #define WAIT_V(n) asm volatile("s_waitcnt vmcnt(%0)" ::"n"(n) : "memory")
; #define RAW_BARRIER() do { asm volatile("s_waitcnt lgkmcnt(0)" ::: "memory"); __builtin_amdgcn_s_barrier(); asm volatile("" ::: "memory"); } while (0)
; #define GLDS_STAGE(slot, kt) do { _Pragma("unroll") for (int i = 0; i < 6; ++i) \
;     __builtin_amdgcn_global_load_lds((const unsigned*)(src[i] + (kt) * 64), (__attribute__((address_space(3))) unsigned*)(smem + (slot) * G_STAGE + (wave + 8 * i) * 1024), 16, 0, 0); } while (0)
; DI void gemm_tile(const u16* __restrict__ X, int ldx, const u16* __restrict__ Wt, int ldw, int K, char* smem,
;                   f32x16 (&acc)[2][2]) {
;     ...
;   int offA[2], offB[2], xa[2], xb[2];
; #pragma unroll
;   for (int ft = 0; ft < 2; ++ft) { const int R = 256 + fw * 64 + ft * 32 + lr; offA[ft] = R * 128; xa[ft] = (R >> 1) & 7; }
; #pragma unroll
;   for (int tt = 0; tt < 2; ++tt) { const int R = tq * 64 + tt * 32 + lr; offB[tt] = R * 128; xb[tt] = (R >> 1) & 7; }
;   GLDS_STAGE(0, 0); GLDS_STAGE(1, 1); WAIT_V(6); RAW_BARRIER();
;   int cur = 0;
;   for (int kt = 0; kt < nk; ++kt) {
;     const int nxt = (cur >= 1) ? cur - 1 : 2;
;     if (kt + 2 < nk) GLDS_STAGE(nxt, kt + 2);
;     __builtin_amdgcn_sched_barrier(0);
;     const char* st = smem + cur * G_STAGE;
; #pragma unroll
;     for (int ks = 0; ks < 4; ++ks) {
;       bf16x8 a[2], b[2];
; #pragma unroll
;       for (int ft = 0; ft < 2; ++ft) a[ft] = *reinterpret_cast<const bf16x8*>(st + offA[ft] + (((ks * 2 + lh) ^ xa[ft]) << 4));
; #pragma unroll
;       for (int tt = 0; tt < 2; ++tt) b[tt] = *reinterpret_cast<const bf16x8*>(st + offB[tt] + (((ks * 2 + lh) ^ xb[tt]) << 4));
; #pragma unroll
;       for (int ft = 0; ft < 2; ++ft)
; #pragma unroll
;         for (int tt = 0; tt < 2; ++tt) acc[ft][tt] = MFMA(a[ft], b[tt], acc[ft][tt]);
;     }
;     if (kt + 2 < nk) { WAIT_V(6); } else { WAIT_V(0); }
;     RAW_BARRIER();
;     cur = (cur == 2) ? 0 : cur + 1;
;   }
	ds_read_b128 v[184:187], v119 offset:32768
	ds_read_b128 v[188:191], v119 offset:36864
	ds_read_b128 v[192:195], v112 offset:49152
	ds_read_b128 v[196:199], v112 offset:53248
	s_waitcnt lgkmcnt(4)
	v_mfma_f32_32x32x16_bf16 v[48:63], v[132:135], v[152:155], v[48:63]
	v_mfma_f32_32x32x16_bf16 v[16:31], v[132:135], v[156:159], v[16:31]
	v_lshl_add_u64 v[132:133], v[80:81], 0, s[50:51]
	global_load_lds_dwordx4 v[132:133], off
	v_mfma_f32_32x32x16_bf16 v[0:15], v[136:139], v[156:159], v[0:15]
	v_mfma_f32_32x32x16_bf16 v[32:47], v[136:139], v[152:155], v[32:47]
	v_lshl_add_u64 v[132:133], v[80:81], 0, s[52:53]
	s_mov_b32 m0, s89
	s_nop 0
	global_load_lds_dwordx4 v[132:133], off
	ds_read_b128 v[132:135], v120 offset:32768
	ds_read_b128 v[136:139], v120 offset:36864
	ds_read_b128 v[152:155], v114 offset:49152
	ds_read_b128 v[156:159], v114 offset:53248
	s_waitcnt lgkmcnt(4)
	v_mfma_f32_32x32x16_bf16 v[48:63], v[184:187], v[192:195], v[48:63]
	v_mfma_f32_32x32x16_bf16 v[16:31], v[184:187], v[196:199], v[16:31]
	v_lshl_add_u64 v[252:253], v[80:81], 0, s[0:1]
	s_mov_b32 m0, s88
	s_mov_b64 s[0:1], 0x60480
	global_load_lds_dwordx4 v[252:253], off
	v_mfma_f32_32x32x16_bf16 v[32:47], v[188:191], v[192:195], v[32:47]
	v_mfma_f32_32x32x16_bf16 v[0:15], v[188:191], v[196:199], v[0:15]
	v_lshl_add_u64 v[252:253], v[80:81], 0, s[0:1]
	s_mov_b32 m0, s87
	s_nop 0
	global_load_lds_dwordx4 v[252:253], off
	ds_read_b128 v[184:187], v121 offset:32768
	ds_read_b128 v[188:191], v121 offset:36864
	ds_read_b128 v[192:195], v116 offset:49152
	ds_read_b128 v[196:199], v116 offset:53248
	s_waitcnt lgkmcnt(4)
	v_mfma_f32_32x32x16_bf16 v[48:63], v[132:135], v[152:155], v[48:63]
	v_mfma_f32_32x32x16_bf16 v[16:31], v[132:135], v[156:159], v[16:31]
	v_lshl_add_u64 v[252:253], v[82:83], 0, s[50:51]
	s_mov_b32 m0, s86
	s_nop 0
	global_load_lds_dwordx4 v[252:253], off
	v_mfma_f32_32x32x16_bf16 v[32:47], v[136:139], v[152:155], v[32:47]
	v_mfma_f32_32x32x16_bf16 v[0:15], v[136:139], v[156:159], v[0:15]
	v_lshl_add_u64 v[252:253], v[82:83], 0, s[52:53]
	s_mov_b32 m0, s55
	s_nop 0
	global_load_lds_dwordx4 v[252:253], off
	s_mov_b32 m0, s54
	s_mov_b64 s[0:1], 0x40500
	ds_read_b128 v[132:135], v122 offset:32768
	ds_read_b128 v[136:139], v122 offset:36864
	ds_read_b128 v[152:155], v118 offset:49152
	ds_read_b128 v[156:159], v118 offset:53248
	s_waitcnt lgkmcnt(4)
	v_mfma_f32_32x32x16_bf16 v[48:63], v[184:187], v[192:195], v[48:63]
	v_mfma_f32_32x32x16_bf16 v[16:31], v[184:187], v[196:199], v[16:31]
	v_mfma_f32_32x32x16_bf16 v[32:47], v[188:191], v[192:195], v[32:47]
	v_mfma_f32_32x32x16_bf16 v[0:15], v[188:191], v[196:199], v[0:15]
	s_waitcnt vmcnt(6)
	s_waitcnt lgkmcnt(0)
	s_barrier
	ds_read_b128 v[184:187], v123 offset:32768
	ds_read_b128 v[188:191], v123 offset:36864
	ds_read_b128 v[192:195], v124
	ds_read_b128 v[196:199], v124 offset:4096
	s_waitcnt lgkmcnt(4)
	v_mfma_f32_32x32x16_bf16 v[48:63], v[132:135], v[152:155], v[48:63]
	v_mfma_f32_32x32x16_bf16 v[16:31], v[132:135], v[156:159], v[16:31]
	v_lshl_add_u64 v[132:133], v[80:81], 0, s[56:57]
	global_load_lds_dwordx4 v[132:133], off
	v_mfma_f32_32x32x16_bf16 v[0:15], v[136:139], v[156:159], v[0:15]
	v_mfma_f32_32x32x16_bf16 v[32:47], v[136:139], v[152:155], v[32:47]
	v_lshl_add_u64 v[132:133], v[80:81], 0, s[58:59]
	s_mov_b32 m0, s10
	s_nop 0
	global_load_lds_dwordx4 v[132:133], off
	ds_read_b128 v[132:135], v125 offset:32768
	ds_read_b128 v[136:139], v125 offset:36864
	ds_read_b128 v[152:155], v126
	ds_read_b128 v[156:159], v126 offset:4096
	s_waitcnt lgkmcnt(4)
	v_mfma_f32_32x32x16_bf16 v[48:63], v[184:187], v[192:195], v[48:63]
	v_mfma_f32_32x32x16_bf16 v[16:31], v[184:187], v[196:199], v[16:31]
	v_lshl_add_u64 v[252:253], v[80:81], 0, s[0:1]
	s_mov_b32 m0, s95
	s_mov_b64 s[0:1], 0x60500
	global_load_lds_dwordx4 v[252:253], off
	v_mfma_f32_32x32x16_bf16 v[32:47], v[188:191], v[192:195], v[32:47]
	v_mfma_f32_32x32x16_bf16 v[0:15], v[188:191], v[196:199], v[0:15]
	v_lshl_add_u64 v[252:253], v[80:81], 0, s[0:1]
	s_mov_b32 m0, s9
	s_nop 0
	global_load_lds_dwordx4 v[252:253], off
	ds_read_b128 v[184:187], v127 offset:32768
	ds_read_b128 v[188:191], v127 offset:36864
	ds_read_b128 v[192:195], v128
	ds_read_b128 v[196:199], v128 offset:4096
	s_waitcnt lgkmcnt(4)
	v_mfma_f32_32x32x16_bf16 v[48:63], v[132:135], v[152:155], v[48:63]
	v_mfma_f32_32x32x16_bf16 v[16:31], v[132:135], v[156:159], v[16:31]
	v_lshl_add_u64 v[252:253], v[82:83], 0, s[56:57]
	s_mov_b32 m0, s8
	s_nop 0
	global_load_lds_dwordx4 v[252:253], off
	v_mfma_f32_32x32x16_bf16 v[32:47], v[136:139], v[152:155], v[32:47]
	v_mfma_f32_32x32x16_bf16 v[0:15], v[136:139], v[156:159], v[0:15]
	v_lshl_add_u64 v[252:253], v[82:83], 0, s[58:59]
	s_mov_b32 m0, s46
	s_nop 0
	global_load_lds_dwordx4 v[252:253], off
	v_readfirstlane_b32 s54, v85
	s_mov_b32 m0, s54
	v_readfirstlane_b32 s7, v86
	s_mov_b64 s[0:1], 0x40580
	v_readfirstlane_b32 s8, v87
	v_readfirstlane_b32 s10, v88
	v_readfirstlane_b32 s9, v89
	v_readfirstlane_b32 s46, v90
	ds_read_b128 v[132:135], v129 offset:32768
	ds_read_b128 v[136:139], v129 offset:36864
	ds_read_b128 v[152:155], v130
	ds_read_b128 v[156:159], v130 offset:4096
	s_waitcnt lgkmcnt(4)
	v_mfma_f32_32x32x16_bf16 v[48:63], v[184:187], v[192:195], v[48:63]
	v_mfma_f32_32x32x16_bf16 v[16:31], v[184:187], v[196:199], v[16:31]
	v_mfma_f32_32x32x16_bf16 v[32:47], v[188:191], v[192:195], v[32:47]
	v_mfma_f32_32x32x16_bf16 v[0:15], v[188:191], v[196:199], v[0:15]
	s_waitcnt vmcnt(6)
	s_waitcnt lgkmcnt(0)
	s_barrier
; #define MFMA(a, b, c) __builtin_amdgcn_mfma_f32_32x32x16_bf16((a), (b), (c), 0, 0, 0)
; #define WAIT_V(n) asm volatile("s_waitcnt vmcnt(%0)" ::"n"(n) : "memory")
; #define RAW_BARRIER() do { asm volatile("s_waitcnt lgkmcnt(0)" ::: "memory"); __builtin_amdgcn_s_barrier(); asm volatile("" ::: "memory"); } while (0)
; #define GLDS_STAGE(slot, kt) do { _Pragma("unroll") for (int i = 0; i < 6; ++i) \
;     __builtin_amdgcn_global_load_lds((const unsigned*)(src[i] + (kt) * 64), (__attribute__((address_space(3))) unsigned*)(smem + (slot) * G_STAGE + (wave + 8 * i) * 1024), 16, 0, 0); } while (0)
; DI void gemm_tile(const u16* __restrict__ X, int ldx, const u16* __restrict__ Wt, int ldw, int K, char* smem,
;                   f32x16 (&acc)[2][2]) {
;     ...
;   int offA[2], offB[2], xa[2], xb[2];
; #pragma unroll
;   for (int ft = 0; ft < 2; ++ft) { const int R = 256 + fw * 64 + ft * 32 + lr; offA[ft] = R * 128; xa[ft] = (R >> 1) & 7; }
; #pragma unroll
;   for (int tt = 0; tt < 2; ++tt) { const int R = tq * 64 + tt * 32 + lr; offB[tt] = R * 128; xb[tt] = (R >> 1) & 7; }
;   GLDS_STAGE(0, 0); GLDS_STAGE(1, 1); WAIT_V(6); RAW_BARRIER();
;   int cur = 0;
;   for (int kt = 0; kt < nk; ++kt) {
;     const int nxt = (cur >= 1) ? cur - 1 : 2;
;     if (kt + 2 < nk) GLDS_STAGE(nxt, kt + 2);
;     __builtin_amdgcn_sched_barrier(0);
;     const char* st = smem + cur * G_STAGE;
; #pragma unroll
;     for (int ks = 0; ks < 4; ++ks) {
;       bf16x8 a[2], b[2];
; #pragma unroll
;       for (int ft = 0; ft < 2; ++ft) a[ft] = *reinterpret_cast<const bf16x8*>(st + offA[ft] + (((ks * 2 + lh) ^ xa[ft]) << 4));
; #pragma unroll
;       for (int tt = 0; tt < 2; ++tt) b[tt] = *reinterpret_cast<const bf16x8*>(st + offB[tt] + (((ks * 2 + lh) ^ xb[tt]) << 4));
; #pragma unroll
;       for (int ft = 0; ft < 2; ++ft)
; #pragma unroll
;         for (int tt = 0; tt < 2; ++tt) acc[ft][tt] = MFMA(a[ft], b[tt], acc[ft][tt]);
;     }
;     if (kt + 2 < nk) { WAIT_V(6); } else { WAIT_V(0); }
;     RAW_BARRIER();
;     cur = (cur == 2) ? 0 : cur + 1;
;   }
	ds_read_b128 v[184:187], v111 offset:32768
	ds_read_b128 v[188:191], v111 offset:36864
	ds_read_b128 v[192:195], v112
	ds_read_b128 v[196:199], v112 offset:4096
	s_waitcnt lgkmcnt(4)
	v_mfma_f32_32x32x16_bf16 v[48:63], v[132:135], v[152:155], v[48:63]
	v_mfma_f32_32x32x16_bf16 v[16:31], v[132:135], v[156:159], v[16:31]
	v_lshl_add_u64 v[132:133], v[80:81], 0, s[60:61]
	global_load_lds_dwordx4 v[132:133], off
	v_mfma_f32_32x32x16_bf16 v[0:15], v[136:139], v[156:159], v[0:15]
	v_mfma_f32_32x32x16_bf16 v[32:47], v[136:139], v[152:155], v[32:47]
	v_lshl_add_u64 v[132:133], v[80:81], 0, s[62:63]
	s_mov_b32 m0, s7
	s_nop 0
	global_load_lds_dwordx4 v[132:133], off
	ds_read_b128 v[132:135], v113 offset:32768
	ds_read_b128 v[136:139], v113 offset:36864
	ds_read_b128 v[152:155], v114
	ds_read_b128 v[156:159], v114 offset:4096
	s_waitcnt lgkmcnt(4)
	v_mfma_f32_32x32x16_bf16 v[48:63], v[184:187], v[192:195], v[48:63]
	v_mfma_f32_32x32x16_bf16 v[16:31], v[184:187], v[196:199], v[16:31]
	v_lshl_add_u64 v[252:253], v[80:81], 0, s[0:1]
	s_mov_b32 m0, s8
	s_mov_b64 s[0:1], 0x60580
	global_load_lds_dwordx4 v[252:253], off
	v_mfma_f32_32x32x16_bf16 v[32:47], v[188:191], v[192:195], v[32:47]
	v_mfma_f32_32x32x16_bf16 v[0:15], v[188:191], v[196:199], v[0:15]
	v_lshl_add_u64 v[252:253], v[80:81], 0, s[0:1]
	s_mov_b32 m0, s10
	s_nop 0
	global_load_lds_dwordx4 v[252:253], off
	ds_read_b128 v[184:187], v115 offset:32768
	ds_read_b128 v[188:191], v115 offset:36864
	ds_read_b128 v[192:195], v116
	ds_read_b128 v[196:199], v116 offset:4096
	s_waitcnt lgkmcnt(4)
	v_mfma_f32_32x32x16_bf16 v[48:63], v[132:135], v[152:155], v[48:63]
	v_mfma_f32_32x32x16_bf16 v[16:31], v[132:135], v[156:159], v[16:31]
	v_lshl_add_u64 v[252:253], v[82:83], 0, s[60:61]
	s_mov_b32 m0, s9
	s_nop 0
	global_load_lds_dwordx4 v[252:253], off
	v_mfma_f32_32x32x16_bf16 v[32:47], v[136:139], v[152:155], v[32:47]
	v_mfma_f32_32x32x16_bf16 v[0:15], v[136:139], v[156:159], v[0:15]
	v_lshl_add_u64 v[252:253], v[82:83], 0, s[62:63]
	s_mov_b32 m0, s46
	s_nop 0
	global_load_lds_dwordx4 v[252:253], off
	v_readfirstlane_b32 s47, v143
	s_mov_b32 m0, s47
	v_readfirstlane_b32 s0, v101
	s_mov_b64 s[4:5], 0x40600
	v_readfirstlane_b32 s1, v102
	v_readfirstlane_b32 s6, v105
	ds_read_b128 v[132:135], v117 offset:32768
	ds_read_b128 v[136:139], v117 offset:36864
	ds_read_b128 v[152:155], v118
	ds_read_b128 v[156:159], v118 offset:4096
	s_waitcnt lgkmcnt(4)
	v_mfma_f32_32x32x16_bf16 v[48:63], v[184:187], v[192:195], v[48:63]
	v_mfma_f32_32x32x16_bf16 v[16:31], v[184:187], v[196:199], v[16:31]
	v_mfma_f32_32x32x16_bf16 v[32:47], v[188:191], v[192:195], v[32:47]
	v_mfma_f32_32x32x16_bf16 v[0:15], v[188:191], v[196:199], v[0:15]
	s_waitcnt vmcnt(6)
	s_waitcnt lgkmcnt(0)
	s_barrier
	ds_read_b128 v[184:187], v119 offset:32768
	ds_read_b128 v[188:191], v119 offset:36864
	ds_read_b128 v[192:195], v112 offset:49152
	ds_read_b128 v[196:199], v112 offset:53248
	s_waitcnt lgkmcnt(4)
	v_mfma_f32_32x32x16_bf16 v[48:63], v[132:135], v[152:155], v[48:63]
	v_mfma_f32_32x32x16_bf16 v[16:31], v[132:135], v[156:159], v[16:31]
	v_lshl_add_u64 v[132:133], v[80:81], 0, s[64:65]
	global_load_lds_dwordx4 v[132:133], off
	v_mfma_f32_32x32x16_bf16 v[0:15], v[136:139], v[156:159], v[0:15]
	v_mfma_f32_32x32x16_bf16 v[32:47], v[136:139], v[152:155], v[32:47]
	v_lshl_add_u64 v[132:133], v[80:81], 0, s[66:67]
	s_mov_b32 m0, s0
	s_nop 0
	global_load_lds_dwordx4 v[132:133], off
	ds_read_b128 v[132:135], v120 offset:32768
	ds_read_b128 v[136:139], v120 offset:36864
	ds_read_b128 v[152:155], v114 offset:49152
	ds_read_b128 v[156:159], v114 offset:53248
	s_waitcnt lgkmcnt(4)
	v_mfma_f32_32x32x16_bf16 v[48:63], v[184:187], v[192:195], v[48:63]
	v_mfma_f32_32x32x16_bf16 v[16:31], v[184:187], v[196:199], v[16:31]
	v_lshl_add_u64 v[252:253], v[80:81], 0, s[4:5]
	s_mov_b32 m0, s1
	s_mov_b64 s[4:5], 0x60600
	global_load_lds_dwordx4 v[252:253], off
	v_mfma_f32_32x32x16_bf16 v[32:47], v[188:191], v[192:195], v[32:47]
	v_mfma_f32_32x32x16_bf16 v[0:15], v[188:191], v[196:199], v[0:15]
	v_lshl_add_u64 v[252:253], v[80:81], 0, s[4:5]
	v_readfirstlane_b32 s5, v103
	s_mov_b32 m0, s5
	v_readfirstlane_b32 s4, v104
	global_load_lds_dwordx4 v[252:253], off
	ds_read_b128 v[184:187], v121 offset:32768
	ds_read_b128 v[188:191], v121 offset:36864
	ds_read_b128 v[192:195], v116 offset:49152
	ds_read_b128 v[196:199], v116 offset:53248
	s_waitcnt lgkmcnt(4)
	v_mfma_f32_32x32x16_bf16 v[48:63], v[132:135], v[152:155], v[48:63]
	v_mfma_f32_32x32x16_bf16 v[16:31], v[132:135], v[156:159], v[16:31]
	v_lshl_add_u64 v[252:253], v[82:83], 0, s[64:65]
	s_mov_b32 m0, s4
	s_nop 0
	global_load_lds_dwordx4 v[252:253], off
	v_mfma_f32_32x32x16_bf16 v[32:47], v[136:139], v[152:155], v[32:47]
	v_mfma_f32_32x32x16_bf16 v[0:15], v[136:139], v[156:159], v[0:15]
	v_lshl_add_u64 v[252:253], v[82:83], 0, s[66:67]
	s_mov_b32 m0, s6
	s_nop 0
	global_load_lds_dwordx4 v[252:253], off
	v_readfirstlane_b32 s55, v84
	s_mov_b32 m0, s55
	v_readfirstlane_b32 s55, v106
	s_mov_b64 s[86:87], 0x40680
	ds_read_b128 v[132:135], v122 offset:32768
	ds_read_b128 v[136:139], v122 offset:36864
	ds_read_b128 v[152:155], v118 offset:49152
	ds_read_b128 v[156:159], v118 offset:53248
	s_waitcnt lgkmcnt(4)
	v_mfma_f32_32x32x16_bf16 v[48:63], v[184:187], v[192:195], v[48:63]
	v_mfma_f32_32x32x16_bf16 v[16:31], v[184:187], v[196:199], v[16:31]
	v_mfma_f32_32x32x16_bf16 v[32:47], v[188:191], v[192:195], v[32:47]
	v_mfma_f32_32x32x16_bf16 v[0:15], v[188:191], v[196:199], v[0:15]
	s_waitcnt vmcnt(6)
	s_waitcnt lgkmcnt(0)
	s_barrier
; #define MFMA(a, b, c) __builtin_amdgcn_mfma_f32_32x32x16_bf16((a), (b), (c), 0, 0, 0)
; #define WAIT_V(n) asm volatile("s_waitcnt vmcnt(%0)" ::"n"(n) : "memory")
; #define RAW_BARRIER() do { asm volatile("s_waitcnt lgkmcnt(0)" ::: "memory"); __builtin_amdgcn_s_barrier(); asm volatile("" ::: "memory"); } while (0)
; #define GLDS_STAGE(slot, kt) do { _Pragma("unroll") for (int i = 0; i < 6; ++i) \
;     __builtin_amdgcn_global_load_lds((const unsigned*)(src[i] + (kt) * 64), (__attribute__((address_space(3))) unsigned*)(smem + (slot) * G_STAGE + (wave + 8 * i) * 1024), 16, 0, 0); } while (0)
; DI void gemm_tile(const u16* __restrict__ X, int ldx, const u16* __restrict__ Wt, int ldw, int K, char* smem,
;                   f32x16 (&acc)[2][2]) {
;     ...
;   for (int kt = 0; kt < nk; ++kt) {
;     const int nxt = (cur >= 1) ? cur - 1 : 2;
;     if (kt + 2 < nk) GLDS_STAGE(nxt, kt + 2);
;     __builtin_amdgcn_sched_barrier(0);
;     const char* st = smem + cur * G_STAGE;
; #pragma unroll
;     for (int ks = 0; ks < 4; ++ks) {
;       bf16x8 a[2], b[2];
; #pragma unroll
;       for (int ft = 0; ft < 2; ++ft) a[ft] = *reinterpret_cast<const bf16x8*>(st + offA[ft] + (((ks * 2 + lh) ^ xa[ft]) << 4));
; #pragma unroll
;       for (int tt = 0; tt < 2; ++tt) b[tt] = *reinterpret_cast<const bf16x8*>(st + offB[tt] + (((ks * 2 + lh) ^ xb[tt]) << 4));
; #pragma unroll
;       for (int ft = 0; ft < 2; ++ft)
; #pragma unroll
;         for (int tt = 0; tt < 2; ++tt) acc[ft][tt] = MFMA(a[ft], b[tt], acc[ft][tt]);
;     }
;     if (kt + 2 < nk) { WAIT_V(6); } else { WAIT_V(0); }
;     RAW_BARRIER();
;     cur = (cur == 2) ? 0 : cur + 1;
	ds_read_b128 v[184:187], v123 offset:32768
	ds_read_b128 v[188:191], v123 offset:36864
	ds_read_b128 v[192:195], v124
	ds_read_b128 v[196:199], v124 offset:4096
	s_waitcnt lgkmcnt(4)
	v_mfma_f32_32x32x16_bf16 v[48:63], v[132:135], v[152:155], v[48:63]
	v_mfma_f32_32x32x16_bf16 v[16:31], v[132:135], v[156:159], v[16:31]
	v_lshl_add_u64 v[132:133], v[80:81], 0, s[68:69]
	global_load_lds_dwordx4 v[132:133], off
	v_mfma_f32_32x32x16_bf16 v[0:15], v[136:139], v[156:159], v[0:15]
	v_mfma_f32_32x32x16_bf16 v[32:47], v[136:139], v[152:155], v[32:47]
	v_lshl_add_u64 v[132:133], v[80:81], 0, s[70:71]
	s_mov_b32 m0, s55
	v_readfirstlane_b32 s55, v91
	global_load_lds_dwordx4 v[132:133], off
	ds_read_b128 v[132:135], v125 offset:32768
	ds_read_b128 v[136:139], v125 offset:36864
	ds_read_b128 v[152:155], v126
	ds_read_b128 v[156:159], v126 offset:4096
	s_waitcnt lgkmcnt(4)
	v_mfma_f32_32x32x16_bf16 v[48:63], v[184:187], v[192:195], v[48:63]
	v_mfma_f32_32x32x16_bf16 v[16:31], v[184:187], v[196:199], v[16:31]
	v_lshl_add_u64 v[252:253], v[80:81], 0, s[86:87]
	s_mov_b32 m0, s55
	s_mov_b64 s[86:87], 0x60680
	v_readfirstlane_b32 s55, v92
	global_load_lds_dwordx4 v[252:253], off
	v_mfma_f32_32x32x16_bf16 v[32:47], v[188:191], v[192:195], v[32:47]
	v_mfma_f32_32x32x16_bf16 v[0:15], v[188:191], v[196:199], v[0:15]
	v_lshl_add_u64 v[252:253], v[80:81], 0, s[86:87]
	s_mov_b32 m0, s55
	v_readfirstlane_b32 s55, v93
	global_load_lds_dwordx4 v[252:253], off
	ds_read_b128 v[184:187], v127 offset:32768
	ds_read_b128 v[188:191], v127 offset:36864
	ds_read_b128 v[192:195], v128
	ds_read_b128 v[196:199], v128 offset:4096
	s_waitcnt lgkmcnt(4)
	v_mfma_f32_32x32x16_bf16 v[48:63], v[132:135], v[152:155], v[48:63]
	v_mfma_f32_32x32x16_bf16 v[16:31], v[132:135], v[156:159], v[16:31]
	v_lshl_add_u64 v[252:253], v[82:83], 0, s[68:69]
	s_mov_b32 m0, s55
	v_readfirstlane_b32 s55, v94
	global_load_lds_dwordx4 v[252:253], off
	v_mfma_f32_32x32x16_bf16 v[32:47], v[136:139], v[152:155], v[32:47]
	v_mfma_f32_32x32x16_bf16 v[0:15], v[136:139], v[156:159], v[0:15]
	v_lshl_add_u64 v[252:253], v[82:83], 0, s[70:71]
	s_mov_b32 m0, s55
	s_nop 0
	global_load_lds_dwordx4 v[252:253], off
	s_mov_b32 m0, s54
	s_mov_b64 s[54:55], 0x40700
	ds_read_b128 v[132:135], v129 offset:32768
	ds_read_b128 v[136:139], v129 offset:36864
	ds_read_b128 v[152:155], v130
	ds_read_b128 v[156:159], v130 offset:4096
	s_waitcnt lgkmcnt(4)
	v_mfma_f32_32x32x16_bf16 v[48:63], v[184:187], v[192:195], v[48:63]
	v_mfma_f32_32x32x16_bf16 v[16:31], v[184:187], v[196:199], v[16:31]
	v_mfma_f32_32x32x16_bf16 v[32:47], v[188:191], v[192:195], v[32:47]
	v_mfma_f32_32x32x16_bf16 v[0:15], v[188:191], v[196:199], v[0:15]
	s_waitcnt vmcnt(6)
	s_waitcnt lgkmcnt(0)
	s_barrier
	ds_read_b128 v[184:187], v111 offset:32768
	ds_read_b128 v[188:191], v111 offset:36864
	ds_read_b128 v[192:195], v112
	ds_read_b128 v[196:199], v112 offset:4096
	s_waitcnt lgkmcnt(4)
	v_mfma_f32_32x32x16_bf16 v[48:63], v[132:135], v[152:155], v[48:63]
	v_mfma_f32_32x32x16_bf16 v[16:31], v[132:135], v[156:159], v[16:31]
	v_lshl_add_u64 v[132:133], v[80:81], 0, s[72:73]
	global_load_lds_dwordx4 v[132:133], off
	v_mfma_f32_32x32x16_bf16 v[0:15], v[136:139], v[156:159], v[0:15]
	v_mfma_f32_32x32x16_bf16 v[32:47], v[136:139], v[152:155], v[32:47]
	v_lshl_add_u64 v[132:133], v[80:81], 0, s[74:75]
	s_mov_b32 m0, s7
	s_nop 0
	global_load_lds_dwordx4 v[132:133], off
	ds_read_b128 v[132:135], v113 offset:32768
	ds_read_b128 v[136:139], v113 offset:36864
	ds_read_b128 v[152:155], v114
	ds_read_b128 v[156:159], v114 offset:4096
	s_waitcnt lgkmcnt(4)
	v_mfma_f32_32x32x16_bf16 v[48:63], v[184:187], v[192:195], v[48:63]
	v_mfma_f32_32x32x16_bf16 v[16:31], v[184:187], v[196:199], v[16:31]
	v_lshl_add_u64 v[252:253], v[80:81], 0, s[54:55]
	s_mov_b32 m0, s8
	s_mov_b64 s[54:55], 0x60700
	global_load_lds_dwordx4 v[252:253], off
	v_mfma_f32_32x32x16_bf16 v[32:47], v[188:191], v[192:195], v[32:47]
	v_mfma_f32_32x32x16_bf16 v[0:15], v[188:191], v[196:199], v[0:15]
	v_lshl_add_u64 v[252:253], v[80:81], 0, s[54:55]
	s_mov_b32 m0, s10
	s_nop 0
	global_load_lds_dwordx4 v[252:253], off
	ds_read_b128 v[184:187], v115 offset:32768
	ds_read_b128 v[188:191], v115 offset:36864
	ds_read_b128 v[192:195], v116
	ds_read_b128 v[196:199], v116 offset:4096
	s_waitcnt lgkmcnt(4)
	v_mfma_f32_32x32x16_bf16 v[48:63], v[132:135], v[152:155], v[48:63]
	v_mfma_f32_32x32x16_bf16 v[16:31], v[132:135], v[156:159], v[16:31]
	v_lshl_add_u64 v[252:253], v[82:83], 0, s[72:73]
	s_mov_b32 m0, s9
	s_nop 0
	global_load_lds_dwordx4 v[252:253], off
	v_mfma_f32_32x32x16_bf16 v[32:47], v[136:139], v[152:155], v[32:47]
	v_mfma_f32_32x32x16_bf16 v[0:15], v[136:139], v[156:159], v[0:15]
	v_lshl_add_u64 v[252:253], v[82:83], 0, s[74:75]
	s_mov_b32 m0, s46
	s_nop 0
	global_load_lds_dwordx4 v[252:253], off
	s_mov_b32 m0, s47
	s_mov_b64 s[8:9], 0x40780
	s_waitcnt lgkmcnt(0)
	v_mfma_f32_32x32x16_bf16 v[48:63], v[184:187], v[192:195], v[48:63]
	v_mfma_f32_32x32x16_bf16 v[16:31], v[184:187], v[196:199], v[16:31]
	v_mfma_f32_32x32x16_bf16 v[32:47], v[188:191], v[192:195], v[32:47]
	v_mfma_f32_32x32x16_bf16 v[0:15], v[188:191], v[196:199], v[0:15]
	ds_read_b128 v[132:135], v117 offset:32768
	ds_read_b128 v[136:139], v117 offset:36864
	ds_read_b128 v[152:155], v118
	ds_read_b128 v[156:159], v118 offset:4096
	s_waitcnt vmcnt(6)
	s_waitcnt lgkmcnt(0)
	s_barrier
; #define MFMA(a, b, c) __builtin_amdgcn_mfma_f32_32x32x16_bf16((a), (b), (c), 0, 0, 0)
; #define WAIT_V(n) asm volatile("s_waitcnt vmcnt(%0)" ::"n"(n) : "memory")
; #define RAW_BARRIER() do { asm volatile("s_waitcnt lgkmcnt(0)" ::: "memory"); __builtin_amdgcn_s_barrier(); asm volatile("" ::: "memory"); } while (0)
; #define GLDS_STAGE(slot, kt) do { _Pragma("unroll") for (int i = 0; i < 6; ++i) \
;     __builtin_amdgcn_global_load_lds((const unsigned*)(src[i] + (kt) * 64), (__attribute__((address_space(3))) unsigned*)(smem + (slot) * G_STAGE + (wave + 8 * i) * 1024), 16, 0, 0); } while (0)
; DI void gemm_tile(const u16* __restrict__ X, int ldx, const u16* __restrict__ Wt, int ldw, int K, char* smem,
;                   f32x16 (&acc)[2][2]) {
;     ...
;   for (int kt = 0; kt < nk; ++kt) {
;     const int nxt = (cur >= 1) ? cur - 1 : 2;
;     if (kt + 2 < nk) GLDS_STAGE(nxt, kt + 2);
;     __builtin_amdgcn_sched_barrier(0);
;     const char* st = smem + cur * G_STAGE;
; #pragma unroll
;     for (int ks = 0; ks < 4; ++ks) {
;       bf16x8 a[2], b[2];
; #pragma unroll
;       for (int ft = 0; ft < 2; ++ft) a[ft] = *reinterpret_cast<const bf16x8*>(st + offA[ft] + (((ks * 2 + lh) ^ xa[ft]) << 4));
; #pragma unroll
;       for (int tt = 0; tt < 2; ++tt) b[tt] = *reinterpret_cast<const bf16x8*>(st + offB[tt] + (((ks * 2 + lh) ^ xb[tt]) << 4));
; #pragma unroll
;       for (int ft = 0; ft < 2; ++ft)
; #pragma unroll
;         for (int tt = 0; tt < 2; ++tt) acc[ft][tt] = MFMA(a[ft], b[tt], acc[ft][tt]);
;     }
;     if (kt + 2 < nk) { WAIT_V(6); } else { WAIT_V(0); }
;     RAW_BARRIER();
;     cur = (cur == 2) ? 0 : cur + 1;
	s_waitcnt lgkmcnt(0)
	v_mfma_f32_32x32x16_bf16 v[48:63], v[132:135], v[152:155], v[48:63]
	v_mfma_f32_32x32x16_bf16 v[16:31], v[132:135], v[156:159], v[16:31]
	v_lshl_add_u64 v[132:133], v[80:81], 0, s[76:77]
	global_load_lds_dwordx4 v[132:133], off
	v_lshl_add_u64 v[132:133], v[80:81], 0, s[80:81]
	s_mov_b32 m0, s0
	s_nop 0
	global_load_lds_dwordx4 v[132:133], off
	v_lshl_add_u64 v[132:133], v[80:81], 0, s[8:9]
	s_mov_b32 m0, s1
	s_mov_b64 s[0:1], 0x60780
	global_load_lds_dwordx4 v[132:133], off
	v_lshl_add_u64 v[80:81], v[80:81], 0, s[0:1]
	s_mov_b32 m0, s5
	v_mfma_f32_32x32x16_bf16 v[0:15], v[136:139], v[156:159], v[0:15]
	global_load_lds_dwordx4 v[80:81], off
	v_lshl_add_u64 v[80:81], v[82:83], 0, s[76:77]
	s_mov_b32 m0, s4
	s_nop 0
	global_load_lds_dwordx4 v[80:81], off
	v_lshl_add_u64 v[80:81], v[82:83], 0, s[80:81]
	s_mov_b32 m0, s6
	v_mfma_f32_32x32x16_bf16 v[32:47], v[136:139], v[152:155], v[32:47]
	global_load_lds_dwordx4 v[80:81], off
	ds_read_b128 v[80:83], v119 offset:32768
	ds_read_b128 v[132:135], v112 offset:49152
	ds_read_b128 v[136:139], v112 offset:53248
	s_waitcnt lgkmcnt(0)
	v_mfma_f32_32x32x16_bf16 v[48:63], v[80:83], v[132:135], v[48:63]
	v_mfma_f32_32x32x16_bf16 v[16:31], v[80:83], v[136:139], v[16:31]
	ds_read_b128 v[80:83], v119 offset:36864
	s_waitcnt lgkmcnt(0)
	v_mfma_f32_32x32x16_bf16 v[32:47], v[80:83], v[132:135], v[32:47]
	v_mfma_f32_32x32x16_bf16 v[0:15], v[80:83], v[136:139], v[0:15]
	ds_read_b128 v[80:83], v120 offset:32768
	ds_read_b128 v[132:135], v114 offset:49152
	ds_read_b128 v[136:139], v114 offset:53248
	s_waitcnt lgkmcnt(0)
	v_mfma_f32_32x32x16_bf16 v[48:63], v[80:83], v[132:135], v[48:63]
	v_mfma_f32_32x32x16_bf16 v[16:31], v[80:83], v[136:139], v[16:31]
	ds_read_b128 v[80:83], v120 offset:36864
	s_waitcnt lgkmcnt(0)
	v_mfma_f32_32x32x16_bf16 v[32:47], v[80:83], v[132:135], v[32:47]
	v_mfma_f32_32x32x16_bf16 v[0:15], v[80:83], v[136:139], v[0:15]
	ds_read_b128 v[80:83], v121 offset:32768
	ds_read_b128 v[132:135], v116 offset:49152
	ds_read_b128 v[136:139], v116 offset:53248
	s_waitcnt lgkmcnt(0)
	v_mfma_f32_32x32x16_bf16 v[48:63], v[80:83], v[132:135], v[48:63]
	v_mfma_f32_32x32x16_bf16 v[16:31], v[80:83], v[136:139], v[16:31]
	ds_read_b128 v[80:83], v121 offset:36864
	s_waitcnt lgkmcnt(0)
	v_mfma_f32_32x32x16_bf16 v[32:47], v[80:83], v[132:135], v[32:47]
	v_mfma_f32_32x32x16_bf16 v[0:15], v[80:83], v[136:139], v[0:15]
	ds_read_b128 v[80:83], v122 offset:32768
	ds_read_b128 v[132:135], v118 offset:49152
	ds_read_b128 v[136:139], v118 offset:53248
	s_waitcnt lgkmcnt(0)
	v_mfma_f32_32x32x16_bf16 v[48:63], v[80:83], v[132:135], v[48:63]
	v_mfma_f32_32x32x16_bf16 v[16:31], v[80:83], v[136:139], v[16:31]
	ds_read_b128 v[80:83], v122 offset:36864
	s_waitcnt vmcnt(6)
	s_waitcnt lgkmcnt(0)
	s_barrier
; #define MFMA(a, b, c) __builtin_amdgcn_mfma_f32_32x32x16_bf16((a), (b), (c), 0, 0, 0)
; #define WAIT_V(n) asm volatile("s_waitcnt vmcnt(%0)" ::"n"(n) : "memory")
; #define RAW_BARRIER() do { asm volatile("s_waitcnt lgkmcnt(0)" ::: "memory"); __builtin_amdgcn_s_barrier(); asm volatile("" ::: "memory"); } while (0)
; #define GLDS_STAGE(slot, kt) do { _Pragma("unroll") for (int i = 0; i < 6; ++i) \
;     __builtin_amdgcn_global_load_lds((const unsigned*)(src[i] + (kt) * 64), (__attribute__((address_space(3))) unsigned*)(smem + (slot) * G_STAGE + (wave + 8 * i) * 1024), 16, 0, 0); } while (0)
; DI void gemm_tile(const u16* __restrict__ X, int ldx, const u16* __restrict__ Wt, int ldw, int K, char* smem,
;                   f32x16 (&acc)[2][2]) {
;     ...
;   for (int kt = 0; kt < nk; ++kt) {
;     const int nxt = (cur >= 1) ? cur - 1 : 2;
;     if (kt + 2 < nk) GLDS_STAGE(nxt, kt + 2);
;     __builtin_amdgcn_sched_barrier(0);
;     const char* st = smem + cur * G_STAGE;
; #pragma unroll
;     for (int ks = 0; ks < 4; ++ks) {
;       bf16x8 a[2], b[2];
; #pragma unroll
;       for (int ft = 0; ft < 2; ++ft) a[ft] = *reinterpret_cast<const bf16x8*>(st + offA[ft] + (((ks * 2 + lh) ^ xa[ft]) << 4));
; #pragma unroll
;       for (int tt = 0; tt < 2; ++tt) b[tt] = *reinterpret_cast<const bf16x8*>(st + offB[tt] + (((ks * 2 + lh) ^ xb[tt]) << 4));
; #pragma unroll
;       for (int ft = 0; ft < 2; ++ft)
; #pragma unroll
;         for (int tt = 0; tt < 2; ++tt) acc[ft][tt] = MFMA(a[ft], b[tt], acc[ft][tt]);
;     }
;     if (kt + 2 < nk) { WAIT_V(6); } else { WAIT_V(0); }
;     RAW_BARRIER();
;     cur = (cur == 2) ? 0 : cur + 1;
; template <int MODE>
; DI void phase_gemm(const Params& p, const u16* X, const u16* Wt, int N, const float* resid, float* outf, u16* outb, int ldo, char* smem) {
;     ...
;       float* wl = (float*)(smem + wave * 17408);
; #pragma unroll
;       for (int tt = 0; tt < 2; ++tt)
; #pragma unroll
;         for (int ft = 0; ft < 2; ++ft)
; #pragma unroll
;           for (int g = 0; g < 4; ++g) {
;             f32x4 v = {acc[ft][tt][4 * g], acc[ft][tt][4 * g + 1], acc[ft][tt][4 * g + 2], acc[ft][tt][4 * g + 3]};
;             *reinterpret_cast<f32x4*>(wl + (tt * 32 + lr) * 68 + ft * 32 + 8 * g + 4 * lh) = v;
;           }
	s_waitcnt lgkmcnt(0)
	v_mfma_f32_32x32x16_bf16 v[0:15], v[80:83], v[136:139], v[0:15]
	v_mfma_f32_32x32x16_bf16 v[32:47], v[80:83], v[132:135], v[32:47]
	ds_read_b128 v[80:83], v123 offset:32768
	ds_read_b128 v[132:135], v124
	ds_read_b128 v[136:139], v124 offset:4096
	s_waitcnt lgkmcnt(0)
	v_mfma_f32_32x32x16_bf16 v[48:63], v[80:83], v[132:135], v[48:63]
	v_mfma_f32_32x32x16_bf16 v[16:31], v[80:83], v[136:139], v[16:31]
	ds_read_b128 v[80:83], v123 offset:36864
	s_waitcnt lgkmcnt(0)
	v_mfma_f32_32x32x16_bf16 v[32:47], v[80:83], v[132:135], v[32:47]
	v_mfma_f32_32x32x16_bf16 v[0:15], v[80:83], v[136:139], v[0:15]
	ds_read_b128 v[80:83], v125 offset:32768
	ds_read_b128 v[132:135], v126
	ds_read_b128 v[136:139], v126 offset:4096
	s_waitcnt lgkmcnt(0)
	v_mfma_f32_32x32x16_bf16 v[48:63], v[80:83], v[132:135], v[48:63]
	v_mfma_f32_32x32x16_bf16 v[16:31], v[80:83], v[136:139], v[16:31]
	ds_read_b128 v[80:83], v125 offset:36864
	s_waitcnt lgkmcnt(0)
	v_mfma_f32_32x32x16_bf16 v[32:47], v[80:83], v[132:135], v[32:47]
	v_mfma_f32_32x32x16_bf16 v[0:15], v[80:83], v[136:139], v[0:15]
	ds_read_b128 v[80:83], v127 offset:32768
	ds_read_b128 v[132:135], v128
	ds_read_b128 v[136:139], v128 offset:4096
	s_waitcnt lgkmcnt(0)
	v_mfma_f32_32x32x16_bf16 v[48:63], v[80:83], v[132:135], v[48:63]
	v_mfma_f32_32x32x16_bf16 v[16:31], v[80:83], v[136:139], v[16:31]
	ds_read_b128 v[80:83], v127 offset:36864
	s_waitcnt lgkmcnt(0)
	v_mfma_f32_32x32x16_bf16 v[32:47], v[80:83], v[132:135], v[32:47]
	v_mfma_f32_32x32x16_bf16 v[0:15], v[80:83], v[136:139], v[0:15]
	ds_read_b128 v[80:83], v129 offset:32768
	ds_read_b128 v[132:135], v130
	ds_read_b128 v[136:139], v130 offset:4096
	s_waitcnt lgkmcnt(0)
	v_mfma_f32_32x32x16_bf16 v[48:63], v[80:83], v[132:135], v[48:63]
	v_mfma_f32_32x32x16_bf16 v[16:31], v[80:83], v[136:139], v[16:31]
	ds_read_b128 v[80:83], v129 offset:36864
	s_waitcnt vmcnt(0)
	s_waitcnt lgkmcnt(0)
	s_barrier
	s_waitcnt lgkmcnt(0)
	v_mfma_f32_32x32x16_bf16 v[0:15], v[80:83], v[136:139], v[0:15]
	v_mfma_f32_32x32x16_bf16 v[32:47], v[80:83], v[132:135], v[32:47]
	ds_read_b128 v[80:83], v111 offset:32768
	ds_read_b128 v[132:135], v112
	ds_read_b128 v[136:139], v111 offset:36864
	ds_read_b128 v[152:155], v112 offset:4096
	s_mov_b64 s[54:55], 0
	s_waitcnt lgkmcnt(0)
	v_mfma_f32_32x32x16_bf16 v[48:63], v[80:83], v[132:135], v[48:63]
	v_mfma_f32_32x32x16_bf16 v[32:47], v[136:139], v[132:135], v[32:47]
	v_mfma_f32_32x32x16_bf16 v[0:15], v[136:139], v[152:155], v[0:15]
	v_mfma_f32_32x32x16_bf16 v[16:31], v[80:83], v[152:155], v[16:31]
	ds_read_b128 v[80:83], v113 offset:32768
	ds_read_b128 v[132:135], v114
	ds_read_b128 v[136:139], v113 offset:36864
	ds_read_b128 v[152:155], v114 offset:4096
	s_waitcnt lgkmcnt(0)
	v_mfma_f32_32x32x16_bf16 v[48:63], v[80:83], v[132:135], v[48:63]
	v_mfma_f32_32x32x16_bf16 v[32:47], v[136:139], v[132:135], v[32:47]
	v_mfma_f32_32x32x16_bf16 v[0:15], v[136:139], v[152:155], v[0:15]
	v_mfma_f32_32x32x16_bf16 v[16:31], v[80:83], v[152:155], v[16:31]
	ds_read_b128 v[80:83], v115 offset:32768
	ds_read_b128 v[132:135], v116
	ds_read_b128 v[136:139], v115 offset:36864
	ds_read_b128 v[152:155], v116 offset:4096
	s_waitcnt lgkmcnt(0)
	v_mfma_f32_32x32x16_bf16 v[48:63], v[80:83], v[132:135], v[48:63]
	v_mfma_f32_32x32x16_bf16 v[32:47], v[136:139], v[132:135], v[32:47]
	v_mfma_f32_32x32x16_bf16 v[0:15], v[136:139], v[152:155], v[0:15]
	v_mfma_f32_32x32x16_bf16 v[16:31], v[80:83], v[152:155], v[16:31]
	ds_read_b128 v[80:83], v117 offset:32768
	ds_read_b128 v[132:135], v118
	ds_read_b128 v[136:139], v117 offset:36864
	ds_read_b128 v[152:155], v118 offset:4096
	s_waitcnt vmcnt(0)
	s_waitcnt lgkmcnt(0)
	s_barrier
	s_waitcnt lgkmcnt(0)
	v_mfma_f32_32x32x16_bf16 v[48:63], v[80:83], v[132:135], v[48:63]
	v_mfma_f32_32x32x16_bf16 v[32:47], v[136:139], v[132:135], v[32:47]
	s_nop 10
	ds_write_b128 v131, v[48:51]
	ds_write_b128 v131, v[52:55] offset:32
	ds_write_b128 v131, v[56:59] offset:64
	ds_write_b128 v131, v[60:63] offset:96
	ds_write_b128 v131, v[32:35] offset:128
	v_mfma_f32_32x32x16_bf16 v[0:15], v[136:139], v[152:155], v[0:15]
	v_mfma_f32_32x32x16_bf16 v[16:31], v[80:83], v[152:155], v[16:31]
	ds_write_b128 v131, v[36:39] offset:160
	ds_write_b128 v131, v[40:43] offset:192
	ds_write_b128 v131, v[44:47] offset:224
	s_nop 8
	ds_write_b128 v131, v[16:19] offset:8704
	ds_write_b128 v131, v[20:23] offset:8736
	ds_write_b128 v131, v[24:27] offset:8768
	ds_write_b128 v131, v[28:31] offset:8800
	ds_write_b128 v131, v[0:3] offset:8832
	ds_write_b128 v131, v[4:7] offset:8864
	ds_write_b128 v131, v[8:11] offset:8896
	ds_write_b128 v131, v[12:15] offset:8928
	v_mov_b32_e32 v0, v95

; #define WAIT_V(n) asm volatile("s_waitcnt vmcnt(%0)" ::"n"(n) : "memory")
; #define RAW_BARRIER() do { asm volatile("s_waitcnt lgkmcnt(0)" ::: "memory"); __builtin_amdgcn_s_barrier(); asm volatile("" ::: "memory"); } while (0)
; #define GLDS_STAGE(slot, kt) do { _Pragma("unroll") for (int i = 0; i < 6; ++i) \
;     __builtin_amdgcn_global_load_lds((const unsigned*)(src[i] + (kt) * 64), (__attribute__((address_space(3))) unsigned*)(smem + (slot) * G_STAGE + (wave + 8 * i) * 1024), 16, 0, 0); } while (0)
; DI void gemm_tile(const u16* __restrict__ X, int ldx, const u16* __restrict__ Wt, int ldw, int K, char* smem,
;                   f32x16 (&acc)[2][2]) {
;     ...
;   const int nk = K / 64;
;   const u16* src[6];
; #pragma unroll
;   for (int i = 0; i < 6; ++i) {
;     const int R = 8 * (wave + 8 * i) + (lane >> 3);
;     const int c = (lane & 7) ^ ((R >> 1) & 7);
;     src[i] = (i < 4) ? (X + (size_t)R * ldx + c * 8) : (Wt + (size_t)(R - 256) * ldw + c * 8);
;   }
;     ...
;   int offA[2], offB[2], xa[2], xb[2];
; #pragma unroll
;   for (int ft = 0; ft < 2; ++ft) { const int R = 256 + fw * 64 + ft * 32 + lr; offA[ft] = R * 128; xa[ft] = (R >> 1) & 7; }
; #pragma unroll
;   for (int tt = 0; tt < 2; ++tt) { const int R = tq * 64 + tt * 32 + lr; offB[tt] = R * 128; xb[tt] = (R >> 1) & 7; }
;   GLDS_STAGE(0, 0); GLDS_STAGE(1, 1); WAIT_V(6); RAW_BARRIER();
;   int cur = 0;
;   for (int kt = 0; kt < nk; ++kt) {
;     const int nxt = (cur >= 1) ? cur - 1 : 2;
;     if (kt + 2 < nk) GLDS_STAGE(nxt, kt + 2);
; template <int MODE>
; DI void phase_gemm(const Params& p, const u16* X, const u16* Wt, int N, const float* resid, float* outf, u16* outb, int ldo, char* smem) {
;     ...
;   const int xg = blockIdx.x & 7, xi = blockIdx.x >> 3, xn = gridDim.x >> 3;
;   const int per_group = 16 * ntn;
;   for (int u = xi; u < per_group; u += xn) {
;     const int mt = xg + 8 * (u / ntn), nt = u % ntn;
;     f32x16 acc[2][2];
;     gemm_tile(X + (size_t)mt * 256 * 1024, 1024, Wt + (size_t)nt * 128 * 1024, 1024, 1024, smem, acc);
.LBB0_906:
	s_lshr_b32 s98, s3, 6
	s_lshl_b32 s98, s98, 6
	s_and_b32 s99, s3, 3
	s_lshl_b32 s99, s99, 4
	s_add_i32 s98, s98, s99
	s_bfe_u32 s99, s3, 0x40002
	s_add_i32 s98, s98, s99
	s_lshl_b32 s99, s98, 17
	s_lshr_b32 s0, s98, 1
	s_and_b32 s0, s0, 0x78
	s_or_b32 s76, s0, s33
	s_and_b32 s6, s99, 0x1e0000
	s_lshl_b32 s0, s76, 19
	v_lshl_add_u64 v[0:1], v[106:107], 0, s[0:1]
	s_lshl_b32 s0, s6, 1
	v_readfirstlane_b32 s6, v143
	v_lshl_add_u64 v[64:65], v[0:1], 0, v[122:123]
	s_mov_b32 m0, s6
	v_readfirstlane_b32 s85, v131
	v_lshl_add_u64 v[0:1], v[64:65], 0, s[8:9]
	s_mov_b64 s[4:5], 0x40000
	global_load_lds_dwordx4 v[64:65], off
	s_mov_b32 m0, s85
	v_readfirstlane_b32 s84, v132
	v_lshl_add_u64 v[2:3], v[64:65], 0, s[4:5]
	s_mov_b64 s[4:5], 0x60000
	global_load_lds_dwordx4 v[0:1], off
	s_mov_b32 m0, s84
	v_readfirstlane_b32 s81, v133
	v_lshl_add_u64 v[4:5], v[64:65], 0, s[4:5]
	v_lshl_add_u64 v[6:7], v[108:109], 0, s[0:1]
	global_load_lds_dwordx4 v[2:3], off
	s_mov_b32 m0, s81
	v_readfirstlane_b32 s80, v134
	v_lshl_add_u64 v[66:67], v[6:7], 0, v[122:123]
	global_load_lds_dwordx4 v[4:5], off
	s_mov_b32 m0, s80
	v_readfirstlane_b32 s79, v135
	v_lshl_add_u64 v[6:7], v[66:67], 0, s[8:9]
	global_load_lds_dwordx4 v[66:67], off
	s_mov_b32 m0, s79
	v_readfirstlane_b32 s77, v115
	global_load_lds_dwordx4 v[6:7], off
	v_lshl_add_u64 v[0:1], v[64:65], 0, s[10:11]
	s_mov_b32 m0, s77
	v_readfirstlane_b32 s0, v136
	global_load_lds_dwordx4 v[0:1], off
	v_lshl_add_u64 v[0:1], v[64:65], 0, s[12:13]
	s_mov_b32 m0, s0
	s_mov_b64 s[4:5], 0x40080
	global_load_lds_dwordx4 v[0:1], off
	v_lshl_add_u64 v[0:1], v[64:65], 0, s[4:5]
	v_readfirstlane_b32 s4, v137
	s_mov_b32 m0, s4
	s_mov_b64 s[4:5], 0x60080
	global_load_lds_dwordx4 v[0:1], off
	v_lshl_add_u64 v[0:1], v[64:65], 0, s[4:5]
	v_readfirstlane_b32 s4, v138
	s_mov_b32 m0, s4
	v_readfirstlane_b32 s4, v139
	global_load_lds_dwordx4 v[0:1], off
	v_lshl_add_u64 v[0:1], v[66:67], 0, s[10:11]
	s_mov_b32 m0, s4
	v_readfirstlane_b32 s4, v144
	global_load_lds_dwordx4 v[0:1], off
	v_lshl_add_u64 v[0:1], v[66:67], 0, s[12:13]
	s_mov_b32 m0, s4
	v_readfirstlane_b32 s4, v117
	global_load_lds_dwordx4 v[0:1], off
	s_waitcnt vmcnt(6)
	s_waitcnt lgkmcnt(0)
	s_barrier
	v_lshl_add_u64 v[0:1], v[64:65], 0, s[14:15]
	s_mov_b32 m0, s4
	v_readfirstlane_b32 s91, v119
	global_load_lds_dwordx4 v[0:1], off
	v_lshl_add_u64 v[0:1], v[64:65], 0, s[16:17]
	s_mov_b32 m0, s91
	s_mov_b64 s[46:47], 0x40100
	v_readfirstlane_b32 s89, v121
	global_load_lds_dwordx4 v[0:1], off
	v_lshl_add_u64 v[0:1], v[64:65], 0, s[46:47]
	s_mov_b32 m0, s89
	s_mov_b64 s[46:47], 0x60100
	v_readfirstlane_b32 s90, v124
	global_load_lds_dwordx4 v[0:1], off
	v_lshl_add_u64 v[0:1], v[64:65], 0, s[46:47]
	s_mov_b32 m0, s90
	v_readfirstlane_b32 s47, v125
	global_load_lds_dwordx4 v[0:1], off
	v_lshl_add_u64 v[0:1], v[66:67], 0, s[14:15]
	s_mov_b32 m0, s47
	v_readfirstlane_b32 s88, v126
	global_load_lds_dwordx4 v[0:1], off
	v_lshl_add_u64 v[0:1], v[66:67], 0, s[16:17]
	s_mov_b32 m0, s88
	s_nop 0
	global_load_lds_dwordx4 v[0:1], off
	ds_read_b128 v[0:3], v145 offset:32768
	ds_read_b128 v[4:7], v145 offset:36864
	ds_read_b128 v[8:11], v146
	ds_read_b128 v[12:15], v146 offset:4096
	ds_read_b128 v[68:71], v147 offset:32768
	ds_read_b128 v[72:75], v147 offset:36864
	ds_read_b128 v[76:79], v148
	ds_read_b128 v[80:83], v148 offset:4096
	s_mov_b32 m0, s6
	s_mov_b64 s[86:87], 0x40180
	s_waitcnt lgkmcnt(0)
	v_mfma_f32_32x32x16_bf16 v[48:63], v[0:3], v[8:11], 0
	v_mfma_f32_32x32x16_bf16 v[16:31], v[0:3], v[12:15], 0
	v_mfma_f32_32x32x16_bf16 v[32:47], v[4:7], v[8:11], 0
	v_mfma_f32_32x32x16_bf16 v[0:15], v[4:7], v[12:15], 0
	ds_read_b128 v[184:187], v149 offset:32768
	ds_read_b128 v[188:191], v149 offset:36864
	ds_read_b128 v[192:195], v150
	ds_read_b128 v[196:199], v150 offset:4096
	s_waitcnt lgkmcnt(4)
	v_mfma_f32_32x32x16_bf16 v[48:63], v[68:71], v[76:79], v[48:63]
	v_mfma_f32_32x32x16_bf16 v[16:31], v[68:71], v[80:83], v[16:31]
	v_mfma_f32_32x32x16_bf16 v[32:47], v[72:75], v[76:79], v[32:47]
	v_mfma_f32_32x32x16_bf16 v[0:15], v[72:75], v[80:83], v[0:15]
	ds_read_b128 v[68:71], v151 offset:32768
	ds_read_b128 v[72:75], v151 offset:36864
	ds_read_b128 v[76:79], v152
	ds_read_b128 v[80:83], v152 offset:4096
	s_waitcnt lgkmcnt(4)
	v_mfma_f32_32x32x16_bf16 v[48:63], v[184:187], v[192:195], v[48:63]
	v_mfma_f32_32x32x16_bf16 v[16:31], v[184:187], v[196:199], v[16:31]
	v_mfma_f32_32x32x16_bf16 v[32:47], v[188:191], v[192:195], v[32:47]
	v_mfma_f32_32x32x16_bf16 v[0:15], v[188:191], v[196:199], v[0:15]
	s_waitcnt vmcnt(6)
	s_waitcnt lgkmcnt(0)
	s_barrier
; #define MFMA(a, b, c) __builtin_amdgcn_mfma_f32_32x32x16_bf16((a), (b), (c), 0, 0, 0)
; #define WAIT_V(n) asm volatile("s_waitcnt vmcnt(%0)" ::"n"(n) : "memory")
; #define RAW_BARRIER() do { asm volatile("s_waitcnt lgkmcnt(0)" ::: "memory"); __builtin_amdgcn_s_barrier(); asm volatile("" ::: "memory"); } while (0)
; #define GLDS_STAGE(slot, kt) do { _Pragma("unroll") for (int i = 0; i < 6; ++i) \
;     __builtin_amdgcn_global_load_lds((const unsigned*)(src[i] + (kt) * 64), (__attribute__((address_space(3))) unsigned*)(smem + (slot) * G_STAGE + (wave + 8 * i) * 1024), 16, 0, 0); } while (0)
; DI void gemm_tile(const u16* __restrict__ X, int ldx, const u16* __restrict__ Wt, int ldw, int K, char* smem,
;                   f32x16 (&acc)[2][2]) {
;     ...
;   for (int kt = 0; kt < nk; ++kt) {
;     const int nxt = (cur >= 1) ? cur - 1 : 2;
;     if (kt + 2 < nk) GLDS_STAGE(nxt, kt + 2);
;     __builtin_amdgcn_sched_barrier(0);
;     const char* st = smem + cur * G_STAGE;
; #pragma unroll
;     for (int ks = 0; ks < 4; ++ks) {
;       bf16x8 a[2], b[2];
; #pragma unroll
;       for (int ft = 0; ft < 2; ++ft) a[ft] = *reinterpret_cast<const bf16x8*>(st + offA[ft] + (((ks * 2 + lh) ^ xa[ft]) << 4));
; #pragma unroll
;       for (int tt = 0; tt < 2; ++tt) b[tt] = *reinterpret_cast<const bf16x8*>(st + offB[tt] + (((ks * 2 + lh) ^ xb[tt]) << 4));
; #pragma unroll
;       for (int ft = 0; ft < 2; ++ft)
; #pragma unroll
;         for (int tt = 0; tt < 2; ++tt) acc[ft][tt] = MFMA(a[ft], b[tt], acc[ft][tt]);
;     }
;     if (kt + 2 < nk) { WAIT_V(6); } else { WAIT_V(0); }
;     RAW_BARRIER();
;     cur = (cur == 2) ? 0 : cur + 1;
	ds_read_b128 v[184:187], v153 offset:32768
	ds_read_b128 v[188:191], v153 offset:36864
	ds_read_b128 v[192:195], v146 offset:49152
	ds_read_b128 v[196:199], v146 offset:53248
	s_waitcnt lgkmcnt(4)
	v_mfma_f32_32x32x16_bf16 v[48:63], v[68:71], v[76:79], v[48:63]
	v_mfma_f32_32x32x16_bf16 v[16:31], v[68:71], v[80:83], v[16:31]
	v_lshl_add_u64 v[68:69], v[64:65], 0, s[18:19]
	global_load_lds_dwordx4 v[68:69], off
	v_mfma_f32_32x32x16_bf16 v[32:47], v[72:75], v[76:79], v[32:47]
	v_mfma_f32_32x32x16_bf16 v[0:15], v[72:75], v[80:83], v[0:15]
	v_lshl_add_u64 v[68:69], v[64:65], 0, s[20:21]
	s_mov_b32 m0, s85
	s_nop 0
	global_load_lds_dwordx4 v[68:69], off
	ds_read_b128 v[68:71], v154 offset:32768
	ds_read_b128 v[72:75], v154 offset:36864
	ds_read_b128 v[76:79], v148 offset:49152
	ds_read_b128 v[80:83], v148 offset:53248
	s_waitcnt lgkmcnt(4)
	v_mfma_f32_32x32x16_bf16 v[48:63], v[184:187], v[192:195], v[48:63]
	v_mfma_f32_32x32x16_bf16 v[16:31], v[184:187], v[196:199], v[16:31]
	v_lshl_add_u64 v[252:253], v[64:65], 0, s[86:87]
	s_mov_b32 m0, s84
	s_mov_b64 s[86:87], 0x60180
	global_load_lds_dwordx4 v[252:253], off
	v_mfma_f32_32x32x16_bf16 v[32:47], v[188:191], v[192:195], v[32:47]
	v_mfma_f32_32x32x16_bf16 v[0:15], v[188:191], v[196:199], v[0:15]
	v_lshl_add_u64 v[252:253], v[64:65], 0, s[86:87]
	s_mov_b32 m0, s81
	s_nop 0
	global_load_lds_dwordx4 v[252:253], off
	ds_read_b128 v[184:187], v155 offset:32768
	ds_read_b128 v[188:191], v155 offset:36864
	ds_read_b128 v[192:195], v150 offset:49152
	ds_read_b128 v[196:199], v150 offset:53248
	s_waitcnt lgkmcnt(4)
	v_mfma_f32_32x32x16_bf16 v[48:63], v[68:71], v[76:79], v[48:63]
	v_mfma_f32_32x32x16_bf16 v[16:31], v[68:71], v[80:83], v[16:31]
	v_lshl_add_u64 v[252:253], v[66:67], 0, s[18:19]
	s_mov_b32 m0, s80
	s_nop 0
	global_load_lds_dwordx4 v[252:253], off
	v_mfma_f32_32x32x16_bf16 v[32:47], v[72:75], v[76:79], v[32:47]
	v_mfma_f32_32x32x16_bf16 v[0:15], v[72:75], v[80:83], v[0:15]
	v_lshl_add_u64 v[252:253], v[66:67], 0, s[20:21]
	s_mov_b32 m0, s79
	s_nop 0
	global_load_lds_dwordx4 v[252:253], off
	s_mov_b32 m0, s77
	s_mov_b64 s[86:87], 0x40200
	v_readfirstlane_b32 s7, v127
	v_readfirstlane_b32 s46, v130
	ds_read_b128 v[68:71], v156 offset:32768
	ds_read_b128 v[72:75], v156 offset:36864
	ds_read_b128 v[76:79], v152 offset:49152
	ds_read_b128 v[80:83], v152 offset:53248
	s_waitcnt lgkmcnt(4)
	v_mfma_f32_32x32x16_bf16 v[48:63], v[184:187], v[192:195], v[48:63]
	v_mfma_f32_32x32x16_bf16 v[16:31], v[184:187], v[196:199], v[16:31]
	v_mfma_f32_32x32x16_bf16 v[32:47], v[188:191], v[192:195], v[32:47]
	v_mfma_f32_32x32x16_bf16 v[0:15], v[188:191], v[196:199], v[0:15]
	s_waitcnt vmcnt(6)
	s_waitcnt lgkmcnt(0)
	s_barrier
	ds_read_b128 v[184:187], v157 offset:32768
	ds_read_b128 v[188:191], v157 offset:36864
	ds_read_b128 v[192:195], v158
	ds_read_b128 v[196:199], v158 offset:4096
	s_waitcnt lgkmcnt(4)
	v_mfma_f32_32x32x16_bf16 v[48:63], v[68:71], v[76:79], v[48:63]
	v_mfma_f32_32x32x16_bf16 v[16:31], v[68:71], v[80:83], v[16:31]
	v_lshl_add_u64 v[68:69], v[64:65], 0, s[22:23]
	global_load_lds_dwordx4 v[68:69], off
	v_mfma_f32_32x32x16_bf16 v[32:47], v[72:75], v[76:79], v[32:47]
	v_mfma_f32_32x32x16_bf16 v[0:15], v[72:75], v[80:83], v[0:15]
	v_lshl_add_u64 v[68:69], v[64:65], 0, s[24:25]
	s_mov_b32 m0, s0
	s_nop 0
	global_load_lds_dwordx4 v[68:69], off
	ds_read_b128 v[68:71], v159 offset:32768
	ds_read_b128 v[72:75], v159 offset:36864
	ds_read_b128 v[76:79], v160
	ds_read_b128 v[80:83], v160 offset:4096
	s_waitcnt lgkmcnt(4)
	v_mfma_f32_32x32x16_bf16 v[48:63], v[184:187], v[192:195], v[48:63]
	v_mfma_f32_32x32x16_bf16 v[16:31], v[184:187], v[196:199], v[16:31]
	v_lshl_add_u64 v[252:253], v[64:65], 0, s[86:87]
	s_mov_b32 m0, s7
	s_mov_b64 s[86:87], 0x60200
	global_load_lds_dwordx4 v[252:253], off
	v_mfma_f32_32x32x16_bf16 v[32:47], v[188:191], v[192:195], v[32:47]
	v_mfma_f32_32x32x16_bf16 v[0:15], v[188:191], v[196:199], v[0:15]
	v_lshl_add_u64 v[252:253], v[64:65], 0, s[86:87]
	v_readfirstlane_b32 s87, v128
	s_mov_b32 m0, s87
	v_readfirstlane_b32 s86, v129
	global_load_lds_dwordx4 v[252:253], off
	ds_read_b128 v[184:187], v161 offset:32768
	ds_read_b128 v[188:191], v161 offset:36864
	ds_read_b128 v[192:195], v163
	ds_read_b128 v[196:199], v163 offset:4096
	s_waitcnt lgkmcnt(4)
	v_mfma_f32_32x32x16_bf16 v[48:63], v[68:71], v[76:79], v[48:63]
	v_mfma_f32_32x32x16_bf16 v[16:31], v[68:71], v[80:83], v[16:31]
	v_lshl_add_u64 v[252:253], v[66:67], 0, s[22:23]
	s_mov_b32 m0, s86
	s_nop 0
	global_load_lds_dwordx4 v[252:253], off
	v_mfma_f32_32x32x16_bf16 v[32:47], v[72:75], v[76:79], v[32:47]
	v_mfma_f32_32x32x16_bf16 v[0:15], v[72:75], v[80:83], v[0:15]
	v_lshl_add_u64 v[252:253], v[66:67], 0, s[24:25]
	s_mov_b32 m0, s46
	s_nop 0
	global_load_lds_dwordx4 v[252:253], off
	s_mov_b32 m0, s4
	s_mov_b64 s[92:93], 0x40280
	ds_read_b128 v[68:71], v165 offset:32768
	ds_read_b128 v[72:75], v165 offset:36864
	ds_read_b128 v[76:79], v167
	ds_read_b128 v[80:83], v167 offset:4096
	s_waitcnt lgkmcnt(4)
	v_mfma_f32_32x32x16_bf16 v[48:63], v[184:187], v[192:195], v[48:63]
	v_mfma_f32_32x32x16_bf16 v[16:31], v[184:187], v[196:199], v[16:31]
	v_mfma_f32_32x32x16_bf16 v[32:47], v[188:191], v[192:195], v[32:47]
	v_mfma_f32_32x32x16_bf16 v[0:15], v[188:191], v[196:199], v[0:15]
	s_waitcnt vmcnt(6)
	s_waitcnt lgkmcnt(0)
	s_barrier
; #define MFMA(a, b, c) __builtin_amdgcn_mfma_f32_32x32x16_bf16((a), (b), (c), 0, 0, 0)
; #define WAIT_V(n) asm volatile("s_waitcnt vmcnt(%0)" ::"n"(n) : "memory")
; #define RAW_BARRIER() do { asm volatile("s_waitcnt lgkmcnt(0)" ::: "memory"); __builtin_amdgcn_s_barrier(); asm volatile("" ::: "memory"); } while (0)
; #define GLDS_STAGE(slot, kt) do { _Pragma("unroll") for (int i = 0; i < 6; ++i) \
;     __builtin_amdgcn_global_load_lds((const unsigned*)(src[i] + (kt) * 64), (__attribute__((address_space(3))) unsigned*)(smem + (slot) * G_STAGE + (wave + 8 * i) * 1024), 16, 0, 0); } while (0)
; DI void gemm_tile(const u16* __restrict__ X, int ldx, const u16* __restrict__ Wt, int ldw, int K, char* smem,
;                   f32x16 (&acc)[2][2]) {
;     ...
;   for (int kt = 0; kt < nk; ++kt) {
;     const int nxt = (cur >= 1) ? cur - 1 : 2;
;     if (kt + 2 < nk) GLDS_STAGE(nxt, kt + 2);
;     __builtin_amdgcn_sched_barrier(0);
;     const char* st = smem + cur * G_STAGE;
; #pragma unroll
;     for (int ks = 0; ks < 4; ++ks) {
;       bf16x8 a[2], b[2];
; #pragma unroll
;       for (int ft = 0; ft < 2; ++ft) a[ft] = *reinterpret_cast<const bf16x8*>(st + offA[ft] + (((ks * 2 + lh) ^ xa[ft]) << 4));
; #pragma unroll
;       for (int tt = 0; tt < 2; ++tt) b[tt] = *reinterpret_cast<const bf16x8*>(st + offB[tt] + (((ks * 2 + lh) ^ xb[tt]) << 4));
; #pragma unroll
;       for (int ft = 0; ft < 2; ++ft)
; #pragma unroll
;         for (int tt = 0; tt < 2; ++tt) acc[ft][tt] = MFMA(a[ft], b[tt], acc[ft][tt]);
;     }
;     if (kt + 2 < nk) { WAIT_V(6); } else { WAIT_V(0); }
;     RAW_BARRIER();
;     cur = (cur == 2) ? 0 : cur + 1;
	ds_read_b128 v[184:187], v145 offset:32768
	ds_read_b128 v[188:191], v145 offset:36864
	ds_read_b128 v[192:195], v146
	ds_read_b128 v[196:199], v146 offset:4096
	s_waitcnt lgkmcnt(4)
	v_mfma_f32_32x32x16_bf16 v[48:63], v[68:71], v[76:79], v[48:63]
	v_mfma_f32_32x32x16_bf16 v[16:31], v[68:71], v[80:83], v[16:31]
	v_lshl_add_u64 v[68:69], v[64:65], 0, s[26:27]
	global_load_lds_dwordx4 v[68:69], off
	v_mfma_f32_32x32x16_bf16 v[32:47], v[72:75], v[76:79], v[32:47]
	v_mfma_f32_32x32x16_bf16 v[0:15], v[72:75], v[80:83], v[0:15]
	v_lshl_add_u64 v[68:69], v[64:65], 0, s[28:29]
	s_mov_b32 m0, s91
	s_nop 0
	global_load_lds_dwordx4 v[68:69], off
	ds_read_b128 v[68:71], v147 offset:32768
	ds_read_b128 v[72:75], v147 offset:36864
	ds_read_b128 v[76:79], v148
	ds_read_b128 v[80:83], v148 offset:4096
	s_waitcnt lgkmcnt(4)
	v_mfma_f32_32x32x16_bf16 v[48:63], v[184:187], v[192:195], v[48:63]
	v_mfma_f32_32x32x16_bf16 v[16:31], v[184:187], v[196:199], v[16:31]
	v_lshl_add_u64 v[252:253], v[64:65], 0, s[92:93]
	s_mov_b32 m0, s89
	s_mov_b64 s[92:93], 0x60280
	global_load_lds_dwordx4 v[252:253], off
	v_mfma_f32_32x32x16_bf16 v[32:47], v[188:191], v[192:195], v[32:47]
	v_mfma_f32_32x32x16_bf16 v[0:15], v[188:191], v[196:199], v[0:15]
	v_lshl_add_u64 v[252:253], v[64:65], 0, s[92:93]
	s_mov_b32 m0, s90
	s_nop 0
	global_load_lds_dwordx4 v[252:253], off
	ds_read_b128 v[184:187], v149 offset:32768
	ds_read_b128 v[188:191], v149 offset:36864
	ds_read_b128 v[192:195], v150
	ds_read_b128 v[196:199], v150 offset:4096
	s_waitcnt lgkmcnt(4)
	v_mfma_f32_32x32x16_bf16 v[48:63], v[68:71], v[76:79], v[48:63]
	v_mfma_f32_32x32x16_bf16 v[16:31], v[68:71], v[80:83], v[16:31]
	v_lshl_add_u64 v[252:253], v[66:67], 0, s[26:27]
	s_mov_b32 m0, s47
	s_nop 0
	global_load_lds_dwordx4 v[252:253], off
	v_mfma_f32_32x32x16_bf16 v[32:47], v[72:75], v[76:79], v[32:47]
	v_mfma_f32_32x32x16_bf16 v[0:15], v[72:75], v[80:83], v[0:15]
	v_lshl_add_u64 v[252:253], v[66:67], 0, s[28:29]
	s_mov_b32 m0, s88
	s_nop 0
	global_load_lds_dwordx4 v[252:253], off
	s_mov_b32 m0, s6
	s_mov_b64 s[92:93], 0x40300
	ds_read_b128 v[68:71], v151 offset:32768
	ds_read_b128 v[72:75], v151 offset:36864
	ds_read_b128 v[76:79], v152
	ds_read_b128 v[80:83], v152 offset:4096
	s_waitcnt lgkmcnt(4)
	v_mfma_f32_32x32x16_bf16 v[48:63], v[184:187], v[192:195], v[48:63]
	v_mfma_f32_32x32x16_bf16 v[16:31], v[184:187], v[196:199], v[16:31]
	v_mfma_f32_32x32x16_bf16 v[32:47], v[188:191], v[192:195], v[32:47]
	v_mfma_f32_32x32x16_bf16 v[0:15], v[188:191], v[196:199], v[0:15]
	s_waitcnt vmcnt(6)
	s_waitcnt lgkmcnt(0)
	s_barrier
	ds_read_b128 v[184:187], v153 offset:32768
	ds_read_b128 v[188:191], v153 offset:36864
	ds_read_b128 v[192:195], v146 offset:49152
	ds_read_b128 v[196:199], v146 offset:53248
	s_waitcnt lgkmcnt(4)
	v_mfma_f32_32x32x16_bf16 v[48:63], v[68:71], v[76:79], v[48:63]
	v_mfma_f32_32x32x16_bf16 v[16:31], v[68:71], v[80:83], v[16:31]
	v_lshl_add_u64 v[68:69], v[64:65], 0, s[30:31]
	global_load_lds_dwordx4 v[68:69], off
	v_mfma_f32_32x32x16_bf16 v[32:47], v[72:75], v[76:79], v[32:47]
	v_mfma_f32_32x32x16_bf16 v[0:15], v[72:75], v[80:83], v[0:15]
	v_lshl_add_u64 v[68:69], v[64:65], 0, s[34:35]
	s_mov_b32 m0, s85
	s_nop 0
	global_load_lds_dwordx4 v[68:69], off
	ds_read_b128 v[68:71], v154 offset:32768
	ds_read_b128 v[72:75], v154 offset:36864
	ds_read_b128 v[76:79], v148 offset:49152
	ds_read_b128 v[80:83], v148 offset:53248
	s_waitcnt lgkmcnt(4)
	v_mfma_f32_32x32x16_bf16 v[48:63], v[184:187], v[192:195], v[48:63]
	v_mfma_f32_32x32x16_bf16 v[16:31], v[184:187], v[196:199], v[16:31]
	v_lshl_add_u64 v[252:253], v[64:65], 0, s[92:93]
	s_mov_b32 m0, s84
	s_mov_b64 s[92:93], 0x60300
	global_load_lds_dwordx4 v[252:253], off
	v_mfma_f32_32x32x16_bf16 v[32:47], v[188:191], v[192:195], v[32:47]
	v_mfma_f32_32x32x16_bf16 v[0:15], v[188:191], v[196:199], v[0:15]
	v_lshl_add_u64 v[252:253], v[64:65], 0, s[92:93]
	s_mov_b32 m0, s81
	s_nop 0
	global_load_lds_dwordx4 v[252:253], off
	ds_read_b128 v[184:187], v155 offset:32768
	ds_read_b128 v[188:191], v155 offset:36864
	ds_read_b128 v[192:195], v150 offset:49152
	ds_read_b128 v[196:199], v150 offset:53248
	s_waitcnt lgkmcnt(4)
	v_mfma_f32_32x32x16_bf16 v[48:63], v[68:71], v[76:79], v[48:63]
	v_mfma_f32_32x32x16_bf16 v[16:31], v[68:71], v[80:83], v[16:31]
	v_lshl_add_u64 v[252:253], v[66:67], 0, s[30:31]
	s_mov_b32 m0, s80
	s_nop 0
	global_load_lds_dwordx4 v[252:253], off
	v_mfma_f32_32x32x16_bf16 v[32:47], v[72:75], v[76:79], v[32:47]
	v_mfma_f32_32x32x16_bf16 v[0:15], v[72:75], v[80:83], v[0:15]
	v_lshl_add_u64 v[252:253], v[66:67], 0, s[34:35]
	s_mov_b32 m0, s79
	s_nop 0
	global_load_lds_dwordx4 v[252:253], off
	s_mov_b32 m0, s77
	s_mov_b64 s[92:93], 0x40380
	ds_read_b128 v[68:71], v156 offset:32768
	ds_read_b128 v[72:75], v156 offset:36864
	ds_read_b128 v[76:79], v152 offset:49152
	ds_read_b128 v[80:83], v152 offset:53248
	s_waitcnt lgkmcnt(4)
	v_mfma_f32_32x32x16_bf16 v[48:63], v[184:187], v[192:195], v[48:63]
	v_mfma_f32_32x32x16_bf16 v[16:31], v[184:187], v[196:199], v[16:31]
	v_mfma_f32_32x32x16_bf16 v[32:47], v[188:191], v[192:195], v[32:47]
	v_mfma_f32_32x32x16_bf16 v[0:15], v[188:191], v[196:199], v[0:15]
	s_waitcnt vmcnt(6)
	s_waitcnt lgkmcnt(0)
	s_barrier
; #define MFMA(a, b, c) __builtin_amdgcn_mfma_f32_32x32x16_bf16((a), (b), (c), 0, 0, 0)
; #define WAIT_V(n) asm volatile("s_waitcnt vmcnt(%0)" ::"n"(n) : "memory")
; #define RAW_BARRIER() do { asm volatile("s_waitcnt lgkmcnt(0)" ::: "memory"); __builtin_amdgcn_s_barrier(); asm volatile("" ::: "memory"); } while (0)
; #define GLDS_STAGE(slot, kt) do { _Pragma("unroll") for (int i = 0; i < 6; ++i) \
;     __builtin_amdgcn_global_load_lds((const unsigned*)(src[i] + (kt) * 64), (__attribute__((address_space(3))) unsigned*)(smem + (slot) * G_STAGE + (wave + 8 * i) * 1024), 16, 0, 0); } while (0)
; DI void gemm_tile(const u16* __restrict__ X, int ldx, const u16* __restrict__ Wt, int ldw, int K, char* smem,
;                   f32x16 (&acc)[2][2]) {
;     ...
;   for (int kt = 0; kt < nk; ++kt) {
;     const int nxt = (cur >= 1) ? cur - 1 : 2;
;     if (kt + 2 < nk) GLDS_STAGE(nxt, kt + 2);
;     __builtin_amdgcn_sched_barrier(0);
;     const char* st = smem + cur * G_STAGE;
; #pragma unroll
;     for (int ks = 0; ks < 4; ++ks) {
;       bf16x8 a[2], b[2];
; #pragma unroll
;       for (int ft = 0; ft < 2; ++ft) a[ft] = *reinterpret_cast<const bf16x8*>(st + offA[ft] + (((ks * 2 + lh) ^ xa[ft]) << 4));
; #pragma unroll
;       for (int tt = 0; tt < 2; ++tt) b[tt] = *reinterpret_cast<const bf16x8*>(st + offB[tt] + (((ks * 2 + lh) ^ xb[tt]) << 4));
; #pragma unroll
;       for (int ft = 0; ft < 2; ++ft)
; #pragma unroll
;         for (int tt = 0; tt < 2; ++tt) acc[ft][tt] = MFMA(a[ft], b[tt], acc[ft][tt]);
;     }
;     if (kt + 2 < nk) { WAIT_V(6); } else { WAIT_V(0); }
;     RAW_BARRIER();
;     cur = (cur == 2) ? 0 : cur + 1;
	ds_read_b128 v[184:187], v157 offset:32768
	ds_read_b128 v[188:191], v157 offset:36864
	ds_read_b128 v[192:195], v158
	ds_read_b128 v[196:199], v158 offset:4096
	s_waitcnt lgkmcnt(4)
	v_mfma_f32_32x32x16_bf16 v[48:63], v[68:71], v[76:79], v[48:63]
	v_mfma_f32_32x32x16_bf16 v[16:31], v[68:71], v[80:83], v[16:31]
	v_lshl_add_u64 v[68:69], v[64:65], 0, s[36:37]
	global_load_lds_dwordx4 v[68:69], off
	v_mfma_f32_32x32x16_bf16 v[32:47], v[72:75], v[76:79], v[32:47]
	v_mfma_f32_32x32x16_bf16 v[0:15], v[72:75], v[80:83], v[0:15]
	v_lshl_add_u64 v[68:69], v[64:65], 0, s[38:39]
	s_mov_b32 m0, s0
	s_nop 0
	global_load_lds_dwordx4 v[68:69], off
	ds_read_b128 v[68:71], v159 offset:32768
	ds_read_b128 v[72:75], v159 offset:36864
	ds_read_b128 v[76:79], v160
	ds_read_b128 v[80:83], v160 offset:4096
	s_waitcnt lgkmcnt(4)
	v_mfma_f32_32x32x16_bf16 v[48:63], v[184:187], v[192:195], v[48:63]
	v_mfma_f32_32x32x16_bf16 v[16:31], v[184:187], v[196:199], v[16:31]
	v_lshl_add_u64 v[252:253], v[64:65], 0, s[92:93]
	s_mov_b32 m0, s7
	s_mov_b64 s[92:93], 0x60380
	global_load_lds_dwordx4 v[252:253], off
	v_mfma_f32_32x32x16_bf16 v[32:47], v[188:191], v[192:195], v[32:47]
	v_mfma_f32_32x32x16_bf16 v[0:15], v[188:191], v[196:199], v[0:15]
	v_lshl_add_u64 v[252:253], v[64:65], 0, s[92:93]
	s_mov_b32 m0, s87
	s_nop 0
	global_load_lds_dwordx4 v[252:253], off
	ds_read_b128 v[184:187], v161 offset:32768
	ds_read_b128 v[188:191], v161 offset:36864
	ds_read_b128 v[192:195], v163
	ds_read_b128 v[196:199], v163 offset:4096
	s_waitcnt lgkmcnt(4)
	v_mfma_f32_32x32x16_bf16 v[48:63], v[68:71], v[76:79], v[48:63]
	v_mfma_f32_32x32x16_bf16 v[16:31], v[68:71], v[80:83], v[16:31]
	v_lshl_add_u64 v[252:253], v[66:67], 0, s[36:37]
	s_mov_b32 m0, s86
	s_nop 0
	global_load_lds_dwordx4 v[252:253], off
	v_mfma_f32_32x32x16_bf16 v[32:47], v[72:75], v[76:79], v[32:47]
	v_mfma_f32_32x32x16_bf16 v[0:15], v[72:75], v[80:83], v[0:15]
	v_lshl_add_u64 v[252:253], v[66:67], 0, s[38:39]
	s_mov_b32 m0, s46
	s_nop 0
	global_load_lds_dwordx4 v[252:253], off
	s_mov_b32 m0, s4
	s_mov_b64 s[4:5], 0x40400
	ds_read_b128 v[68:71], v165 offset:32768
	ds_read_b128 v[72:75], v165 offset:36864
	ds_read_b128 v[76:79], v167
	ds_read_b128 v[80:83], v167 offset:4096
	s_waitcnt lgkmcnt(4)
	v_mfma_f32_32x32x16_bf16 v[48:63], v[184:187], v[192:195], v[48:63]
	v_mfma_f32_32x32x16_bf16 v[16:31], v[184:187], v[196:199], v[16:31]
	v_mfma_f32_32x32x16_bf16 v[32:47], v[188:191], v[192:195], v[32:47]
	v_mfma_f32_32x32x16_bf16 v[0:15], v[188:191], v[196:199], v[0:15]
	s_waitcnt vmcnt(6)
	s_waitcnt lgkmcnt(0)
	s_barrier
	ds_read_b128 v[184:187], v145 offset:32768
	ds_read_b128 v[188:191], v145 offset:36864
	ds_read_b128 v[192:195], v146
	ds_read_b128 v[196:199], v146 offset:4096
	s_waitcnt lgkmcnt(4)
	v_mfma_f32_32x32x16_bf16 v[48:63], v[68:71], v[76:79], v[48:63]
	v_mfma_f32_32x32x16_bf16 v[16:31], v[68:71], v[80:83], v[16:31]
	v_lshl_add_u64 v[68:69], v[64:65], 0, s[40:41]
	global_load_lds_dwordx4 v[68:69], off
	v_mfma_f32_32x32x16_bf16 v[32:47], v[72:75], v[76:79], v[32:47]
	v_mfma_f32_32x32x16_bf16 v[0:15], v[72:75], v[80:83], v[0:15]
	v_lshl_add_u64 v[68:69], v[64:65], 0, s[42:43]
	s_mov_b32 m0, s91
	s_nop 0
	global_load_lds_dwordx4 v[68:69], off
	ds_read_b128 v[68:71], v147 offset:32768
	ds_read_b128 v[72:75], v147 offset:36864
	ds_read_b128 v[76:79], v148
	ds_read_b128 v[80:83], v148 offset:4096
	s_waitcnt lgkmcnt(4)
	v_mfma_f32_32x32x16_bf16 v[48:63], v[184:187], v[192:195], v[48:63]
	v_mfma_f32_32x32x16_bf16 v[16:31], v[184:187], v[196:199], v[16:31]
	v_lshl_add_u64 v[252:253], v[64:65], 0, s[4:5]
	s_mov_b32 m0, s89
	s_mov_b64 s[4:5], 0x60400
	global_load_lds_dwordx4 v[252:253], off
	v_mfma_f32_32x32x16_bf16 v[32:47], v[188:191], v[192:195], v[32:47]
	v_mfma_f32_32x32x16_bf16 v[0:15], v[188:191], v[196:199], v[0:15]
	v_lshl_add_u64 v[252:253], v[64:65], 0, s[4:5]
	s_mov_b32 m0, s90
	s_nop 0
	global_load_lds_dwordx4 v[252:253], off
	ds_read_b128 v[184:187], v149 offset:32768
	ds_read_b128 v[188:191], v149 offset:36864
	ds_read_b128 v[192:195], v150
	ds_read_b128 v[196:199], v150 offset:4096
	s_waitcnt lgkmcnt(4)
	v_mfma_f32_32x32x16_bf16 v[48:63], v[68:71], v[76:79], v[48:63]
	v_mfma_f32_32x32x16_bf16 v[16:31], v[68:71], v[80:83], v[16:31]
	v_lshl_add_u64 v[252:253], v[66:67], 0, s[40:41]
	s_mov_b32 m0, s47
	s_nop 0
	global_load_lds_dwordx4 v[252:253], off
	v_mfma_f32_32x32x16_bf16 v[32:47], v[72:75], v[76:79], v[32:47]
	v_mfma_f32_32x32x16_bf16 v[0:15], v[72:75], v[80:83], v[0:15]
	v_lshl_add_u64 v[252:253], v[66:67], 0, s[42:43]
	s_mov_b32 m0, s88
	s_nop 0
	global_load_lds_dwordx4 v[252:253], off
	s_mov_b32 m0, s6
	s_mov_b64 s[4:5], 0x40480
	ds_read_b128 v[68:71], v151 offset:32768
	ds_read_b128 v[72:75], v151 offset:36864
	ds_read_b128 v[76:79], v152
	ds_read_b128 v[80:83], v152 offset:4096
	s_waitcnt lgkmcnt(4)
	v_mfma_f32_32x32x16_bf16 v[48:63], v[184:187], v[192:195], v[48:63]
	v_mfma_f32_32x32x16_bf16 v[16:31], v[184:187], v[196:199], v[16:31]
	v_mfma_f32_32x32x16_bf16 v[32:47], v[188:191], v[192:195], v[32:47]
	v_mfma_f32_32x32x16_bf16 v[0:15], v[188:191], v[196:199], v[0:15]
	s_waitcnt vmcnt(6)
	s_waitcnt lgkmcnt(0)
	s_barrier
; #define MFMA(a, b, c) __builtin_amdgcn_mfma_f32_32x32x16_bf16((a), (b), (c), 0, 0, 0)
; #define WAIT_V(n) asm volatile("s_waitcnt vmcnt(%0)" ::"n"(n) : "memory")
; #define RAW_BARRIER() do { asm volatile("s_waitcnt lgkmcnt(0)" ::: "memory"); __builtin_amdgcn_s_barrier(); asm volatile("" ::: "memory"); } while (0)
; #define GLDS_STAGE(slot, kt) do { _Pragma("unroll") for (int i = 0; i < 6; ++i) \
;     __builtin_amdgcn_global_load_lds((const unsigned*)(src[i] + (kt) * 64), (__attribute__((address_space(3))) unsigned*)(smem + (slot) * G_STAGE + (wave + 8 * i) * 1024), 16, 0, 0); } while (0)
; DI void gemm_tile(const u16* __restrict__ X, int ldx, const u16* __restrict__ Wt, int ldw, int K, char* smem,
;                   f32x16 (&acc)[2][2]) {
;     ...
;   for (int kt = 0; kt < nk; ++kt) {
;     const int nxt = (cur >= 1) ? cur - 1 : 2;
;     if (kt + 2 < nk) GLDS_STAGE(nxt, kt + 2);
;     __builtin_amdgcn_sched_barrier(0);
;     const char* st = smem + cur * G_STAGE;
; #pragma unroll
;     for (int ks = 0; ks < 4; ++ks) {
;       bf16x8 a[2], b[2];
; #pragma unroll
;       for (int ft = 0; ft < 2; ++ft) a[ft] = *reinterpret_cast<const bf16x8*>(st + offA[ft] + (((ks * 2 + lh) ^ xa[ft]) << 4));
; #pragma unroll
;       for (int tt = 0; tt < 2; ++tt) b[tt] = *reinterpret_cast<const bf16x8*>(st + offB[tt] + (((ks * 2 + lh) ^ xb[tt]) << 4));
; #pragma unroll
;       for (int ft = 0; ft < 2; ++ft)
; #pragma unroll
;         for (int tt = 0; tt < 2; ++tt) acc[ft][tt] = MFMA(a[ft], b[tt], acc[ft][tt]);
;     }
;     if (kt + 2 < nk) { WAIT_V(6); } else { WAIT_V(0); }
;     RAW_BARRIER();
;     cur = (cur == 2) ? 0 : cur + 1;
	ds_read_b128 v[184:187], v153 offset:32768
	ds_read_b128 v[188:191], v153 offset:36864
	ds_read_b128 v[192:195], v146 offset:49152
	ds_read_b128 v[196:199], v146 offset:53248
	s_waitcnt lgkmcnt(4)
	v_mfma_f32_32x32x16_bf16 v[48:63], v[68:71], v[76:79], v[48:63]
	v_mfma_f32_32x32x16_bf16 v[16:31], v[68:71], v[80:83], v[16:31]
	v_lshl_add_u64 v[68:69], v[64:65], 0, s[44:45]
	global_load_lds_dwordx4 v[68:69], off
	v_mfma_f32_32x32x16_bf16 v[32:47], v[72:75], v[76:79], v[32:47]
	v_mfma_f32_32x32x16_bf16 v[0:15], v[72:75], v[80:83], v[0:15]
	v_lshl_add_u64 v[68:69], v[64:65], 0, s[48:49]
	s_mov_b32 m0, s85
	s_nop 0
	global_load_lds_dwordx4 v[68:69], off
	ds_read_b128 v[68:71], v154 offset:32768
	ds_read_b128 v[72:75], v154 offset:36864
	ds_read_b128 v[76:79], v148 offset:49152
	ds_read_b128 v[80:83], v148 offset:53248
	s_waitcnt lgkmcnt(4)
	v_mfma_f32_32x32x16_bf16 v[48:63], v[184:187], v[192:195], v[48:63]
	v_mfma_f32_32x32x16_bf16 v[16:31], v[184:187], v[196:199], v[16:31]
	v_lshl_add_u64 v[252:253], v[64:65], 0, s[4:5]
	s_mov_b32 m0, s84
	s_mov_b64 s[4:5], 0x60480
	global_load_lds_dwordx4 v[252:253], off
	v_mfma_f32_32x32x16_bf16 v[32:47], v[188:191], v[192:195], v[32:47]
	v_mfma_f32_32x32x16_bf16 v[0:15], v[188:191], v[196:199], v[0:15]
	v_lshl_add_u64 v[252:253], v[64:65], 0, s[4:5]
	s_mov_b32 m0, s81
	s_nop 0
	global_load_lds_dwordx4 v[252:253], off
	ds_read_b128 v[184:187], v155 offset:32768
	ds_read_b128 v[188:191], v155 offset:36864
	ds_read_b128 v[192:195], v150 offset:49152
	ds_read_b128 v[196:199], v150 offset:53248
	s_waitcnt lgkmcnt(4)
	v_mfma_f32_32x32x16_bf16 v[48:63], v[68:71], v[76:79], v[48:63]
	v_mfma_f32_32x32x16_bf16 v[16:31], v[68:71], v[80:83], v[16:31]
	v_lshl_add_u64 v[252:253], v[66:67], 0, s[44:45]
	s_mov_b32 m0, s80
	s_nop 0
	global_load_lds_dwordx4 v[252:253], off
	v_mfma_f32_32x32x16_bf16 v[32:47], v[72:75], v[76:79], v[32:47]
	v_mfma_f32_32x32x16_bf16 v[0:15], v[72:75], v[80:83], v[0:15]
	v_lshl_add_u64 v[252:253], v[66:67], 0, s[48:49]
	s_mov_b32 m0, s79
	s_nop 0
	global_load_lds_dwordx4 v[252:253], off
	s_mov_b32 m0, s77
	s_mov_b64 s[4:5], 0x40500
	ds_read_b128 v[68:71], v156 offset:32768
	ds_read_b128 v[72:75], v156 offset:36864
	ds_read_b128 v[76:79], v152 offset:49152
	ds_read_b128 v[80:83], v152 offset:53248
	s_waitcnt lgkmcnt(4)
	v_mfma_f32_32x32x16_bf16 v[48:63], v[184:187], v[192:195], v[48:63]
	v_mfma_f32_32x32x16_bf16 v[16:31], v[184:187], v[196:199], v[16:31]
	v_mfma_f32_32x32x16_bf16 v[32:47], v[188:191], v[192:195], v[32:47]
	v_mfma_f32_32x32x16_bf16 v[0:15], v[188:191], v[196:199], v[0:15]
	s_waitcnt vmcnt(6)
	s_waitcnt lgkmcnt(0)
	s_barrier
	ds_read_b128 v[184:187], v157 offset:32768
	ds_read_b128 v[188:191], v157 offset:36864
	ds_read_b128 v[192:195], v158
	ds_read_b128 v[196:199], v158 offset:4096
	s_waitcnt lgkmcnt(4)
	v_mfma_f32_32x32x16_bf16 v[48:63], v[68:71], v[76:79], v[48:63]
	v_mfma_f32_32x32x16_bf16 v[16:31], v[68:71], v[80:83], v[16:31]
	v_lshl_add_u64 v[68:69], v[64:65], 0, s[50:51]
	global_load_lds_dwordx4 v[68:69], off
	v_mfma_f32_32x32x16_bf16 v[32:47], v[72:75], v[76:79], v[32:47]
	v_mfma_f32_32x32x16_bf16 v[0:15], v[72:75], v[80:83], v[0:15]
	v_lshl_add_u64 v[68:69], v[64:65], 0, s[52:53]
	s_mov_b32 m0, s0
	s_nop 0
	global_load_lds_dwordx4 v[68:69], off
	ds_read_b128 v[68:71], v159 offset:32768
	ds_read_b128 v[72:75], v159 offset:36864
	ds_read_b128 v[76:79], v160
	ds_read_b128 v[80:83], v160 offset:4096
	s_waitcnt lgkmcnt(4)
	v_mfma_f32_32x32x16_bf16 v[48:63], v[184:187], v[192:195], v[48:63]
	v_mfma_f32_32x32x16_bf16 v[16:31], v[184:187], v[196:199], v[16:31]
	v_lshl_add_u64 v[252:253], v[64:65], 0, s[4:5]
	s_mov_b32 m0, s7
	s_mov_b64 s[4:5], 0x60500
	global_load_lds_dwordx4 v[252:253], off
	v_mfma_f32_32x32x16_bf16 v[32:47], v[188:191], v[192:195], v[32:47]
	v_mfma_f32_32x32x16_bf16 v[0:15], v[188:191], v[196:199], v[0:15]
	v_lshl_add_u64 v[252:253], v[64:65], 0, s[4:5]
	s_mov_b32 m0, s87
	s_nop 0
	global_load_lds_dwordx4 v[252:253], off
	ds_read_b128 v[184:187], v161 offset:32768
	ds_read_b128 v[188:191], v161 offset:36864
	ds_read_b128 v[192:195], v163
	ds_read_b128 v[196:199], v163 offset:4096
	s_waitcnt lgkmcnt(4)
	v_mfma_f32_32x32x16_bf16 v[48:63], v[68:71], v[76:79], v[48:63]
	v_mfma_f32_32x32x16_bf16 v[16:31], v[68:71], v[80:83], v[16:31]
	v_lshl_add_u64 v[252:253], v[66:67], 0, s[50:51]
	s_mov_b32 m0, s86
	s_nop 0
	global_load_lds_dwordx4 v[252:253], off
	v_mfma_f32_32x32x16_bf16 v[32:47], v[72:75], v[76:79], v[32:47]
	v_mfma_f32_32x32x16_bf16 v[0:15], v[72:75], v[80:83], v[0:15]
	v_lshl_add_u64 v[252:253], v[66:67], 0, s[52:53]
	s_mov_b32 m0, s46
	s_nop 0
	global_load_lds_dwordx4 v[252:253], off
	v_readfirstlane_b32 s84, v117
	s_mov_b32 m0, s84
	v_readfirstlane_b32 s46, v119
	s_mov_b64 s[4:5], 0x40580
	v_readfirstlane_b32 s47, v121
	v_readfirstlane_b32 s79, v124
	v_readfirstlane_b32 s77, v125
	v_readfirstlane_b32 s80, v126
	ds_read_b128 v[68:71], v165 offset:32768
	ds_read_b128 v[72:75], v165 offset:36864
	ds_read_b128 v[76:79], v167
	ds_read_b128 v[80:83], v167 offset:4096
	s_waitcnt lgkmcnt(4)
	v_mfma_f32_32x32x16_bf16 v[48:63], v[184:187], v[192:195], v[48:63]
	v_mfma_f32_32x32x16_bf16 v[16:31], v[184:187], v[196:199], v[16:31]
	v_mfma_f32_32x32x16_bf16 v[32:47], v[188:191], v[192:195], v[32:47]
	v_mfma_f32_32x32x16_bf16 v[0:15], v[188:191], v[196:199], v[0:15]
	s_waitcnt vmcnt(6)
	s_waitcnt lgkmcnt(0)
	s_barrier
; #define MFMA(a, b, c) __builtin_amdgcn_mfma_f32_32x32x16_bf16((a), (b), (c), 0, 0, 0)
; #define WAIT_V(n) asm volatile("s_waitcnt vmcnt(%0)" ::"n"(n) : "memory")
; #define RAW_BARRIER() do { asm volatile("s_waitcnt lgkmcnt(0)" ::: "memory"); __builtin_amdgcn_s_barrier(); asm volatile("" ::: "memory"); } while (0)
; #define GLDS_STAGE(slot, kt) do { _Pragma("unroll") for (int i = 0; i < 6; ++i) \
;     __builtin_amdgcn_global_load_lds((const unsigned*)(src[i] + (kt) * 64), (__attribute__((address_space(3))) unsigned*)(smem + (slot) * G_STAGE + (wave + 8 * i) * 1024), 16, 0, 0); } while (0)
; DI void gemm_tile(const u16* __restrict__ X, int ldx, const u16* __restrict__ Wt, int ldw, int K, char* smem,
;                   f32x16 (&acc)[2][2]) {
;     ...
;   for (int kt = 0; kt < nk; ++kt) {
;     const int nxt = (cur >= 1) ? cur - 1 : 2;
;     if (kt + 2 < nk) GLDS_STAGE(nxt, kt + 2);
;     __builtin_amdgcn_sched_barrier(0);
;     const char* st = smem + cur * G_STAGE;
; #pragma unroll
;     for (int ks = 0; ks < 4; ++ks) {
;       bf16x8 a[2], b[2];
; #pragma unroll
;       for (int ft = 0; ft < 2; ++ft) a[ft] = *reinterpret_cast<const bf16x8*>(st + offA[ft] + (((ks * 2 + lh) ^ xa[ft]) << 4));
; #pragma unroll
;       for (int tt = 0; tt < 2; ++tt) b[tt] = *reinterpret_cast<const bf16x8*>(st + offB[tt] + (((ks * 2 + lh) ^ xb[tt]) << 4));
; #pragma unroll
;       for (int ft = 0; ft < 2; ++ft)
; #pragma unroll
;         for (int tt = 0; tt < 2; ++tt) acc[ft][tt] = MFMA(a[ft], b[tt], acc[ft][tt]);
;     }
;     if (kt + 2 < nk) { WAIT_V(6); } else { WAIT_V(0); }
;     RAW_BARRIER();
;     cur = (cur == 2) ? 0 : cur + 1;
	ds_read_b128 v[184:187], v145 offset:32768
	ds_read_b128 v[188:191], v145 offset:36864
	ds_read_b128 v[192:195], v146
	ds_read_b128 v[196:199], v146 offset:4096
	s_waitcnt lgkmcnt(4)
	v_mfma_f32_32x32x16_bf16 v[48:63], v[68:71], v[76:79], v[48:63]
	v_mfma_f32_32x32x16_bf16 v[16:31], v[68:71], v[80:83], v[16:31]
	v_lshl_add_u64 v[68:69], v[64:65], 0, s[56:57]
	global_load_lds_dwordx4 v[68:69], off
	v_mfma_f32_32x32x16_bf16 v[32:47], v[72:75], v[76:79], v[32:47]
	v_mfma_f32_32x32x16_bf16 v[0:15], v[72:75], v[80:83], v[0:15]
	v_lshl_add_u64 v[68:69], v[64:65], 0, s[58:59]
	s_mov_b32 m0, s46
	s_nop 0
	global_load_lds_dwordx4 v[68:69], off
	ds_read_b128 v[68:71], v147 offset:32768
	ds_read_b128 v[72:75], v147 offset:36864
	ds_read_b128 v[76:79], v148
	ds_read_b128 v[80:83], v148 offset:4096
	s_waitcnt lgkmcnt(4)
	v_mfma_f32_32x32x16_bf16 v[48:63], v[184:187], v[192:195], v[48:63]
	v_mfma_f32_32x32x16_bf16 v[16:31], v[184:187], v[196:199], v[16:31]
	v_lshl_add_u64 v[252:253], v[64:65], 0, s[4:5]
	s_mov_b32 m0, s47
	s_mov_b64 s[4:5], 0x60580
	global_load_lds_dwordx4 v[252:253], off
	v_mfma_f32_32x32x16_bf16 v[32:47], v[188:191], v[192:195], v[32:47]
	v_mfma_f32_32x32x16_bf16 v[0:15], v[188:191], v[196:199], v[0:15]
	v_lshl_add_u64 v[252:253], v[64:65], 0, s[4:5]
	s_mov_b32 m0, s79
	s_nop 0
	global_load_lds_dwordx4 v[252:253], off
	ds_read_b128 v[184:187], v149 offset:32768
	ds_read_b128 v[188:191], v149 offset:36864
	ds_read_b128 v[192:195], v150
	ds_read_b128 v[196:199], v150 offset:4096
	s_waitcnt lgkmcnt(4)
	v_mfma_f32_32x32x16_bf16 v[48:63], v[68:71], v[76:79], v[48:63]
	v_mfma_f32_32x32x16_bf16 v[16:31], v[68:71], v[80:83], v[16:31]
	v_lshl_add_u64 v[252:253], v[66:67], 0, s[56:57]
	s_mov_b32 m0, s77
	s_nop 0
	global_load_lds_dwordx4 v[252:253], off
	v_mfma_f32_32x32x16_bf16 v[32:47], v[72:75], v[76:79], v[32:47]
	v_mfma_f32_32x32x16_bf16 v[0:15], v[72:75], v[80:83], v[0:15]
	v_lshl_add_u64 v[252:253], v[66:67], 0, s[58:59]
	s_mov_b32 m0, s80
	s_nop 0
	global_load_lds_dwordx4 v[252:253], off
	v_readfirstlane_b32 s81, v143
	s_mov_b32 m0, s81
	v_readfirstlane_b32 s0, v131
	s_mov_b64 s[4:5], 0x40600
	s_mov_b64 s[6:7], 0x60600
	ds_read_b128 v[68:71], v151 offset:32768
	ds_read_b128 v[72:75], v151 offset:36864
	ds_read_b128 v[76:79], v152
	ds_read_b128 v[80:83], v152 offset:4096
	s_waitcnt lgkmcnt(4)
	v_mfma_f32_32x32x16_bf16 v[48:63], v[184:187], v[192:195], v[48:63]
	v_mfma_f32_32x32x16_bf16 v[16:31], v[184:187], v[196:199], v[16:31]
	v_mfma_f32_32x32x16_bf16 v[32:47], v[188:191], v[192:195], v[32:47]
	v_mfma_f32_32x32x16_bf16 v[0:15], v[188:191], v[196:199], v[0:15]
	s_waitcnt vmcnt(6)
	s_waitcnt lgkmcnt(0)
	s_barrier
	ds_read_b128 v[184:187], v153 offset:32768
	ds_read_b128 v[188:191], v153 offset:36864
	ds_read_b128 v[192:195], v146 offset:49152
	ds_read_b128 v[196:199], v146 offset:53248
	s_waitcnt lgkmcnt(4)
	v_mfma_f32_32x32x16_bf16 v[48:63], v[68:71], v[76:79], v[48:63]
	v_mfma_f32_32x32x16_bf16 v[16:31], v[68:71], v[80:83], v[16:31]
	v_lshl_add_u64 v[68:69], v[64:65], 0, s[60:61]
	global_load_lds_dwordx4 v[68:69], off
	v_mfma_f32_32x32x16_bf16 v[32:47], v[72:75], v[76:79], v[32:47]
	v_mfma_f32_32x32x16_bf16 v[0:15], v[72:75], v[80:83], v[0:15]
	v_lshl_add_u64 v[68:69], v[64:65], 0, s[62:63]
	s_mov_b32 m0, s0
	s_nop 0
	global_load_lds_dwordx4 v[68:69], off
	ds_read_b128 v[68:71], v154 offset:32768
	ds_read_b128 v[72:75], v154 offset:36864
	ds_read_b128 v[76:79], v148 offset:49152
	ds_read_b128 v[80:83], v148 offset:53248
	s_waitcnt lgkmcnt(4)
	v_mfma_f32_32x32x16_bf16 v[48:63], v[184:187], v[192:195], v[48:63]
	v_mfma_f32_32x32x16_bf16 v[16:31], v[184:187], v[196:199], v[16:31]
	v_lshl_add_u64 v[252:253], v[64:65], 0, s[4:5]
	v_readfirstlane_b32 s4, v132
	s_mov_b32 m0, s4
	v_readfirstlane_b32 s5, v134
	global_load_lds_dwordx4 v[252:253], off
	v_mfma_f32_32x32x16_bf16 v[32:47], v[188:191], v[192:195], v[32:47]
	v_mfma_f32_32x32x16_bf16 v[0:15], v[188:191], v[196:199], v[0:15]
	v_lshl_add_u64 v[252:253], v[64:65], 0, s[6:7]
	v_readfirstlane_b32 s6, v133
	s_mov_b32 m0, s6
	v_readfirstlane_b32 s7, v135
	global_load_lds_dwordx4 v[252:253], off
	ds_read_b128 v[184:187], v155 offset:32768
	ds_read_b128 v[188:191], v155 offset:36864
	ds_read_b128 v[192:195], v150 offset:49152
	ds_read_b128 v[196:199], v150 offset:53248
	s_waitcnt lgkmcnt(4)
	v_mfma_f32_32x32x16_bf16 v[48:63], v[68:71], v[76:79], v[48:63]
	v_mfma_f32_32x32x16_bf16 v[16:31], v[68:71], v[80:83], v[16:31]
	v_lshl_add_u64 v[252:253], v[66:67], 0, s[60:61]
	s_mov_b32 m0, s5
	s_nop 0
	global_load_lds_dwordx4 v[252:253], off
	v_mfma_f32_32x32x16_bf16 v[32:47], v[72:75], v[76:79], v[32:47]
	v_mfma_f32_32x32x16_bf16 v[0:15], v[72:75], v[80:83], v[0:15]
	v_lshl_add_u64 v[252:253], v[66:67], 0, s[62:63]
	s_mov_b32 m0, s7
	s_nop 0
	global_load_lds_dwordx4 v[252:253], off
	v_readfirstlane_b32 s85, v115
	s_mov_b32 m0, s85
	v_readfirstlane_b32 s85, v136
	s_mov_b64 s[86:87], 0x40680
	ds_read_b128 v[68:71], v156 offset:32768
	ds_read_b128 v[72:75], v156 offset:36864
	ds_read_b128 v[76:79], v152 offset:49152
	ds_read_b128 v[80:83], v152 offset:53248
	s_waitcnt lgkmcnt(4)
	v_mfma_f32_32x32x16_bf16 v[48:63], v[184:187], v[192:195], v[48:63]
	v_mfma_f32_32x32x16_bf16 v[16:31], v[184:187], v[196:199], v[16:31]
	v_mfma_f32_32x32x16_bf16 v[32:47], v[188:191], v[192:195], v[32:47]
	v_mfma_f32_32x32x16_bf16 v[0:15], v[188:191], v[196:199], v[0:15]
	s_waitcnt vmcnt(6)
	s_waitcnt lgkmcnt(0)
	s_barrier
; #define MFMA(a, b, c) __builtin_amdgcn_mfma_f32_32x32x16_bf16((a), (b), (c), 0, 0, 0)
; #define WAIT_V(n) asm volatile("s_waitcnt vmcnt(%0)" ::"n"(n) : "memory")
; #define RAW_BARRIER() do { asm volatile("s_waitcnt lgkmcnt(0)" ::: "memory"); __builtin_amdgcn_s_barrier(); asm volatile("" ::: "memory"); } while (0)
; #define GLDS_STAGE(slot, kt) do { _Pragma("unroll") for (int i = 0; i < 6; ++i) \
;     __builtin_amdgcn_global_load_lds((const unsigned*)(src[i] + (kt) * 64), (__attribute__((address_space(3))) unsigned*)(smem + (slot) * G_STAGE + (wave + 8 * i) * 1024), 16, 0, 0); } while (0)
; DI void gemm_tile(const u16* __restrict__ X, int ldx, const u16* __restrict__ Wt, int ldw, int K, char* smem,
;                   f32x16 (&acc)[2][2]) {
;     ...
;   for (int kt = 0; kt < nk; ++kt) {
;     const int nxt = (cur >= 1) ? cur - 1 : 2;
;     if (kt + 2 < nk) GLDS_STAGE(nxt, kt + 2);
;     __builtin_amdgcn_sched_barrier(0);
;     const char* st = smem + cur * G_STAGE;
; #pragma unroll
;     for (int ks = 0; ks < 4; ++ks) {
;       bf16x8 a[2], b[2];
; #pragma unroll
;       for (int ft = 0; ft < 2; ++ft) a[ft] = *reinterpret_cast<const bf16x8*>(st + offA[ft] + (((ks * 2 + lh) ^ xa[ft]) << 4));
; #pragma unroll
;       for (int tt = 0; tt < 2; ++tt) b[tt] = *reinterpret_cast<const bf16x8*>(st + offB[tt] + (((ks * 2 + lh) ^ xb[tt]) << 4));
; #pragma unroll
;       for (int ft = 0; ft < 2; ++ft)
; #pragma unroll
;         for (int tt = 0; tt < 2; ++tt) acc[ft][tt] = MFMA(a[ft], b[tt], acc[ft][tt]);
;     }
;     if (kt + 2 < nk) { WAIT_V(6); } else { WAIT_V(0); }
;     RAW_BARRIER();
;     cur = (cur == 2) ? 0 : cur + 1;
	ds_read_b128 v[184:187], v157 offset:32768
	ds_read_b128 v[188:191], v157 offset:36864
	ds_read_b128 v[192:195], v158
	ds_read_b128 v[196:199], v158 offset:4096
	s_waitcnt lgkmcnt(4)
	v_mfma_f32_32x32x16_bf16 v[48:63], v[68:71], v[76:79], v[48:63]
	v_mfma_f32_32x32x16_bf16 v[16:31], v[68:71], v[80:83], v[16:31]
	v_lshl_add_u64 v[68:69], v[64:65], 0, s[64:65]
	global_load_lds_dwordx4 v[68:69], off
	v_mfma_f32_32x32x16_bf16 v[32:47], v[72:75], v[76:79], v[32:47]
	v_mfma_f32_32x32x16_bf16 v[0:15], v[72:75], v[80:83], v[0:15]
	v_lshl_add_u64 v[68:69], v[64:65], 0, s[66:67]
	s_mov_b32 m0, s85
	v_readfirstlane_b32 s85, v127
	global_load_lds_dwordx4 v[68:69], off
	ds_read_b128 v[68:71], v159 offset:32768
	ds_read_b128 v[72:75], v159 offset:36864
	ds_read_b128 v[76:79], v160
	ds_read_b128 v[80:83], v160 offset:4096
	s_waitcnt lgkmcnt(4)
	v_mfma_f32_32x32x16_bf16 v[48:63], v[184:187], v[192:195], v[48:63]
	v_mfma_f32_32x32x16_bf16 v[16:31], v[184:187], v[196:199], v[16:31]
	v_lshl_add_u64 v[252:253], v[64:65], 0, s[86:87]
	s_mov_b32 m0, s85
	s_mov_b64 s[86:87], 0x60680
	v_readfirstlane_b32 s85, v128
	global_load_lds_dwordx4 v[252:253], off
	v_mfma_f32_32x32x16_bf16 v[32:47], v[188:191], v[192:195], v[32:47]
	v_mfma_f32_32x32x16_bf16 v[0:15], v[188:191], v[196:199], v[0:15]
	v_lshl_add_u64 v[252:253], v[64:65], 0, s[86:87]
	s_mov_b32 m0, s85
	v_readfirstlane_b32 s85, v129
	global_load_lds_dwordx4 v[252:253], off
	ds_read_b128 v[184:187], v161 offset:32768
	ds_read_b128 v[188:191], v161 offset:36864
	ds_read_b128 v[192:195], v163
	ds_read_b128 v[196:199], v163 offset:4096
	s_waitcnt lgkmcnt(4)
	v_mfma_f32_32x32x16_bf16 v[48:63], v[68:71], v[76:79], v[48:63]
	v_mfma_f32_32x32x16_bf16 v[16:31], v[68:71], v[80:83], v[16:31]
	v_lshl_add_u64 v[252:253], v[66:67], 0, s[64:65]
	s_mov_b32 m0, s85
	v_readfirstlane_b32 s85, v130
	global_load_lds_dwordx4 v[252:253], off
	v_mfma_f32_32x32x16_bf16 v[32:47], v[72:75], v[76:79], v[32:47]
	v_mfma_f32_32x32x16_bf16 v[0:15], v[72:75], v[80:83], v[0:15]
	v_lshl_add_u64 v[252:253], v[66:67], 0, s[66:67]
	s_mov_b32 m0, s85
	s_nop 0
	global_load_lds_dwordx4 v[252:253], off
	s_mov_b32 m0, s84
	s_mov_b64 s[84:85], 0x40700
	ds_read_b128 v[68:71], v165 offset:32768
	ds_read_b128 v[72:75], v165 offset:36864
	ds_read_b128 v[76:79], v167
	ds_read_b128 v[80:83], v167 offset:4096
	s_waitcnt lgkmcnt(4)
	v_mfma_f32_32x32x16_bf16 v[48:63], v[184:187], v[192:195], v[48:63]
	v_mfma_f32_32x32x16_bf16 v[16:31], v[184:187], v[196:199], v[16:31]
	v_mfma_f32_32x32x16_bf16 v[32:47], v[188:191], v[192:195], v[32:47]
	v_mfma_f32_32x32x16_bf16 v[0:15], v[188:191], v[196:199], v[0:15]
	s_waitcnt vmcnt(6)
	s_waitcnt lgkmcnt(0)
	s_barrier
	ds_read_b128 v[184:187], v145 offset:32768
	ds_read_b128 v[188:191], v145 offset:36864
	ds_read_b128 v[192:195], v146
	ds_read_b128 v[196:199], v146 offset:4096
	s_waitcnt lgkmcnt(4)
	v_mfma_f32_32x32x16_bf16 v[48:63], v[68:71], v[76:79], v[48:63]
	v_mfma_f32_32x32x16_bf16 v[16:31], v[68:71], v[80:83], v[16:31]
	v_lshl_add_u64 v[68:69], v[64:65], 0, s[68:69]
	global_load_lds_dwordx4 v[68:69], off
	v_mfma_f32_32x32x16_bf16 v[32:47], v[72:75], v[76:79], v[32:47]
	v_mfma_f32_32x32x16_bf16 v[0:15], v[72:75], v[80:83], v[0:15]
	v_lshl_add_u64 v[68:69], v[64:65], 0, s[70:71]
	s_mov_b32 m0, s46
	s_nop 0
	global_load_lds_dwordx4 v[68:69], off
	ds_read_b128 v[68:71], v147 offset:32768
	ds_read_b128 v[72:75], v147 offset:36864
	ds_read_b128 v[76:79], v148
	ds_read_b128 v[80:83], v148 offset:4096
	s_waitcnt lgkmcnt(4)
	v_mfma_f32_32x32x16_bf16 v[48:63], v[184:187], v[192:195], v[48:63]
	v_mfma_f32_32x32x16_bf16 v[16:31], v[184:187], v[196:199], v[16:31]
	v_lshl_add_u64 v[252:253], v[64:65], 0, s[84:85]
	s_mov_b32 m0, s47
	s_mov_b64 s[46:47], 0x60700
	global_load_lds_dwordx4 v[252:253], off
	v_mfma_f32_32x32x16_bf16 v[32:47], v[188:191], v[192:195], v[32:47]
	v_mfma_f32_32x32x16_bf16 v[0:15], v[188:191], v[196:199], v[0:15]
	v_lshl_add_u64 v[252:253], v[64:65], 0, s[46:47]
	s_mov_b32 m0, s79
	s_nop 0
	global_load_lds_dwordx4 v[252:253], off
	ds_read_b128 v[184:187], v149 offset:32768
	ds_read_b128 v[188:191], v149 offset:36864
	ds_read_b128 v[192:195], v150
	ds_read_b128 v[196:199], v150 offset:4096
	s_waitcnt lgkmcnt(4)
	v_mfma_f32_32x32x16_bf16 v[48:63], v[68:71], v[76:79], v[48:63]
	v_mfma_f32_32x32x16_bf16 v[16:31], v[68:71], v[80:83], v[16:31]
	v_lshl_add_u64 v[252:253], v[66:67], 0, s[68:69]
	s_mov_b32 m0, s77
	s_nop 0
	global_load_lds_dwordx4 v[252:253], off
	v_mfma_f32_32x32x16_bf16 v[32:47], v[72:75], v[76:79], v[32:47]
	v_mfma_f32_32x32x16_bf16 v[0:15], v[72:75], v[80:83], v[0:15]
	v_lshl_add_u64 v[252:253], v[66:67], 0, s[70:71]
	s_mov_b32 m0, s80
	s_nop 0
	global_load_lds_dwordx4 v[252:253], off
	s_mov_b32 m0, s81
	s_mov_b64 s[46:47], 0x40780
	ds_read_b128 v[68:71], v151 offset:32768
	ds_read_b128 v[72:75], v151 offset:36864
	ds_read_b128 v[76:79], v152
	ds_read_b128 v[80:83], v152 offset:4096
	s_waitcnt lgkmcnt(4)
	v_mfma_f32_32x32x16_bf16 v[48:63], v[184:187], v[192:195], v[48:63]
	v_mfma_f32_32x32x16_bf16 v[16:31], v[184:187], v[196:199], v[16:31]
	v_mfma_f32_32x32x16_bf16 v[32:47], v[188:191], v[192:195], v[32:47]
	v_mfma_f32_32x32x16_bf16 v[0:15], v[188:191], v[196:199], v[0:15]
	s_waitcnt vmcnt(6)
	s_waitcnt lgkmcnt(0)
	s_barrier
; #define MFMA(a, b, c) __builtin_amdgcn_mfma_f32_32x32x16_bf16((a), (b), (c), 0, 0, 0)
; #define WAIT_V(n) asm volatile("s_waitcnt vmcnt(%0)" ::"n"(n) : "memory")
; #define RAW_BARRIER() do { asm volatile("s_waitcnt lgkmcnt(0)" ::: "memory"); __builtin_amdgcn_s_barrier(); asm volatile("" ::: "memory"); } while (0)
; #define GLDS_STAGE(slot, kt) do { _Pragma("unroll") for (int i = 0; i < 6; ++i) \
;     __builtin_amdgcn_global_load_lds((const unsigned*)(src[i] + (kt) * 64), (__attribute__((address_space(3))) unsigned*)(smem + (slot) * G_STAGE + (wave + 8 * i) * 1024), 16, 0, 0); } while (0)
; DI void gemm_tile(const u16* __restrict__ X, int ldx, const u16* __restrict__ Wt, int ldw, int K, char* smem,
;                   f32x16 (&acc)[2][2]) {
;     ...
;   for (int kt = 0; kt < nk; ++kt) {
;     const int nxt = (cur >= 1) ? cur - 1 : 2;
;     if (kt + 2 < nk) GLDS_STAGE(nxt, kt + 2);
;     __builtin_amdgcn_sched_barrier(0);
;     const char* st = smem + cur * G_STAGE;
; #pragma unroll
;     for (int ks = 0; ks < 4; ++ks) {
;       bf16x8 a[2], b[2];
; #pragma unroll
;       for (int ft = 0; ft < 2; ++ft) a[ft] = *reinterpret_cast<const bf16x8*>(st + offA[ft] + (((ks * 2 + lh) ^ xa[ft]) << 4));
; #pragma unroll
;       for (int tt = 0; tt < 2; ++tt) b[tt] = *reinterpret_cast<const bf16x8*>(st + offB[tt] + (((ks * 2 + lh) ^ xb[tt]) << 4));
; #pragma unroll
;       for (int ft = 0; ft < 2; ++ft)
; #pragma unroll
;         for (int tt = 0; tt < 2; ++tt) acc[ft][tt] = MFMA(a[ft], b[tt], acc[ft][tt]);
;     }
;     if (kt + 2 < nk) { WAIT_V(6); } else { WAIT_V(0); }
;     RAW_BARRIER();
;     cur = (cur == 2) ? 0 : cur + 1;
	ds_read_b128 v[184:187], v153 offset:32768
	ds_read_b128 v[192:195], v146 offset:49152
	ds_read_b128 v[196:199], v146 offset:53248
	ds_read_b128 v[188:191], v153 offset:36864
	s_waitcnt lgkmcnt(4)
	v_mfma_f32_32x32x16_bf16 v[48:63], v[68:71], v[76:79], v[48:63]
	v_mfma_f32_32x32x16_bf16 v[16:31], v[68:71], v[80:83], v[16:31]
	v_lshl_add_u64 v[68:69], v[64:65], 0, s[72:73]
	global_load_lds_dwordx4 v[68:69], off
	v_lshl_add_u64 v[68:69], v[64:65], 0, s[74:75]
	s_mov_b32 m0, s0
	s_nop 0
	global_load_lds_dwordx4 v[68:69], off
	v_lshl_add_u64 v[68:69], v[64:65], 0, s[46:47]
	s_mov_b32 m0, s4
	s_mov_b64 s[46:47], 0x60780
	global_load_lds_dwordx4 v[68:69], off
	v_lshl_add_u64 v[64:65], v[64:65], 0, s[46:47]
	s_mov_b32 m0, s6
	v_mfma_f32_32x32x16_bf16 v[32:47], v[72:75], v[76:79], v[32:47]
	global_load_lds_dwordx4 v[64:65], off
	v_lshl_add_u64 v[64:65], v[66:67], 0, s[72:73]
	s_mov_b32 m0, s5
	s_nop 0
	global_load_lds_dwordx4 v[64:65], off
	v_lshl_add_u64 v[64:65], v[66:67], 0, s[74:75]
	s_mov_b32 m0, s7
	v_mfma_f32_32x32x16_bf16 v[0:15], v[72:75], v[80:83], v[0:15]
	global_load_lds_dwordx4 v[64:65], off
	ds_read_b128 v[64:67], v154 offset:32768
	ds_read_b128 v[68:71], v148 offset:49152
	ds_read_b128 v[72:75], v148 offset:53248
	ds_read_b128 v[76:79], v154 offset:36864
	s_waitcnt lgkmcnt(4)
	v_mfma_f32_32x32x16_bf16 v[48:63], v[184:187], v[192:195], v[48:63]
	v_mfma_f32_32x32x16_bf16 v[16:31], v[184:187], v[196:199], v[16:31]
	v_mfma_f32_32x32x16_bf16 v[32:47], v[188:191], v[192:195], v[32:47]
	v_mfma_f32_32x32x16_bf16 v[0:15], v[188:191], v[196:199], v[0:15]
	ds_read_b128 v[184:187], v155 offset:32768
	ds_read_b128 v[192:195], v150 offset:49152
	ds_read_b128 v[196:199], v150 offset:53248
	ds_read_b128 v[188:191], v155 offset:36864
	s_waitcnt lgkmcnt(4)
	v_mfma_f32_32x32x16_bf16 v[48:63], v[64:67], v[68:71], v[48:63]
	v_mfma_f32_32x32x16_bf16 v[16:31], v[64:67], v[72:75], v[16:31]
	v_mfma_f32_32x32x16_bf16 v[32:47], v[76:79], v[68:71], v[32:47]
	v_mfma_f32_32x32x16_bf16 v[0:15], v[76:79], v[72:75], v[0:15]
	ds_read_b128 v[64:67], v156 offset:32768
	ds_read_b128 v[68:71], v152 offset:49152
	ds_read_b128 v[72:75], v152 offset:53248
	ds_read_b128 v[76:79], v156 offset:36864
	s_waitcnt lgkmcnt(4)
	v_mfma_f32_32x32x16_bf16 v[48:63], v[184:187], v[192:195], v[48:63]
	v_mfma_f32_32x32x16_bf16 v[16:31], v[184:187], v[196:199], v[16:31]
	v_mfma_f32_32x32x16_bf16 v[32:47], v[188:191], v[192:195], v[32:47]
	v_mfma_f32_32x32x16_bf16 v[0:15], v[188:191], v[196:199], v[0:15]
	s_waitcnt vmcnt(6)
	s_waitcnt lgkmcnt(0)
	s_barrier
	ds_read_b128 v[184:187], v157 offset:32768
	ds_read_b128 v[192:195], v158
	ds_read_b128 v[196:199], v158 offset:4096
	ds_read_b128 v[188:191], v157 offset:36864
	s_waitcnt lgkmcnt(4)
	v_mfma_f32_32x32x16_bf16 v[48:63], v[64:67], v[68:71], v[48:63]
	v_mfma_f32_32x32x16_bf16 v[16:31], v[64:67], v[72:75], v[16:31]
	v_mfma_f32_32x32x16_bf16 v[32:47], v[76:79], v[68:71], v[32:47]
	v_mfma_f32_32x32x16_bf16 v[0:15], v[76:79], v[72:75], v[0:15]
	ds_read_b128 v[64:67], v159 offset:32768
	ds_read_b128 v[68:71], v160
	ds_read_b128 v[72:75], v160 offset:4096
	ds_read_b128 v[76:79], v159 offset:36864
	s_waitcnt lgkmcnt(4)
	v_mfma_f32_32x32x16_bf16 v[48:63], v[184:187], v[192:195], v[48:63]
	v_mfma_f32_32x32x16_bf16 v[16:31], v[184:187], v[196:199], v[16:31]
	v_mfma_f32_32x32x16_bf16 v[32:47], v[188:191], v[192:195], v[32:47]
	v_mfma_f32_32x32x16_bf16 v[0:15], v[188:191], v[196:199], v[0:15]
	ds_read_b128 v[184:187], v161 offset:32768
	ds_read_b128 v[192:195], v163
	ds_read_b128 v[196:199], v163 offset:4096
	ds_read_b128 v[188:191], v161 offset:36864
	s_waitcnt lgkmcnt(4)
	v_mfma_f32_32x32x16_bf16 v[48:63], v[64:67], v[68:71], v[48:63]
	v_mfma_f32_32x32x16_bf16 v[16:31], v[64:67], v[72:75], v[16:31]
	v_mfma_f32_32x32x16_bf16 v[32:47], v[76:79], v[68:71], v[32:47]
	v_mfma_f32_32x32x16_bf16 v[0:15], v[76:79], v[72:75], v[0:15]
	s_waitcnt lgkmcnt(0)
	v_mfma_f32_32x32x16_bf16 v[48:63], v[184:187], v[192:195], v[48:63]
	v_mfma_f32_32x32x16_bf16 v[16:31], v[184:187], v[196:199], v[16:31]
	v_mfma_f32_32x32x16_bf16 v[32:47], v[188:191], v[192:195], v[32:47]
	v_mfma_f32_32x32x16_bf16 v[0:15], v[188:191], v[196:199], v[0:15]
	ds_read_b128 v[64:67], v165 offset:32768
	ds_read_b128 v[68:71], v167
	ds_read_b128 v[72:75], v167 offset:4096
	ds_read_b128 v[76:79], v165 offset:36864
	s_waitcnt vmcnt(0)
	s_waitcnt lgkmcnt(0)
	s_barrier
; #define MFMA(a, b, c) __builtin_amdgcn_mfma_f32_32x32x16_bf16((a), (b), (c), 0, 0, 0)
; #define WAIT_V(n) asm volatile("s_waitcnt vmcnt(%0)" ::"n"(n) : "memory")
; #define RAW_BARRIER() do { asm volatile("s_waitcnt lgkmcnt(0)" ::: "memory"); __builtin_amdgcn_s_barrier(); asm volatile("" ::: "memory"); } while (0)
; DI void gemm_tile(const u16* __restrict__ X, int ldx, const u16* __restrict__ Wt, int ldw, int K, char* smem,
;                   f32x16 (&acc)[2][2]) {
;     ...
;   for (int kt = 0; kt < nk; ++kt) {
;     const int nxt = (cur >= 1) ? cur - 1 : 2;
;     if (kt + 2 < nk) GLDS_STAGE(nxt, kt + 2);
;     __builtin_amdgcn_sched_barrier(0);
;     const char* st = smem + cur * G_STAGE;
; #pragma unroll
;     for (int ks = 0; ks < 4; ++ks) {
;       bf16x8 a[2], b[2];
; #pragma unroll
;       for (int ft = 0; ft < 2; ++ft) a[ft] = *reinterpret_cast<const bf16x8*>(st + offA[ft] + (((ks * 2 + lh) ^ xa[ft]) << 4));
; #pragma unroll
;       for (int tt = 0; tt < 2; ++tt) b[tt] = *reinterpret_cast<const bf16x8*>(st + offB[tt] + (((ks * 2 + lh) ^ xb[tt]) << 4));
; #pragma unroll
;       for (int ft = 0; ft < 2; ++ft)
; #pragma unroll
;         for (int tt = 0; tt < 2; ++tt) acc[ft][tt] = MFMA(a[ft], b[tt], acc[ft][tt]);
;     }
;     if (kt + 2 < nk) { WAIT_V(6); } else { WAIT_V(0); }
;     RAW_BARRIER();
;     cur = (cur == 2) ? 0 : cur + 1;
; template <int MODE>
; DI void phase_gemm(const Params& p, const u16* X, const u16* Wt, int N, const float* resid, float* outf, u16* outb, int ldo, char* smem) {
;     ...
;           for (int g = 0; g < 4; ++g) {
;             const int f = nt * 128 + fw * 64 + ft * 32 + 8 * g + 4 * lh;
;             if (MODE == 2) {
;               const int hh = f >> 8, fh = f & 255, ks = fh >> 4, lane2 = ((fh >> 3) & 1) * 32 + lr;
;               st4bf(outb + ((((size_t)(tok >> 5) * 4 + hh) * 16 + ks) * 64 + lane2) * 8 + 4 * lh, acc[ft][tt][4 * g], acc[ft][tt][4 * g + 1], acc[ft][tt][4 * g + 2], acc[ft][tt][4 * g + 3]);
;             } else {
;               const int hh = f >> 8, fq = f & 127, half = (f >> 7) & 1, ks = fq >> 4, lane2 = ((fq >> 3) & 1) * 32 + lr;
;               st4bf(outb + (((((size_t)(tok >> 5) * 8 + hh) * 2 + half) * 8 + ks) * 64 + lane2) * 8 + 4 * lh, acc[ft][tt][4 * g], acc[ft][tt][4 * g + 1], acc[ft][tt][4 * g + 2], acc[ft][tt][4 * g + 3]);
;             }
	s_waitcnt lgkmcnt(0)
	v_mfma_f32_32x32x16_bf16 v[48:63], v[64:67], v[68:71], v[48:63]
	v_mfma_f32_32x32x16_bf16 v[16:31], v[64:67], v[72:75], v[16:31]
	v_mfma_f32_32x32x16_bf16 v[32:47], v[76:79], v[68:71], v[32:47]
	v_mfma_f32_32x32x16_bf16 v[0:15], v[76:79], v[72:75], v[0:15]
	ds_read_b128 v[64:67], v145 offset:32768
	ds_read_b128 v[68:71], v146
	ds_read_b128 v[72:75], v145 offset:36864
	ds_read_b128 v[76:79], v146 offset:4096
	v_lshl_add_u32 v104, s76, 8, v111
	s_add_i32 s54, s54, s55
	s_waitcnt lgkmcnt(0)
	v_mfma_f32_32x32x16_bf16 v[48:63], v[64:67], v[68:71], v[48:63]
	v_mfma_f32_32x32x16_bf16 v[16:31], v[64:67], v[76:79], v[16:31]
	v_mfma_f32_32x32x16_bf16 v[32:47], v[72:75], v[68:71], v[32:47]
	ds_read_b128 v[64:67], v147 offset:32768
	ds_read_b128 v[68:71], v148
	ds_read_b128 v[96:99], v147 offset:36864
	ds_read_b128 v[100:103], v148 offset:4096
	v_mfma_f32_32x32x16_bf16 v[0:15], v[72:75], v[76:79], v[0:15]
	ds_read_b128 v[92:95], v149 offset:32768
	ds_read_b128 v[72:75], v149 offset:36864
	ds_read_b128 v[88:91], v150
	ds_read_b128 v[80:83], v150 offset:4096
	s_waitcnt lgkmcnt(0)
	v_mfma_f32_32x32x16_bf16 v[48:63], v[64:67], v[68:71], v[48:63]
	v_mfma_f32_32x32x16_bf16 v[16:31], v[64:67], v[100:103], v[16:31]
	v_mfma_f32_32x32x16_bf16 v[32:47], v[96:99], v[68:71], v[32:47]
	ds_read_b128 v[84:87], v151 offset:32768
	ds_read_b128 v[64:67], v151 offset:36864
	ds_read_b128 v[76:79], v152
	ds_read_b128 v[68:71], v152 offset:4096
	s_waitcnt vmcnt(0)
	s_waitcnt lgkmcnt(0)
	s_barrier
	v_mfma_f32_32x32x16_bf16 v[0:15], v[96:99], v[100:103], v[0:15]
	v_lshrrev_b32_e32 v96, 1, v104
	v_and_or_b32 v169, s98, 15, v96
	v_lshlrev_b32_e32 v96, 9, v169
	v_or_b32_e32 v98, v110, v96
	v_or_b32_e32 v104, v98, v168
	v_or_b32_e32 v99, v118, v96
	v_or_b32_e32 v100, v114, v96
	v_mfma_f32_32x32x16_bf16 v[48:63], v[92:95], v[88:91], v[48:63]
	v_or_b32_e32 v102, v120, v96
	v_lshl_add_u64 v[96:97], v[104:105], 4, v[112:113]
	v_or_b32_e32 v104, v98, v116
	s_add_i32 s3, s3, s94
	s_cmpk_lt_u32 s3, 0x100
	v_mfma_f32_32x32x16_bf16 v[16:31], v[92:95], v[80:83], v[16:31]
	v_lshl_add_u64 v[92:93], v[104:105], 4, v[112:113]
	v_or_b32_e32 v104, v99, v168
	v_lshl_add_u64 v[94:95], v[104:105], 4, v[112:113]
	v_or_b32_e32 v104, v99, v116
	v_lshl_add_u64 v[98:99], v[104:105], 4, v[112:113]
	v_or_b32_e32 v104, v100, v168
	v_mfma_f32_32x32x16_bf16 v[32:47], v[72:75], v[88:91], v[32:47]
	v_lshl_add_u64 v[88:89], v[104:105], 4, v[112:113]
	v_or_b32_e32 v104, v100, v116
	v_lshl_add_u64 v[90:91], v[104:105], 4, v[112:113]
	v_or_b32_e32 v104, v102, v168
	v_lshl_add_u64 v[100:101], v[104:105], 4, v[112:113]
	v_or_b32_e32 v104, v102, v116
	v_lshl_add_u64 v[102:103], v[104:105], 4, v[112:113]
	v_mfma_f32_32x32x16_bf16 v[0:15], v[72:75], v[80:83], v[0:15]
	v_or_b32_e32 v104, 16, v169
	v_lshlrev_b64 v[72:73], 9, v[104:105]
	v_or_b32_e32 v171, v72, v120
	v_or_b32_e32 v80, v72, v110
	v_or_b32_e32 v104, v72, v118
	v_or_b32_e32 v169, v72, v114
	v_or_b32_e32 v72, v171, v168
	s_waitcnt lgkmcnt(0)
	v_mfma_f32_32x32x16_bf16 v[48:63], v[84:87], v[76:79], v[48:63]
	v_mov_b32_e32 v75, v73
	v_mov_b32_e32 v81, v73
	v_mov_b32_e32 v83, v73
	v_mov_b32_e32 v173, v73
	v_mov_b32_e32 v175, v73
	v_mov_b32_e32 v181, v73
	v_or_b32_e32 v74, v80, v168
	v_mfma_f32_32x32x16_bf16 v[16:31], v[84:87], v[68:71], v[16:31]
	v_or_b32_e32 v80, v80, v116
	v_or_b32_e32 v82, v104, v168
	v_or_b32_e32 v172, v104, v116
	v_or_b32_e32 v174, v169, v168
	v_or_b32_e32 v180, v169, v116
	v_lshl_add_u64 v[86:87], v[72:73], 4, v[112:113]
	v_or_b32_e32 v72, v171, v116
	v_mfma_f32_32x32x16_bf16 v[32:47], v[64:67], v[76:79], v[32:47]
	v_cvt_pk_bf16_f32 v48, v48, v49
	v_cvt_pk_bf16_f32 v49, v50, v51
	v_lshl_add_u64 v[74:75], v[74:75], 4, v[112:113]
	v_lshl_add_u64 v[80:81], v[80:81], 4, v[112:113]
	v_lshl_add_u64 v[76:77], v[82:83], 4, v[112:113]
	v_lshl_add_u64 v[78:79], v[172:173], 4, v[112:113]
	v_lshl_add_u64 v[82:83], v[174:175], 4, v[112:113]
	v_mfma_f32_32x32x16_bf16 v[0:15], v[64:67], v[68:71], v[0:15]
	v_lshl_add_u64 v[84:85], v[180:181], 4, v[112:113]
	v_lshl_add_u64 v[72:73], v[72:73], 4, v[112:113]
	v_cvt_pk_bf16_f32 v50, v52, v53
	v_cvt_pk_bf16_f32 v51, v54, v55
	v_cvt_pk_bf16_f32 v52, v56, v57
	v_cvt_pk_bf16_f32 v53, v58, v59
	v_cvt_pk_bf16_f32 v54, v60, v61
	v_cvt_pk_bf16_f32 v55, v62, v63
	v_cvt_pk_bf16_f32 v32, v32, v33
	v_cvt_pk_bf16_f32 v33, v34, v35
	v_cvt_pk_bf16_f32 v34, v36, v37
	v_cvt_pk_bf16_f32 v35, v38, v39
	v_cvt_pk_bf16_f32 v36, v40, v41
	v_cvt_pk_bf16_f32 v37, v42, v43
	v_cvt_pk_bf16_f32 v38, v44, v45
	v_cvt_pk_bf16_f32 v39, v46, v47
	v_cvt_pk_bf16_f32 v16, v16, v17
	v_cvt_pk_bf16_f32 v17, v18, v19
	v_cvt_pk_bf16_f32 v18, v20, v21
	v_cvt_pk_bf16_f32 v19, v22, v23
	v_cvt_pk_bf16_f32 v20, v24, v25
	v_cvt_pk_bf16_f32 v21, v26, v27
	v_cvt_pk_bf16_f32 v22, v28, v29
	v_cvt_pk_bf16_f32 v23, v30, v31
	v_cvt_pk_bf16_f32 v0, v0, v1
	v_cvt_pk_bf16_f32 v1, v2, v3
	v_cvt_pk_bf16_f32 v2, v4, v5
	v_cvt_pk_bf16_f32 v3, v6, v7
	v_cvt_pk_bf16_f32 v4, v8, v9
	v_cvt_pk_bf16_f32 v5, v10, v11
	v_cvt_pk_bf16_f32 v6, v12, v13
	v_cvt_pk_bf16_f32 v7, v14, v15
	global_store_dwordx2 v[96:97], v[48:49], off
	global_store_dwordx2 v[92:93], v[50:51], off
	global_store_dwordx2 v[94:95], v[52:53], off
	global_store_dwordx2 v[98:99], v[54:55], off
	global_store_dwordx2 v[88:89], v[32:33], off
	global_store_dwordx2 v[90:91], v[34:35], off
	global_store_dwordx2 v[100:101], v[36:37], off
	global_store_dwordx2 v[102:103], v[38:39], off
	global_store_dwordx2 v[74:75], v[16:17], off
	global_store_dwordx2 v[80:81], v[18:19], off
	global_store_dwordx2 v[76:77], v[20:21], off
	global_store_dwordx2 v[78:79], v[22:23], off
	global_store_dwordx2 v[82:83], v[0:1], off
	global_store_dwordx2 v[84:85], v[2:3], off
	global_store_dwordx2 v[86:87], v[4:5], off
	global_store_dwordx2 v[72:73], v[6:7], off
	s_cbranch_scc1 .LBB0_906
	v_readlane_b32 s60, v255, 43
	v_readlane_b32 s61, v255, 44
